# speedup vs baseline: 1.0212x; 1.0111x over previous
; #define RS for (int rep_ = 0; rep_ < REPS; ++rep_)
; #define PH_BEGIN if (ph >= lo && ph < hi) {
; DEVI void convT(const float* __restrict__ src, int K, int N, bf16* __restrict__ dst, int ldd, int blk, int blk_stride,
;                 int row_off, const float* __restrict__ nscale, const float* __restrict__ kscale, float* lds) {
;   const int tid = threadIdx.x;
;   const int tilesN = (N + 63) / 64, tilesK = K / 64;
;   const int ntl = tilesN * tilesK;
;   const int lk = tid / 16, ln = (tid % 16) * 4;
;   int tile = blockIdx.x;
;   float4 c0 = make_float4(0.f, 0.f, 0.f, 0.f), c1 = c0;
;   if (tile < ntl) {
;     const int n0 = (tile % tilesN) * 64, k0 = (tile / tilesN) * 64;
;     if (n0 + ln < N) {
;       c0 = *reinterpret_cast<const float4*>(src + (long)(k0 + lk) * N + n0 + ln);
;       c1 = *reinterpret_cast<const float4*>(src + (long)(k0 + lk + 32) * N + n0 + ln);
;     }
;   }
; template <int L>
; DEVI void run_layer(const Params& p, const int lo, const int hi, int& ph, unsigned& nbar, cg::grid_group& grid, bf16* shm) {
;     ...
;   PH_BEGIN
;    RS {
;     if constexpr (type == 0) {
;       convT(p.in[base + 1], DM, DM, (bf16*)(ws + W_IN), DM, DM, 0, 0, nullptr, p.in[base], lds);
_Z4mega6Paramsii:
	s_load_dwordx8 s[24:31], s[0:1], 0x140
	s_load_dwordx16 s[8:23], s[0:1], 0x0
	s_load_dwordx16 s[80:95], s[0:1], 0x40
	v_writelane_b32 v250, s2, 0
	s_add_u32 s2, s0, 0x160
	s_addc_u32 s3, s1, 0
	v_writelane_b32 v250, s2, 1
	s_load_dword s33, s[0:1], 0x160
	v_bfe_u32 v162, v0, 3, 7
	v_writelane_b32 v250, s3, 2
	s_waitcnt lgkmcnt(0)
	s_add_u32 s2, s28, 0x6e00000
	s_addc_u32 s3, s29, 0
	s_add_u32 s96, s28, 0x7000000
	v_writelane_b32 v250, s2, 3
	s_addc_u32 s97, s29, 0
	v_bfe_u32 v1, v0, 4, 6
	v_writelane_b32 v250, s3, 4
	s_add_u32 s2, s28, 0x6c00000
	s_addc_u32 s3, s29, 0
	v_writelane_b32 v250, s2, 5
	s_cmp_gt_i32 s30, 0
	v_lshl_add_u32 v163, v162, 2, 0
	v_writelane_b32 v250, s3, 6
	s_mov_b32 s2, 0
	v_writelane_b32 v250, s2, 7
	s_cselect_b64 s[2:3], -1, 0
	s_cmp_lt_i32 s31, 1
	s_cselect_b64 s[4:5], -1, 0
	s_or_b64 s[2:3], s[2:3], s[4:5]
	s_and_b64 vcc, exec, s[2:3]
	s_cbranch_vccnz .LBB0_152
	v_readlane_b32 s4, v250, 0
	s_cmpk_lt_i32 s4, 0x400
	s_cselect_b64 s[6:7], -1, 0
	s_ashr_i32 s2, s4, 31
	s_lshr_b32 s2, s2, 27
	s_add_i32 s2, s4, s2
	v_and_b32_e32 v40, 0x3ff, v0
	s_and_b32 s3, s2, 0x3ffffe0
	s_lshl_b32 s2, s2, 1
	v_lshlrev_b32_e32 v2, 2, v40
	s_andn2_b32 s2, s2, 63
	v_and_b32_e32 v28, 60, v2
	v_or_b32_e32 v2, s2, v1
	v_ashrrev_i32_e32 v3, 31, v2
	v_lshlrev_b64 v[20:21], 13, v[2:3]
	v_mul_u32_u24_e32 v2, 0x41, v1
	s_sub_i32 s3, s4, s3
	v_lshlrev_b32_e32 v18, 2, v28
	v_lshlrev_b32_e32 v2, 2, v2
	s_lshl_b32 s34, s3, 6
	v_add3_u32 v30, 0, v18, v2
	v_add3_u32 v31, 0, v2, v18
	v_lshlrev_b32_e32 v2, 3, v40
	s_ashr_i32 s35, s34, 31
	v_and_b32_e32 v32, 56, v2
	v_or_b32_e32 v2, s34, v28
	s_movk_i32 s2, 0x800
	s_cmpk_gt_i32 s4, 0x3ff
	v_mov_b32_e32 v10, 0
	v_or_b32_e32 v22, 0x40000, v20
	v_mov_b32_e32 v23, v21
	v_mul_u32_u24_e32 v33, 0x104, v32
	v_cmp_gt_i32_e64 s[2:3], s2, v2
	s_cbranch_scc1 .LBB0_28
	v_mov_b32_e32 v11, 0
	v_mov_b32_e32 v12, 0
	v_mov_b32_e32 v13, 0
	v_mov_b32_e32 v14, 0
	v_mov_b32_e32 v15, 0
	v_mov_b32_e32 v16, 0
	v_mov_b32_e32 v17, 0
	s_and_saveexec_b64 s[4:5], s[2:3]
	s_cbranch_execz .LBB0_4
	s_lshl_b64 s[36:37], s[34:35], 2
	v_lshl_add_u64 v[4:5], s[12:13], 0, v[20:21]
	v_lshl_add_u64 v[2:3], s[12:13], 0, v[22:23]
	v_mov_b32_e32 v19, 0
	v_lshl_add_u64 v[4:5], v[4:5], 0, s[36:37]
	v_lshl_add_u64 v[2:3], v[2:3], 0, s[36:37]
	v_lshl_add_u64 v[4:5], v[4:5], 0, v[18:19]
	v_lshl_add_u64 v[2:3], v[2:3], 0, v[18:19]
	global_load_dwordx4 v[14:17], v[4:5], off nt
	global_load_dwordx4 v[10:13], v[2:3], off nt

; DEVI void convT(const float* __restrict__ src, int K, int N, bf16* __restrict__ dst, int ldd, int blk, int blk_stride,
;                 int row_off, const float* __restrict__ nscale, const float* __restrict__ kscale, float* lds) {
;     ...
;   while (tile < ntl) {
;     const int n0 = (tile % tilesN) * 64, k0 = (tile / tilesN) * 64;
;     const int nxt = tile + gridDim.x;
;     float4 d0 = make_float4(0.f, 0.f, 0.f, 0.f), d1 = d0;
;     if (nxt < ntl) {
;       const int n2 = (nxt % tilesN) * 64, k2 = (nxt / tilesN) * 64;
;       if (n2 + ln < N) {
;         d0 = *reinterpret_cast<const float4*>(src + (long)(k2 + lk) * N + n2 + ln);
;         d1 = *reinterpret_cast<const float4*>(src + (long)(k2 + lk + 32) * N + n2 + ln);
;       }
;     }
.LBB0_7:
	s_add_i32 s46, s43, s40
	s_cmpk_gt_i32 s46, 0x3ff
	s_cselect_b64 s[36:37], -1, 0
	s_and_b64 vcc, exec, s[36:37]
	v_mov_b32_e32 v6, 0
	v_mov_b32_e32 v7, 0
	v_mov_b32_e32 v8, 0
	v_mov_b32_e32 v9, 0
	v_mov_b32_e32 v2, 0
	v_mov_b32_e32 v3, 0
	v_mov_b32_e32 v4, 0
	v_mov_b32_e32 v5, 0
	s_cbranch_vccnz .LBB0_11
	s_ashr_i32 s38, s46, 31
	s_lshr_b32 s38, s38, 27
	s_add_i32 s38, s46, s38
	s_ashr_i32 s41, s38, 5
	s_lshl_b32 s47, s41, 11
	s_sub_i32 s38, s44, s47
	v_add_u32_e32 v2, s38, v26
	v_cmp_gt_i32_e32 vcc, s42, v2
	v_mov_b32_e32 v5, 0
	v_mov_b32_e32 v4, 0
	v_mov_b32_e32 v3, 0
	v_mov_b32_e32 v2, 0
	v_mov_b32_e32 v9, 0
	v_mov_b32_e32 v8, 0
	v_mov_b32_e32 v7, 0
	v_mov_b32_e32 v6, 0
	s_and_saveexec_b64 s[38:39], vcc
	s_cbranch_execz .LBB0_10
	v_lshl_or_b32 v2, s41, 6, v1
	s_sub_i32 s47, 0, s47
	s_add_i32 s48, s45, s44
	v_ashrrev_i32_e32 v3, 31, v2
	s_add_i32 s48, s48, s47
	v_lshlrev_b64 v[2:3], 13, v[2:3]
	v_lshl_add_u64 v[2:3], s[12:13], 0, v[2:3]
	s_ashr_i32 s49, s48, 31
	v_lshl_add_u64 v[2:3], s[48:49], 2, v[2:3]
	v_mov_b32_e32 v19, v25
	v_lshl_add_u64 v[2:3], v[2:3], 0, v[18:19]
	v_add_co_u32_e32 v6, vcc, 0x40000, v2
	s_nop 1
	v_addc_co_u32_e32 v7, vcc, 0, v3, vcc
	global_load_dwordx4 v[2:5], v[2:3], off nt
	s_nop 0
	global_load_dwordx4 v[6:9], v[6:7], off nt

; DEVI void convT(const float* __restrict__ src, int K, int N, bf16* __restrict__ dst, int ldd, int blk, int blk_stride,
;                 int row_off, const float* __restrict__ nscale, const float* __restrict__ kscale, float* lds) {
;     ...
;   if (tile < ntl) {
;     const int n0 = (tile % tilesN) * 64, k0 = (tile / tilesN) * 64;
;     if (n0 + ln < N) {
;       c0 = *reinterpret_cast<const float4*>(src + (long)(k0 + lk) * N + n0 + ln);
;       c1 = *reinterpret_cast<const float4*>(src + (long)(k0 + lk + 32) * N + n0 + ln);
;     }
;   }
.LBB0_31:
	s_or_b64 exec, exec, s[4:5]
	s_andn2_b64 vcc, exec, s[6:7]
	s_cbranch_vccnz .LBB0_58
	v_mov_b32_e32 v25, 0
	v_mov_b32_e32 v10, 0
	v_mov_b32_e32 v11, 0
	v_mov_b32_e32 v12, 0
	v_mov_b32_e32 v13, 0
	v_mov_b32_e32 v14, 0
	v_mov_b32_e32 v15, 0
	v_mov_b32_e32 v16, 0
	v_mov_b32_e32 v17, 0
	s_and_saveexec_b64 s[4:5], s[2:3]
	s_cbranch_execz .LBB0_34
	s_lshl_b64 s[6:7], s[34:35], 2
	v_lshl_add_u64 v[4:5], s[18:19], 0, v[20:21]
	v_lshl_add_u64 v[2:3], s[18:19], 0, v[22:23]
	v_mov_b32_e32 v19, 0
	v_lshl_add_u64 v[4:5], v[4:5], 0, s[6:7]
	v_lshl_add_u64 v[2:3], v[2:3], 0, s[6:7]
	v_lshl_add_u64 v[4:5], v[4:5], 0, v[18:19]
	v_lshl_add_u64 v[2:3], v[2:3], 0, v[18:19]
	global_load_dwordx4 v[14:17], v[4:5], off nt
	global_load_dwordx4 v[10:13], v[2:3], off nt

; DEVI void convT(const float* __restrict__ src, int K, int N, bf16* __restrict__ dst, int ldd, int blk, int blk_stride,
;                 int row_off, const float* __restrict__ nscale, const float* __restrict__ kscale, float* lds) {
;     ...
;   while (tile < ntl) {
;     const int n0 = (tile % tilesN) * 64, k0 = (tile / tilesN) * 64;
;     const int nxt = tile + gridDim.x;
;     float4 d0 = make_float4(0.f, 0.f, 0.f, 0.f), d1 = d0;
;     if (nxt < ntl) {
;       const int n2 = (nxt % tilesN) * 64, k2 = (nxt / tilesN) * 64;
;       if (n2 + ln < N) {
;         d0 = *reinterpret_cast<const float4*>(src + (long)(k2 + lk) * N + n2 + ln);
;         d1 = *reinterpret_cast<const float4*>(src + (long)(k2 + lk + 32) * N + n2 + ln);
;       }
;     }
.LBB0_37:
	s_add_i32 s40, s36, s14
	s_cmpk_gt_i32 s40, 0x3ff
	s_cselect_b64 s[10:11], -1, 0
	v_mov_b32_e32 v2, 0
	s_and_b64 vcc, exec, s[10:11]
	v_mov_b32_e32 v3, 0
	v_mov_b32_e32 v4, 0
	v_mov_b32_e32 v5, 0
	v_mov_b32_e32 v6, 0
	v_mov_b32_e32 v7, 0
	v_mov_b32_e32 v8, 0
	v_mov_b32_e32 v9, 0
	s_cbranch_vccnz .LBB0_41
	s_ashr_i32 s12, s40, 31
	s_lshr_b32 s12, s12, 27
	s_add_i32 s12, s40, s12
	s_ashr_i32 s15, s12, 5
	s_lshl_b32 s41, s15, 11
	s_sub_i32 s12, s37, s41
	v_add_u32_e32 v2, s12, v26
	v_cmp_gt_i32_e32 vcc, s39, v2
	v_mov_b32_e32 v9, 0
	v_mov_b32_e32 v8, 0
	v_mov_b32_e32 v7, 0
	v_mov_b32_e32 v6, 0
	v_mov_b32_e32 v5, 0
	v_mov_b32_e32 v4, 0
	v_mov_b32_e32 v3, 0
	v_mov_b32_e32 v2, 0
	s_and_saveexec_b64 s[12:13], vcc
	s_cbranch_execz .LBB0_40
	v_lshl_or_b32 v2, s15, 6, v1
	s_sub_i32 s41, 0, s41
	s_add_i32 s42, s38, s37
	v_ashrrev_i32_e32 v3, 31, v2
	s_add_i32 s42, s42, s41
	v_lshlrev_b64 v[2:3], 13, v[2:3]
	v_lshl_add_u64 v[2:3], s[18:19], 0, v[2:3]
	s_ashr_i32 s43, s42, 31
	v_lshl_add_u64 v[2:3], s[42:43], 2, v[2:3]
	v_mov_b32_e32 v19, v25
	v_lshl_add_u64 v[2:3], v[2:3], 0, v[18:19]
	v_add_co_u32_e32 v4, vcc, 0x40000, v2
	s_nop 1
	v_addc_co_u32_e32 v5, vcc, 0, v3, vcc
	global_load_dwordx4 v[6:9], v[2:3], off nt
	s_nop 0
	global_load_dwordx4 v[2:5], v[4:5], off nt

; DEVI void convT(const float* __restrict__ src, int K, int N, bf16* __restrict__ dst, int ldd, int blk, int blk_stride,
;                 int row_off, const float* __restrict__ nscale, const float* __restrict__ kscale, float* lds) {
;     ...
;   if (tile < ntl) {
;     const int n0 = (tile % tilesN) * 64, k0 = (tile / tilesN) * 64;
;     if (n0 + ln < N) {
;       c0 = *reinterpret_cast<const float4*>(src + (long)(k0 + lk) * N + n0 + ln);
;       c1 = *reinterpret_cast<const float4*>(src + (long)(k0 + lk + 32) * N + n0 + ln);
;     }
;   }
; DEVI void convert_ffn(const Params& p, int ig, bf16* shm) {
;   float* lds = reinterpret_cast<float*>(shm);
;   convT(p.in[ig], DM, DFF, (bf16*)(p.ws + W_GU), DM, 128, 256, 0, nullptr, p.in[ig - 1], lds);
.LBB0_60:
	s_andn2_b64 vcc, exec, s[4:5]
	s_cbranch_vccnz .LBB0_123
	v_readlane_b32 s6, v250, 0
	s_mul_hi_i32 s4, s6, 0x2e8ba2e9
	s_lshr_b32 s5, s4, 31
	s_ashr_i32 s4, s4, 4
	s_add_i32 s4, s4, s5
	s_mul_i32 s5, s4, 0x58
	s_sub_i32 s5, s6, s5
	s_lshl_b32 s12, s5, 6
	v_or_b32_e32 v2, s12, v28
	s_movk_i32 s39, 0x1600
	v_cmp_gt_i32_e64 s[6:7], s39, v2
	v_lshl_or_b32 v2, s4, 6, v1
	s_movk_i32 s40, 0x5800
	v_mad_i64_i32 v[24:25], s[4:5], v2, s40, 0
	v_add_u32_e32 v2, 32, v2
	s_ashr_i32 s13, s12, 31
	v_mad_i64_i32 v[26:27], s[4:5], v2, s40, 0
	v_mov_b32_e32 v29, 0
	v_mov_b32_e32 v10, 0
	v_mov_b32_e32 v11, 0
	v_mov_b32_e32 v12, 0
	v_mov_b32_e32 v13, 0
	v_mov_b32_e32 v14, 0
	v_mov_b32_e32 v15, 0
	v_mov_b32_e32 v16, 0
	v_mov_b32_e32 v17, 0
	s_and_saveexec_b64 s[4:5], s[6:7]
	s_cbranch_execz .LBB0_63
	s_lshl_b64 s[10:11], s[12:13], 2
	v_lshl_add_u64 v[4:5], s[22:23], 0, v[24:25]
	v_lshl_add_u64 v[2:3], s[22:23], 0, v[26:27]
	v_mov_b32_e32 v19, 0
	v_lshl_add_u64 v[4:5], v[4:5], 0, s[10:11]
	v_lshl_add_u64 v[2:3], v[2:3], 0, s[10:11]
	v_lshl_add_u64 v[4:5], v[4:5], 0, v[18:19]
	v_lshl_add_u64 v[2:3], v[2:3], 0, v[18:19]
	global_load_dwordx4 v[14:17], v[4:5], off nt
	global_load_dwordx4 v[10:13], v[2:3], off nt

; DEVI void convT(const float* __restrict__ src, int K, int N, bf16* __restrict__ dst, int ldd, int blk, int blk_stride,
;                 int row_off, const float* __restrict__ nscale, const float* __restrict__ kscale, float* lds) {
;     ...
;   while (tile < ntl) {
;     const int n0 = (tile % tilesN) * 64, k0 = (tile / tilesN) * 64;
;     const int nxt = tile + gridDim.x;
;     float4 d0 = make_float4(0.f, 0.f, 0.f, 0.f), d1 = d0;
;     if (nxt < ntl) {
;       const int n2 = (nxt % tilesN) * 64, k2 = (nxt / tilesN) * 64;
;       if (n2 + ln < N) {
;         d0 = *reinterpret_cast<const float4*>(src + (long)(k2 + lk) * N + n2 + ln);
;         d1 = *reinterpret_cast<const float4*>(src + (long)(k2 + lk + 32) * N + n2 + ln);
;       }
;     }
.LBB0_66:
	s_add_i32 s42, s36, s18
	s_cmpk_gt_i32 s42, 0xaff
	s_cselect_b64 s[14:15], -1, 0
	v_mov_b32_e32 v2, 0
	s_and_b64 vcc, exec, s[14:15]
	v_mov_b32_e32 v3, 0
	v_mov_b32_e32 v4, 0
	v_mov_b32_e32 v5, 0
	v_mov_b32_e32 v6, 0
	v_mov_b32_e32 v7, 0
	v_mov_b32_e32 v8, 0
	v_mov_b32_e32 v9, 0
	s_cbranch_vccnz .LBB0_70
	s_mul_hi_i32 s16, s42, 0x2e8ba2e9
	s_lshr_b32 s17, s16, 31
	s_ashr_i32 s19, s16, 4
	s_add_i32 s19, s19, s17
	s_mul_i32 s43, s19, 0xffffea00
	s_add_i32 s16, s43, s41
	v_add_u32_e32 v2, s16, v34
	v_cmp_gt_i32_e32 vcc, s39, v2
	v_mov_b32_e32 v9, 0
	v_mov_b32_e32 v8, 0
	v_mov_b32_e32 v7, 0
	v_mov_b32_e32 v6, 0
	v_mov_b32_e32 v5, 0
	v_mov_b32_e32 v4, 0
	v_mov_b32_e32 v3, 0
	v_mov_b32_e32 v2, 0
	s_and_saveexec_b64 s[16:17], vcc
	s_cbranch_execz .LBB0_69
	s_add_i32 s44, s38, s41
	s_add_i32 s44, s44, s43
	v_lshl_or_b32 v6, s19, 6, v1
	v_mov_b64_e32 v[2:3], s[22:23]
	v_mad_i64_i32 v[4:5], s[46:47], v6, s40, v[2:3]
	s_ashr_i32 s45, s44, 31
	v_add_u32_e32 v6, 32, v6
	s_lshl_b64 s[44:45], s[44:45], 2
	v_mad_i64_i32 v[2:3], s[46:47], v6, s40, v[2:3]
	v_lshl_add_u64 v[4:5], v[4:5], 0, s[44:45]
	v_mov_b32_e32 v19, v29
	v_lshl_add_u64 v[2:3], v[2:3], 0, s[44:45]
	v_lshl_add_u64 v[4:5], v[4:5], 0, v[18:19]
	v_lshl_add_u64 v[2:3], v[2:3], 0, v[18:19]
	global_load_dwordx4 v[6:9], v[4:5], off nt
	s_nop 0
	global_load_dwordx4 v[2:5], v[2:3], off nt

; DEVI void convT(const float* __restrict__ src, int K, int N, bf16* __restrict__ dst, int ldd, int blk, int blk_stride,
;                 int row_off, const float* __restrict__ nscale, const float* __restrict__ kscale, float* lds) {
;     ...
;   if (tile < ntl) {
;     const int n0 = (tile % tilesN) * 64, k0 = (tile / tilesN) * 64;
;     if (n0 + ln < N) {
;       c0 = *reinterpret_cast<const float4*>(src + (long)(k0 + lk) * N + n0 + ln);
;       c1 = *reinterpret_cast<const float4*>(src + (long)(k0 + lk + 32) * N + n0 + ln);
;     }
;   }
; DEVI void convert_ffn(const Params& p, int ig, bf16* shm) {
;     ...
;   convT(p.in[ig + 1], DM, DFF, (bf16*)(p.ws + W_GU), DM, 128, 256, 128, nullptr, p.in[ig - 1], lds);
.LBB0_87:
	v_mov_b32_e32 v29, 0
	v_mov_b32_e32 v10, 0
	v_mov_b32_e32 v11, 0
	v_mov_b32_e32 v12, 0
	v_mov_b32_e32 v13, 0
	v_mov_b32_e32 v14, 0
	v_mov_b32_e32 v15, 0
	v_mov_b32_e32 v16, 0
	v_mov_b32_e32 v17, 0
	s_and_saveexec_b64 s[14:15], s[6:7]
	s_cbranch_execz .LBB0_89
	s_lshl_b64 s[6:7], s[12:13], 2
	v_lshl_add_u64 v[4:5], s[80:81], 0, v[24:25]
	v_lshl_add_u64 v[2:3], s[80:81], 0, v[26:27]
	v_mov_b32_e32 v19, 0
	v_lshl_add_u64 v[4:5], v[4:5], 0, s[6:7]
	v_lshl_add_u64 v[2:3], v[2:3], 0, s[6:7]
	v_lshl_add_u64 v[4:5], v[4:5], 0, v[18:19]
	v_lshl_add_u64 v[2:3], v[2:3], 0, v[18:19]
	global_load_dwordx4 v[10:13], v[4:5], off nt
	global_load_dwordx4 v[14:17], v[2:3], off nt

; DEVI void convT(const float* __restrict__ src, int K, int N, bf16* __restrict__ dst, int ldd, int blk, int blk_stride,
;                 int row_off, const float* __restrict__ nscale, const float* __restrict__ kscale, float* lds) {
;     ...
;   while (tile < ntl) {
;     const int n0 = (tile % tilesN) * 64, k0 = (tile / tilesN) * 64;
;     const int nxt = tile + gridDim.x;
;     float4 d0 = make_float4(0.f, 0.f, 0.f, 0.f), d1 = d0;
;     if (nxt < ntl) {
;       const int n2 = (nxt % tilesN) * 64, k2 = (nxt / tilesN) * 64;
;       if (n2 + ln < N) {
;         d0 = *reinterpret_cast<const float4*>(src + (long)(k2 + lk) * N + n2 + ln);
;         d1 = *reinterpret_cast<const float4*>(src + (long)(k2 + lk + 32) * N + n2 + ln);
;       }
;     }
.LBB0_92:
	s_add_i32 s19, s14, s36
	s_cmpk_gt_i32 s19, 0xaff
	s_cselect_b64 s[6:7], -1, 0
	v_mov_b32_e32 v2, 0
	s_and_b64 vcc, exec, s[6:7]
	v_mov_b32_e32 v3, 0
	v_mov_b32_e32 v4, 0
	v_mov_b32_e32 v5, 0
	v_mov_b32_e32 v6, 0
	v_mov_b32_e32 v7, 0
	v_mov_b32_e32 v8, 0
	v_mov_b32_e32 v9, 0
	s_cbranch_vccnz .LBB0_96
	s_mul_hi_i32 s12, s19, 0x2e8ba2e9
	s_lshr_b32 s13, s12, 31
	s_ashr_i32 s15, s12, 4
	s_add_i32 s15, s15, s13
	s_mul_i32 s22, s15, 0xffffea00
	s_add_i32 s12, s22, s18
	v_add_u32_e32 v2, s12, v34
	v_cmp_gt_i32_e32 vcc, s16, v2
	v_mov_b32_e32 v9, 0
	v_mov_b32_e32 v8, 0
	v_mov_b32_e32 v7, 0
	v_mov_b32_e32 v6, 0
	v_mov_b32_e32 v5, 0
	v_mov_b32_e32 v4, 0
	v_mov_b32_e32 v3, 0
	v_mov_b32_e32 v2, 0
	s_and_saveexec_b64 s[12:13], vcc
	s_cbranch_execz .LBB0_95
	s_add_i32 s23, s38, s18
	s_add_i32 s22, s23, s22
	v_lshl_or_b32 v6, s15, 6, v1
	v_mov_b64_e32 v[2:3], s[80:81]
	v_mad_i64_i32 v[4:5], s[40:41], v6, s17, v[2:3]
	s_ashr_i32 s23, s22, 31
	v_add_u32_e32 v6, 32, v6
	s_lshl_b64 s[22:23], s[22:23], 2
	v_mad_i64_i32 v[2:3], s[40:41], v6, s17, v[2:3]
	v_lshl_add_u64 v[4:5], v[4:5], 0, s[22:23]
	v_mov_b32_e32 v19, v29
	v_lshl_add_u64 v[2:3], v[2:3], 0, s[22:23]
	v_lshl_add_u64 v[4:5], v[4:5], 0, v[18:19]
	v_lshl_add_u64 v[2:3], v[2:3], 0, v[18:19]
	global_load_dwordx4 v[6:9], v[4:5], off nt
	s_nop 0
	global_load_dwordx4 v[2:5], v[2:3], off nt

; DEVI void convT(const float* __restrict__ src, int K, int N, bf16* __restrict__ dst, int ldd, int blk, int blk_stride,
;                 int row_off, const float* __restrict__ nscale, const float* __restrict__ kscale, float* lds) {
;     ...
;   if (tile < ntl) {
;     const int n0 = (tile % tilesN) * 64, k0 = (tile / tilesN) * 64;
;     if (n0 + ln < N) {
;       c0 = *reinterpret_cast<const float4*>(src + (long)(k0 + lk) * N + n0 + ln);
;       c1 = *reinterpret_cast<const float4*>(src + (long)(k0 + lk + 32) * N + n0 + ln);
;     }
;   }
; DEVI void convert_ffn(const Params& p, int ig, bf16* shm) {
;     ...
;   convT(p.in[ig + 2], DFF, DM, (bf16*)(p.ws + W_DN), DFF, DM, 0, 0, nullptr, nullptr, lds);
.LBB0_113:
	v_mov_b32_e32 v19, 0
	v_mov_b32_e32 v2, v19
	v_mov_b32_e32 v3, v19
	v_mov_b32_e32 v4, v19
	v_mov_b32_e32 v5, v19
	v_mov_b32_e32 v6, v19
	v_mov_b32_e32 v7, v19
	v_mov_b32_e32 v8, v19
	v_mov_b32_e32 v9, v19
	s_and_saveexec_b64 s[4:5], s[2:3]
	s_cbranch_execz .LBB0_115
	v_lshl_add_u64 v[2:3], s[82:83], 0, v[22:23]
	s_lshl_b64 s[2:3], s[34:35], 2
	v_lshl_add_u64 v[2:3], v[2:3], 0, s[2:3]
	v_mov_b32_e32 v5, 0
	v_mov_b32_e32 v4, v18
	v_lshl_add_u64 v[10:11], v[2:3], 0, v[4:5]
	v_lshl_add_u64 v[2:3], s[82:83], 0, v[20:21]
	v_lshl_add_u64 v[2:3], v[2:3], 0, s[2:3]
	v_lshl_add_u64 v[12:13], v[2:3], 0, v[4:5]
	global_load_dwordx4 v[2:5], v[12:13], off nt
	global_load_dwordx4 v[6:9], v[10:11], off nt

; DEVI void convT(const float* __restrict__ src, int K, int N, bf16* __restrict__ dst, int ldd, int blk, int blk_stride,
;                 int row_off, const float* __restrict__ nscale, const float* __restrict__ kscale, float* lds) {
;     ...
;   while (tile < ntl) {
;     const int n0 = (tile % tilesN) * 64, k0 = (tile / tilesN) * 64;
;     const int nxt = tile + gridDim.x;
;     float4 d0 = make_float4(0.f, 0.f, 0.f, 0.f), d1 = d0;
;     if (nxt < ntl) {
;       const int n2 = (nxt % tilesN) * 64, k2 = (nxt / tilesN) * 64;
;       if (n2 + ln < N) {
;         d0 = *reinterpret_cast<const float4*>(src + (long)(k2 + lk) * N + n2 + ln);
;         d1 = *reinterpret_cast<const float4*>(src + (long)(k2 + lk + 32) * N + n2 + ln);
;       }
;     }
.LBB0_117:
	s_add_i32 s11, s12, s36
	s_cmpk_gt_i32 s11, 0xaff
	s_cselect_b64 s[4:5], -1, 0
	v_mov_b32_e32 v10, 0
	s_and_b64 vcc, exec, s[4:5]
	v_mov_b32_e32 v11, 0
	v_mov_b32_e32 v12, 0
	v_mov_b32_e32 v13, 0
	v_mov_b32_e32 v14, 0
	v_mov_b32_e32 v15, 0
	v_mov_b32_e32 v16, 0
	v_mov_b32_e32 v17, 0
	s_cbranch_vccnz .LBB0_121
	s_ashr_i32 s6, s11, 31
	s_lshr_b32 s6, s6, 27
	s_add_i32 s6, s11, s6
	s_ashr_i32 s13, s6, 5
	s_lshl_b32 s14, s13, 11
	s_sub_i32 s6, s37, s14
	v_add_u32_e32 v10, s6, v34
	v_cmp_gt_i32_e32 vcc, s10, v10
	v_mov_b32_e32 v17, 0
	v_mov_b32_e32 v16, 0
	v_mov_b32_e32 v15, 0
	v_mov_b32_e32 v14, 0
	v_mov_b32_e32 v13, 0
	v_mov_b32_e32 v12, 0
	v_mov_b32_e32 v11, 0
	v_mov_b32_e32 v10, 0
	s_and_saveexec_b64 s[6:7], vcc
	s_cbranch_execz .LBB0_120
	v_lshl_or_b32 v10, s13, 6, v1
	s_sub_i32 s14, 0, s14
	s_add_i32 s15, s38, s37
	v_ashrrev_i32_e32 v11, 31, v10
	s_add_i32 s14, s15, s14
	v_lshlrev_b64 v[10:11], 13, v[10:11]
	v_lshl_add_u64 v[10:11], s[82:83], 0, v[10:11]
	s_ashr_i32 s15, s14, 31
	v_lshl_add_u64 v[10:11], s[14:15], 2, v[10:11]
	v_lshl_add_u64 v[26:27], v[10:11], 0, v[18:19]
	v_add_co_u32_e32 v28, vcc, 0x40000, v26
	s_nop 1
	v_addc_co_u32_e32 v29, vcc, 0, v27, vcc
	global_load_dwordx4 v[14:17], v[26:27], off nt
	global_load_dwordx4 v[10:13], v[28:29], off nt

; DEVI void phase_xb(const float* __restrict__ x, bf16* __restrict__ H, float* __restrict__ st) {
;   const int wave = threadIdx.x >> 6, lane = threadIdx.x & 63;
;   for (int row = blockIdx.x * 8 + wave; row < TOK; row += gridDim.x * 8) {
;     const float4* xr = reinterpret_cast<const float4*>(x + (long)row * DM);
;     float4 v[8]; float ss = 0.f;
; #pragma unroll
;     for (int i = 0; i < 8; ++i) { v[i] = xr[lane + i * 64]; ss += v[i].x * v[i].x + v[i].y * v[i].y + v[i].z * v[i].z + v[i].w * v[i].w; }
;     ss = wave_sum(ss);
;     if (lane < 16) st[lane * TOK + row] = (lane == 0) ? ss : 0.f;
; #pragma unroll
.LBB0_126:
	v_ashrrev_i32_e32 v35, 31, v34
	v_lshlrev_b64 v[2:3], 13, v[34:35]
	v_lshl_add_u64 v[18:19], v[36:37], 0, v[2:3]
	global_load_dwordx4 v[2:5], v[18:19], off nt
	global_load_dwordx4 v[6:9], v[18:19], off offset:1024 nt
	global_load_dwordx4 v[10:13], v[18:19], off offset:2048 nt
	global_load_dwordx4 v[14:17], v[18:19], off offset:3072 nt
	v_add_co_u32_e64 v48, s[4:5], s13, v18
	s_waitcnt vmcnt(1)
	v_mul_f32_e32 v50, v11, v11
	v_addc_co_u32_e64 v49, s[4:5], 0, v19, s[4:5]
	global_load_dwordx4 v[18:21], v[48:49], off nt
	global_load_dwordx4 v[22:25], v[48:49], off offset:1024 nt
	global_load_dwordx4 v[26:29], v[48:49], off offset:2048 nt
	global_load_dwordx4 v[30:33], v[48:49], off offset:3072 nt
	v_mul_f32_e32 v48, v3, v3
	v_mul_f32_e32 v49, v7, v7
	v_fmac_f32_e32 v48, v2, v2
	v_fmac_f32_e32 v49, v6, v6
	s_waitcnt vmcnt(4)
	v_mul_f32_e32 v51, v15, v15
	v_fmac_f32_e32 v50, v10, v10
	v_fmac_f32_e32 v48, v4, v4
	v_fmac_f32_e32 v49, v8, v8
	v_fmac_f32_e32 v51, v14, v14
	v_fmac_f32_e32 v50, v12, v12
	v_fmac_f32_e32 v48, v5, v5
	v_fmac_f32_e32 v49, v9, v9
	v_fmac_f32_e32 v51, v16, v16
	v_fmac_f32_e32 v50, v13, v13
	v_add_f32_e32 v48, v48, v49
	v_fmac_f32_e32 v51, v17, v17
	v_add_f32_e32 v48, v48, v50
	v_add_f32_e32 v48, v48, v51
	s_waitcnt vmcnt(3)
	v_mul_f32_e32 v52, v19, v19
	s_waitcnt vmcnt(2)
	v_mul_f32_e32 v53, v23, v23
	v_fmac_f32_e32 v52, v18, v18
	s_waitcnt vmcnt(1)
	v_mul_f32_e32 v54, v27, v27
	v_fmac_f32_e32 v53, v22, v22
	v_fmac_f32_e32 v52, v20, v20
	s_waitcnt vmcnt(0)
	v_mul_f32_e32 v55, v31, v31
	v_fmac_f32_e32 v54, v26, v26
	v_fmac_f32_e32 v53, v24, v24
	v_fmac_f32_e32 v52, v21, v21
	v_fmac_f32_e32 v55, v30, v30
	v_fmac_f32_e32 v54, v28, v28
	v_fmac_f32_e32 v53, v25, v25
	v_add_f32_e32 v48, v48, v52
	v_fmac_f32_e32 v55, v32, v32
	v_fmac_f32_e32 v54, v29, v29
	v_add_f32_e32 v48, v48, v53
	v_add_f32_e32 v48, v48, v54
	v_fmac_f32_e32 v55, v33, v33
	v_add_f32_e32 v48, v48, v55
	ds_bpermute_b32 v49, v42, v48
	s_waitcnt lgkmcnt(0)
	v_add_f32_e32 v48, v48, v49
	ds_bpermute_b32 v49, v43, v48
	s_waitcnt lgkmcnt(0)
	v_add_f32_e32 v48, v48, v49
	ds_bpermute_b32 v49, v44, v48
	s_waitcnt lgkmcnt(0)
	v_add_f32_e32 v48, v48, v49
	ds_bpermute_b32 v49, v45, v48
	s_waitcnt lgkmcnt(0)
	v_add_f32_e32 v48, v48, v49
	ds_bpermute_b32 v49, v46, v48
	s_waitcnt lgkmcnt(0)
	v_add_f32_e32 v48, v48, v49
	ds_bpermute_b32 v49, v47, v48
	s_and_saveexec_b64 s[4:5], vcc
	s_cbranch_execz .LBB0_125
	v_add_u32_e32 v50, v41, v34
	v_readlane_b32 s16, v250, 5
	v_ashrrev_i32_e32 v51, 31, v50
	v_readlane_b32 s17, v250, 6
	s_waitcnt lgkmcnt(0)
	v_add_f32_e32 v48, v48, v49
	v_cndmask_b32_e64 v48, 0, v48, s[2:3]
	v_lshl_add_u64 v[50:51], v[50:51], 2, s[16:17]
	global_store_dword v[50:51], v48, off
	s_branch .LBB0_125

; template <int EPI, int NRM>
; DEVI void epilogue(acc_t& acc, int pn, int trow, const EpiArgs& e, const float* rl, bf16* shmx) {
;     ...
;   if constexpr (EPI == EPI_RESID) {
;     float ss[2][2] = {{0.f, 0.f}, {0.f, 0.f}};
;     __amdgpu_buffer_rsrc_t rsX = __builtin_amdgcn_make_buffer_rsrc((void*)e.xin, 0, 0x7fffffff, 0x00020000);
;     char* lbase = reinterpret_cast<char*>(shmx) + wid * 16384;
;     const int vx = ((tk0 * DM) + pn * 256 + fl0) * 4;
; #pragma unroll
;     for (int ai = 0; ai < 2; ++ai) {
; #pragma unroll
;       for (int bj = 0; bj < 2; ++bj)
; #pragma unroll
;         for (int m = 0; m < 4; ++m)
; #pragma unroll
;           for (int n = 0; n < 2; ++n) {
;             const int idx = (bj * 4 + m) * 2 + n;
;             const int so = ((bj * 128 + n * 16) * DM + ai * 128 + m * 16) * 4;
;             __builtin_amdgcn_raw_ptr_buffer_load_lds(rsX, (__attribute__((address_space(3))) unsigned*)(lbase + idx * 1024 + lane * 16), 16, vx, so, 0, 0);
;           }
;       asm volatile("s_waitcnt vmcnt(0)" ::: "memory");
; #pragma unroll
;       for (int bj = 0; bj < 2; ++bj)
; #pragma unroll
;         for (int m = 0; m < 4; ++m)
; #pragma unroll
;           for (int n = 0; n < 2; ++n) {
;             const int idx = (bj * 4 + m) * 2 + n;
;             const unsigned off = (unsigned)((tk0 + bj * 128 + n * 16) * DM + pn * 256 + ai * 128 + m * 16 + fl0);
;             const float4 xx = *reinterpret_cast<const float4*>(lbase + idx * 1024 + lane * 16);
;             float4 o;
;             o.x = xx.x + acc[ai][bj][m][n][0]; o.y = xx.y + acc[ai][bj][m][n][1];
;             o.z = xx.z + acc[ai][bj][m][n][2]; o.w = xx.w + acc[ai][bj][m][n][3];
;             *reinterpret_cast<float4*>(e.xout + off) = o;
;             uint2 ob; ob.x = pack2(o.x, o.y); ob.y = pack2(o.z, o.w);
;             *reinterpret_cast<uint2*>(e.o0 + off) = ob;
;             ss[bj][n] += o.x * o.x + o.y * o.y + o.z * o.z + o.w * o.w;
.LBB0_288:
	v_and_b32_e32 v138, 15, v134
	v_bfe_u32 v198, v134, 4, 2
	v_lshrrev_b32_e32 v199, 6, v134
	v_and_b32_e32 v200, 3, v199
	v_lshrrev_b32_e32 v201, 2, v199
	v_lshlrev_b32_e32 v202, 14, v199
	v_and_b32_e32 v203, 63, v134
	v_lshl_add_u32 v143, v203, 4, v202
	v_lshl_add_u32 v202, v138, 8, v202
	v_and_b32_e32 v203, 7, v138
	v_add_u32_e32 v204, 0, v198
	v_xor_b32_e32 v204, v204, v203
	v_lshl_add_u32 v139, v204, 4, v202
	v_add_u32_e32 v204, 4, v198
	v_xor_b32_e32 v204, v204, v203
	v_lshl_add_u32 v140, v204, 4, v202
	v_add_u32_e32 v204, 8, v198
	v_xor_b32_e32 v204, v204, v203
	v_lshl_add_u32 v141, v204, 4, v202
	v_add_u32_e32 v204, 12, v198
	v_xor_b32_e32 v204, v204, v203
	v_lshl_add_u32 v142, v204, 4, v202
	s_lshl_b32 s4, s10, 8
	v_lshl_add_u32 v202, v200, 5, v198
	v_add_u32_e32 v202, s4, v202
	s_lshl_b32 s4, s12, 1
	v_add_u32_e32 v204, s4, v201
	v_lshl_add_u32 v204, v204, 15, v202
	v_lshlrev_b32_e32 v148, 2, v204
	v_lshlrev_b32_e32 v202, 11, v202
	s_lshl_b32 s4, s12, 8
	v_lshl_add_u32 v204, v201, 6, s4
	v_add_u32_e32 v202, v202, v204
	v_add_u32_e32 v203, 0, v198
	v_xor_b32_e32 v203, v203, v138
	v_lshl_add_u32 v203, v203, 2, v202
	v_lshlrev_b32_e32 v144, 2, v203
	v_lshlrev_b32_e32 v146, 1, v203
	v_add_u32_e32 v203, 4, v198
	v_xor_b32_e32 v203, v203, v138
	v_lshl_add_u32 v203, v203, 2, v202
	v_lshlrev_b32_e32 v145, 2, v203
	v_lshlrev_b32_e32 v147, 1, v203
	v_readlane_b32 s10, v250, 24
	v_readlane_b32 s11, v250, 25
	v_add_u32_e32 v157, 0x0, v144
	global_load_dwordx4 v[166:169], v157, s[8:9] nt
	v_add_u32_e32 v160, 0x8000, v145
	global_load_dwordx4 v[170:173], v160, s[8:9] nt
	v_add_u32_e32 v157, 0x10000, v144
	global_load_dwordx4 v[174:177], v157, s[8:9] nt
	v_add_u32_e32 v160, 0x18000, v145
	global_load_dwordx4 v[178:181], v160, s[8:9] nt
	v_add_u32_e32 v157, 0x20000, v144
	global_load_dwordx4 v[182:185], v157, s[8:9] nt
	v_add_u32_e32 v160, 0x28000, v145
	global_load_dwordx4 v[186:189], v160, s[8:9] nt
	v_add_u32_e32 v157, 0x30000, v144
	global_load_dwordx4 v[190:193], v157, s[8:9] nt
	v_add_u32_e32 v160, 0x38000, v145
	global_load_dwordx4 v[194:197], v160, s[8:9] nt
	v_add_u32_e32 v157, 0x200, v144
	global_load_dwordx4 v[198:201], v157, s[8:9] nt
	v_add_u32_e32 v160, 0x8200, v145
	global_load_dwordx4 v[202:205], v160, s[8:9] nt
	v_add_u32_e32 v157, 0x10200, v144
	global_load_dwordx4 v[206:209], v157, s[8:9] nt
	v_add_u32_e32 v160, 0x18200, v145
	global_load_dwordx4 v[210:213], v160, s[8:9] nt
	v_add_u32_e32 v157, 0x20200, v144
	global_load_dwordx4 v[214:217], v157, s[8:9] nt
	v_add_u32_e32 v160, 0x28200, v145
	global_load_dwordx4 v[218:221], v160, s[8:9] nt
	v_add_u32_e32 v157, 0x30200, v144
	global_load_dwordx4 v[222:225], v157, s[8:9] nt
	v_add_u32_e32 v160, 0x38200, v145
	global_load_dwordx4 v[226:229], v160, s[8:9] nt
	ds_write_b128 v139, v[126:129]
	ds_write_b128 v139, v[22:25] offset:4096
	ds_write_b128 v140, v[122:125]
	ds_write_b128 v140, v[34:37] offset:4096
	ds_write_b128 v141, v[118:121]
	ds_write_b128 v141, v[46:49] offset:4096
	ds_write_b128 v142, v[114:117]
	ds_write_b128 v142, v[54:57] offset:4096
	ds_write_b128 v139, v[110:113] offset:8192
	ds_write_b128 v139, v[106:109] offset:12288
	ds_write_b128 v140, v[98:101] offset:8192
	ds_write_b128 v140, v[90:93] offset:12288
	ds_write_b128 v141, v[82:85] offset:8192
	ds_write_b128 v141, v[70:73] offset:12288
	ds_write_b128 v142, v[66:69] offset:8192
	ds_write_b128 v142, v[42:45] offset:12288
	s_waitcnt lgkmcnt(0)
	ds_read_b128 v[126:129], v143
	ds_read_b128 v[22:25], v143 offset:1024
	ds_read_b128 v[122:125], v143 offset:2048
	ds_read_b128 v[34:37], v143 offset:3072
	ds_read_b128 v[118:121], v143 offset:4096
	ds_read_b128 v[46:49], v143 offset:5120
	ds_read_b128 v[114:117], v143 offset:6144
	ds_read_b128 v[54:57], v143 offset:7168
	ds_read_b128 v[110:113], v143 offset:8192
	ds_read_b128 v[106:109], v143 offset:9216
	ds_read_b128 v[98:101], v143 offset:10240
	ds_read_b128 v[90:93], v143 offset:11264
	ds_read_b128 v[82:85], v143 offset:12288
	ds_read_b128 v[70:73], v143 offset:13312
	ds_read_b128 v[66:69], v143 offset:14336
	ds_read_b128 v[42:45], v143 offset:15360
	s_waitcnt lgkmcnt(0)
	ds_write_b128 v139, v[50:53]
	ds_write_b128 v139, v[58:61] offset:4096
	ds_write_b128 v140, v[62:65]
	ds_write_b128 v140, v[74:77] offset:4096
	ds_write_b128 v141, v[78:81]
	ds_write_b128 v141, v[86:89] offset:4096
	ds_write_b128 v142, v[94:97]
	ds_write_b128 v142, v[102:105] offset:4096
	ds_write_b128 v139, v[38:41] offset:8192
	ds_write_b128 v139, v[30:33] offset:12288
	ds_write_b128 v140, v[26:29] offset:8192
	ds_write_b128 v140, v[18:21] offset:12288
	ds_write_b128 v141, v[14:17] offset:8192
	ds_write_b128 v141, v[10:13] offset:12288
	ds_write_b128 v142, v[6:9] offset:8192
	ds_write_b128 v142, v[2:5] offset:12288
	s_waitcnt vmcnt(15)
	v_pk_add_f32 v[166:167], v[166:167], v[126:127]
	v_pk_add_f32 v[168:169], v[168:169], v[128:129]
	v_add_u32_e32 v157, 0x0, v144
	v_cvt_pk_bf16_f32 v158, v166, v167
	v_cvt_pk_bf16_f32 v159, v168, v169
	global_store_dwordx4 v157, v[166:169], s[26:27] nt
	v_add_u32_e32 v126, 0x0, v146
	v_mul_f32_e32 v149, v166, v166
	global_store_dwordx2 v126, v[158:159], s[96:97]
	v_fmac_f32_e32 v149, v167, v167
	v_fmac_f32_e32 v149, v168, v168
	v_fmac_f32_e32 v149, v169, v169
	s_waitcnt vmcnt(16)
	v_pk_add_f32 v[170:171], v[170:171], v[22:23]
	v_pk_add_f32 v[172:173], v[172:173], v[24:25]
	v_add_u32_e32 v160, 0x8000, v145
	v_cvt_pk_bf16_f32 v164, v170, v171
	v_cvt_pk_bf16_f32 v165, v172, v173
	global_store_dwordx4 v160, v[170:173], s[26:27] nt
	v_add_u32_e32 v22, 0x4000, v147
	v_mul_f32_e32 v150, v170, v170
	global_store_dwordx2 v22, v[164:165], s[96:97]
	v_fmac_f32_e32 v150, v171, v171
	v_fmac_f32_e32 v150, v172, v172
	v_fmac_f32_e32 v150, v173, v173
	s_waitcnt vmcnt(17)
; template <int EPI, int NRM>
; DEVI void epilogue(acc_t& acc, int pn, int trow, const EpiArgs& e, const float* rl, bf16* shmx) {
;     ...
; #pragma unroll
;       for (int bj = 0; bj < 2; ++bj)
; #pragma unroll
;         for (int m = 0; m < 4; ++m)
; #pragma unroll
;           for (int n = 0; n < 2; ++n) {
;             const int idx = (bj * 4 + m) * 2 + n;
;             const unsigned off = (unsigned)((tk0 + bj * 128 + n * 16) * DM + pn * 256 + ai * 128 + m * 16 + fl0);
;             const float4 xx = *reinterpret_cast<const float4*>(lbase + idx * 1024 + lane * 16);
;             float4 o;
;             o.x = xx.x + acc[ai][bj][m][n][0]; o.y = xx.y + acc[ai][bj][m][n][1];
;             o.z = xx.z + acc[ai][bj][m][n][2]; o.w = xx.w + acc[ai][bj][m][n][3];
;             *reinterpret_cast<float4*>(e.xout + off) = o;
;             uint2 ob; ob.x = pack2(o.x, o.y); ob.y = pack2(o.z, o.w);
;             *reinterpret_cast<uint2*>(e.o0 + off) = ob;
;             ss[bj][n] += o.x * o.x + o.y * o.y + o.z * o.z + o.w * o.w;
;           }
	v_pk_add_f32 v[174:175], v[174:175], v[122:123]
	v_pk_add_f32 v[176:177], v[176:177], v[124:125]
	v_add_u32_e32 v157, 0x10000, v144
	v_cvt_pk_bf16_f32 v158, v174, v175
	v_cvt_pk_bf16_f32 v159, v176, v177
	global_store_dwordx4 v157, v[174:177], s[26:27] nt
	v_add_u32_e32 v122, 0x8000, v146
	v_mul_f32_e32 v151, v174, v174
	global_store_dwordx2 v122, v[158:159], s[96:97]
	v_fmac_f32_e32 v151, v175, v175
	v_fmac_f32_e32 v151, v176, v176
	v_fmac_f32_e32 v151, v177, v177
	s_waitcnt vmcnt(18)
	v_pk_add_f32 v[178:179], v[178:179], v[34:35]
	v_pk_add_f32 v[180:181], v[180:181], v[36:37]
	v_add_u32_e32 v160, 0x18000, v145
	v_cvt_pk_bf16_f32 v164, v178, v179
	v_cvt_pk_bf16_f32 v165, v180, v181
	global_store_dwordx4 v160, v[178:181], s[26:27] nt
	v_add_u32_e32 v34, 0xc000, v147
	v_mul_f32_e32 v152, v178, v178
	global_store_dwordx2 v34, v[164:165], s[96:97]
	v_fmac_f32_e32 v152, v179, v179
	v_fmac_f32_e32 v152, v180, v180
	v_fmac_f32_e32 v152, v181, v181
	s_waitcnt vmcnt(19)
	v_pk_add_f32 v[182:183], v[182:183], v[118:119]
	v_pk_add_f32 v[184:185], v[184:185], v[120:121]
	v_add_u32_e32 v157, 0x20000, v144
	v_cvt_pk_bf16_f32 v158, v182, v183
	v_cvt_pk_bf16_f32 v159, v184, v185
	global_store_dwordx4 v157, v[182:185], s[26:27] nt
	v_add_u32_e32 v118, 0x10000, v146
	v_mul_f32_e32 v153, v182, v182
	global_store_dwordx2 v118, v[158:159], s[96:97]
	v_fmac_f32_e32 v153, v183, v183
	v_fmac_f32_e32 v153, v184, v184
	v_fmac_f32_e32 v153, v185, v185
	s_waitcnt vmcnt(20)
	v_pk_add_f32 v[186:187], v[186:187], v[46:47]
	v_pk_add_f32 v[188:189], v[188:189], v[48:49]
	v_add_u32_e32 v160, 0x28000, v145
	v_cvt_pk_bf16_f32 v164, v186, v187
	v_cvt_pk_bf16_f32 v165, v188, v189
	global_store_dwordx4 v160, v[186:189], s[26:27] nt
	v_add_u32_e32 v46, 0x14000, v147
	v_mul_f32_e32 v154, v186, v186
	global_store_dwordx2 v46, v[164:165], s[96:97]
	v_fmac_f32_e32 v154, v187, v187
	v_fmac_f32_e32 v154, v188, v188
	v_fmac_f32_e32 v154, v189, v189
	s_waitcnt vmcnt(21)
	v_pk_add_f32 v[190:191], v[190:191], v[114:115]
	v_pk_add_f32 v[192:193], v[192:193], v[116:117]
	v_add_u32_e32 v157, 0x30000, v144
	v_cvt_pk_bf16_f32 v158, v190, v191
	v_cvt_pk_bf16_f32 v159, v192, v193
	global_store_dwordx4 v157, v[190:193], s[26:27] nt
	v_add_u32_e32 v114, 0x18000, v146
	v_mul_f32_e32 v155, v190, v190
	global_store_dwordx2 v114, v[158:159], s[96:97]
	v_fmac_f32_e32 v155, v191, v191
	v_fmac_f32_e32 v155, v192, v192
	v_fmac_f32_e32 v155, v193, v193
	s_waitcnt vmcnt(22)
	v_pk_add_f32 v[194:195], v[194:195], v[54:55]
	v_pk_add_f32 v[196:197], v[196:197], v[56:57]
	v_add_u32_e32 v160, 0x38000, v145
	v_cvt_pk_bf16_f32 v164, v194, v195
	v_cvt_pk_bf16_f32 v165, v196, v197
	global_store_dwordx4 v160, v[194:197], s[26:27] nt
	v_add_u32_e32 v54, 0x1c000, v147
	v_mul_f32_e32 v156, v194, v194
	global_store_dwordx2 v54, v[164:165], s[96:97]
	v_fmac_f32_e32 v156, v195, v195
	v_fmac_f32_e32 v156, v196, v196
	v_fmac_f32_e32 v156, v197, v197
	v_add_u32_e32 v157, 0x100000, v144
	global_load_dwordx4 v[166:169], v157, s[8:9] nt
	v_add_u32_e32 v160, 0x108000, v145
	global_load_dwordx4 v[170:173], v160, s[8:9] nt
	v_add_u32_e32 v157, 0x110000, v144
	global_load_dwordx4 v[174:177], v157, s[8:9] nt
	v_add_u32_e32 v160, 0x118000, v145
	global_load_dwordx4 v[178:181], v160, s[8:9] nt
	v_add_u32_e32 v157, 0x120000, v144
	global_load_dwordx4 v[182:185], v157, s[8:9] nt
	v_add_u32_e32 v160, 0x128000, v145
	global_load_dwordx4 v[186:189], v160, s[8:9] nt
	v_add_u32_e32 v157, 0x130000, v144
	global_load_dwordx4 v[190:193], v157, s[8:9] nt
	v_add_u32_e32 v160, 0x138000, v145
	global_load_dwordx4 v[194:197], v160, s[8:9] nt
	s_waitcnt vmcnt(31)
	v_pk_add_f32 v[198:199], v[198:199], v[110:111]
	v_pk_add_f32 v[200:201], v[200:201], v[112:113]
	v_add_u32_e32 v157, 0x200, v144
	v_cvt_pk_bf16_f32 v158, v198, v199
	v_cvt_pk_bf16_f32 v159, v200, v201
	global_store_dwordx4 v157, v[198:201], s[26:27] nt
	v_add_u32_e32 v110, 0x100, v146
	v_fmac_f32_e32 v149, v198, v198
	global_store_dwordx2 v110, v[158:159], s[96:97]
	v_fmac_f32_e32 v149, v199, v199
	v_fmac_f32_e32 v149, v200, v200
	v_fmac_f32_e32 v149, v201, v201
	s_waitcnt vmcnt(32)
	v_pk_add_f32 v[202:203], v[202:203], v[106:107]
	v_pk_add_f32 v[204:205], v[204:205], v[108:109]
	v_add_u32_e32 v160, 0x8200, v145
	v_cvt_pk_bf16_f32 v164, v202, v203
	v_cvt_pk_bf16_f32 v165, v204, v205
	global_store_dwordx4 v160, v[202:205], s[26:27] nt
	v_add_u32_e32 v106, 0x4100, v147
	v_fmac_f32_e32 v150, v202, v202
	global_store_dwordx2 v106, v[164:165], s[96:97]
	v_fmac_f32_e32 v150, v203, v203
	v_fmac_f32_e32 v150, v204, v204
	v_fmac_f32_e32 v150, v205, v205
	s_waitcnt vmcnt(33)
	v_pk_add_f32 v[206:207], v[206:207], v[98:99]
	v_pk_add_f32 v[208:209], v[208:209], v[100:101]
	v_add_u32_e32 v157, 0x10200, v144
	v_cvt_pk_bf16_f32 v158, v206, v207
	v_cvt_pk_bf16_f32 v159, v208, v209
	global_store_dwordx4 v157, v[206:209], s[26:27] nt
	v_add_u32_e32 v98, 0x8100, v146
	v_fmac_f32_e32 v151, v206, v206
	global_store_dwordx2 v98, v[158:159], s[96:97]
	v_fmac_f32_e32 v151, v207, v207
	v_fmac_f32_e32 v151, v208, v208
	v_fmac_f32_e32 v151, v209, v209
	s_waitcnt vmcnt(34)
	v_pk_add_f32 v[210:211], v[210:211], v[90:91]
	v_pk_add_f32 v[212:213], v[212:213], v[92:93]
	v_add_u32_e32 v160, 0x18200, v145
	v_cvt_pk_bf16_f32 v164, v210, v211
	v_cvt_pk_bf16_f32 v165, v212, v213
	global_store_dwordx4 v160, v[210:213], s[26:27] nt
	v_add_u32_e32 v90, 0xc100, v147
	v_fmac_f32_e32 v152, v210, v210
	global_store_dwordx2 v90, v[164:165], s[96:97]
	v_fmac_f32_e32 v152, v211, v211
	v_fmac_f32_e32 v152, v212, v212
	v_fmac_f32_e32 v152, v213, v213
	s_waitcnt vmcnt(35)
; template <int EPI, int NRM>
; DEVI void epilogue(acc_t& acc, int pn, int trow, const EpiArgs& e, const float* rl, bf16* shmx) {
;     ...
;             const float4 xx = *reinterpret_cast<const float4*>(lbase + idx * 1024 + lane * 16);
;             float4 o;
;             o.x = xx.x + acc[ai][bj][m][n][0]; o.y = xx.y + acc[ai][bj][m][n][1];
;             o.z = xx.z + acc[ai][bj][m][n][2]; o.w = xx.w + acc[ai][bj][m][n][3];
;             *reinterpret_cast<float4*>(e.xout + off) = o;
;             uint2 ob; ob.x = pack2(o.x, o.y); ob.y = pack2(o.z, o.w);
;             *reinterpret_cast<uint2*>(e.o0 + off) = ob;
;             ss[bj][n] += o.x * o.x + o.y * o.y + o.z * o.z + o.w * o.w;
;           }
;       asm volatile("s_waitcnt lgkmcnt(0)" ::: "memory");
;     }
; #pragma unroll
;     for (int bj = 0; bj < 2; ++bj)
; #pragma unroll
;       for (int n = 0; n < 2; ++n) {
;         float v = ss[bj][n];
;         v += __shfl_xor(v, 16); v += __shfl_xor(v, 32);
;         if (fq == 0) e.stw[(pn * 2 + wr) * TOK + tk0 + bj * 128 + n * 16] = v;
;       }
	v_pk_add_f32 v[214:215], v[214:215], v[82:83]
	v_pk_add_f32 v[216:217], v[216:217], v[84:85]
	v_add_u32_e32 v157, 0x20200, v144
	v_cvt_pk_bf16_f32 v158, v214, v215
	v_cvt_pk_bf16_f32 v159, v216, v217
	global_store_dwordx4 v157, v[214:217], s[26:27] nt
	v_add_u32_e32 v82, 0x10100, v146
	v_fmac_f32_e32 v153, v214, v214
	global_store_dwordx2 v82, v[158:159], s[96:97]
	v_fmac_f32_e32 v153, v215, v215
	v_fmac_f32_e32 v153, v216, v216
	v_fmac_f32_e32 v153, v217, v217
	s_waitcnt vmcnt(36)
	v_pk_add_f32 v[218:219], v[218:219], v[70:71]
	v_pk_add_f32 v[220:221], v[220:221], v[72:73]
	v_add_u32_e32 v160, 0x28200, v145
	v_cvt_pk_bf16_f32 v164, v218, v219
	v_cvt_pk_bf16_f32 v165, v220, v221
	global_store_dwordx4 v160, v[218:221], s[26:27] nt
	v_add_u32_e32 v70, 0x14100, v147
	v_fmac_f32_e32 v154, v218, v218
	global_store_dwordx2 v70, v[164:165], s[96:97]
	v_fmac_f32_e32 v154, v219, v219
	v_fmac_f32_e32 v154, v220, v220
	v_fmac_f32_e32 v154, v221, v221
	s_waitcnt vmcnt(37)
	v_pk_add_f32 v[222:223], v[222:223], v[66:67]
	v_pk_add_f32 v[224:225], v[224:225], v[68:69]
	v_add_u32_e32 v157, 0x30200, v144
	v_cvt_pk_bf16_f32 v158, v222, v223
	v_cvt_pk_bf16_f32 v159, v224, v225
	global_store_dwordx4 v157, v[222:225], s[26:27] nt
	v_add_u32_e32 v66, 0x18100, v146
	v_fmac_f32_e32 v155, v222, v222
	global_store_dwordx2 v66, v[158:159], s[96:97]
	v_fmac_f32_e32 v155, v223, v223
	v_fmac_f32_e32 v155, v224, v224
	v_fmac_f32_e32 v155, v225, v225
	s_waitcnt vmcnt(38)
	v_pk_add_f32 v[226:227], v[226:227], v[42:43]
	v_pk_add_f32 v[228:229], v[228:229], v[44:45]
	v_add_u32_e32 v160, 0x38200, v145
	v_cvt_pk_bf16_f32 v164, v226, v227
	v_cvt_pk_bf16_f32 v165, v228, v229
	global_store_dwordx4 v160, v[226:229], s[26:27] nt
	v_add_u32_e32 v42, 0x1c100, v147
	v_fmac_f32_e32 v156, v226, v226
	global_store_dwordx2 v42, v[164:165], s[96:97]
	v_fmac_f32_e32 v156, v227, v227
	v_fmac_f32_e32 v156, v228, v228
	v_fmac_f32_e32 v156, v229, v229
	v_add_u32_e32 v157, 0x100200, v144
	global_load_dwordx4 v[198:201], v157, s[8:9] nt
	v_add_u32_e32 v160, 0x108200, v145
	global_load_dwordx4 v[202:205], v160, s[8:9] nt
	v_add_u32_e32 v157, 0x110200, v144
	global_load_dwordx4 v[206:209], v157, s[8:9] nt
	v_add_u32_e32 v160, 0x118200, v145
	global_load_dwordx4 v[210:213], v160, s[8:9] nt
	v_add_u32_e32 v157, 0x120200, v144
	global_load_dwordx4 v[214:217], v157, s[8:9] nt
	v_add_u32_e32 v160, 0x128200, v145
	global_load_dwordx4 v[218:221], v160, s[8:9] nt
	v_add_u32_e32 v157, 0x130200, v144
	global_load_dwordx4 v[222:225], v157, s[8:9] nt
	v_add_u32_e32 v160, 0x138200, v145
	global_load_dwordx4 v[226:229], v160, s[8:9] nt
	v_add_f32_dpp v149, v149, v149 row_shr:1 row_mask:0xf bank_mask:0xf bound_ctrl:0
	v_add_f32_dpp v150, v150, v150 row_shr:1 row_mask:0xf bank_mask:0xf bound_ctrl:0
	v_add_f32_dpp v151, v151, v151 row_shr:1 row_mask:0xf bank_mask:0xf bound_ctrl:0
	v_add_f32_dpp v152, v152, v152 row_shr:1 row_mask:0xf bank_mask:0xf bound_ctrl:0
	v_add_f32_dpp v153, v153, v153 row_shr:1 row_mask:0xf bank_mask:0xf bound_ctrl:0
	v_add_f32_dpp v154, v154, v154 row_shr:1 row_mask:0xf bank_mask:0xf bound_ctrl:0
	v_add_f32_dpp v155, v155, v155 row_shr:1 row_mask:0xf bank_mask:0xf bound_ctrl:0
	v_add_f32_dpp v156, v156, v156 row_shr:1 row_mask:0xf bank_mask:0xf bound_ctrl:0
	v_add_f32_dpp v149, v149, v149 row_shr:2 row_mask:0xf bank_mask:0xf bound_ctrl:0
	v_add_f32_dpp v150, v150, v150 row_shr:2 row_mask:0xf bank_mask:0xf bound_ctrl:0
	v_add_f32_dpp v151, v151, v151 row_shr:2 row_mask:0xf bank_mask:0xf bound_ctrl:0
	v_add_f32_dpp v152, v152, v152 row_shr:2 row_mask:0xf bank_mask:0xf bound_ctrl:0
	v_add_f32_dpp v153, v153, v153 row_shr:2 row_mask:0xf bank_mask:0xf bound_ctrl:0
	v_add_f32_dpp v154, v154, v154 row_shr:2 row_mask:0xf bank_mask:0xf bound_ctrl:0
	v_add_f32_dpp v155, v155, v155 row_shr:2 row_mask:0xf bank_mask:0xf bound_ctrl:0
	v_add_f32_dpp v156, v156, v156 row_shr:2 row_mask:0xf bank_mask:0xf bound_ctrl:0
	v_add_f32_dpp v149, v149, v149 row_shr:4 row_mask:0xf bank_mask:0xf bound_ctrl:0
	v_add_f32_dpp v150, v150, v150 row_shr:4 row_mask:0xf bank_mask:0xf bound_ctrl:0
	v_add_f32_dpp v151, v151, v151 row_shr:4 row_mask:0xf bank_mask:0xf bound_ctrl:0
	v_add_f32_dpp v152, v152, v152 row_shr:4 row_mask:0xf bank_mask:0xf bound_ctrl:0
	v_add_f32_dpp v153, v153, v153 row_shr:4 row_mask:0xf bank_mask:0xf bound_ctrl:0
	v_add_f32_dpp v154, v154, v154 row_shr:4 row_mask:0xf bank_mask:0xf bound_ctrl:0
	v_add_f32_dpp v155, v155, v155 row_shr:4 row_mask:0xf bank_mask:0xf bound_ctrl:0
	v_add_f32_dpp v156, v156, v156 row_shr:4 row_mask:0xf bank_mask:0xf bound_ctrl:0
	v_add_f32_dpp v149, v149, v149 row_shr:8 row_mask:0xf bank_mask:0xf bound_ctrl:0
	v_add_f32_dpp v150, v150, v150 row_shr:8 row_mask:0xf bank_mask:0xf bound_ctrl:0
	v_add_f32_dpp v151, v151, v151 row_shr:8 row_mask:0xf bank_mask:0xf bound_ctrl:0
	v_add_f32_dpp v152, v152, v152 row_shr:8 row_mask:0xf bank_mask:0xf bound_ctrl:0
	v_add_f32_dpp v153, v153, v153 row_shr:8 row_mask:0xf bank_mask:0xf bound_ctrl:0
	v_add_f32_dpp v154, v154, v154 row_shr:8 row_mask:0xf bank_mask:0xf bound_ctrl:0
	v_add_f32_dpp v155, v155, v155 row_shr:8 row_mask:0xf bank_mask:0xf bound_ctrl:0
	v_add_f32_dpp v156, v156, v156 row_shr:8 row_mask:0xf bank_mask:0xf bound_ctrl:0
	v_cmp_eq_u32_e32 vcc, 15, v138
	s_and_saveexec_b64 s[4:5], vcc
	global_store_dword v148, v149, s[10:11]
	global_store_dword v148, v150, s[10:11] offset:16
	global_store_dword v148, v151, s[10:11] offset:32
	global_store_dword v148, v152, s[10:11] offset:48
	global_store_dword v148, v153, s[10:11] offset:64
	global_store_dword v148, v154, s[10:11] offset:80
	global_store_dword v148, v155, s[10:11] offset:96
	global_store_dword v148, v156, s[10:11] offset:112
	s_or_b64 exec, exec, s[4:5]
	s_waitcnt lgkmcnt(0)
; template <int EPI, int NRM>
; DEVI void epilogue(acc_t& acc, int pn, int trow, const EpiArgs& e, const float* rl, bf16* shmx) {
;     ...
; #pragma unroll
;       for (int bj = 0; bj < 2; ++bj)
; #pragma unroll
;         for (int m = 0; m < 4; ++m)
; #pragma unroll
;           for (int n = 0; n < 2; ++n) {
;             const int idx = (bj * 4 + m) * 2 + n;
;             const unsigned off = (unsigned)((tk0 + bj * 128 + n * 16) * DM + pn * 256 + ai * 128 + m * 16 + fl0);
;             const float4 xx = *reinterpret_cast<const float4*>(lbase + idx * 1024 + lane * 16);
;             float4 o;
;             o.x = xx.x + acc[ai][bj][m][n][0]; o.y = xx.y + acc[ai][bj][m][n][1];
;             o.z = xx.z + acc[ai][bj][m][n][2]; o.w = xx.w + acc[ai][bj][m][n][3];
;             *reinterpret_cast<float4*>(e.xout + off) = o;
;             uint2 ob; ob.x = pack2(o.x, o.y); ob.y = pack2(o.z, o.w);
;             *reinterpret_cast<uint2*>(e.o0 + off) = ob;
;             ss[bj][n] += o.x * o.x + o.y * o.y + o.z * o.z + o.w * o.w;
;           }
	ds_read_b128 v[50:53], v143
	ds_read_b128 v[58:61], v143 offset:1024
	ds_read_b128 v[62:65], v143 offset:2048
	ds_read_b128 v[74:77], v143 offset:3072
	ds_read_b128 v[78:81], v143 offset:4096
	ds_read_b128 v[86:89], v143 offset:5120
	ds_read_b128 v[94:97], v143 offset:6144
	ds_read_b128 v[102:105], v143 offset:7168
	ds_read_b128 v[38:41], v143 offset:8192
	ds_read_b128 v[30:33], v143 offset:9216
	ds_read_b128 v[26:29], v143 offset:10240
	ds_read_b128 v[18:21], v143 offset:11264
	ds_read_b128 v[14:17], v143 offset:12288
	ds_read_b128 v[10:13], v143 offset:13312
	ds_read_b128 v[6:9], v143 offset:14336
	ds_read_b128 v[2:5], v143 offset:15360
	s_waitcnt lgkmcnt(0)
	s_waitcnt vmcnt(39)
	v_pk_add_f32 v[166:167], v[166:167], v[50:51]
	v_pk_add_f32 v[168:169], v[168:169], v[52:53]
	v_add_u32_e32 v157, 0x100000, v144
	v_cvt_pk_bf16_f32 v158, v166, v167
	v_cvt_pk_bf16_f32 v159, v168, v169
	global_store_dwordx4 v157, v[166:169], s[26:27] nt
	v_add_u32_e32 v50, 0x80000, v146
	v_mul_f32_e32 v149, v166, v166
	global_store_dwordx2 v50, v[158:159], s[96:97]
	v_fmac_f32_e32 v149, v167, v167
	v_fmac_f32_e32 v149, v168, v168
	v_fmac_f32_e32 v149, v169, v169
	s_waitcnt vmcnt(40)
	v_pk_add_f32 v[170:171], v[170:171], v[58:59]
	v_pk_add_f32 v[172:173], v[172:173], v[60:61]
	v_add_u32_e32 v160, 0x108000, v145
	v_cvt_pk_bf16_f32 v164, v170, v171
	v_cvt_pk_bf16_f32 v165, v172, v173
	global_store_dwordx4 v160, v[170:173], s[26:27] nt
	v_add_u32_e32 v58, 0x84000, v147
	v_mul_f32_e32 v150, v170, v170
	global_store_dwordx2 v58, v[164:165], s[96:97]
	v_fmac_f32_e32 v150, v171, v171
	v_fmac_f32_e32 v150, v172, v172
	v_fmac_f32_e32 v150, v173, v173
	s_waitcnt vmcnt(41)
	v_pk_add_f32 v[174:175], v[174:175], v[62:63]
	v_pk_add_f32 v[176:177], v[176:177], v[64:65]
	v_add_u32_e32 v157, 0x110000, v144
	v_cvt_pk_bf16_f32 v158, v174, v175
	v_cvt_pk_bf16_f32 v159, v176, v177
	global_store_dwordx4 v157, v[174:177], s[26:27] nt
	v_add_u32_e32 v62, 0x88000, v146
	v_mul_f32_e32 v151, v174, v174
	global_store_dwordx2 v62, v[158:159], s[96:97]
	v_fmac_f32_e32 v151, v175, v175
	v_fmac_f32_e32 v151, v176, v176
	v_fmac_f32_e32 v151, v177, v177
	s_waitcnt vmcnt(42)
	v_pk_add_f32 v[178:179], v[178:179], v[74:75]
	v_pk_add_f32 v[180:181], v[180:181], v[76:77]
	v_add_u32_e32 v160, 0x118000, v145
	v_cvt_pk_bf16_f32 v164, v178, v179
	v_cvt_pk_bf16_f32 v165, v180, v181
	global_store_dwordx4 v160, v[178:181], s[26:27] nt
	v_add_u32_e32 v74, 0x8c000, v147
	v_mul_f32_e32 v152, v178, v178
	global_store_dwordx2 v74, v[164:165], s[96:97]
	v_fmac_f32_e32 v152, v179, v179
	v_fmac_f32_e32 v152, v180, v180
	v_fmac_f32_e32 v152, v181, v181
	s_waitcnt vmcnt(43)
	v_pk_add_f32 v[182:183], v[182:183], v[78:79]
	v_pk_add_f32 v[184:185], v[184:185], v[80:81]
	v_add_u32_e32 v157, 0x120000, v144
	v_cvt_pk_bf16_f32 v158, v182, v183
	v_cvt_pk_bf16_f32 v159, v184, v185
	global_store_dwordx4 v157, v[182:185], s[26:27] nt
	v_add_u32_e32 v78, 0x90000, v146
	v_mul_f32_e32 v153, v182, v182
	global_store_dwordx2 v78, v[158:159], s[96:97]
	v_fmac_f32_e32 v153, v183, v183
	v_fmac_f32_e32 v153, v184, v184
	v_fmac_f32_e32 v153, v185, v185
	s_waitcnt vmcnt(44)
	v_pk_add_f32 v[186:187], v[186:187], v[86:87]
	v_pk_add_f32 v[188:189], v[188:189], v[88:89]
	v_add_u32_e32 v160, 0x128000, v145
	v_cvt_pk_bf16_f32 v164, v186, v187
	v_cvt_pk_bf16_f32 v165, v188, v189
	global_store_dwordx4 v160, v[186:189], s[26:27] nt
	v_add_u32_e32 v86, 0x94000, v147
	v_mul_f32_e32 v154, v186, v186
	global_store_dwordx2 v86, v[164:165], s[96:97]
	v_fmac_f32_e32 v154, v187, v187
	v_fmac_f32_e32 v154, v188, v188
	v_fmac_f32_e32 v154, v189, v189
	s_waitcnt vmcnt(45)
	v_pk_add_f32 v[190:191], v[190:191], v[94:95]
	v_pk_add_f32 v[192:193], v[192:193], v[96:97]
	v_add_u32_e32 v157, 0x130000, v144
	v_cvt_pk_bf16_f32 v158, v190, v191
	v_cvt_pk_bf16_f32 v159, v192, v193
	global_store_dwordx4 v157, v[190:193], s[26:27] nt
	v_add_u32_e32 v94, 0x98000, v146
	v_mul_f32_e32 v155, v190, v190
	global_store_dwordx2 v94, v[158:159], s[96:97]
	v_fmac_f32_e32 v155, v191, v191
	v_fmac_f32_e32 v155, v192, v192
	v_fmac_f32_e32 v155, v193, v193
	s_waitcnt vmcnt(46)
	v_pk_add_f32 v[194:195], v[194:195], v[102:103]
	v_pk_add_f32 v[196:197], v[196:197], v[104:105]
	v_add_u32_e32 v160, 0x138000, v145
	v_cvt_pk_bf16_f32 v164, v194, v195
	v_cvt_pk_bf16_f32 v165, v196, v197
	global_store_dwordx4 v160, v[194:197], s[26:27] nt
	v_add_u32_e32 v102, 0x9c000, v147
	v_mul_f32_e32 v156, v194, v194
	global_store_dwordx2 v102, v[164:165], s[96:97]
	v_fmac_f32_e32 v156, v195, v195
	v_fmac_f32_e32 v156, v196, v196
	v_fmac_f32_e32 v156, v197, v197
	s_waitcnt vmcnt(31)
	v_pk_add_f32 v[198:199], v[198:199], v[38:39]
	v_pk_add_f32 v[200:201], v[200:201], v[40:41]
	v_add_u32_e32 v157, 0x100200, v144
	v_cvt_pk_bf16_f32 v158, v198, v199
	v_cvt_pk_bf16_f32 v159, v200, v201
	global_store_dwordx4 v157, v[198:201], s[26:27] nt
	v_add_u32_e32 v38, 0x80100, v146
	v_fmac_f32_e32 v149, v198, v198
	global_store_dwordx2 v38, v[158:159], s[96:97]
	v_fmac_f32_e32 v149, v199, v199
	v_fmac_f32_e32 v149, v200, v200
	v_fmac_f32_e32 v149, v201, v201
	s_waitcnt vmcnt(32)
	v_pk_add_f32 v[202:203], v[202:203], v[30:31]
	v_pk_add_f32 v[204:205], v[204:205], v[32:33]
	v_add_u32_e32 v160, 0x108200, v145
	v_cvt_pk_bf16_f32 v164, v202, v203
	v_cvt_pk_bf16_f32 v165, v204, v205
	global_store_dwordx4 v160, v[202:205], s[26:27] nt
	v_add_u32_e32 v30, 0x84100, v147
	v_fmac_f32_e32 v150, v202, v202
	global_store_dwordx2 v30, v[164:165], s[96:97]
	v_fmac_f32_e32 v150, v203, v203
	v_fmac_f32_e32 v150, v204, v204
	v_fmac_f32_e32 v150, v205, v205
	s_waitcnt vmcnt(33)
; template <int EPI, int NRM>
; DEVI void epilogue(acc_t& acc, int pn, int trow, const EpiArgs& e, const float* rl, bf16* shmx) {
;     ...
;             const float4 xx = *reinterpret_cast<const float4*>(lbase + idx * 1024 + lane * 16);
;             float4 o;
;             o.x = xx.x + acc[ai][bj][m][n][0]; o.y = xx.y + acc[ai][bj][m][n][1];
;             o.z = xx.z + acc[ai][bj][m][n][2]; o.w = xx.w + acc[ai][bj][m][n][3];
;             *reinterpret_cast<float4*>(e.xout + off) = o;
;             uint2 ob; ob.x = pack2(o.x, o.y); ob.y = pack2(o.z, o.w);
;             *reinterpret_cast<uint2*>(e.o0 + off) = ob;
;             ss[bj][n] += o.x * o.x + o.y * o.y + o.z * o.z + o.w * o.w;
;           }
;       asm volatile("s_waitcnt lgkmcnt(0)" ::: "memory");
;     }
; #pragma unroll
;     for (int bj = 0; bj < 2; ++bj)
; #pragma unroll
;       for (int n = 0; n < 2; ++n) {
;         float v = ss[bj][n];
;         v += __shfl_xor(v, 16); v += __shfl_xor(v, 32);
;         if (fq == 0) e.stw[(pn * 2 + wr) * TOK + tk0 + bj * 128 + n * 16] = v;
;       }
	v_pk_add_f32 v[206:207], v[206:207], v[26:27]
	v_pk_add_f32 v[208:209], v[208:209], v[28:29]
	v_add_u32_e32 v157, 0x110200, v144
	v_cvt_pk_bf16_f32 v158, v206, v207
	v_cvt_pk_bf16_f32 v159, v208, v209
	global_store_dwordx4 v157, v[206:209], s[26:27] nt
	v_add_u32_e32 v26, 0x88100, v146
	v_fmac_f32_e32 v151, v206, v206
	global_store_dwordx2 v26, v[158:159], s[96:97]
	v_fmac_f32_e32 v151, v207, v207
	v_fmac_f32_e32 v151, v208, v208
	v_fmac_f32_e32 v151, v209, v209
	s_waitcnt vmcnt(34)
	v_pk_add_f32 v[210:211], v[210:211], v[18:19]
	v_pk_add_f32 v[212:213], v[212:213], v[20:21]
	v_add_u32_e32 v160, 0x118200, v145
	v_cvt_pk_bf16_f32 v164, v210, v211
	v_cvt_pk_bf16_f32 v165, v212, v213
	global_store_dwordx4 v160, v[210:213], s[26:27] nt
	v_add_u32_e32 v18, 0x8c100, v147
	v_fmac_f32_e32 v152, v210, v210
	global_store_dwordx2 v18, v[164:165], s[96:97]
	v_fmac_f32_e32 v152, v211, v211
	v_fmac_f32_e32 v152, v212, v212
	v_fmac_f32_e32 v152, v213, v213
	s_waitcnt vmcnt(35)
	v_pk_add_f32 v[214:215], v[214:215], v[14:15]
	v_pk_add_f32 v[216:217], v[216:217], v[16:17]
	v_add_u32_e32 v157, 0x120200, v144
	v_cvt_pk_bf16_f32 v158, v214, v215
	v_cvt_pk_bf16_f32 v159, v216, v217
	global_store_dwordx4 v157, v[214:217], s[26:27] nt
	v_add_u32_e32 v14, 0x90100, v146
	v_fmac_f32_e32 v153, v214, v214
	global_store_dwordx2 v14, v[158:159], s[96:97]
	v_fmac_f32_e32 v153, v215, v215
	v_fmac_f32_e32 v153, v216, v216
	v_fmac_f32_e32 v153, v217, v217
	s_waitcnt vmcnt(36)
	v_pk_add_f32 v[218:219], v[218:219], v[10:11]
	v_pk_add_f32 v[220:221], v[220:221], v[12:13]
	v_add_u32_e32 v160, 0x128200, v145
	v_cvt_pk_bf16_f32 v164, v218, v219
	v_cvt_pk_bf16_f32 v165, v220, v221
	global_store_dwordx4 v160, v[218:221], s[26:27] nt
	v_add_u32_e32 v10, 0x94100, v147
	v_fmac_f32_e32 v154, v218, v218
	global_store_dwordx2 v10, v[164:165], s[96:97]
	v_fmac_f32_e32 v154, v219, v219
	v_fmac_f32_e32 v154, v220, v220
	v_fmac_f32_e32 v154, v221, v221
	s_waitcnt vmcnt(37)
	v_pk_add_f32 v[222:223], v[222:223], v[6:7]
	v_pk_add_f32 v[224:225], v[224:225], v[8:9]
	v_add_u32_e32 v157, 0x130200, v144
	v_cvt_pk_bf16_f32 v158, v222, v223
	v_cvt_pk_bf16_f32 v159, v224, v225
	global_store_dwordx4 v157, v[222:225], s[26:27] nt
	v_add_u32_e32 v6, 0x98100, v146
	v_fmac_f32_e32 v155, v222, v222
	global_store_dwordx2 v6, v[158:159], s[96:97]
	v_fmac_f32_e32 v155, v223, v223
	v_fmac_f32_e32 v155, v224, v224
	v_fmac_f32_e32 v155, v225, v225
	s_waitcnt vmcnt(38)
	v_pk_add_f32 v[226:227], v[226:227], v[2:3]
	v_pk_add_f32 v[228:229], v[228:229], v[4:5]
	v_add_u32_e32 v160, 0x138200, v145
	v_cvt_pk_bf16_f32 v164, v226, v227
	v_cvt_pk_bf16_f32 v165, v228, v229
	global_store_dwordx4 v160, v[226:229], s[26:27] nt
	v_add_u32_e32 v2, 0x9c100, v147
	v_fmac_f32_e32 v156, v226, v226
	global_store_dwordx2 v2, v[164:165], s[96:97]
	v_fmac_f32_e32 v156, v227, v227
	v_fmac_f32_e32 v156, v228, v228
	v_fmac_f32_e32 v156, v229, v229
	v_add_f32_dpp v149, v149, v149 row_shr:1 row_mask:0xf bank_mask:0xf bound_ctrl:0
	v_add_f32_dpp v150, v150, v150 row_shr:1 row_mask:0xf bank_mask:0xf bound_ctrl:0
	v_add_f32_dpp v151, v151, v151 row_shr:1 row_mask:0xf bank_mask:0xf bound_ctrl:0
	v_add_f32_dpp v152, v152, v152 row_shr:1 row_mask:0xf bank_mask:0xf bound_ctrl:0
	v_add_f32_dpp v153, v153, v153 row_shr:1 row_mask:0xf bank_mask:0xf bound_ctrl:0
	v_add_f32_dpp v154, v154, v154 row_shr:1 row_mask:0xf bank_mask:0xf bound_ctrl:0
	v_add_f32_dpp v155, v155, v155 row_shr:1 row_mask:0xf bank_mask:0xf bound_ctrl:0
	v_add_f32_dpp v156, v156, v156 row_shr:1 row_mask:0xf bank_mask:0xf bound_ctrl:0
	v_add_f32_dpp v149, v149, v149 row_shr:2 row_mask:0xf bank_mask:0xf bound_ctrl:0
	v_add_f32_dpp v150, v150, v150 row_shr:2 row_mask:0xf bank_mask:0xf bound_ctrl:0
	v_add_f32_dpp v151, v151, v151 row_shr:2 row_mask:0xf bank_mask:0xf bound_ctrl:0
	v_add_f32_dpp v152, v152, v152 row_shr:2 row_mask:0xf bank_mask:0xf bound_ctrl:0
	v_add_f32_dpp v153, v153, v153 row_shr:2 row_mask:0xf bank_mask:0xf bound_ctrl:0
	v_add_f32_dpp v154, v154, v154 row_shr:2 row_mask:0xf bank_mask:0xf bound_ctrl:0
	v_add_f32_dpp v155, v155, v155 row_shr:2 row_mask:0xf bank_mask:0xf bound_ctrl:0
	v_add_f32_dpp v156, v156, v156 row_shr:2 row_mask:0xf bank_mask:0xf bound_ctrl:0
	v_add_f32_dpp v149, v149, v149 row_shr:4 row_mask:0xf bank_mask:0xf bound_ctrl:0
	v_add_f32_dpp v150, v150, v150 row_shr:4 row_mask:0xf bank_mask:0xf bound_ctrl:0
	v_add_f32_dpp v151, v151, v151 row_shr:4 row_mask:0xf bank_mask:0xf bound_ctrl:0
	v_add_f32_dpp v152, v152, v152 row_shr:4 row_mask:0xf bank_mask:0xf bound_ctrl:0
	v_add_f32_dpp v153, v153, v153 row_shr:4 row_mask:0xf bank_mask:0xf bound_ctrl:0
	v_add_f32_dpp v154, v154, v154 row_shr:4 row_mask:0xf bank_mask:0xf bound_ctrl:0
	v_add_f32_dpp v155, v155, v155 row_shr:4 row_mask:0xf bank_mask:0xf bound_ctrl:0
	v_add_f32_dpp v156, v156, v156 row_shr:4 row_mask:0xf bank_mask:0xf bound_ctrl:0
	v_add_f32_dpp v149, v149, v149 row_shr:8 row_mask:0xf bank_mask:0xf bound_ctrl:0
	v_add_f32_dpp v150, v150, v150 row_shr:8 row_mask:0xf bank_mask:0xf bound_ctrl:0
	v_add_f32_dpp v151, v151, v151 row_shr:8 row_mask:0xf bank_mask:0xf bound_ctrl:0
	v_add_f32_dpp v152, v152, v152 row_shr:8 row_mask:0xf bank_mask:0xf bound_ctrl:0
	v_add_f32_dpp v153, v153, v153 row_shr:8 row_mask:0xf bank_mask:0xf bound_ctrl:0
	v_add_f32_dpp v154, v154, v154 row_shr:8 row_mask:0xf bank_mask:0xf bound_ctrl:0
	v_add_f32_dpp v155, v155, v155 row_shr:8 row_mask:0xf bank_mask:0xf bound_ctrl:0
	v_add_f32_dpp v156, v156, v156 row_shr:8 row_mask:0xf bank_mask:0xf bound_ctrl:0
	v_cmp_eq_u32_e32 vcc, 15, v138
	s_and_saveexec_b64 s[4:5], vcc
	global_store_dword v148, v149, s[10:11] offset:512
	global_store_dword v148, v150, s[10:11] offset:528
	global_store_dword v148, v151, s[10:11] offset:544
	global_store_dword v148, v152, s[10:11] offset:560
	global_store_dword v148, v153, s[10:11] offset:576
	global_store_dword v148, v154, s[10:11] offset:592
	global_store_dword v148, v155, s[10:11] offset:608
	global_store_dword v148, v156, s[10:11] offset:624
	s_branch .LBB0_275

; DEVI float silu(float x) { return x * __builtin_amdgcn_rcpf(1.f + __expf(-x)); }
; template <int EPI, int NRM>
; DEVI void epilogue(acc_t& acc, int pn, int trow, const EpiArgs& e, const float* rl, bf16* shmx) {
;     ...
;   float rs[2][2];
;   if constexpr (NRM) {
; #pragma unroll
;     for (int bj = 0; bj < 2; ++bj)
; #pragma unroll
;       for (int n = 0; n < 2; ++n) rs[bj][n] = rl[wc * 32 + fr + bj * 128 + n * 16];
;     ...
;   } else if constexpr (EPI == EPI_SWIGLU) {
; #pragma unroll
;     for (int bj = 0; bj < 2; ++bj)
; #pragma unroll
;       for (int m = 0; m < 4; ++m)
; #pragma unroll
;         for (int n = 0; n < 2; ++n) {
;           float r[4];
; #pragma unroll
;           for (int j = 0; j < 4; ++j) r[j] = silu(acc[0][bj][m][n][j] * rs[bj][n]) * (acc[1][bj][m][n][j] * rs[bj][n]);
;           uint2 o; o.x = pack2(r[0], r[1]); o.y = pack2(r[2], r[3]);
;           const unsigned off = (unsigned)((tk0 + bj * 128 + n * 16) * DFF + pn * 128 + m * 16 + fl0);
;           *reinterpret_cast<uint2*>(e.o0 + off) = o;
;         }
.LBB0_325:
	v_and_b32_e32 v170, 15, v136
	v_bfe_u32 v171, v136, 4, 2
	v_lshrrev_b32_e32 v172, 6, v136
	v_and_b32_e32 v173, 3, v172
	v_lshrrev_b32_e32 v174, 2, v172
	v_lshlrev_b32_e32 v175, 13, v173
	v_lshl_add_u32 v175, v174, 16, v175
	v_add_u32_e32 v175, 0x8000, v175
	v_lshl_add_u32 v176, v170, 7, v175
	v_and_b32_e32 v177, 1, v171
	v_lshl_add_u32 v176, v177, 3, v176
	v_lshrrev_b32_e32 v177, 1, v171
	v_and_b32_e32 v178, 7, v170
	v_add_u32_e32 v179, 0, v177
	v_xor_b32_e32 v179, v179, v178
	v_lshl_add_u32 v164, v179, 4, v176
	v_add_u32_e32 v179, 2, v177
	v_xor_b32_e32 v179, v179, v178
	v_lshl_add_u32 v165, v179, 4, v176
	v_add_u32_e32 v179, 4, v177
	v_xor_b32_e32 v179, v179, v178
	v_lshl_add_u32 v166, v179, 4, v176
	v_add_u32_e32 v179, 6, v177
	v_xor_b32_e32 v179, v179, v178
	v_lshl_add_u32 v167, v179, 4, v176
	v_and_b32_e32 v180, 63, v136
	v_lshl_add_u32 v168, v180, 4, v175
	v_lshrrev_b32_e32 v181, 3, v180
	v_and_b32_e32 v182, 7, v180
	v_xor_b32_e32 v182, v182, v181
	s_lshl_b32 s9, s12, 8
	v_lshl_add_u32 v183, v173, 5, v181
	v_add_u32_e32 v183, s9, v183
	v_mul_u32_u24_e32 v183, 0x1600, v183
	s_lshl_b32 s9, s14, 7
	v_lshl_add_u32 v179, v174, 6, s9
	v_lshl_add_u32 v179, v182, 3, v179
	v_add_lshl_u32 v169, v183, v179, 1
	v_mov_b32_e32 v130, v136
	s_lshl_b32 s11, s16, 10
	s_and_b32 s11, s11, 0x400
	v_and_b32_e32 v141, 15, v130
	v_ashrrev_i32_e32 v142, 2, v130
	v_lshrrev_b32_e32 v143, 2, v130
	v_lshrrev_b32_e32 v130, 1, v130
	s_add_i32 s11, s11, 0
	v_and_b32_e32 v130, 0x60, v130
	s_add_i32 s11, s11, 0x20000
	v_lshlrev_b32_e32 v132, 2, v130
	v_lshlrev_b32_e32 v133, 2, v141
	v_add3_u32 v132, s11, v132, v133
	ds_read2_b32 v[134:135], v132 offset1:16
	ds_read2_b32 v[132:133], v132 offset0:128 offset1:144
	s_lshl_b32 s9, s12, 8
	v_or3_b32 v130, v141, s9, v130
	s_lshl_b32 s9, s14, 7
	v_and_b32_e32 v142, 0xffffffc0, v142
	v_and_or_b32 v141, v143, 12, s9
	s_waitcnt lgkmcnt(1)
	v_pk_mul_f32 v[122:123], v[122:123], v[134:135] op_sel_hi:[1,0]
	v_add_u32_e32 v141, v141, v142
	v_mul_f32_e32 v142, 0xbfb8aa3b, v122
	v_mul_f32_e32 v143, 0xbfb8aa3b, v123
	v_exp_f32_e32 v142, v142
	v_exp_f32_e32 v143, v143
	v_pk_mul_f32 v[126:127], v[126:127], v[134:135] op_sel_hi:[1,0]
	s_movk_i32 s9, 0x1600
	v_add_f32_e32 v142, 1.0, v142
	v_add_f32_e32 v143, 1.0, v143
	v_rcp_f32_e32 v142, v142
	v_rcp_f32_e32 v143, v143
	v_pk_mul_f32 v[106:107], v[106:107], v[134:135] op_sel_hi:[1,0]
	v_pk_mul_f32 v[110:111], v[110:111], v[134:135] op_sel_hi:[1,0]
	v_pk_mul_f32 v[108:109], v[108:109], v[134:135] op_sel_hi:[1,0]
	v_pk_mul_f32 v[122:123], v[122:123], v[142:143]
	v_pk_mul_f32 v[90:91], v[90:91], v[134:135] op_sel_hi:[1,0]
	v_pk_mul_f32 v[122:123], v[126:127], v[122:123]
	v_pk_mul_f32 v[94:95], v[94:95], v[134:135] op_sel_hi:[1,0]
	v_cvt_pk_bf16_f32 v126, v122, v123
	v_pk_mul_f32 v[122:123], v[124:125], v[134:135] op_sel_hi:[1,0]
	v_pk_mul_f32 v[92:93], v[92:93], v[134:135] op_sel_hi:[1,0]
	v_mul_f32_e32 v124, 0xbfb8aa3b, v122
	v_mul_f32_e32 v125, 0xbfb8aa3b, v123
	v_exp_f32_e32 v124, v124
	v_exp_f32_e32 v125, v125
	v_pk_mul_f32 v[74:75], v[74:75], v[134:135] op_sel_hi:[1,0]
	v_pk_mul_f32 v[78:79], v[78:79], v[134:135] op_sel_hi:[1,0]
	v_add_f32_e32 v124, 1.0, v124
	v_add_f32_e32 v125, 1.0, v125
	v_rcp_f32_e32 v124, v124
	v_rcp_f32_e32 v125, v125
	v_pk_mul_f32 v[76:77], v[76:77], v[134:135] op_sel_hi:[1,0]
	s_waitcnt lgkmcnt(0)
	v_pk_mul_f32 v[58:59], v[58:59], v[132:133] op_sel_hi:[1,0]
	v_pk_mul_f32 v[62:63], v[62:63], v[132:133] op_sel_hi:[1,0]
	v_pk_mul_f32 v[122:123], v[122:123], v[124:125]
	v_pk_mul_f32 v[124:125], v[128:129], v[134:135] op_sel_hi:[1,0]
	v_pk_mul_f32 v[42:43], v[42:43], v[132:133] op_sel_hi:[1,0]
	v_pk_mul_f32 v[122:123], v[124:125], v[122:123]
	v_pk_mul_f32 v[46:47], v[46:47], v[132:133] op_sel_hi:[1,0]
	v_cvt_pk_bf16_f32 v127, v122, v123
	v_mul_lo_u32 v123, v130, s9
	v_add_u32_e32 v130, v141, v123
	v_mov_b32_e32 v122, v135
	v_lshl_add_u64 v[124:125], v[130:131], 1, s[2:3]
	v_pk_mul_f32 v[114:115], v[114:115], v[122:123] op_sel_hi:[1,0]
	ds_write_b64 v164, v[126:127]
	v_mul_f32_e32 v124, 0xbfb8aa3b, v114
	v_mul_f32_e32 v125, 0xbfb8aa3b, v115
	v_exp_f32_e32 v124, v124
	v_exp_f32_e32 v125, v125
	v_pk_mul_f32 v[118:119], v[118:119], v[122:123] op_sel_hi:[1,0]
	v_pk_mul_f32 v[98:99], v[98:99], v[122:123] op_sel_hi:[1,0]
	v_add_f32_e32 v124, 1.0, v124
	v_add_f32_e32 v125, 1.0, v125
	v_rcp_f32_e32 v124, v124
	v_rcp_f32_e32 v125, v125
	v_pk_mul_f32 v[102:103], v[102:103], v[122:123] op_sel_hi:[1,0]
	v_pk_mul_f32 v[100:101], v[100:101], v[122:123] op_sel_hi:[1,0]
	v_pk_mul_f32 v[82:83], v[82:83], v[122:123] op_sel_hi:[1,0]
	v_pk_mul_f32 v[114:115], v[114:115], v[124:125]
	v_pk_mul_f32 v[86:87], v[86:87], v[122:123] op_sel_hi:[1,0]
	v_pk_mul_f32 v[114:115], v[118:119], v[114:115]
	v_pk_mul_f32 v[84:85], v[84:85], v[122:123] op_sel_hi:[1,0]
	v_cvt_pk_bf16_f32 v118, v114, v115
	v_pk_mul_f32 v[114:115], v[116:117], v[122:123] op_sel_hi:[1,0]
	v_pk_mul_f32 v[66:67], v[66:67], v[122:123] op_sel_hi:[1,0]
	v_mul_f32_e32 v116, 0xbfb8aa3b, v114
	v_mul_f32_e32 v117, 0xbfb8aa3b, v115
	v_exp_f32_e32 v116, v116
	v_exp_f32_e32 v117, v117
	v_pk_mul_f32 v[70:71], v[70:71], v[122:123] op_sel_hi:[1,0]
	v_pk_mul_f32 v[68:69], v[68:69], v[122:123] op_sel_hi:[1,0]
	v_add_f32_e32 v116, 1.0, v116
	v_add_f32_e32 v117, 1.0, v117
	v_rcp_f32_e32 v116, v116
	v_rcp_f32_e32 v117, v117
	v_pk_mul_f32 v[44:45], v[44:45], v[132:133] op_sel_hi:[1,0]
	v_pk_mul_f32 v[26:27], v[26:27], v[132:133] op_sel_hi:[1,0]
	v_pk_mul_f32 v[30:31], v[30:31], v[132:133] op_sel_hi:[1,0]
	v_pk_mul_f32 v[114:115], v[114:115], v[116:117]
	v_pk_mul_f32 v[116:117], v[120:121], v[122:123] op_sel_hi:[1,0]
; DEVI float silu(float x) { return x * __builtin_amdgcn_rcpf(1.f + __expf(-x)); }
; template <int EPI, int NRM>
; DEVI void epilogue(acc_t& acc, int pn, int trow, const EpiArgs& e, const float* rl, bf16* shmx) {
;     ...
;   } else if constexpr (EPI == EPI_SWIGLU) {
; #pragma unroll
;     for (int bj = 0; bj < 2; ++bj)
; #pragma unroll
;       for (int m = 0; m < 4; ++m)
; #pragma unroll
;         for (int n = 0; n < 2; ++n) {
;           float r[4];
; #pragma unroll
;           for (int j = 0; j < 4; ++j) r[j] = silu(acc[0][bj][m][n][j] * rs[bj][n]) * (acc[1][bj][m][n][j] * rs[bj][n]);
;           uint2 o; o.x = pack2(r[0], r[1]); o.y = pack2(r[2], r[3]);
;           const unsigned off = (unsigned)((tk0 + bj * 128 + n * 16) * DFF + pn * 128 + m * 16 + fl0);
;           *reinterpret_cast<uint2*>(e.o0 + off) = o;
;         }
	v_pk_mul_f32 v[28:29], v[28:29], v[132:133] op_sel_hi:[1,0]
	v_pk_mul_f32 v[114:115], v[116:117], v[114:115]
	v_pk_mul_f32 v[10:11], v[10:11], v[132:133] op_sel_hi:[1,0]
	v_cvt_pk_bf16_f32 v119, v114, v115
	v_add_u32_e32 v115, 0x16000, v123
	v_add_u32_e32 v130, v115, v141
	v_lshl_add_u64 v[116:117], v[130:131], 1, s[2:3]
	ds_write_b64 v164, v[118:119] offset:2048
	v_mul_f32_e32 v116, 0xbfb8aa3b, v106
	v_mul_f32_e32 v117, 0xbfb8aa3b, v107
	v_exp_f32_e32 v116, v116
	v_exp_f32_e32 v117, v117
	v_or_b32_e32 v114, 16, v141
	v_add_u32_e32 v130, v114, v123
	v_add_f32_e32 v116, 1.0, v116
	v_add_f32_e32 v117, 1.0, v117
	v_rcp_f32_e32 v116, v116
	v_rcp_f32_e32 v117, v117
	v_pk_mul_f32 v[14:15], v[14:15], v[132:133] op_sel_hi:[1,0]
	v_pk_mul_f32 v[12:13], v[12:13], v[132:133] op_sel_hi:[1,0]
	s_add_i32 s16, s16, 1
	v_pk_mul_f32 v[106:107], v[106:107], v[116:117]
	s_andn2_b64 vcc, exec, s[4:5]
	v_pk_mul_f32 v[106:107], v[110:111], v[106:107]
	s_mov_b32 s14, s8
	v_cvt_pk_bf16_f32 v106, v106, v107
	v_mul_f32_e32 v107, 0xbfb8aa3b, v108
	v_exp_f32_e32 v107, v107
	s_mov_b32 s12, s10
	v_add_f32_e32 v107, 1.0, v107
	v_rcp_f32_e32 v110, v107
	v_mul_f32_e32 v107, 0xbfb8aa3b, v109
	v_exp_f32_e32 v107, v107
	s_nop 0
	v_add_f32_e32 v107, 1.0, v107
	v_rcp_f32_e32 v111, v107
	s_nop 0
	v_pk_mul_f32 v[108:109], v[108:109], v[110:111]
	v_pk_mul_f32 v[110:111], v[112:113], v[134:135] op_sel_hi:[1,0]
	s_nop 0
	v_pk_mul_f32 v[108:109], v[110:111], v[108:109]
	s_nop 0
	v_cvt_pk_bf16_f32 v107, v108, v109
	v_lshl_add_u64 v[108:109], v[130:131], 1, s[2:3]
	ds_write_b64 v165, v[106:107]
	v_mul_f32_e32 v106, 0xbfb8aa3b, v98
	v_mul_f32_e32 v107, 0xbfb8aa3b, v99
	v_exp_f32_e32 v106, v106
	v_exp_f32_e32 v107, v107
	v_add_u32_e32 v130, v114, v115
	v_add_f32_e32 v106, 1.0, v106
	v_add_f32_e32 v107, 1.0, v107
	v_rcp_f32_e32 v106, v106
	v_rcp_f32_e32 v107, v107
	s_nop 0
	v_pk_mul_f32 v[98:99], v[98:99], v[106:107]
	s_nop 0
	v_pk_mul_f32 v[98:99], v[102:103], v[98:99]
	s_nop 0
	v_cvt_pk_bf16_f32 v98, v98, v99
	v_mul_f32_e32 v99, 0xbfb8aa3b, v100
	v_exp_f32_e32 v99, v99
	s_nop 0
	v_add_f32_e32 v99, 1.0, v99
	v_rcp_f32_e32 v102, v99
	v_mul_f32_e32 v99, 0xbfb8aa3b, v101
	v_exp_f32_e32 v99, v99
	s_nop 0
	v_add_f32_e32 v99, 1.0, v99
	v_rcp_f32_e32 v103, v99
	s_nop 0
	v_pk_mul_f32 v[100:101], v[100:101], v[102:103]
	v_pk_mul_f32 v[102:103], v[104:105], v[122:123] op_sel_hi:[1,0]
	s_nop 0
	v_pk_mul_f32 v[100:101], v[102:103], v[100:101]
	s_nop 0
	v_cvt_pk_bf16_f32 v99, v100, v101
	v_lshl_add_u64 v[100:101], v[130:131], 1, s[2:3]
	ds_write_b64 v165, v[98:99] offset:2048
	v_mul_f32_e32 v99, 0xbfb8aa3b, v90
	v_exp_f32_e32 v99, v99
	v_or_b32_e32 v98, 32, v141
	v_add_u32_e32 v130, v98, v123
	v_add_f32_e32 v99, 1.0, v99
	v_rcp_f32_e32 v100, v99
	v_mul_f32_e32 v99, 0xbfb8aa3b, v91
	v_exp_f32_e32 v99, v99
	s_nop 0
	v_add_f32_e32 v99, 1.0, v99
	v_rcp_f32_e32 v101, v99
	s_nop 0
	v_pk_mul_f32 v[90:91], v[90:91], v[100:101]
	s_nop 0
	v_pk_mul_f32 v[90:91], v[94:95], v[90:91]
	s_nop 0
	v_cvt_pk_bf16_f32 v90, v90, v91
	v_mul_f32_e32 v91, 0xbfb8aa3b, v92
	v_exp_f32_e32 v91, v91
	s_nop 0
	v_add_f32_e32 v91, 1.0, v91
	v_rcp_f32_e32 v94, v91
	v_mul_f32_e32 v91, 0xbfb8aa3b, v93
	v_exp_f32_e32 v91, v91
	s_nop 0
	v_add_f32_e32 v91, 1.0, v91
	v_rcp_f32_e32 v95, v91
	s_nop 0
	v_pk_mul_f32 v[92:93], v[92:93], v[94:95]
	v_pk_mul_f32 v[94:95], v[96:97], v[134:135] op_sel_hi:[1,0]
	s_nop 0
	v_pk_mul_f32 v[92:93], v[94:95], v[92:93]
	s_nop 0
	v_cvt_pk_bf16_f32 v91, v92, v93
	v_lshl_add_u64 v[92:93], v[130:131], 1, s[2:3]
	ds_write_b64 v166, v[90:91]
	v_mul_f32_e32 v90, 0xbfb8aa3b, v82
	v_mul_f32_e32 v91, 0xbfb8aa3b, v83
	v_exp_f32_e32 v90, v90
	v_exp_f32_e32 v91, v91
	v_add_u32_e32 v130, v98, v115
	v_add_f32_e32 v90, 1.0, v90
	v_add_f32_e32 v91, 1.0, v91
	v_rcp_f32_e32 v90, v90
	v_rcp_f32_e32 v91, v91
	s_nop 0
	v_pk_mul_f32 v[82:83], v[82:83], v[90:91]
	s_nop 0
	v_pk_mul_f32 v[82:83], v[86:87], v[82:83]
	s_nop 0
	v_cvt_pk_bf16_f32 v82, v82, v83
	v_mul_f32_e32 v83, 0xbfb8aa3b, v84
	v_exp_f32_e32 v83, v83
	s_nop 0
	v_add_f32_e32 v83, 1.0, v83
	v_rcp_f32_e32 v86, v83
	v_mul_f32_e32 v83, 0xbfb8aa3b, v85
	v_exp_f32_e32 v83, v83
	s_nop 0
	v_add_f32_e32 v83, 1.0, v83
	v_rcp_f32_e32 v87, v83
	s_nop 0
	v_pk_mul_f32 v[84:85], v[84:85], v[86:87]
	v_pk_mul_f32 v[86:87], v[88:89], v[122:123] op_sel_hi:[1,0]
	s_nop 0
	v_pk_mul_f32 v[84:85], v[86:87], v[84:85]
	s_nop 0
	v_cvt_pk_bf16_f32 v83, v84, v85
	v_lshl_add_u64 v[84:85], v[130:131], 1, s[2:3]
	ds_write_b64 v166, v[82:83] offset:2048
	v_mul_f32_e32 v83, 0xbfb8aa3b, v74
	v_exp_f32_e32 v83, v83
	v_or_b32_e32 v82, 48, v141
	v_add_u32_e32 v130, v82, v123
	v_add_f32_e32 v83, 1.0, v83
	v_rcp_f32_e32 v84, v83
	v_mul_f32_e32 v83, 0xbfb8aa3b, v75
	v_exp_f32_e32 v83, v83
	s_nop 0
	v_add_f32_e32 v83, 1.0, v83
	v_rcp_f32_e32 v85, v83
	s_nop 0
	v_pk_mul_f32 v[74:75], v[74:75], v[84:85]
	s_nop 0
	v_pk_mul_f32 v[74:75], v[78:79], v[74:75]
	s_nop 0
	v_cvt_pk_bf16_f32 v74, v74, v75
	v_mul_f32_e32 v75, 0xbfb8aa3b, v76
	v_exp_f32_e32 v75, v75
	s_nop 0
	v_add_f32_e32 v75, 1.0, v75
	v_rcp_f32_e32 v78, v75
	v_mul_f32_e32 v75, 0xbfb8aa3b, v77
	v_exp_f32_e32 v75, v75
	s_nop 0
	v_add_f32_e32 v75, 1.0, v75
	v_rcp_f32_e32 v79, v75
	s_nop 0
	v_pk_mul_f32 v[76:77], v[76:77], v[78:79]
	v_pk_mul_f32 v[78:79], v[80:81], v[134:135] op_sel_hi:[1,0]
	s_nop 0
	v_pk_mul_f32 v[76:77], v[78:79], v[76:77]
	s_nop 0
	v_cvt_pk_bf16_f32 v75, v76, v77
	v_lshl_add_u64 v[76:77], v[130:131], 1, s[2:3]
	ds_write_b64 v167, v[74:75]
	v_mul_f32_e32 v74, 0xbfb8aa3b, v66
	v_mul_f32_e32 v75, 0xbfb8aa3b, v67
	v_exp_f32_e32 v74, v74
	v_exp_f32_e32 v75, v75
	v_add_u32_e32 v130, v82, v115
	v_add_f32_e32 v74, 1.0, v74
; DEVI float silu(float x) { return x * __builtin_amdgcn_rcpf(1.f + __expf(-x)); }
; template <int EPI, int NRM>
; DEVI void epilogue(acc_t& acc, int pn, int trow, const EpiArgs& e, const float* rl, bf16* shmx) {
;     ...
;   } else if constexpr (EPI == EPI_SWIGLU) {
; #pragma unroll
;     for (int bj = 0; bj < 2; ++bj)
; #pragma unroll
;       for (int m = 0; m < 4; ++m)
; #pragma unroll
;         for (int n = 0; n < 2; ++n) {
;           float r[4];
; #pragma unroll
;           for (int j = 0; j < 4; ++j) r[j] = silu(acc[0][bj][m][n][j] * rs[bj][n]) * (acc[1][bj][m][n][j] * rs[bj][n]);
;           uint2 o; o.x = pack2(r[0], r[1]); o.y = pack2(r[2], r[3]);
;           const unsigned off = (unsigned)((tk0 + bj * 128 + n * 16) * DFF + pn * 128 + m * 16 + fl0);
;           *reinterpret_cast<uint2*>(e.o0 + off) = o;
;         }
	v_add_f32_e32 v75, 1.0, v75
	v_rcp_f32_e32 v74, v74
	v_rcp_f32_e32 v75, v75
	s_nop 0
	v_pk_mul_f32 v[66:67], v[66:67], v[74:75]
	s_nop 0
	v_pk_mul_f32 v[66:67], v[70:71], v[66:67]
	s_nop 0
	v_cvt_pk_bf16_f32 v66, v66, v67
	v_mul_f32_e32 v67, 0xbfb8aa3b, v68
	v_exp_f32_e32 v67, v67
	s_nop 0
	v_add_f32_e32 v67, 1.0, v67
	v_rcp_f32_e32 v70, v67
	v_mul_f32_e32 v67, 0xbfb8aa3b, v69
	v_exp_f32_e32 v67, v67
	s_nop 0
	v_add_f32_e32 v67, 1.0, v67
	v_rcp_f32_e32 v71, v67
	s_nop 0
	v_pk_mul_f32 v[68:69], v[68:69], v[70:71]
	v_pk_mul_f32 v[70:71], v[72:73], v[122:123] op_sel_hi:[1,0]
	s_nop 0
	v_pk_mul_f32 v[68:69], v[70:71], v[68:69]
	s_nop 0
	v_cvt_pk_bf16_f32 v67, v68, v69
	v_lshl_add_u64 v[68:69], v[130:131], 1, s[2:3]
	ds_write_b64 v167, v[66:67] offset:2048
	v_mul_f32_e32 v66, 0xbfb8aa3b, v58
	v_mul_f32_e32 v67, 0xbfb8aa3b, v59
	v_exp_f32_e32 v66, v66
	v_exp_f32_e32 v67, v67
	v_add_f32_e32 v66, 1.0, v66
	v_add_f32_e32 v67, 1.0, v67
	v_rcp_f32_e32 v66, v66
	v_rcp_f32_e32 v67, v67
	s_nop 0
	v_pk_mul_f32 v[58:59], v[58:59], v[66:67]
	s_nop 0
	v_pk_mul_f32 v[58:59], v[62:63], v[58:59]
	s_nop 0
	v_cvt_pk_bf16_f32 v62, v58, v59
	v_pk_mul_f32 v[58:59], v[60:61], v[132:133] op_sel_hi:[1,0]
	s_nop 0
	v_mul_f32_e32 v60, 0xbfb8aa3b, v58
	v_mul_f32_e32 v61, 0xbfb8aa3b, v59
	v_exp_f32_e32 v60, v60
	v_exp_f32_e32 v61, v61
	v_add_f32_e32 v60, 1.0, v60
	v_add_f32_e32 v61, 1.0, v61
	v_rcp_f32_e32 v60, v60
	v_rcp_f32_e32 v61, v61
	s_nop 0
	v_pk_mul_f32 v[58:59], v[58:59], v[60:61]
	v_pk_mul_f32 v[60:61], v[64:65], v[132:133] op_sel_hi:[1,0]
	s_nop 0
	v_pk_mul_f32 v[58:59], v[60:61], v[58:59]
	s_nop 0
	v_cvt_pk_bf16_f32 v63, v58, v59
	v_add_u32_e32 v59, 0xb0000, v123
	v_add_u32_e32 v130, v59, v141
	v_mov_b32_e32 v58, v133
	v_lshl_add_u64 v[60:61], v[130:131], 1, s[2:3]
	v_pk_mul_f32 v[50:51], v[50:51], v[58:59] op_sel_hi:[1,0]
	ds_write_b64 v164, v[62:63] offset:4096
	v_mul_f32_e32 v60, 0xbfb8aa3b, v50
	v_mul_f32_e32 v61, 0xbfb8aa3b, v51
	v_exp_f32_e32 v60, v60
	v_exp_f32_e32 v61, v61
	v_pk_mul_f32 v[54:55], v[54:55], v[58:59] op_sel_hi:[1,0]
	v_pk_mul_f32 v[34:35], v[34:35], v[58:59] op_sel_hi:[1,0]
	v_add_f32_e32 v60, 1.0, v60
	v_add_f32_e32 v61, 1.0, v61
	v_rcp_f32_e32 v60, v60
	v_rcp_f32_e32 v61, v61
	v_pk_mul_f32 v[38:39], v[38:39], v[58:59] op_sel_hi:[1,0]
	v_pk_mul_f32 v[36:37], v[36:37], v[58:59] op_sel_hi:[1,0]
	v_pk_mul_f32 v[18:19], v[18:19], v[58:59] op_sel_hi:[1,0]
	v_pk_mul_f32 v[50:51], v[50:51], v[60:61]
	v_pk_mul_f32 v[22:23], v[22:23], v[58:59] op_sel_hi:[1,0]
	v_pk_mul_f32 v[50:51], v[54:55], v[50:51]
	v_pk_mul_f32 v[20:21], v[20:21], v[58:59] op_sel_hi:[1,0]
	v_cvt_pk_bf16_f32 v54, v50, v51
	v_pk_mul_f32 v[50:51], v[52:53], v[58:59] op_sel_hi:[1,0]
	v_pk_mul_f32 v[2:3], v[2:3], v[58:59] op_sel_hi:[1,0]
	v_mul_f32_e32 v52, 0xbfb8aa3b, v50
	v_mul_f32_e32 v53, 0xbfb8aa3b, v51
	v_exp_f32_e32 v52, v52
	v_exp_f32_e32 v53, v53
	v_pk_mul_f32 v[6:7], v[6:7], v[58:59] op_sel_hi:[1,0]
	v_pk_mul_f32 v[4:5], v[4:5], v[58:59] op_sel_hi:[1,0]
	v_add_f32_e32 v52, 1.0, v52
	v_add_f32_e32 v53, 1.0, v53
	v_rcp_f32_e32 v52, v52
	v_rcp_f32_e32 v53, v53
	s_nop 0
	v_pk_mul_f32 v[50:51], v[50:51], v[52:53]
	v_pk_mul_f32 v[52:53], v[56:57], v[58:59] op_sel_hi:[1,0]
	s_nop 0
	v_pk_mul_f32 v[50:51], v[52:53], v[50:51]
	s_nop 0
	v_cvt_pk_bf16_f32 v55, v50, v51
	v_mul_f32_e32 v51, 0xbfb8aa3b, v42
	v_exp_f32_e32 v51, v51
	v_add_u32_e32 v50, 0xc6000, v123
	v_add_u32_e32 v130, v50, v141
	v_lshl_add_u64 v[52:53], v[130:131], 1, s[2:3]
	v_add_f32_e32 v51, 1.0, v51
	ds_write_b64 v164, v[54:55] offset:6144
	v_rcp_f32_e32 v52, v51
	v_mul_f32_e32 v51, 0xbfb8aa3b, v43
	v_exp_f32_e32 v51, v51
	v_add_u32_e32 v130, v114, v59
	v_add_f32_e32 v51, 1.0, v51
	v_rcp_f32_e32 v53, v51
	s_nop 0
	v_pk_mul_f32 v[42:43], v[42:43], v[52:53]
	s_nop 0
	v_pk_mul_f32 v[42:43], v[46:47], v[42:43]
	s_nop 0
	v_cvt_pk_bf16_f32 v42, v42, v43
	v_mul_f32_e32 v43, 0xbfb8aa3b, v44
	v_exp_f32_e32 v43, v43
	s_nop 0
	v_add_f32_e32 v43, 1.0, v43
	v_rcp_f32_e32 v46, v43
	v_mul_f32_e32 v43, 0xbfb8aa3b, v45
	v_exp_f32_e32 v43, v43
	s_nop 0
	v_add_f32_e32 v43, 1.0, v43
	v_rcp_f32_e32 v47, v43
	s_nop 0
	v_pk_mul_f32 v[44:45], v[44:45], v[46:47]
	v_pk_mul_f32 v[46:47], v[48:49], v[132:133] op_sel_hi:[1,0]
	s_nop 0
	v_pk_mul_f32 v[44:45], v[46:47], v[44:45]
	s_nop 0
	v_cvt_pk_bf16_f32 v43, v44, v45
	v_lshl_add_u64 v[44:45], v[130:131], 1, s[2:3]
	ds_write_b64 v165, v[42:43] offset:4096
	v_mul_f32_e32 v42, 0xbfb8aa3b, v34
	v_mul_f32_e32 v43, 0xbfb8aa3b, v35
	v_exp_f32_e32 v42, v42
	v_exp_f32_e32 v43, v43
	v_add_u32_e32 v130, v114, v50
	v_add_f32_e32 v42, 1.0, v42
	v_add_f32_e32 v43, 1.0, v43
	v_rcp_f32_e32 v42, v42
	v_rcp_f32_e32 v43, v43
	s_nop 0
	v_pk_mul_f32 v[34:35], v[34:35], v[42:43]
	s_nop 0
	v_pk_mul_f32 v[34:35], v[38:39], v[34:35]
	s_nop 0
	v_cvt_pk_bf16_f32 v34, v34, v35
	v_mul_f32_e32 v35, 0xbfb8aa3b, v36
	v_exp_f32_e32 v35, v35
	s_nop 0
	v_add_f32_e32 v35, 1.0, v35
	v_rcp_f32_e32 v38, v35
	v_mul_f32_e32 v35, 0xbfb8aa3b, v37
	v_exp_f32_e32 v35, v35
	s_nop 0
	v_add_f32_e32 v35, 1.0, v35
	v_rcp_f32_e32 v39, v35
	s_nop 0
	v_pk_mul_f32 v[36:37], v[36:37], v[38:39]
	v_pk_mul_f32 v[38:39], v[40:41], v[58:59] op_sel_hi:[1,0]
; DEVI float silu(float x) { return x * __builtin_amdgcn_rcpf(1.f + __expf(-x)); }
; template <int EPI, int NRM>
; DEVI void epilogue(acc_t& acc, int pn, int trow, const EpiArgs& e, const float* rl, bf16* shmx) {
;     ...
;   } else if constexpr (EPI == EPI_SWIGLU) {
; #pragma unroll
;     for (int bj = 0; bj < 2; ++bj)
; #pragma unroll
;       for (int m = 0; m < 4; ++m)
; #pragma unroll
;         for (int n = 0; n < 2; ++n) {
;           float r[4];
; #pragma unroll
;           for (int j = 0; j < 4; ++j) r[j] = silu(acc[0][bj][m][n][j] * rs[bj][n]) * (acc[1][bj][m][n][j] * rs[bj][n]);
;           uint2 o; o.x = pack2(r[0], r[1]); o.y = pack2(r[2], r[3]);
;           const unsigned off = (unsigned)((tk0 + bj * 128 + n * 16) * DFF + pn * 128 + m * 16 + fl0);
;           *reinterpret_cast<uint2*>(e.o0 + off) = o;
;         }
	s_nop 0
	v_pk_mul_f32 v[36:37], v[38:39], v[36:37]
	s_nop 0
	v_cvt_pk_bf16_f32 v35, v36, v37
	v_lshl_add_u64 v[36:37], v[130:131], 1, s[2:3]
	ds_write_b64 v165, v[34:35] offset:6144
	v_mul_f32_e32 v34, 0xbfb8aa3b, v26
	v_mul_f32_e32 v35, 0xbfb8aa3b, v27
	v_exp_f32_e32 v34, v34
	v_exp_f32_e32 v35, v35
	v_add_u32_e32 v130, v98, v59
	v_add_f32_e32 v34, 1.0, v34
	v_add_f32_e32 v35, 1.0, v35
	v_rcp_f32_e32 v34, v34
	v_rcp_f32_e32 v35, v35
	s_nop 0
	v_pk_mul_f32 v[26:27], v[26:27], v[34:35]
	s_nop 0
	v_pk_mul_f32 v[26:27], v[30:31], v[26:27]
	s_nop 0
	v_cvt_pk_bf16_f32 v26, v26, v27
	v_mul_f32_e32 v27, 0xbfb8aa3b, v28
	v_exp_f32_e32 v27, v27
	s_nop 0
	v_add_f32_e32 v27, 1.0, v27
	v_rcp_f32_e32 v30, v27
	v_mul_f32_e32 v27, 0xbfb8aa3b, v29
	v_exp_f32_e32 v27, v27
	s_nop 0
	v_add_f32_e32 v27, 1.0, v27
	v_rcp_f32_e32 v31, v27
	s_nop 0
	v_pk_mul_f32 v[28:29], v[28:29], v[30:31]
	v_pk_mul_f32 v[30:31], v[32:33], v[132:133] op_sel_hi:[1,0]
	s_nop 0
	v_pk_mul_f32 v[28:29], v[30:31], v[28:29]
	s_nop 0
	v_cvt_pk_bf16_f32 v27, v28, v29
	v_lshl_add_u64 v[28:29], v[130:131], 1, s[2:3]
	ds_write_b64 v166, v[26:27] offset:4096
	v_mul_f32_e32 v26, 0xbfb8aa3b, v18
	v_mul_f32_e32 v27, 0xbfb8aa3b, v19
	v_exp_f32_e32 v26, v26
	v_exp_f32_e32 v27, v27
	v_add_u32_e32 v130, v98, v50
	v_add_f32_e32 v26, 1.0, v26
	v_add_f32_e32 v27, 1.0, v27
	v_rcp_f32_e32 v26, v26
	v_rcp_f32_e32 v27, v27
	s_nop 0
	v_pk_mul_f32 v[18:19], v[18:19], v[26:27]
	s_nop 0
	v_pk_mul_f32 v[18:19], v[22:23], v[18:19]
	s_nop 0
	v_cvt_pk_bf16_f32 v18, v18, v19
	v_mul_f32_e32 v19, 0xbfb8aa3b, v20
	v_exp_f32_e32 v19, v19
	s_nop 0
	v_add_f32_e32 v19, 1.0, v19
	v_rcp_f32_e32 v22, v19
	v_mul_f32_e32 v19, 0xbfb8aa3b, v21
	v_exp_f32_e32 v19, v19
	s_nop 0
	v_add_f32_e32 v19, 1.0, v19
	v_rcp_f32_e32 v23, v19
	s_nop 0
	v_pk_mul_f32 v[20:21], v[20:21], v[22:23]
	v_pk_mul_f32 v[22:23], v[24:25], v[58:59] op_sel_hi:[1,0]
	s_nop 0
	v_pk_mul_f32 v[20:21], v[22:23], v[20:21]
	s_nop 0
	v_cvt_pk_bf16_f32 v19, v20, v21
	v_lshl_add_u64 v[20:21], v[130:131], 1, s[2:3]
	ds_write_b64 v166, v[18:19] offset:6144
	v_mul_f32_e32 v18, 0xbfb8aa3b, v10
	v_mul_f32_e32 v19, 0xbfb8aa3b, v11
	v_exp_f32_e32 v18, v18
	v_exp_f32_e32 v19, v19
	v_add_u32_e32 v130, v82, v59
	v_add_f32_e32 v18, 1.0, v18
	v_add_f32_e32 v19, 1.0, v19
	v_rcp_f32_e32 v18, v18
	v_rcp_f32_e32 v19, v19
	s_nop 0
	v_pk_mul_f32 v[10:11], v[10:11], v[18:19]
	s_nop 0
	v_pk_mul_f32 v[10:11], v[14:15], v[10:11]
	s_nop 0
	v_cvt_pk_bf16_f32 v10, v10, v11
	v_mul_f32_e32 v11, 0xbfb8aa3b, v12
	v_exp_f32_e32 v11, v11
	s_nop 0
	v_add_f32_e32 v11, 1.0, v11
	v_rcp_f32_e32 v14, v11
	v_mul_f32_e32 v11, 0xbfb8aa3b, v13
	v_exp_f32_e32 v11, v11
	s_nop 0
	v_add_f32_e32 v11, 1.0, v11
	v_rcp_f32_e32 v15, v11
	s_nop 0
	v_pk_mul_f32 v[12:13], v[12:13], v[14:15]
	v_pk_mul_f32 v[14:15], v[16:17], v[132:133] op_sel_hi:[1,0]
	s_nop 0
	v_pk_mul_f32 v[12:13], v[14:15], v[12:13]
	s_nop 0
	v_cvt_pk_bf16_f32 v11, v12, v13
	v_lshl_add_u64 v[12:13], v[130:131], 1, s[2:3]
	ds_write_b64 v167, v[10:11] offset:4096
	v_mul_f32_e32 v10, 0xbfb8aa3b, v2
	v_mul_f32_e32 v11, 0xbfb8aa3b, v3
	v_exp_f32_e32 v10, v10
	v_exp_f32_e32 v11, v11
	v_add_u32_e32 v130, v82, v50
	v_add_f32_e32 v10, 1.0, v10
	v_add_f32_e32 v11, 1.0, v11
	v_rcp_f32_e32 v10, v10
	v_rcp_f32_e32 v11, v11
	s_nop 0
	v_pk_mul_f32 v[2:3], v[2:3], v[10:11]
	s_nop 0
	v_pk_mul_f32 v[2:3], v[6:7], v[2:3]
	s_nop 0
	v_cvt_pk_bf16_f32 v2, v2, v3
	v_mul_f32_e32 v3, 0xbfb8aa3b, v4
	v_exp_f32_e32 v3, v3
	s_nop 0
	v_add_f32_e32 v3, 1.0, v3
	v_rcp_f32_e32 v6, v3
	v_mul_f32_e32 v3, 0xbfb8aa3b, v5
	v_exp_f32_e32 v3, v3
	s_nop 0
	v_add_f32_e32 v3, 1.0, v3
	v_rcp_f32_e32 v7, v3
	s_nop 0
	v_pk_mul_f32 v[4:5], v[4:5], v[6:7]
	v_pk_mul_f32 v[6:7], v[8:9], v[58:59] op_sel_hi:[1,0]
	s_nop 0
	v_pk_mul_f32 v[4:5], v[6:7], v[4:5]
	s_nop 0
	v_cvt_pk_bf16_f32 v3, v4, v5
	v_lshl_add_u64 v[4:5], v[130:131], 1, s[2:3]
	ds_write_b64 v167, v[2:3] offset:6144
	s_waitcnt lgkmcnt(0)
	ds_read_b128 v[172:175], v168
	ds_read_b128 v[176:179], v168 offset:1024
	ds_read_b128 v[180:183], v168 offset:2048
	ds_read_b128 v[184:187], v168 offset:3072
	ds_read_b128 v[188:191], v168 offset:4096
	ds_read_b128 v[192:195], v168 offset:5120
	ds_read_b128 v[196:199], v168 offset:6144
	ds_read_b128 v[200:203], v168 offset:7168
	v_add_u32_e32 v204, 0x16000, v169
	v_add_u32_e32 v205, 0x2c000, v169
	v_add_u32_e32 v206, 0x42000, v169
	v_add_u32_e32 v207, 0x160000, v169
	v_add_u32_e32 v208, 0x176000, v169
	v_add_u32_e32 v209, 0x18c000, v169
	v_add_u32_e32 v210, 0x1a2000, v169
	s_waitcnt lgkmcnt(7)
	global_store_dwordx4 v169, v[172:175], s[2:3] nt
	s_waitcnt lgkmcnt(6)
	global_store_dwordx4 v204, v[176:179], s[2:3] nt
	s_waitcnt lgkmcnt(5)
	global_store_dwordx4 v205, v[180:183], s[2:3] nt
	s_waitcnt lgkmcnt(4)
	global_store_dwordx4 v206, v[184:187], s[2:3] nt
	s_waitcnt lgkmcnt(3)
	global_store_dwordx4 v207, v[188:191], s[2:3] nt
	s_waitcnt lgkmcnt(2)
	global_store_dwordx4 v208, v[192:195], s[2:3] nt
	s_waitcnt lgkmcnt(1)
	global_store_dwordx4 v209, v[196:199], s[2:3] nt
	s_waitcnt lgkmcnt(0)
	global_store_dwordx4 v210, v[200:203], s[2:3] nt
	s_cbranch_vccz .LBB0_338

; template <int EPI, int NRM>
; DEVI void epilogue(acc_t& acc, int pn, int trow, const EpiArgs& e, const float* rl, bf16* shmx) {
;     ...
;   if constexpr (EPI == EPI_RESID) {
;     float ss[2][2] = {{0.f, 0.f}, {0.f, 0.f}};
;     __amdgpu_buffer_rsrc_t rsX = __builtin_amdgcn_make_buffer_rsrc((void*)e.xin, 0, 0x7fffffff, 0x00020000);
;     char* lbase = reinterpret_cast<char*>(shmx) + wid * 16384;
;     const int vx = ((tk0 * DM) + pn * 256 + fl0) * 4;
; #pragma unroll
;     for (int ai = 0; ai < 2; ++ai) {
; #pragma unroll
;       for (int bj = 0; bj < 2; ++bj)
; #pragma unroll
;         for (int m = 0; m < 4; ++m)
; #pragma unroll
;           for (int n = 0; n < 2; ++n) {
;             const int idx = (bj * 4 + m) * 2 + n;
;             const int so = ((bj * 128 + n * 16) * DM + ai * 128 + m * 16) * 4;
;             __builtin_amdgcn_raw_ptr_buffer_load_lds(rsX, (__attribute__((address_space(3))) unsigned*)(lbase + idx * 1024 + lane * 16), 16, vx, so, 0, 0);
;           }
;       asm volatile("s_waitcnt vmcnt(0)" ::: "memory");
; #pragma unroll
;       for (int bj = 0; bj < 2; ++bj)
; #pragma unroll
;         for (int m = 0; m < 4; ++m)
; #pragma unroll
;           for (int n = 0; n < 2; ++n) {
;             const int idx = (bj * 4 + m) * 2 + n;
;             const unsigned off = (unsigned)((tk0 + bj * 128 + n * 16) * DM + pn * 256 + ai * 128 + m * 16 + fl0);
;             const float4 xx = *reinterpret_cast<const float4*>(lbase + idx * 1024 + lane * 16);
;             float4 o;
;             o.x = xx.x + acc[ai][bj][m][n][0]; o.y = xx.y + acc[ai][bj][m][n][1];
;             o.z = xx.z + acc[ai][bj][m][n][2]; o.w = xx.w + acc[ai][bj][m][n][3];
;             *reinterpret_cast<float4*>(e.xout + off) = o;
;             uint2 ob; ob.x = pack2(o.x, o.y); ob.y = pack2(o.z, o.w);
;             *reinterpret_cast<uint2*>(e.o0 + off) = ob;
;             ss[bj][n] += o.x * o.x + o.y * o.y + o.z * o.z + o.w * o.w;
.LBB0_381:
	v_and_b32_e32 v138, 15, v134
	v_bfe_u32 v198, v134, 4, 2
	v_lshrrev_b32_e32 v199, 6, v134
	v_and_b32_e32 v200, 3, v199
	v_lshrrev_b32_e32 v201, 2, v199
	v_lshlrev_b32_e32 v202, 14, v199
	v_and_b32_e32 v203, 63, v134
	v_lshl_add_u32 v143, v203, 4, v202
	v_lshl_add_u32 v202, v138, 8, v202
	v_and_b32_e32 v203, 7, v138
	v_add_u32_e32 v204, 0, v198
	v_xor_b32_e32 v204, v204, v203
	v_lshl_add_u32 v139, v204, 4, v202
	v_add_u32_e32 v204, 4, v198
	v_xor_b32_e32 v204, v204, v203
	v_lshl_add_u32 v140, v204, 4, v202
	v_add_u32_e32 v204, 8, v198
	v_xor_b32_e32 v204, v204, v203
	v_lshl_add_u32 v141, v204, 4, v202
	v_add_u32_e32 v204, 12, v198
	v_xor_b32_e32 v204, v204, v203
	v_lshl_add_u32 v142, v204, 4, v202
	s_lshl_b32 s6, s37, 8
	v_lshl_add_u32 v202, v200, 5, v198
	v_add_u32_e32 v202, s6, v202
	s_lshl_b32 s6, s36, 1
	v_add_u32_e32 v204, s6, v201
	v_lshl_add_u32 v204, v204, 15, v202
	v_lshlrev_b32_e32 v148, 2, v204
	v_lshlrev_b32_e32 v202, 11, v202
	s_lshl_b32 s6, s36, 8
	v_lshl_add_u32 v204, v201, 6, s6
	v_add_u32_e32 v202, v202, v204
	v_add_u32_e32 v203, 0, v198
	v_xor_b32_e32 v203, v203, v138
	v_lshl_add_u32 v203, v203, 2, v202
	v_lshlrev_b32_e32 v144, 2, v203
	v_lshlrev_b32_e32 v146, 1, v203
	v_add_u32_e32 v203, 4, v198
	v_xor_b32_e32 v203, v203, v138
	v_lshl_add_u32 v203, v203, 2, v202
	v_lshlrev_b32_e32 v145, 2, v203
	v_lshlrev_b32_e32 v147, 1, v203
	v_readlane_b32 s10, v250, 5
	v_readlane_b32 s11, v250, 6
	v_add_u32_e32 v157, 0x0, v144
	global_load_dwordx4 v[166:169], v157, s[4:5] nt
	v_add_u32_e32 v160, 0x8000, v145
	global_load_dwordx4 v[170:173], v160, s[4:5] nt
	v_add_u32_e32 v157, 0x10000, v144
	global_load_dwordx4 v[174:177], v157, s[4:5] nt
	v_add_u32_e32 v160, 0x18000, v145
	global_load_dwordx4 v[178:181], v160, s[4:5] nt
	v_add_u32_e32 v157, 0x20000, v144
	global_load_dwordx4 v[182:185], v157, s[4:5] nt
	v_add_u32_e32 v160, 0x28000, v145
	global_load_dwordx4 v[186:189], v160, s[4:5] nt
	v_add_u32_e32 v157, 0x30000, v144
	global_load_dwordx4 v[190:193], v157, s[4:5] nt
	v_add_u32_e32 v160, 0x38000, v145
	global_load_dwordx4 v[194:197], v160, s[4:5] nt
	v_add_u32_e32 v157, 0x200, v144
	global_load_dwordx4 v[198:201], v157, s[4:5] nt
	v_add_u32_e32 v160, 0x8200, v145
	global_load_dwordx4 v[202:205], v160, s[4:5] nt
	v_add_u32_e32 v157, 0x10200, v144
	global_load_dwordx4 v[206:209], v157, s[4:5] nt
	v_add_u32_e32 v160, 0x18200, v145
	global_load_dwordx4 v[210:213], v160, s[4:5] nt
	v_add_u32_e32 v157, 0x20200, v144
	global_load_dwordx4 v[214:217], v157, s[4:5] nt
	v_add_u32_e32 v160, 0x28200, v145
	global_load_dwordx4 v[218:221], v160, s[4:5] nt
	v_add_u32_e32 v157, 0x30200, v144
	global_load_dwordx4 v[222:225], v157, s[4:5] nt
	v_add_u32_e32 v160, 0x38200, v145
	global_load_dwordx4 v[226:229], v160, s[4:5] nt
	ds_write_b128 v139, v[126:129]
	ds_write_b128 v139, v[14:17] offset:4096
	ds_write_b128 v140, v[122:125]
	ds_write_b128 v140, v[30:33] offset:4096
	ds_write_b128 v141, v[118:121]
	ds_write_b128 v141, v[46:49] offset:4096
	ds_write_b128 v142, v[114:117]
	ds_write_b128 v142, v[54:57] offset:4096
	ds_write_b128 v139, v[110:113] offset:8192
	ds_write_b128 v139, v[106:109] offset:12288
	ds_write_b128 v140, v[102:105] offset:8192
	ds_write_b128 v140, v[90:93] offset:12288
	ds_write_b128 v141, v[86:89] offset:8192
	ds_write_b128 v141, v[74:77] offset:12288
	ds_write_b128 v142, v[70:73] offset:8192
	ds_write_b128 v142, v[42:45] offset:12288
	s_waitcnt lgkmcnt(0)
	ds_read_b128 v[126:129], v143
	ds_read_b128 v[14:17], v143 offset:1024
	ds_read_b128 v[122:125], v143 offset:2048
	ds_read_b128 v[30:33], v143 offset:3072
	ds_read_b128 v[118:121], v143 offset:4096
	ds_read_b128 v[46:49], v143 offset:5120
	ds_read_b128 v[114:117], v143 offset:6144
	ds_read_b128 v[54:57], v143 offset:7168
	ds_read_b128 v[110:113], v143 offset:8192
	ds_read_b128 v[106:109], v143 offset:9216
	ds_read_b128 v[102:105], v143 offset:10240
	ds_read_b128 v[90:93], v143 offset:11264
	ds_read_b128 v[86:89], v143 offset:12288
	ds_read_b128 v[74:77], v143 offset:13312
	ds_read_b128 v[70:73], v143 offset:14336
	ds_read_b128 v[42:45], v143 offset:15360
	s_waitcnt lgkmcnt(0)
	ds_write_b128 v139, v[50:53]
	ds_write_b128 v139, v[58:61] offset:4096
	ds_write_b128 v140, v[62:65]
	ds_write_b128 v140, v[66:69] offset:4096
	ds_write_b128 v141, v[78:81]
	ds_write_b128 v141, v[82:85] offset:4096
	ds_write_b128 v142, v[94:97]
	ds_write_b128 v142, v[98:101] offset:4096
	ds_write_b128 v139, v[38:41] offset:8192
	ds_write_b128 v139, v[34:37] offset:12288
	ds_write_b128 v140, v[26:29] offset:8192
	ds_write_b128 v140, v[22:25] offset:12288
	ds_write_b128 v141, v[18:21] offset:8192
	ds_write_b128 v141, v[10:13] offset:12288
	ds_write_b128 v142, v[6:9] offset:8192
	ds_write_b128 v142, v[2:5] offset:12288
	s_waitcnt vmcnt(15)
	v_pk_add_f32 v[166:167], v[166:167], v[126:127]
	v_pk_add_f32 v[168:169], v[168:169], v[128:129]
	v_add_u32_e32 v157, 0x0, v144
	v_cvt_pk_bf16_f32 v158, v166, v167
	v_cvt_pk_bf16_f32 v159, v168, v169
	global_store_dwordx4 v157, v[166:169], s[26:27] nt
	v_add_u32_e32 v126, 0x0, v146
	v_mul_f32_e32 v149, v166, v166
	global_store_dwordx2 v126, v[158:159], s[96:97]
	v_fmac_f32_e32 v149, v167, v167
	v_fmac_f32_e32 v149, v168, v168
	v_fmac_f32_e32 v149, v169, v169
	s_waitcnt vmcnt(16)
	v_pk_add_f32 v[170:171], v[170:171], v[14:15]
	v_pk_add_f32 v[172:173], v[172:173], v[16:17]
	v_add_u32_e32 v160, 0x8000, v145
	v_cvt_pk_bf16_f32 v164, v170, v171
	v_cvt_pk_bf16_f32 v165, v172, v173
	global_store_dwordx4 v160, v[170:173], s[26:27] nt
	v_add_u32_e32 v14, 0x4000, v147
	v_mul_f32_e32 v150, v170, v170
	global_store_dwordx2 v14, v[164:165], s[96:97]
	v_fmac_f32_e32 v150, v171, v171
	v_fmac_f32_e32 v150, v172, v172
	v_fmac_f32_e32 v150, v173, v173
	s_waitcnt vmcnt(17)
; template <int EPI, int NRM>
; DEVI void epilogue(acc_t& acc, int pn, int trow, const EpiArgs& e, const float* rl, bf16* shmx) {
;     ...
; #pragma unroll
;       for (int bj = 0; bj < 2; ++bj)
; #pragma unroll
;         for (int m = 0; m < 4; ++m)
; #pragma unroll
;           for (int n = 0; n < 2; ++n) {
;             const int idx = (bj * 4 + m) * 2 + n;
;             const unsigned off = (unsigned)((tk0 + bj * 128 + n * 16) * DM + pn * 256 + ai * 128 + m * 16 + fl0);
;             const float4 xx = *reinterpret_cast<const float4*>(lbase + idx * 1024 + lane * 16);
;             float4 o;
;             o.x = xx.x + acc[ai][bj][m][n][0]; o.y = xx.y + acc[ai][bj][m][n][1];
;             o.z = xx.z + acc[ai][bj][m][n][2]; o.w = xx.w + acc[ai][bj][m][n][3];
;             *reinterpret_cast<float4*>(e.xout + off) = o;
;             uint2 ob; ob.x = pack2(o.x, o.y); ob.y = pack2(o.z, o.w);
;             *reinterpret_cast<uint2*>(e.o0 + off) = ob;
;             ss[bj][n] += o.x * o.x + o.y * o.y + o.z * o.z + o.w * o.w;
;           }
	v_pk_add_f32 v[174:175], v[174:175], v[122:123]
	v_pk_add_f32 v[176:177], v[176:177], v[124:125]
	v_add_u32_e32 v157, 0x10000, v144
	v_cvt_pk_bf16_f32 v158, v174, v175
	v_cvt_pk_bf16_f32 v159, v176, v177
	global_store_dwordx4 v157, v[174:177], s[26:27] nt
	v_add_u32_e32 v122, 0x8000, v146
	v_mul_f32_e32 v151, v174, v174
	global_store_dwordx2 v122, v[158:159], s[96:97]
	v_fmac_f32_e32 v151, v175, v175
	v_fmac_f32_e32 v151, v176, v176
	v_fmac_f32_e32 v151, v177, v177
	s_waitcnt vmcnt(18)
	v_pk_add_f32 v[178:179], v[178:179], v[30:31]
	v_pk_add_f32 v[180:181], v[180:181], v[32:33]
	v_add_u32_e32 v160, 0x18000, v145
	v_cvt_pk_bf16_f32 v164, v178, v179
	v_cvt_pk_bf16_f32 v165, v180, v181
	global_store_dwordx4 v160, v[178:181], s[26:27] nt
	v_add_u32_e32 v30, 0xc000, v147
	v_mul_f32_e32 v152, v178, v178
	global_store_dwordx2 v30, v[164:165], s[96:97]
	v_fmac_f32_e32 v152, v179, v179
	v_fmac_f32_e32 v152, v180, v180
	v_fmac_f32_e32 v152, v181, v181
	s_waitcnt vmcnt(19)
	v_pk_add_f32 v[182:183], v[182:183], v[118:119]
	v_pk_add_f32 v[184:185], v[184:185], v[120:121]
	v_add_u32_e32 v157, 0x20000, v144
	v_cvt_pk_bf16_f32 v158, v182, v183
	v_cvt_pk_bf16_f32 v159, v184, v185
	global_store_dwordx4 v157, v[182:185], s[26:27] nt
	v_add_u32_e32 v118, 0x10000, v146
	v_mul_f32_e32 v153, v182, v182
	global_store_dwordx2 v118, v[158:159], s[96:97]
	v_fmac_f32_e32 v153, v183, v183
	v_fmac_f32_e32 v153, v184, v184
	v_fmac_f32_e32 v153, v185, v185
	s_waitcnt vmcnt(20)
	v_pk_add_f32 v[186:187], v[186:187], v[46:47]
	v_pk_add_f32 v[188:189], v[188:189], v[48:49]
	v_add_u32_e32 v160, 0x28000, v145
	v_cvt_pk_bf16_f32 v164, v186, v187
	v_cvt_pk_bf16_f32 v165, v188, v189
	global_store_dwordx4 v160, v[186:189], s[26:27] nt
	v_add_u32_e32 v46, 0x14000, v147
	v_mul_f32_e32 v154, v186, v186
	global_store_dwordx2 v46, v[164:165], s[96:97]
	v_fmac_f32_e32 v154, v187, v187
	v_fmac_f32_e32 v154, v188, v188
	v_fmac_f32_e32 v154, v189, v189
	s_waitcnt vmcnt(21)
	v_pk_add_f32 v[190:191], v[190:191], v[114:115]
	v_pk_add_f32 v[192:193], v[192:193], v[116:117]
	v_add_u32_e32 v157, 0x30000, v144
	v_cvt_pk_bf16_f32 v158, v190, v191
	v_cvt_pk_bf16_f32 v159, v192, v193
	global_store_dwordx4 v157, v[190:193], s[26:27] nt
	v_add_u32_e32 v114, 0x18000, v146
	v_mul_f32_e32 v155, v190, v190
	global_store_dwordx2 v114, v[158:159], s[96:97]
	v_fmac_f32_e32 v155, v191, v191
	v_fmac_f32_e32 v155, v192, v192
	v_fmac_f32_e32 v155, v193, v193
	s_waitcnt vmcnt(22)
	v_pk_add_f32 v[194:195], v[194:195], v[54:55]
	v_pk_add_f32 v[196:197], v[196:197], v[56:57]
	v_add_u32_e32 v160, 0x38000, v145
	v_cvt_pk_bf16_f32 v164, v194, v195
	v_cvt_pk_bf16_f32 v165, v196, v197
	global_store_dwordx4 v160, v[194:197], s[26:27] nt
	v_add_u32_e32 v54, 0x1c000, v147
	v_mul_f32_e32 v156, v194, v194
	global_store_dwordx2 v54, v[164:165], s[96:97]
	v_fmac_f32_e32 v156, v195, v195
	v_fmac_f32_e32 v156, v196, v196
	v_fmac_f32_e32 v156, v197, v197
	v_add_u32_e32 v157, 0x100000, v144
	global_load_dwordx4 v[166:169], v157, s[4:5] nt
	v_add_u32_e32 v160, 0x108000, v145
	global_load_dwordx4 v[170:173], v160, s[4:5] nt
	v_add_u32_e32 v157, 0x110000, v144
	global_load_dwordx4 v[174:177], v157, s[4:5] nt
	v_add_u32_e32 v160, 0x118000, v145
	global_load_dwordx4 v[178:181], v160, s[4:5] nt
	v_add_u32_e32 v157, 0x120000, v144
	global_load_dwordx4 v[182:185], v157, s[4:5] nt
	v_add_u32_e32 v160, 0x128000, v145
	global_load_dwordx4 v[186:189], v160, s[4:5] nt
	v_add_u32_e32 v157, 0x130000, v144
	global_load_dwordx4 v[190:193], v157, s[4:5] nt
	v_add_u32_e32 v160, 0x138000, v145
	global_load_dwordx4 v[194:197], v160, s[4:5] nt
	s_waitcnt vmcnt(31)
	v_pk_add_f32 v[198:199], v[198:199], v[110:111]
	v_pk_add_f32 v[200:201], v[200:201], v[112:113]
	v_add_u32_e32 v157, 0x200, v144
	v_cvt_pk_bf16_f32 v158, v198, v199
	v_cvt_pk_bf16_f32 v159, v200, v201
	global_store_dwordx4 v157, v[198:201], s[26:27] nt
	v_add_u32_e32 v110, 0x100, v146
	v_fmac_f32_e32 v149, v198, v198
	global_store_dwordx2 v110, v[158:159], s[96:97]
	v_fmac_f32_e32 v149, v199, v199
	v_fmac_f32_e32 v149, v200, v200
	v_fmac_f32_e32 v149, v201, v201
	s_waitcnt vmcnt(32)
	v_pk_add_f32 v[202:203], v[202:203], v[106:107]
	v_pk_add_f32 v[204:205], v[204:205], v[108:109]
	v_add_u32_e32 v160, 0x8200, v145
	v_cvt_pk_bf16_f32 v164, v202, v203
	v_cvt_pk_bf16_f32 v165, v204, v205
	global_store_dwordx4 v160, v[202:205], s[26:27] nt
	v_add_u32_e32 v106, 0x4100, v147
	v_fmac_f32_e32 v150, v202, v202
	global_store_dwordx2 v106, v[164:165], s[96:97]
	v_fmac_f32_e32 v150, v203, v203
	v_fmac_f32_e32 v150, v204, v204
	v_fmac_f32_e32 v150, v205, v205
	s_waitcnt vmcnt(33)
	v_pk_add_f32 v[206:207], v[206:207], v[102:103]
	v_pk_add_f32 v[208:209], v[208:209], v[104:105]
	v_add_u32_e32 v157, 0x10200, v144
	v_cvt_pk_bf16_f32 v158, v206, v207
	v_cvt_pk_bf16_f32 v159, v208, v209
	global_store_dwordx4 v157, v[206:209], s[26:27] nt
	v_add_u32_e32 v102, 0x8100, v146
	v_fmac_f32_e32 v151, v206, v206
	global_store_dwordx2 v102, v[158:159], s[96:97]
	v_fmac_f32_e32 v151, v207, v207
	v_fmac_f32_e32 v151, v208, v208
	v_fmac_f32_e32 v151, v209, v209
	s_waitcnt vmcnt(34)
	v_pk_add_f32 v[210:211], v[210:211], v[90:91]
	v_pk_add_f32 v[212:213], v[212:213], v[92:93]
	v_add_u32_e32 v160, 0x18200, v145
	v_cvt_pk_bf16_f32 v164, v210, v211
	v_cvt_pk_bf16_f32 v165, v212, v213
	global_store_dwordx4 v160, v[210:213], s[26:27] nt
	v_add_u32_e32 v90, 0xc100, v147
	v_fmac_f32_e32 v152, v210, v210
	global_store_dwordx2 v90, v[164:165], s[96:97]
	v_fmac_f32_e32 v152, v211, v211
	v_fmac_f32_e32 v152, v212, v212
	v_fmac_f32_e32 v152, v213, v213
	s_waitcnt vmcnt(35)
; template <int EPI, int NRM>
; DEVI void epilogue(acc_t& acc, int pn, int trow, const EpiArgs& e, const float* rl, bf16* shmx) {
;     ...
;             const float4 xx = *reinterpret_cast<const float4*>(lbase + idx * 1024 + lane * 16);
;             float4 o;
;             o.x = xx.x + acc[ai][bj][m][n][0]; o.y = xx.y + acc[ai][bj][m][n][1];
;             o.z = xx.z + acc[ai][bj][m][n][2]; o.w = xx.w + acc[ai][bj][m][n][3];
;             *reinterpret_cast<float4*>(e.xout + off) = o;
;             uint2 ob; ob.x = pack2(o.x, o.y); ob.y = pack2(o.z, o.w);
;             *reinterpret_cast<uint2*>(e.o0 + off) = ob;
;             ss[bj][n] += o.x * o.x + o.y * o.y + o.z * o.z + o.w * o.w;
;           }
;       asm volatile("s_waitcnt lgkmcnt(0)" ::: "memory");
;     }
; #pragma unroll
;     for (int bj = 0; bj < 2; ++bj)
; #pragma unroll
;       for (int n = 0; n < 2; ++n) {
;         float v = ss[bj][n];
;         v += __shfl_xor(v, 16); v += __shfl_xor(v, 32);
;         if (fq == 0) e.stw[(pn * 2 + wr) * TOK + tk0 + bj * 128 + n * 16] = v;
;       }
	v_pk_add_f32 v[214:215], v[214:215], v[86:87]
	v_pk_add_f32 v[216:217], v[216:217], v[88:89]
	v_add_u32_e32 v157, 0x20200, v144
	v_cvt_pk_bf16_f32 v158, v214, v215
	v_cvt_pk_bf16_f32 v159, v216, v217
	global_store_dwordx4 v157, v[214:217], s[26:27] nt
	v_add_u32_e32 v86, 0x10100, v146
	v_fmac_f32_e32 v153, v214, v214
	global_store_dwordx2 v86, v[158:159], s[96:97]
	v_fmac_f32_e32 v153, v215, v215
	v_fmac_f32_e32 v153, v216, v216
	v_fmac_f32_e32 v153, v217, v217
	s_waitcnt vmcnt(36)
	v_pk_add_f32 v[218:219], v[218:219], v[74:75]
	v_pk_add_f32 v[220:221], v[220:221], v[76:77]
	v_add_u32_e32 v160, 0x28200, v145
	v_cvt_pk_bf16_f32 v164, v218, v219
	v_cvt_pk_bf16_f32 v165, v220, v221
	global_store_dwordx4 v160, v[218:221], s[26:27] nt
	v_add_u32_e32 v74, 0x14100, v147
	v_fmac_f32_e32 v154, v218, v218
	global_store_dwordx2 v74, v[164:165], s[96:97]
	v_fmac_f32_e32 v154, v219, v219
	v_fmac_f32_e32 v154, v220, v220
	v_fmac_f32_e32 v154, v221, v221
	s_waitcnt vmcnt(37)
	v_pk_add_f32 v[222:223], v[222:223], v[70:71]
	v_pk_add_f32 v[224:225], v[224:225], v[72:73]
	v_add_u32_e32 v157, 0x30200, v144
	v_cvt_pk_bf16_f32 v158, v222, v223
	v_cvt_pk_bf16_f32 v159, v224, v225
	global_store_dwordx4 v157, v[222:225], s[26:27] nt
	v_add_u32_e32 v70, 0x18100, v146
	v_fmac_f32_e32 v155, v222, v222
	global_store_dwordx2 v70, v[158:159], s[96:97]
	v_fmac_f32_e32 v155, v223, v223
	v_fmac_f32_e32 v155, v224, v224
	v_fmac_f32_e32 v155, v225, v225
	s_waitcnt vmcnt(38)
	v_pk_add_f32 v[226:227], v[226:227], v[42:43]
	v_pk_add_f32 v[228:229], v[228:229], v[44:45]
	v_add_u32_e32 v160, 0x38200, v145
	v_cvt_pk_bf16_f32 v164, v226, v227
	v_cvt_pk_bf16_f32 v165, v228, v229
	global_store_dwordx4 v160, v[226:229], s[26:27] nt
	v_add_u32_e32 v42, 0x1c100, v147
	v_fmac_f32_e32 v156, v226, v226
	global_store_dwordx2 v42, v[164:165], s[96:97]
	v_fmac_f32_e32 v156, v227, v227
	v_fmac_f32_e32 v156, v228, v228
	v_fmac_f32_e32 v156, v229, v229
	v_add_u32_e32 v157, 0x100200, v144
	global_load_dwordx4 v[198:201], v157, s[4:5] nt
	v_add_u32_e32 v160, 0x108200, v145
	global_load_dwordx4 v[202:205], v160, s[4:5] nt
	v_add_u32_e32 v157, 0x110200, v144
	global_load_dwordx4 v[206:209], v157, s[4:5] nt
	v_add_u32_e32 v160, 0x118200, v145
	global_load_dwordx4 v[210:213], v160, s[4:5] nt
	v_add_u32_e32 v157, 0x120200, v144
	global_load_dwordx4 v[214:217], v157, s[4:5] nt
	v_add_u32_e32 v160, 0x128200, v145
	global_load_dwordx4 v[218:221], v160, s[4:5] nt
	v_add_u32_e32 v157, 0x130200, v144
	global_load_dwordx4 v[222:225], v157, s[4:5] nt
	v_add_u32_e32 v160, 0x138200, v145
	global_load_dwordx4 v[226:229], v160, s[4:5] nt
	v_add_f32_dpp v149, v149, v149 row_shr:1 row_mask:0xf bank_mask:0xf bound_ctrl:0
	v_add_f32_dpp v150, v150, v150 row_shr:1 row_mask:0xf bank_mask:0xf bound_ctrl:0
	v_add_f32_dpp v151, v151, v151 row_shr:1 row_mask:0xf bank_mask:0xf bound_ctrl:0
	v_add_f32_dpp v152, v152, v152 row_shr:1 row_mask:0xf bank_mask:0xf bound_ctrl:0
	v_add_f32_dpp v153, v153, v153 row_shr:1 row_mask:0xf bank_mask:0xf bound_ctrl:0
	v_add_f32_dpp v154, v154, v154 row_shr:1 row_mask:0xf bank_mask:0xf bound_ctrl:0
	v_add_f32_dpp v155, v155, v155 row_shr:1 row_mask:0xf bank_mask:0xf bound_ctrl:0
	v_add_f32_dpp v156, v156, v156 row_shr:1 row_mask:0xf bank_mask:0xf bound_ctrl:0
	v_add_f32_dpp v149, v149, v149 row_shr:2 row_mask:0xf bank_mask:0xf bound_ctrl:0
	v_add_f32_dpp v150, v150, v150 row_shr:2 row_mask:0xf bank_mask:0xf bound_ctrl:0
	v_add_f32_dpp v151, v151, v151 row_shr:2 row_mask:0xf bank_mask:0xf bound_ctrl:0
	v_add_f32_dpp v152, v152, v152 row_shr:2 row_mask:0xf bank_mask:0xf bound_ctrl:0
	v_add_f32_dpp v153, v153, v153 row_shr:2 row_mask:0xf bank_mask:0xf bound_ctrl:0
	v_add_f32_dpp v154, v154, v154 row_shr:2 row_mask:0xf bank_mask:0xf bound_ctrl:0
	v_add_f32_dpp v155, v155, v155 row_shr:2 row_mask:0xf bank_mask:0xf bound_ctrl:0
	v_add_f32_dpp v156, v156, v156 row_shr:2 row_mask:0xf bank_mask:0xf bound_ctrl:0
	v_add_f32_dpp v149, v149, v149 row_shr:4 row_mask:0xf bank_mask:0xf bound_ctrl:0
	v_add_f32_dpp v150, v150, v150 row_shr:4 row_mask:0xf bank_mask:0xf bound_ctrl:0
	v_add_f32_dpp v151, v151, v151 row_shr:4 row_mask:0xf bank_mask:0xf bound_ctrl:0
	v_add_f32_dpp v152, v152, v152 row_shr:4 row_mask:0xf bank_mask:0xf bound_ctrl:0
	v_add_f32_dpp v153, v153, v153 row_shr:4 row_mask:0xf bank_mask:0xf bound_ctrl:0
	v_add_f32_dpp v154, v154, v154 row_shr:4 row_mask:0xf bank_mask:0xf bound_ctrl:0
	v_add_f32_dpp v155, v155, v155 row_shr:4 row_mask:0xf bank_mask:0xf bound_ctrl:0
	v_add_f32_dpp v156, v156, v156 row_shr:4 row_mask:0xf bank_mask:0xf bound_ctrl:0
	v_add_f32_dpp v149, v149, v149 row_shr:8 row_mask:0xf bank_mask:0xf bound_ctrl:0
	v_add_f32_dpp v150, v150, v150 row_shr:8 row_mask:0xf bank_mask:0xf bound_ctrl:0
	v_add_f32_dpp v151, v151, v151 row_shr:8 row_mask:0xf bank_mask:0xf bound_ctrl:0
	v_add_f32_dpp v152, v152, v152 row_shr:8 row_mask:0xf bank_mask:0xf bound_ctrl:0
	v_add_f32_dpp v153, v153, v153 row_shr:8 row_mask:0xf bank_mask:0xf bound_ctrl:0
	v_add_f32_dpp v154, v154, v154 row_shr:8 row_mask:0xf bank_mask:0xf bound_ctrl:0
	v_add_f32_dpp v155, v155, v155 row_shr:8 row_mask:0xf bank_mask:0xf bound_ctrl:0
	v_add_f32_dpp v156, v156, v156 row_shr:8 row_mask:0xf bank_mask:0xf bound_ctrl:0
	v_cmp_eq_u32_e32 vcc, 15, v138
	s_and_saveexec_b64 s[6:7], vcc
	global_store_dword v148, v149, s[10:11]
	global_store_dword v148, v150, s[10:11] offset:16
	global_store_dword v148, v151, s[10:11] offset:32
	global_store_dword v148, v152, s[10:11] offset:48
	global_store_dword v148, v153, s[10:11] offset:64
	global_store_dword v148, v154, s[10:11] offset:80
	global_store_dword v148, v155, s[10:11] offset:96
	global_store_dword v148, v156, s[10:11] offset:112
	s_or_b64 exec, exec, s[6:7]
	s_waitcnt lgkmcnt(0)
; template <int EPI, int NRM>
; DEVI void epilogue(acc_t& acc, int pn, int trow, const EpiArgs& e, const float* rl, bf16* shmx) {
;     ...
; #pragma unroll
;       for (int bj = 0; bj < 2; ++bj)
; #pragma unroll
;         for (int m = 0; m < 4; ++m)
; #pragma unroll
;           for (int n = 0; n < 2; ++n) {
;             const int idx = (bj * 4 + m) * 2 + n;
;             const unsigned off = (unsigned)((tk0 + bj * 128 + n * 16) * DM + pn * 256 + ai * 128 + m * 16 + fl0);
;             const float4 xx = *reinterpret_cast<const float4*>(lbase + idx * 1024 + lane * 16);
;             float4 o;
;             o.x = xx.x + acc[ai][bj][m][n][0]; o.y = xx.y + acc[ai][bj][m][n][1];
;             o.z = xx.z + acc[ai][bj][m][n][2]; o.w = xx.w + acc[ai][bj][m][n][3];
;             *reinterpret_cast<float4*>(e.xout + off) = o;
;             uint2 ob; ob.x = pack2(o.x, o.y); ob.y = pack2(o.z, o.w);
;             *reinterpret_cast<uint2*>(e.o0 + off) = ob;
;             ss[bj][n] += o.x * o.x + o.y * o.y + o.z * o.z + o.w * o.w;
;           }
	ds_read_b128 v[50:53], v143
	ds_read_b128 v[58:61], v143 offset:1024
	ds_read_b128 v[62:65], v143 offset:2048
	ds_read_b128 v[66:69], v143 offset:3072
	ds_read_b128 v[78:81], v143 offset:4096
	ds_read_b128 v[82:85], v143 offset:5120
	ds_read_b128 v[94:97], v143 offset:6144
	ds_read_b128 v[98:101], v143 offset:7168
	ds_read_b128 v[38:41], v143 offset:8192
	ds_read_b128 v[34:37], v143 offset:9216
	ds_read_b128 v[26:29], v143 offset:10240
	ds_read_b128 v[22:25], v143 offset:11264
	ds_read_b128 v[18:21], v143 offset:12288
	ds_read_b128 v[10:13], v143 offset:13312
	ds_read_b128 v[6:9], v143 offset:14336
	ds_read_b128 v[2:5], v143 offset:15360
	s_waitcnt lgkmcnt(0)
	s_waitcnt vmcnt(39)
	v_pk_add_f32 v[166:167], v[166:167], v[50:51]
	v_pk_add_f32 v[168:169], v[168:169], v[52:53]
	v_add_u32_e32 v157, 0x100000, v144
	v_cvt_pk_bf16_f32 v158, v166, v167
	v_cvt_pk_bf16_f32 v159, v168, v169
	global_store_dwordx4 v157, v[166:169], s[26:27] nt
	v_add_u32_e32 v50, 0x80000, v146
	v_mul_f32_e32 v149, v166, v166
	global_store_dwordx2 v50, v[158:159], s[96:97]
	v_fmac_f32_e32 v149, v167, v167
	v_fmac_f32_e32 v149, v168, v168
	v_fmac_f32_e32 v149, v169, v169
	s_waitcnt vmcnt(40)
	v_pk_add_f32 v[170:171], v[170:171], v[58:59]
	v_pk_add_f32 v[172:173], v[172:173], v[60:61]
	v_add_u32_e32 v160, 0x108000, v145
	v_cvt_pk_bf16_f32 v164, v170, v171
	v_cvt_pk_bf16_f32 v165, v172, v173
	global_store_dwordx4 v160, v[170:173], s[26:27] nt
	v_add_u32_e32 v58, 0x84000, v147
	v_mul_f32_e32 v150, v170, v170
	global_store_dwordx2 v58, v[164:165], s[96:97]
	v_fmac_f32_e32 v150, v171, v171
	v_fmac_f32_e32 v150, v172, v172
	v_fmac_f32_e32 v150, v173, v173
	s_waitcnt vmcnt(41)
	v_pk_add_f32 v[174:175], v[174:175], v[62:63]
	v_pk_add_f32 v[176:177], v[176:177], v[64:65]
	v_add_u32_e32 v157, 0x110000, v144
	v_cvt_pk_bf16_f32 v158, v174, v175
	v_cvt_pk_bf16_f32 v159, v176, v177
	global_store_dwordx4 v157, v[174:177], s[26:27] nt
	v_add_u32_e32 v62, 0x88000, v146
	v_mul_f32_e32 v151, v174, v174
	global_store_dwordx2 v62, v[158:159], s[96:97]
	v_fmac_f32_e32 v151, v175, v175
	v_fmac_f32_e32 v151, v176, v176
	v_fmac_f32_e32 v151, v177, v177
	s_waitcnt vmcnt(42)
	v_pk_add_f32 v[178:179], v[178:179], v[66:67]
	v_pk_add_f32 v[180:181], v[180:181], v[68:69]
	v_add_u32_e32 v160, 0x118000, v145
	v_cvt_pk_bf16_f32 v164, v178, v179
	v_cvt_pk_bf16_f32 v165, v180, v181
	global_store_dwordx4 v160, v[178:181], s[26:27] nt
	v_add_u32_e32 v66, 0x8c000, v147
	v_mul_f32_e32 v152, v178, v178
	global_store_dwordx2 v66, v[164:165], s[96:97]
	v_fmac_f32_e32 v152, v179, v179
	v_fmac_f32_e32 v152, v180, v180
	v_fmac_f32_e32 v152, v181, v181
	s_waitcnt vmcnt(43)
	v_pk_add_f32 v[182:183], v[182:183], v[78:79]
	v_pk_add_f32 v[184:185], v[184:185], v[80:81]
	v_add_u32_e32 v157, 0x120000, v144
	v_cvt_pk_bf16_f32 v158, v182, v183
	v_cvt_pk_bf16_f32 v159, v184, v185
	global_store_dwordx4 v157, v[182:185], s[26:27] nt
	v_add_u32_e32 v78, 0x90000, v146
	v_mul_f32_e32 v153, v182, v182
	global_store_dwordx2 v78, v[158:159], s[96:97]
	v_fmac_f32_e32 v153, v183, v183
	v_fmac_f32_e32 v153, v184, v184
	v_fmac_f32_e32 v153, v185, v185
	s_waitcnt vmcnt(44)
	v_pk_add_f32 v[186:187], v[186:187], v[82:83]
	v_pk_add_f32 v[188:189], v[188:189], v[84:85]
	v_add_u32_e32 v160, 0x128000, v145
	v_cvt_pk_bf16_f32 v164, v186, v187
	v_cvt_pk_bf16_f32 v165, v188, v189
	global_store_dwordx4 v160, v[186:189], s[26:27] nt
	v_add_u32_e32 v82, 0x94000, v147
	v_mul_f32_e32 v154, v186, v186
	global_store_dwordx2 v82, v[164:165], s[96:97]
	v_fmac_f32_e32 v154, v187, v187
	v_fmac_f32_e32 v154, v188, v188
	v_fmac_f32_e32 v154, v189, v189
	s_waitcnt vmcnt(45)
	v_pk_add_f32 v[190:191], v[190:191], v[94:95]
	v_pk_add_f32 v[192:193], v[192:193], v[96:97]
	v_add_u32_e32 v157, 0x130000, v144
	v_cvt_pk_bf16_f32 v158, v190, v191
	v_cvt_pk_bf16_f32 v159, v192, v193
	global_store_dwordx4 v157, v[190:193], s[26:27] nt
	v_add_u32_e32 v94, 0x98000, v146
	v_mul_f32_e32 v155, v190, v190
	global_store_dwordx2 v94, v[158:159], s[96:97]
	v_fmac_f32_e32 v155, v191, v191
	v_fmac_f32_e32 v155, v192, v192
	v_fmac_f32_e32 v155, v193, v193
	s_waitcnt vmcnt(46)
	v_pk_add_f32 v[194:195], v[194:195], v[98:99]
	v_pk_add_f32 v[196:197], v[196:197], v[100:101]
	v_add_u32_e32 v160, 0x138000, v145
	v_cvt_pk_bf16_f32 v164, v194, v195
	v_cvt_pk_bf16_f32 v165, v196, v197
	global_store_dwordx4 v160, v[194:197], s[26:27] nt
	v_add_u32_e32 v98, 0x9c000, v147
	v_mul_f32_e32 v156, v194, v194
	global_store_dwordx2 v98, v[164:165], s[96:97]
	v_fmac_f32_e32 v156, v195, v195
	v_fmac_f32_e32 v156, v196, v196
	v_fmac_f32_e32 v156, v197, v197
	s_waitcnt vmcnt(31)
	v_pk_add_f32 v[198:199], v[198:199], v[38:39]
	v_pk_add_f32 v[200:201], v[200:201], v[40:41]
	v_add_u32_e32 v157, 0x100200, v144
	v_cvt_pk_bf16_f32 v158, v198, v199
	v_cvt_pk_bf16_f32 v159, v200, v201
	global_store_dwordx4 v157, v[198:201], s[26:27] nt
	v_add_u32_e32 v38, 0x80100, v146
	v_fmac_f32_e32 v149, v198, v198
	global_store_dwordx2 v38, v[158:159], s[96:97]
	v_fmac_f32_e32 v149, v199, v199
	v_fmac_f32_e32 v149, v200, v200
	v_fmac_f32_e32 v149, v201, v201
	s_waitcnt vmcnt(32)
	v_pk_add_f32 v[202:203], v[202:203], v[34:35]
	v_pk_add_f32 v[204:205], v[204:205], v[36:37]
	v_add_u32_e32 v160, 0x108200, v145
	v_cvt_pk_bf16_f32 v164, v202, v203
	v_cvt_pk_bf16_f32 v165, v204, v205
	global_store_dwordx4 v160, v[202:205], s[26:27] nt
	v_add_u32_e32 v34, 0x84100, v147
	v_fmac_f32_e32 v150, v202, v202
	global_store_dwordx2 v34, v[164:165], s[96:97]
	v_fmac_f32_e32 v150, v203, v203
	v_fmac_f32_e32 v150, v204, v204
	v_fmac_f32_e32 v150, v205, v205
	s_waitcnt vmcnt(33)
; template <int EPI, int NRM>
; DEVI void epilogue(acc_t& acc, int pn, int trow, const EpiArgs& e, const float* rl, bf16* shmx) {
;     ...
;       for (int bj = 0; bj < 2; ++bj)
; #pragma unroll
;         for (int m = 0; m < 4; ++m)
; #pragma unroll
;           for (int n = 0; n < 2; ++n) {
;             const int idx = (bj * 4 + m) * 2 + n;
;             const unsigned off = (unsigned)((tk0 + bj * 128 + n * 16) * DM + pn * 256 + ai * 128 + m * 16 + fl0);
;             const float4 xx = *reinterpret_cast<const float4*>(lbase + idx * 1024 + lane * 16);
;             float4 o;
;             o.x = xx.x + acc[ai][bj][m][n][0]; o.y = xx.y + acc[ai][bj][m][n][1];
;             o.z = xx.z + acc[ai][bj][m][n][2]; o.w = xx.w + acc[ai][bj][m][n][3];
;             *reinterpret_cast<float4*>(e.xout + off) = o;
;             uint2 ob; ob.x = pack2(o.x, o.y); ob.y = pack2(o.z, o.w);
;             *reinterpret_cast<uint2*>(e.o0 + off) = ob;
;             ss[bj][n] += o.x * o.x + o.y * o.y + o.z * o.z + o.w * o.w;
;           }
;       asm volatile("s_waitcnt lgkmcnt(0)" ::: "memory");
;     }
; #pragma unroll
;     for (int bj = 0; bj < 2; ++bj)
; #pragma unroll
;       for (int n = 0; n < 2; ++n) {
;         float v = ss[bj][n];
;         v += __shfl_xor(v, 16); v += __shfl_xor(v, 32);
;         if (fq == 0) e.stw[(pn * 2 + wr) * TOK + tk0 + bj * 128 + n * 16] = v;
;       }
;     asm volatile("s_waitcnt lgkmcnt(0)" ::: "memory");
;     __builtin_amdgcn_s_barrier();
	v_pk_add_f32 v[206:207], v[206:207], v[26:27]
	v_pk_add_f32 v[208:209], v[208:209], v[28:29]
	v_add_u32_e32 v157, 0x110200, v144
	v_cvt_pk_bf16_f32 v158, v206, v207
	v_cvt_pk_bf16_f32 v159, v208, v209
	global_store_dwordx4 v157, v[206:209], s[26:27] nt
	v_add_u32_e32 v26, 0x88100, v146
	v_fmac_f32_e32 v151, v206, v206
	global_store_dwordx2 v26, v[158:159], s[96:97]
	v_fmac_f32_e32 v151, v207, v207
	v_fmac_f32_e32 v151, v208, v208
	v_fmac_f32_e32 v151, v209, v209
	s_waitcnt vmcnt(34)
	v_pk_add_f32 v[210:211], v[210:211], v[22:23]
	v_pk_add_f32 v[212:213], v[212:213], v[24:25]
	v_add_u32_e32 v160, 0x118200, v145
	v_cvt_pk_bf16_f32 v164, v210, v211
	v_cvt_pk_bf16_f32 v165, v212, v213
	global_store_dwordx4 v160, v[210:213], s[26:27] nt
	v_add_u32_e32 v22, 0x8c100, v147
	v_fmac_f32_e32 v152, v210, v210
	global_store_dwordx2 v22, v[164:165], s[96:97]
	v_fmac_f32_e32 v152, v211, v211
	v_fmac_f32_e32 v152, v212, v212
	v_fmac_f32_e32 v152, v213, v213
	s_waitcnt vmcnt(35)
	v_pk_add_f32 v[214:215], v[214:215], v[18:19]
	v_pk_add_f32 v[216:217], v[216:217], v[20:21]
	v_add_u32_e32 v157, 0x120200, v144
	v_cvt_pk_bf16_f32 v158, v214, v215
	v_cvt_pk_bf16_f32 v159, v216, v217
	global_store_dwordx4 v157, v[214:217], s[26:27] nt
	v_add_u32_e32 v18, 0x90100, v146
	v_fmac_f32_e32 v153, v214, v214
	global_store_dwordx2 v18, v[158:159], s[96:97]
	v_fmac_f32_e32 v153, v215, v215
	v_fmac_f32_e32 v153, v216, v216
	v_fmac_f32_e32 v153, v217, v217
	s_waitcnt vmcnt(36)
	v_pk_add_f32 v[218:219], v[218:219], v[10:11]
	v_pk_add_f32 v[220:221], v[220:221], v[12:13]
	v_add_u32_e32 v160, 0x128200, v145
	v_cvt_pk_bf16_f32 v164, v218, v219
	v_cvt_pk_bf16_f32 v165, v220, v221
	global_store_dwordx4 v160, v[218:221], s[26:27] nt
	v_add_u32_e32 v10, 0x94100, v147
	v_fmac_f32_e32 v154, v218, v218
	global_store_dwordx2 v10, v[164:165], s[96:97]
	v_fmac_f32_e32 v154, v219, v219
	v_fmac_f32_e32 v154, v220, v220
	v_fmac_f32_e32 v154, v221, v221
	s_waitcnt vmcnt(37)
	v_pk_add_f32 v[222:223], v[222:223], v[6:7]
	v_pk_add_f32 v[224:225], v[224:225], v[8:9]
	v_add_u32_e32 v157, 0x130200, v144
	v_cvt_pk_bf16_f32 v158, v222, v223
	v_cvt_pk_bf16_f32 v159, v224, v225
	global_store_dwordx4 v157, v[222:225], s[26:27] nt
	v_add_u32_e32 v6, 0x98100, v146
	v_fmac_f32_e32 v155, v222, v222
	global_store_dwordx2 v6, v[158:159], s[96:97]
	v_fmac_f32_e32 v155, v223, v223
	v_fmac_f32_e32 v155, v224, v224
	v_fmac_f32_e32 v155, v225, v225
	s_waitcnt vmcnt(38)
	v_pk_add_f32 v[226:227], v[226:227], v[2:3]
	v_pk_add_f32 v[228:229], v[228:229], v[4:5]
	v_add_u32_e32 v160, 0x138200, v145
	v_cvt_pk_bf16_f32 v164, v226, v227
	v_cvt_pk_bf16_f32 v165, v228, v229
	global_store_dwordx4 v160, v[226:229], s[26:27] nt
	v_add_u32_e32 v2, 0x9c100, v147
	v_fmac_f32_e32 v156, v226, v226
	global_store_dwordx2 v2, v[164:165], s[96:97]
	v_fmac_f32_e32 v156, v227, v227
	v_fmac_f32_e32 v156, v228, v228
	v_fmac_f32_e32 v156, v229, v229
	v_add_f32_dpp v149, v149, v149 row_shr:1 row_mask:0xf bank_mask:0xf bound_ctrl:0
	v_add_f32_dpp v150, v150, v150 row_shr:1 row_mask:0xf bank_mask:0xf bound_ctrl:0
	v_add_f32_dpp v151, v151, v151 row_shr:1 row_mask:0xf bank_mask:0xf bound_ctrl:0
	v_add_f32_dpp v152, v152, v152 row_shr:1 row_mask:0xf bank_mask:0xf bound_ctrl:0
	v_add_f32_dpp v153, v153, v153 row_shr:1 row_mask:0xf bank_mask:0xf bound_ctrl:0
	v_add_f32_dpp v154, v154, v154 row_shr:1 row_mask:0xf bank_mask:0xf bound_ctrl:0
	v_add_f32_dpp v155, v155, v155 row_shr:1 row_mask:0xf bank_mask:0xf bound_ctrl:0
	v_add_f32_dpp v156, v156, v156 row_shr:1 row_mask:0xf bank_mask:0xf bound_ctrl:0
	v_add_f32_dpp v149, v149, v149 row_shr:2 row_mask:0xf bank_mask:0xf bound_ctrl:0
	v_add_f32_dpp v150, v150, v150 row_shr:2 row_mask:0xf bank_mask:0xf bound_ctrl:0
	v_add_f32_dpp v151, v151, v151 row_shr:2 row_mask:0xf bank_mask:0xf bound_ctrl:0
	v_add_f32_dpp v152, v152, v152 row_shr:2 row_mask:0xf bank_mask:0xf bound_ctrl:0
	v_add_f32_dpp v153, v153, v153 row_shr:2 row_mask:0xf bank_mask:0xf bound_ctrl:0
	v_add_f32_dpp v154, v154, v154 row_shr:2 row_mask:0xf bank_mask:0xf bound_ctrl:0
	v_add_f32_dpp v155, v155, v155 row_shr:2 row_mask:0xf bank_mask:0xf bound_ctrl:0
	v_add_f32_dpp v156, v156, v156 row_shr:2 row_mask:0xf bank_mask:0xf bound_ctrl:0
	v_add_f32_dpp v149, v149, v149 row_shr:4 row_mask:0xf bank_mask:0xf bound_ctrl:0
	v_add_f32_dpp v150, v150, v150 row_shr:4 row_mask:0xf bank_mask:0xf bound_ctrl:0
	v_add_f32_dpp v151, v151, v151 row_shr:4 row_mask:0xf bank_mask:0xf bound_ctrl:0
	v_add_f32_dpp v152, v152, v152 row_shr:4 row_mask:0xf bank_mask:0xf bound_ctrl:0
	v_add_f32_dpp v153, v153, v153 row_shr:4 row_mask:0xf bank_mask:0xf bound_ctrl:0
	v_add_f32_dpp v154, v154, v154 row_shr:4 row_mask:0xf bank_mask:0xf bound_ctrl:0
	v_add_f32_dpp v155, v155, v155 row_shr:4 row_mask:0xf bank_mask:0xf bound_ctrl:0
	v_add_f32_dpp v156, v156, v156 row_shr:4 row_mask:0xf bank_mask:0xf bound_ctrl:0
	v_add_f32_dpp v149, v149, v149 row_shr:8 row_mask:0xf bank_mask:0xf bound_ctrl:0
	v_add_f32_dpp v150, v150, v150 row_shr:8 row_mask:0xf bank_mask:0xf bound_ctrl:0
	v_add_f32_dpp v151, v151, v151 row_shr:8 row_mask:0xf bank_mask:0xf bound_ctrl:0
	v_add_f32_dpp v152, v152, v152 row_shr:8 row_mask:0xf bank_mask:0xf bound_ctrl:0
	v_add_f32_dpp v153, v153, v153 row_shr:8 row_mask:0xf bank_mask:0xf bound_ctrl:0
	v_add_f32_dpp v154, v154, v154 row_shr:8 row_mask:0xf bank_mask:0xf bound_ctrl:0
	v_add_f32_dpp v155, v155, v155 row_shr:8 row_mask:0xf bank_mask:0xf bound_ctrl:0
	v_add_f32_dpp v156, v156, v156 row_shr:8 row_mask:0xf bank_mask:0xf bound_ctrl:0
	v_cmp_eq_u32_e32 vcc, 15, v138
	s_and_saveexec_b64 s[6:7], vcc
	global_store_dword v148, v149, s[10:11] offset:512
	global_store_dword v148, v150, s[10:11] offset:528
	global_store_dword v148, v151, s[10:11] offset:544
	global_store_dword v148, v152, s[10:11] offset:560
	global_store_dword v148, v153, s[10:11] offset:576
	global_store_dword v148, v154, s[10:11] offset:592
	global_store_dword v148, v155, s[10:11] offset:608
	global_store_dword v148, v156, s[10:11] offset:624
	s_branch .LBB0_368

; DEVI void convT(const float* __restrict__ src, int K, int N, bf16* __restrict__ dst, int ldd, int blk, int blk_stride,
;                 int row_off, const float* __restrict__ nscale, const float* __restrict__ kscale, float* lds) {
;   const int tid = threadIdx.x;
;   const int tilesN = (N + 63) / 64, tilesK = K / 64;
;   const int ntl = tilesN * tilesK;
;   const int lk = tid / 16, ln = (tid % 16) * 4;
;   int tile = blockIdx.x;
;   float4 c0 = make_float4(0.f, 0.f, 0.f, 0.f), c1 = c0;
;   if (tile < ntl) {
;     const int n0 = (tile % tilesN) * 64, k0 = (tile / tilesN) * 64;
;     if (n0 + ln < N) {
;       c0 = *reinterpret_cast<const float4*>(src + (long)(k0 + lk) * N + n0 + ln);
;       c1 = *reinterpret_cast<const float4*>(src + (long)(k0 + lk + 32) * N + n0 + ln);
;     }
.LBB0_412:
	s_cmp_gt_i32 s30, 6
	s_cselect_b64 s[0:1], -1, 0
	s_cmp_lt_i32 s31, 7
	s_cselect_b64 s[2:3], -1, 0
	s_or_b64 s[0:1], s[0:1], s[2:3]
	s_and_b64 vcc, exec, s[0:1]
	s_cbranch_vccnz .LBB0_440
	v_and_b32_e32 v30, 0x3ff, v0
	v_lshlrev_b32_e32 v2, 2, v30
	v_and_b32_e32 v28, 60, v2
	v_mul_u32_u24_e32 v2, 0x41, v1
	v_lshlrev_b32_e32 v18, 2, v28
	v_lshlrev_b32_e32 v2, 2, v2
	v_add3_u32 v31, 0, v18, v2
	v_add3_u32 v32, 0, v2, v18
	v_lshlrev_b32_e32 v2, 3, v30
	v_readlane_b32 s0, v250, 0
	v_and_b32_e32 v33, 56, v2
	s_cmpk_gt_i32 s0, 0x7ff
	v_mov_b32_e32 v10, 0
	v_mul_u32_u24_e32 v35, 0x104, v33
	s_cbranch_scc1 .LBB0_441
	v_readlane_b32 s1, v250, 0
	s_ashr_i32 s0, s1, 31
	s_lshr_b32 s0, s0, 26
	s_add_i32 s3, s1, s0
	s_and_b32 s0, s3, 0x3ffffc0
	s_sub_i32 s0, s1, s0
	s_lshl_b32 s2, s0, 6
	v_or_b32_e32 v2, s2, v28
	s_movk_i32 s8, 0x1000
	v_cmp_gt_i32_e32 vcc, s8, v2
	v_mov_b32_e32 v11, 0
	v_mov_b32_e32 v12, 0
	v_mov_b32_e32 v13, 0
	v_mov_b32_e32 v14, 0
	v_mov_b32_e32 v15, 0
	v_mov_b32_e32 v16, 0
	v_mov_b32_e32 v17, 0
	s_and_saveexec_b64 s[0:1], vcc
	s_cbranch_execz .LBB0_416
	s_ashr_i32 s3, s3, 6
	v_lshl_or_b32 v2, s3, 6, v1
	s_waitcnt lgkmcnt(0)
	v_ashrrev_i32_e32 v3, 31, v2
	v_lshlrev_b64 v[2:3], 14, v[2:3]
	s_ashr_i32 s3, s2, 31
	v_lshl_add_u64 v[2:3], s[86:87], 0, v[2:3]
	v_mov_b32_e32 v19, 0
	v_lshl_add_u64 v[2:3], s[2:3], 2, v[2:3]
	v_lshl_add_u64 v[2:3], v[2:3], 0, v[18:19]
	v_add_co_u32_e32 v4, vcc, 0x80000, v2
	s_nop 1
	v_addc_co_u32_e32 v5, vcc, 0, v3, vcc
	global_load_dwordx4 v[14:17], v[2:3], off nt
	global_load_dwordx4 v[10:13], v[4:5], off nt

; DEVI void convT(const float* __restrict__ src, int K, int N, bf16* __restrict__ dst, int ldd, int blk, int blk_stride,
;                 int row_off, const float* __restrict__ nscale, const float* __restrict__ kscale, float* lds) {
;     ...
;   while (tile < ntl) {
;     const int n0 = (tile % tilesN) * 64, k0 = (tile / tilesN) * 64;
;     const int nxt = tile + gridDim.x;
;     float4 d0 = make_float4(0.f, 0.f, 0.f, 0.f), d1 = d0;
;     if (nxt < ntl) {
;       const int n2 = (nxt % tilesN) * 64, k2 = (nxt / tilesN) * 64;
;       if (n2 + ln < N) {
;         d0 = *reinterpret_cast<const float4*>(src + (long)(k2 + lk) * N + n2 + ln);
;         d1 = *reinterpret_cast<const float4*>(src + (long)(k2 + lk + 32) * N + n2 + ln);
;       }
.LBB0_419:
	s_add_i32 s12, s9, s6
	s_cmpk_gt_i32 s12, 0x7ff
	s_cselect_b64 s[2:3], -1, 0
	s_and_b64 vcc, exec, s[2:3]
	v_mov_b32_e32 v6, 0
	v_mov_b32_e32 v7, 0
	v_mov_b32_e32 v8, 0
	v_mov_b32_e32 v9, 0
	v_mov_b32_e32 v2, 0
	v_mov_b32_e32 v3, 0
	v_mov_b32_e32 v4, 0
	v_mov_b32_e32 v5, 0
	s_cbranch_vccnz .LBB0_423
	s_ashr_i32 s4, s12, 31
	s_lshr_b32 s4, s4, 26
	s_add_i32 s4, s12, s4
	s_ashr_i32 s7, s4, 6
	s_lshl_b32 s13, s7, 12
	s_sub_i32 s4, s10, s13
	v_add_u32_e32 v2, s4, v23
	v_cmp_gt_i32_e32 vcc, s8, v2
	v_mov_b32_e32 v5, 0
	v_mov_b32_e32 v4, 0
	v_mov_b32_e32 v3, 0
	v_mov_b32_e32 v2, 0
	v_mov_b32_e32 v9, 0
	v_mov_b32_e32 v8, 0
	v_mov_b32_e32 v7, 0
	v_mov_b32_e32 v6, 0
	s_and_saveexec_b64 s[4:5], vcc
	s_cbranch_execz .LBB0_422
	v_lshl_or_b32 v2, s7, 6, v1
	s_sub_i32 s13, 0, s13
	s_add_i32 s14, s11, s10
	v_ashrrev_i32_e32 v3, 31, v2
	s_add_i32 s14, s14, s13
	v_lshlrev_b64 v[2:3], 14, v[2:3]
	v_lshl_add_u64 v[2:3], s[86:87], 0, v[2:3]
	s_ashr_i32 s15, s14, 31
	v_lshl_add_u64 v[2:3], s[14:15], 2, v[2:3]
	v_mov_b32_e32 v19, v21
	v_lshl_add_u64 v[2:3], v[2:3], 0, v[18:19]
	v_add_co_u32_e32 v6, vcc, 0x80000, v2
	s_nop 1
	v_addc_co_u32_e32 v7, vcc, 0, v3, vcc
	global_load_dwordx4 v[2:5], v[2:3], off nt
	s_nop 0
	global_load_dwordx4 v[6:9], v[6:7], off nt

; DEVI void convT(const float* __restrict__ src, int K, int N, bf16* __restrict__ dst, int ldd, int blk, int blk_stride,
;                 int row_off, const float* __restrict__ nscale, const float* __restrict__ kscale, float* lds) {
;   const int tid = threadIdx.x;
;   const int tilesN = (N + 63) / 64, tilesK = K / 64;
;   const int ntl = tilesN * tilesK;
;   const int lk = tid / 16, ln = (tid % 16) * 4;
;   int tile = blockIdx.x;
;   float4 c0 = make_float4(0.f, 0.f, 0.f, 0.f), c1 = c0;
;   if (tile < ntl) {
;     const int n0 = (tile % tilesN) * 64, k0 = (tile / tilesN) * 64;
;     if (n0 + ln < N) {
;       c0 = *reinterpret_cast<const float4*>(src + (long)(k0 + lk) * N + n0 + ln);
;       c1 = *reinterpret_cast<const float4*>(src + (long)(k0 + lk + 32) * N + n0 + ln);
;     }
.LBB0_446:
	s_or_b64 exec, exec, s[0:1]
	v_readlane_b32 s92, v250, 0
	s_ashr_i32 s0, s92, 31
	s_lshr_b32 s0, s0, 27
	s_add_i32 s0, s92, s0
	s_and_b32 s1, s0, 0x3ffffe0
	s_sub_i32 s1, s92, s1
	s_lshl_b32 s6, s1, 6
	s_lshl_b32 s0, s0, 1
	s_and_b32 s2, s0, 0xffffffc0
	v_or_b32_e32 v2, s6, v28
	s_movk_i32 s0, 0x800
	v_cmp_gt_i32_e64 s[0:1], s0, v2
	v_or_b32_e32 v2, s2, v1
	s_waitcnt lgkmcnt(0)
	v_ashrrev_i32_e32 v3, 31, v2
	s_ashr_i32 s7, s6, 31
	v_lshlrev_b64 v[20:21], 13, v[2:3]
	s_mov_b64 s[2:3], 0x40000
	s_cmpk_gt_i32 s92, 0x3ff
	v_lshl_add_u64 v[22:23], v[20:21], 0, s[2:3]
	s_cbranch_scc1 .LBB0_457
	v_mov_b32_e32 v19, 0
	v_mov_b32_e32 v2, v19
	v_mov_b32_e32 v3, v19
	v_mov_b32_e32 v4, v19
	v_mov_b32_e32 v5, v19
	v_mov_b32_e32 v6, v19
	v_mov_b32_e32 v7, v19
	v_mov_b32_e32 v8, v19
	v_mov_b32_e32 v9, v19
	s_and_saveexec_b64 s[2:3], s[0:1]
	s_cbranch_execz .LBB0_449
	v_lshl_add_u64 v[2:3], s[68:69], 0, v[22:23]
	s_lshl_b64 s[4:5], s[6:7], 2
	v_lshl_add_u64 v[6:7], s[68:69], 0, v[20:21]
	v_lshl_add_u64 v[2:3], v[2:3], 0, s[4:5]
	v_mov_b32_e32 v5, 0
	v_mov_b32_e32 v4, v18
	v_lshl_add_u64 v[6:7], v[6:7], 0, s[4:5]
	v_lshl_add_u64 v[2:3], v[2:3], 0, v[4:5]
	v_lshl_add_u64 v[4:5], v[6:7], 0, v[4:5]
	global_load_dwordx4 v[6:9], v[4:5], off nt
	s_nop 0
	global_load_dwordx4 v[2:5], v[2:3], off nt

; DEVI void convT(const float* __restrict__ src, int K, int N, bf16* __restrict__ dst, int ldd, int blk, int blk_stride,
;                 int row_off, const float* __restrict__ nscale, const float* __restrict__ kscale, float* lds) {
;     ...
;   while (tile < ntl) {
;     const int n0 = (tile % tilesN) * 64, k0 = (tile / tilesN) * 64;
;     const int nxt = tile + gridDim.x;
;     float4 d0 = make_float4(0.f, 0.f, 0.f, 0.f), d1 = d0;
;     if (nxt < ntl) {
;       const int n2 = (nxt % tilesN) * 64, k2 = (nxt / tilesN) * 64;
;       if (n2 + ln < N) {
;         d0 = *reinterpret_cast<const float4*>(src + (long)(k2 + lk) * N + n2 + ln);
;         d1 = *reinterpret_cast<const float4*>(src + (long)(k2 + lk + 32) * N + n2 + ln);
;       }
.LBB0_451:
	s_add_i32 s14, s11, s15
	s_cmpk_gt_i32 s14, 0x3ff
	s_cselect_b64 s[4:5], -1, 0
	v_mov_b32_e32 v10, 0
	s_and_b64 vcc, exec, s[4:5]
	v_mov_b32_e32 v11, 0
	v_mov_b32_e32 v12, 0
	v_mov_b32_e32 v13, 0
	v_mov_b32_e32 v14, 0
	v_mov_b32_e32 v15, 0
	v_mov_b32_e32 v16, 0
	v_mov_b32_e32 v17, 0
	s_cbranch_vccnz .LBB0_455
	s_ashr_i32 s8, s14, 31
	s_lshr_b32 s8, s8, 27
	s_add_i32 s8, s14, s8
	s_ashr_i32 s16, s8, 5
	s_lshl_b32 s17, s16, 11
	s_sub_i32 s8, s12, s17
	v_add_u32_e32 v10, s8, v26
	v_cmp_gt_i32_e32 vcc, s10, v10
	v_mov_b32_e32 v17, 0
	v_mov_b32_e32 v16, 0
	v_mov_b32_e32 v15, 0
	v_mov_b32_e32 v14, 0
	v_mov_b32_e32 v13, 0
	v_mov_b32_e32 v12, 0
	v_mov_b32_e32 v11, 0
	v_mov_b32_e32 v10, 0
	s_and_saveexec_b64 s[8:9], vcc
	s_cbranch_execz .LBB0_454
	v_lshl_or_b32 v10, s16, 6, v1
	s_sub_i32 s17, 0, s17
	s_add_i32 s18, s13, s12
	v_ashrrev_i32_e32 v11, 31, v10
	s_add_i32 s18, s18, s17
	v_lshlrev_b64 v[10:11], 13, v[10:11]
	v_lshl_add_u64 v[10:11], s[68:69], 0, v[10:11]
	s_ashr_i32 s19, s18, 31
	v_lshl_add_u64 v[10:11], s[18:19], 2, v[10:11]
	v_lshl_add_u64 v[10:11], v[10:11], 0, v[18:19]
	v_add_co_u32_e32 v12, vcc, 0x40000, v10
	s_nop 1
	v_addc_co_u32_e32 v13, vcc, 0, v11, vcc
	global_load_dwordx4 v[14:17], v[10:11], off nt
	s_nop 0
	global_load_dwordx4 v[10:13], v[12:13], off nt

; DEVI void convT(const float* __restrict__ src, int K, int N, bf16* __restrict__ dst, int ldd, int blk, int blk_stride,
;                 int row_off, const float* __restrict__ nscale, const float* __restrict__ kscale, float* lds) {
;   const int tid = threadIdx.x;
;   const int tilesN = (N + 63) / 64, tilesK = K / 64;
;   const int ntl = tilesN * tilesK;
;   const int lk = tid / 16, ln = (tid % 16) * 4;
;   int tile = blockIdx.x;
;   float4 c0 = make_float4(0.f, 0.f, 0.f, 0.f), c1 = c0;
;   if (tile < ntl) {
;     const int n0 = (tile % tilesN) * 64, k0 = (tile / tilesN) * 64;
;     if (n0 + ln < N) {
;       c0 = *reinterpret_cast<const float4*>(src + (long)(k0 + lk) * N + n0 + ln);
;       c1 = *reinterpret_cast<const float4*>(src + (long)(k0 + lk + 32) * N + n0 + ln);
;     }
; DEVI void convert_ffn(const Params& p, int ig, bf16* shm) {
;     ...
;   convT(p.in[ig], DM, DFF, (bf16*)(p.ws + W_GU), DM, 128, 256, 0, nullptr, p.in[ig - 1], lds);
.LBB0_459:
	s_andn2_b64 vcc, exec, s[2:3]
	s_cbranch_vccnz .LBB0_522
	s_mul_hi_i32 s2, s92, 0x2e8ba2e9
	s_lshr_b32 s3, s2, 31
	s_ashr_i32 s2, s2, 4
	s_add_i32 s2, s2, s3
	s_mul_i32 s3, s2, 0x58
	s_sub_i32 s3, s92, s3
	s_lshl_b32 s10, s3, 6
	v_or_b32_e32 v2, s10, v28
	s_movk_i32 s21, 0x1600
	v_cmp_gt_i32_e64 s[4:5], s21, v2
	v_lshl_or_b32 v2, s2, 6, v1
	s_movk_i32 s22, 0x5800
	v_mad_i64_i32 v[24:25], s[2:3], v2, s22, 0
	v_add_u32_e32 v2, 32, v2
	s_ashr_i32 s11, s10, 31
	v_mad_i64_i32 v[26:27], s[2:3], v2, s22, 0
	v_mov_b32_e32 v29, 0
	v_mov_b32_e32 v10, 0
	v_mov_b32_e32 v11, 0
	v_mov_b32_e32 v12, 0
	v_mov_b32_e32 v13, 0
	v_mov_b32_e32 v14, 0
	v_mov_b32_e32 v15, 0
	v_mov_b32_e32 v16, 0
	v_mov_b32_e32 v17, 0
	s_and_saveexec_b64 s[2:3], s[4:5]
	s_cbranch_execz .LBB0_462
	s_lshl_b64 s[8:9], s[10:11], 2
	v_lshl_add_u64 v[4:5], s[72:73], 0, v[24:25]
	v_lshl_add_u64 v[2:3], s[72:73], 0, v[26:27]
	v_mov_b32_e32 v19, 0
	v_lshl_add_u64 v[4:5], v[4:5], 0, s[8:9]
	v_lshl_add_u64 v[2:3], v[2:3], 0, s[8:9]
	v_lshl_add_u64 v[4:5], v[4:5], 0, v[18:19]
	v_lshl_add_u64 v[2:3], v[2:3], 0, v[18:19]
	global_load_dwordx4 v[14:17], v[4:5], off nt
	global_load_dwordx4 v[10:13], v[2:3], off nt

; DEVI void convT(const float* __restrict__ src, int K, int N, bf16* __restrict__ dst, int ldd, int blk, int blk_stride,
;                 int row_off, const float* __restrict__ nscale, const float* __restrict__ kscale, float* lds) {
;     ...
;   while (tile < ntl) {
;     const int n0 = (tile % tilesN) * 64, k0 = (tile / tilesN) * 64;
;     const int nxt = tile + gridDim.x;
;     float4 d0 = make_float4(0.f, 0.f, 0.f, 0.f), d1 = d0;
;     if (nxt < ntl) {
;       const int n2 = (nxt % tilesN) * 64, k2 = (nxt / tilesN) * 64;
;       if (n2 + ln < N) {
;         d0 = *reinterpret_cast<const float4*>(src + (long)(k2 + lk) * N + n2 + ln);
;         d1 = *reinterpret_cast<const float4*>(src + (long)(k2 + lk + 32) * N + n2 + ln);
;       }
; DEVI void convert_ffn(const Params& p, int ig, bf16* shm) {
;     ...
;   convT(p.in[ig], DM, DFF, (bf16*)(p.ws + W_GU), DM, 128, 256, 0, nullptr, p.in[ig - 1], lds);
.LBB0_465:
	s_add_i32 s34, s18, s16
	s_cmpk_gt_i32 s34, 0xaff
	s_cselect_b64 s[12:13], -1, 0
	v_mov_b32_e32 v2, 0
	s_and_b64 vcc, exec, s[12:13]
	v_mov_b32_e32 v3, 0
	v_mov_b32_e32 v4, 0
	v_mov_b32_e32 v5, 0
	v_mov_b32_e32 v6, 0
	v_mov_b32_e32 v7, 0
	v_mov_b32_e32 v8, 0
	v_mov_b32_e32 v9, 0
	s_cbranch_vccnz .LBB0_469
	s_mul_hi_i32 s14, s34, 0x2e8ba2e9
	s_lshr_b32 s15, s14, 31
	s_ashr_i32 s17, s14, 4
	s_add_i32 s17, s17, s15
	s_mul_i32 s35, s17, 0xffffea00
	s_add_i32 s14, s35, s23
	v_add_u32_e32 v2, s14, v34
	v_cmp_gt_i32_e32 vcc, s21, v2
	v_mov_b32_e32 v9, 0
	v_mov_b32_e32 v8, 0
	v_mov_b32_e32 v7, 0
	v_mov_b32_e32 v6, 0
	v_mov_b32_e32 v5, 0
	v_mov_b32_e32 v4, 0
	v_mov_b32_e32 v3, 0
	v_mov_b32_e32 v2, 0
	s_and_saveexec_b64 s[14:15], vcc
	s_cbranch_execz .LBB0_468
	s_add_i32 s36, s20, s23
	s_add_i32 s36, s36, s35
	v_lshl_or_b32 v6, s17, 6, v1
	v_mov_b64_e32 v[2:3], s[72:73]
	v_mad_i64_i32 v[4:5], s[38:39], v6, s22, v[2:3]
	s_ashr_i32 s37, s36, 31
	v_add_u32_e32 v6, 32, v6
	s_lshl_b64 s[36:37], s[36:37], 2
	v_mad_i64_i32 v[2:3], s[38:39], v6, s22, v[2:3]
	v_lshl_add_u64 v[4:5], v[4:5], 0, s[36:37]
	v_mov_b32_e32 v19, v29
	v_lshl_add_u64 v[2:3], v[2:3], 0, s[36:37]
	v_lshl_add_u64 v[4:5], v[4:5], 0, v[18:19]
	v_lshl_add_u64 v[2:3], v[2:3], 0, v[18:19]
	global_load_dwordx4 v[6:9], v[4:5], off nt
	s_nop 0
	global_load_dwordx4 v[2:5], v[2:3], off nt

; DEVI void convT(const float* __restrict__ src, int K, int N, bf16* __restrict__ dst, int ldd, int blk, int blk_stride,
;                 int row_off, const float* __restrict__ nscale, const float* __restrict__ kscale, float* lds) {
;   const int tid = threadIdx.x;
;   const int tilesN = (N + 63) / 64, tilesK = K / 64;
;   const int ntl = tilesN * tilesK;
;   const int lk = tid / 16, ln = (tid % 16) * 4;
;   int tile = blockIdx.x;
;   float4 c0 = make_float4(0.f, 0.f, 0.f, 0.f), c1 = c0;
;   if (tile < ntl) {
;     const int n0 = (tile % tilesN) * 64, k0 = (tile / tilesN) * 64;
;     if (n0 + ln < N) {
;       c0 = *reinterpret_cast<const float4*>(src + (long)(k0 + lk) * N + n0 + ln);
;       c1 = *reinterpret_cast<const float4*>(src + (long)(k0 + lk + 32) * N + n0 + ln);
;     }
; DEVI void convert_ffn(const Params& p, int ig, bf16* shm) {
;     ...
;   convT(p.in[ig + 1], DM, DFF, (bf16*)(p.ws + W_GU), DM, 128, 256, 128, nullptr, p.in[ig - 1], lds);
.LBB0_486:
	v_mov_b32_e32 v29, 0
	v_mov_b32_e32 v10, 0
	v_mov_b32_e32 v11, 0
	v_mov_b32_e32 v12, 0
	v_mov_b32_e32 v13, 0
	v_mov_b32_e32 v14, 0
	v_mov_b32_e32 v15, 0
	v_mov_b32_e32 v16, 0
	v_mov_b32_e32 v17, 0
	s_and_saveexec_b64 s[12:13], s[4:5]
	s_cbranch_execz .LBB0_488
	s_lshl_b64 s[4:5], s[10:11], 2
	v_lshl_add_u64 v[4:5], s[74:75], 0, v[24:25]
	v_lshl_add_u64 v[2:3], s[74:75], 0, v[26:27]
	v_mov_b32_e32 v19, 0
	v_lshl_add_u64 v[4:5], v[4:5], 0, s[4:5]
	v_lshl_add_u64 v[2:3], v[2:3], 0, s[4:5]
	v_lshl_add_u64 v[4:5], v[4:5], 0, v[18:19]
	v_lshl_add_u64 v[2:3], v[2:3], 0, v[18:19]
	global_load_dwordx4 v[10:13], v[4:5], off nt
	global_load_dwordx4 v[14:17], v[2:3], off nt

; DEVI void convT(const float* __restrict__ src, int K, int N, bf16* __restrict__ dst, int ldd, int blk, int blk_stride,
;                 int row_off, const float* __restrict__ nscale, const float* __restrict__ kscale, float* lds) {
;     ...
;   while (tile < ntl) {
;     const int n0 = (tile % tilesN) * 64, k0 = (tile / tilesN) * 64;
;     const int nxt = tile + gridDim.x;
;     float4 d0 = make_float4(0.f, 0.f, 0.f, 0.f), d1 = d0;
;     if (nxt < ntl) {
;       const int n2 = (nxt % tilesN) * 64, k2 = (nxt / tilesN) * 64;
;       if (n2 + ln < N) {
;         d0 = *reinterpret_cast<const float4*>(src + (long)(k2 + lk) * N + n2 + ln);
;         d1 = *reinterpret_cast<const float4*>(src + (long)(k2 + lk + 32) * N + n2 + ln);
;       }
; DEVI void convert_ffn(const Params& p, int ig, bf16* shm) {
;     ...
;   convT(p.in[ig + 1], DM, DFF, (bf16*)(p.ws + W_GU), DM, 128, 256, 128, nullptr, p.in[ig - 1], lds);
.LBB0_491:
	s_add_i32 s17, s12, s18
	s_cmpk_gt_i32 s17, 0xaff
	s_cselect_b64 s[4:5], -1, 0
	v_mov_b32_e32 v2, 0
	s_and_b64 vcc, exec, s[4:5]
	v_mov_b32_e32 v3, 0
	v_mov_b32_e32 v4, 0
	v_mov_b32_e32 v5, 0
	v_mov_b32_e32 v6, 0
	v_mov_b32_e32 v7, 0
	v_mov_b32_e32 v8, 0
	v_mov_b32_e32 v9, 0
	s_cbranch_vccnz .LBB0_495
	s_mul_hi_i32 s10, s17, 0x2e8ba2e9
	s_lshr_b32 s11, s10, 31
	s_ashr_i32 s13, s10, 4
	s_add_i32 s13, s13, s11
	s_mul_i32 s21, s13, 0xffffea00
	s_add_i32 s10, s21, s16
	v_add_u32_e32 v2, s10, v34
	v_cmp_gt_i32_e32 vcc, s14, v2
	v_mov_b32_e32 v9, 0
	v_mov_b32_e32 v8, 0
	v_mov_b32_e32 v7, 0
	v_mov_b32_e32 v6, 0
	v_mov_b32_e32 v5, 0
	v_mov_b32_e32 v4, 0
	v_mov_b32_e32 v3, 0
	v_mov_b32_e32 v2, 0
	s_and_saveexec_b64 s[10:11], vcc
	s_cbranch_execz .LBB0_494
	s_add_i32 s22, s20, s16
	s_add_i32 s22, s22, s21
	v_lshl_or_b32 v6, s13, 6, v1
	v_mov_b64_e32 v[2:3], s[74:75]
	v_mad_i64_i32 v[4:5], s[34:35], v6, s15, v[2:3]
	s_ashr_i32 s23, s22, 31
	v_add_u32_e32 v6, 32, v6
	s_lshl_b64 s[22:23], s[22:23], 2
	v_mad_i64_i32 v[2:3], s[34:35], v6, s15, v[2:3]
	v_lshl_add_u64 v[4:5], v[4:5], 0, s[22:23]
	v_mov_b32_e32 v19, v29
	v_lshl_add_u64 v[2:3], v[2:3], 0, s[22:23]
	v_lshl_add_u64 v[4:5], v[4:5], 0, v[18:19]
	v_lshl_add_u64 v[2:3], v[2:3], 0, v[18:19]
	global_load_dwordx4 v[6:9], v[4:5], off nt
	s_nop 0
	global_load_dwordx4 v[2:5], v[2:3], off nt

; DEVI void convT(const float* __restrict__ src, int K, int N, bf16* __restrict__ dst, int ldd, int blk, int blk_stride,
;                 int row_off, const float* __restrict__ nscale, const float* __restrict__ kscale, float* lds) {
;   const int tid = threadIdx.x;
;   const int tilesN = (N + 63) / 64, tilesK = K / 64;
;   const int ntl = tilesN * tilesK;
;   const int lk = tid / 16, ln = (tid % 16) * 4;
;   int tile = blockIdx.x;
;   float4 c0 = make_float4(0.f, 0.f, 0.f, 0.f), c1 = c0;
;   if (tile < ntl) {
;     const int n0 = (tile % tilesN) * 64, k0 = (tile / tilesN) * 64;
;     if (n0 + ln < N) {
;       c0 = *reinterpret_cast<const float4*>(src + (long)(k0 + lk) * N + n0 + ln);
;       c1 = *reinterpret_cast<const float4*>(src + (long)(k0 + lk + 32) * N + n0 + ln);
;     }
; DEVI void convert_ffn(const Params& p, int ig, bf16* shm) {
;     ...
;   convT(p.in[ig + 2], DFF, DM, (bf16*)(p.ws + W_DN), DFF, DM, 0, 0, nullptr, nullptr, lds);
.LBB0_512:
	v_mov_b32_e32 v19, 0
	v_mov_b32_e32 v2, v19
	v_mov_b32_e32 v3, v19
	v_mov_b32_e32 v4, v19
	v_mov_b32_e32 v5, v19
	v_mov_b32_e32 v6, v19
	v_mov_b32_e32 v7, v19
	v_mov_b32_e32 v8, v19
	v_mov_b32_e32 v9, v19
	s_and_saveexec_b64 s[2:3], s[0:1]
	s_cbranch_execz .LBB0_514
	v_lshl_add_u64 v[2:3], s[76:77], 0, v[22:23]
	s_lshl_b64 s[0:1], s[6:7], 2
	v_lshl_add_u64 v[2:3], v[2:3], 0, s[0:1]
	v_mov_b32_e32 v5, 0
	v_mov_b32_e32 v4, v18
	v_lshl_add_u64 v[6:7], v[2:3], 0, v[4:5]
	v_lshl_add_u64 v[2:3], s[76:77], 0, v[20:21]
	v_lshl_add_u64 v[2:3], v[2:3], 0, s[0:1]
	v_lshl_add_u64 v[2:3], v[2:3], 0, v[4:5]
	global_load_dwordx4 v[2:5], v[2:3], off nt
	s_nop 0
	global_load_dwordx4 v[6:9], v[6:7], off nt

; DEVI void convT(const float* __restrict__ src, int K, int N, bf16* __restrict__ dst, int ldd, int blk, int blk_stride,
;                 int row_off, const float* __restrict__ nscale, const float* __restrict__ kscale, float* lds) {
;     ...
;   while (tile < ntl) {
;     const int n0 = (tile % tilesN) * 64, k0 = (tile / tilesN) * 64;
;     const int nxt = tile + gridDim.x;
;     float4 d0 = make_float4(0.f, 0.f, 0.f, 0.f), d1 = d0;
;     if (nxt < ntl) {
;       const int n2 = (nxt % tilesN) * 64, k2 = (nxt / tilesN) * 64;
;       if (n2 + ln < N) {
;         d0 = *reinterpret_cast<const float4*>(src + (long)(k2 + lk) * N + n2 + ln);
;         d1 = *reinterpret_cast<const float4*>(src + (long)(k2 + lk + 32) * N + n2 + ln);
;       }
; DEVI void convert_ffn(const Params& p, int ig, bf16* shm) {
;     ...
;   convT(p.in[ig + 2], DFF, DM, (bf16*)(p.ws + W_DN), DFF, DM, 0, 0, nullptr, nullptr, lds);
.LBB0_516:
	s_add_i32 s7, s8, s18
	s_cmpk_gt_i32 s7, 0xaff
	s_cselect_b64 s[2:3], -1, 0
	v_mov_b32_e32 v10, 0
	s_and_b64 vcc, exec, s[2:3]
	v_mov_b32_e32 v11, 0
	v_mov_b32_e32 v12, 0
	v_mov_b32_e32 v13, 0
	v_mov_b32_e32 v14, 0
	v_mov_b32_e32 v15, 0
	v_mov_b32_e32 v16, 0
	v_mov_b32_e32 v17, 0
	s_cbranch_vccnz .LBB0_520
	s_ashr_i32 s4, s7, 31
	s_lshr_b32 s4, s4, 27
	s_add_i32 s4, s7, s4
	s_ashr_i32 s9, s4, 5
	s_lshl_b32 s10, s9, 11
	s_sub_i32 s4, s19, s10
	v_add_u32_e32 v10, s4, v34
	v_cmp_gt_i32_e32 vcc, s6, v10
	v_mov_b32_e32 v17, 0
	v_mov_b32_e32 v16, 0
	v_mov_b32_e32 v15, 0
	v_mov_b32_e32 v14, 0
	v_mov_b32_e32 v13, 0
	v_mov_b32_e32 v12, 0
	v_mov_b32_e32 v11, 0
	v_mov_b32_e32 v10, 0
	s_and_saveexec_b64 s[4:5], vcc
	s_cbranch_execz .LBB0_519
	v_lshl_or_b32 v10, s9, 6, v1
	s_sub_i32 s10, 0, s10
	s_add_i32 s11, s20, s19
	v_ashrrev_i32_e32 v11, 31, v10
	s_add_i32 s10, s11, s10
	v_lshlrev_b64 v[10:11], 13, v[10:11]
	v_lshl_add_u64 v[10:11], s[76:77], 0, v[10:11]
	s_ashr_i32 s11, s10, 31
	v_lshl_add_u64 v[10:11], s[10:11], 2, v[10:11]
	v_lshl_add_u64 v[10:11], v[10:11], 0, v[18:19]
	v_add_co_u32_e32 v12, vcc, 0x40000, v10
	s_nop 1
	v_addc_co_u32_e32 v13, vcc, 0, v11, vcc
	global_load_dwordx4 v[14:17], v[10:11], off nt
	s_nop 0
	global_load_dwordx4 v[10:13], v[12:13], off nt

; template <int EPI, int NRM>
; DEVI void epilogue(acc_t& acc, int pn, int trow, const EpiArgs& e, const float* rl, bf16* shmx) {
;     ...
;   if constexpr (EPI == EPI_RESID) {
;     float ss[2][2] = {{0.f, 0.f}, {0.f, 0.f}};
;     __amdgpu_buffer_rsrc_t rsX = __builtin_amdgcn_make_buffer_rsrc((void*)e.xin, 0, 0x7fffffff, 0x00020000);
;     char* lbase = reinterpret_cast<char*>(shmx) + wid * 16384;
;     const int vx = ((tk0 * DM) + pn * 256 + fl0) * 4;
; #pragma unroll
;     for (int ai = 0; ai < 2; ++ai) {
; #pragma unroll
;       for (int bj = 0; bj < 2; ++bj)
; #pragma unroll
;         for (int m = 0; m < 4; ++m)
; #pragma unroll
;           for (int n = 0; n < 2; ++n) {
;             const int idx = (bj * 4 + m) * 2 + n;
;             const int so = ((bj * 128 + n * 16) * DM + ai * 128 + m * 16) * 4;
;             __builtin_amdgcn_raw_ptr_buffer_load_lds(rsX, (__attribute__((address_space(3))) unsigned*)(lbase + idx * 1024 + lane * 16), 16, vx, so, 0, 0);
;           }
;       asm volatile("s_waitcnt vmcnt(0)" ::: "memory");
; #pragma unroll
;       for (int bj = 0; bj < 2; ++bj)
; #pragma unroll
;         for (int m = 0; m < 4; ++m)
; #pragma unroll
;           for (int n = 0; n < 2; ++n) {
;             const int idx = (bj * 4 + m) * 2 + n;
;             const unsigned off = (unsigned)((tk0 + bj * 128 + n * 16) * DM + pn * 256 + ai * 128 + m * 16 + fl0);
;             const float4 xx = *reinterpret_cast<const float4*>(lbase + idx * 1024 + lane * 16);
;             float4 o;
;             o.x = xx.x + acc[ai][bj][m][n][0]; o.y = xx.y + acc[ai][bj][m][n][1];
;             o.z = xx.z + acc[ai][bj][m][n][2]; o.w = xx.w + acc[ai][bj][m][n][3];
;             *reinterpret_cast<float4*>(e.xout + off) = o;
;             uint2 ob; ob.x = pack2(o.x, o.y); ob.y = pack2(o.z, o.w);
;             *reinterpret_cast<uint2*>(e.o0 + off) = ob;
;             ss[bj][n] += o.x * o.x + o.y * o.y + o.z * o.z + o.w * o.w;
;           }
.LBB0_1188:
	v_and_b32_e32 v138, 15, v134
	v_bfe_u32 v198, v134, 4, 2
	v_lshrrev_b32_e32 v199, 6, v134
	v_and_b32_e32 v200, 3, v199
	v_lshrrev_b32_e32 v201, 2, v199
	v_lshlrev_b32_e32 v202, 14, v199
	v_and_b32_e32 v203, 63, v134
	v_lshl_add_u32 v143, v203, 4, v202
	v_lshl_add_u32 v202, v138, 8, v202
	v_and_b32_e32 v203, 7, v138
	v_add_u32_e32 v204, 0, v198
	v_xor_b32_e32 v204, v204, v203
	v_lshl_add_u32 v139, v204, 4, v202
	v_add_u32_e32 v204, 4, v198
	v_xor_b32_e32 v204, v204, v203
	v_lshl_add_u32 v140, v204, 4, v202
	v_add_u32_e32 v204, 8, v198
	v_xor_b32_e32 v204, v204, v203
	v_lshl_add_u32 v141, v204, 4, v202
	v_add_u32_e32 v204, 12, v198
	v_xor_b32_e32 v204, v204, v203
	v_lshl_add_u32 v142, v204, 4, v202
	s_lshl_b32 s6, s6, 8
	v_lshl_add_u32 v202, v200, 5, v198
	v_add_u32_e32 v202, s6, v202
	s_lshl_b32 s6, s12, 1
	v_add_u32_e32 v204, s6, v201
	v_lshl_add_u32 v204, v204, 15, v202
	v_lshlrev_b32_e32 v148, 2, v204
	v_lshlrev_b32_e32 v202, 11, v202
	s_lshl_b32 s6, s12, 8
	v_lshl_add_u32 v204, v201, 6, s6
	v_add_u32_e32 v202, v202, v204
	v_add_u32_e32 v203, 0, v198
	v_xor_b32_e32 v203, v203, v138
	v_lshl_add_u32 v203, v203, 2, v202
	v_lshlrev_b32_e32 v144, 2, v203
	v_lshlrev_b32_e32 v146, 1, v203
	v_add_u32_e32 v203, 4, v198
	v_xor_b32_e32 v203, v203, v138
	v_lshl_add_u32 v203, v203, 2, v202
	v_lshlrev_b32_e32 v145, 2, v203
	v_lshlrev_b32_e32 v147, 1, v203
	v_add_u32_e32 v157, 0x0, v144
	global_load_dwordx4 v[166:169], v157, s[4:5] nt
	v_add_u32_e32 v160, 0x8000, v145
	global_load_dwordx4 v[170:173], v160, s[4:5] nt
	v_add_u32_e32 v157, 0x10000, v144
	global_load_dwordx4 v[174:177], v157, s[4:5] nt
	v_add_u32_e32 v160, 0x18000, v145
	global_load_dwordx4 v[178:181], v160, s[4:5] nt
	v_add_u32_e32 v157, 0x20000, v144
	global_load_dwordx4 v[182:185], v157, s[4:5] nt
	v_add_u32_e32 v160, 0x28000, v145
	global_load_dwordx4 v[186:189], v160, s[4:5] nt
	v_add_u32_e32 v157, 0x30000, v144
	global_load_dwordx4 v[190:193], v157, s[4:5] nt
	v_add_u32_e32 v160, 0x38000, v145
	global_load_dwordx4 v[194:197], v160, s[4:5] nt
	v_add_u32_e32 v157, 0x200, v144
	global_load_dwordx4 v[198:201], v157, s[4:5] nt
	v_add_u32_e32 v160, 0x8200, v145
	global_load_dwordx4 v[202:205], v160, s[4:5] nt
	v_add_u32_e32 v157, 0x10200, v144
	global_load_dwordx4 v[206:209], v157, s[4:5] nt
	v_add_u32_e32 v160, 0x18200, v145
	global_load_dwordx4 v[210:213], v160, s[4:5] nt
	v_add_u32_e32 v157, 0x20200, v144
	global_load_dwordx4 v[214:217], v157, s[4:5] nt
	v_add_u32_e32 v160, 0x28200, v145
	global_load_dwordx4 v[218:221], v160, s[4:5] nt
	v_add_u32_e32 v157, 0x30200, v144
	global_load_dwordx4 v[222:225], v157, s[4:5] nt
	v_add_u32_e32 v160, 0x38200, v145
	global_load_dwordx4 v[226:229], v160, s[4:5] nt
	ds_write_b128 v139, v[126:129]
	ds_write_b128 v139, v[14:17] offset:4096
	ds_write_b128 v140, v[122:125]
	ds_write_b128 v140, v[30:33] offset:4096
	ds_write_b128 v141, v[118:121]
	ds_write_b128 v141, v[46:49] offset:4096
	ds_write_b128 v142, v[114:117]
	ds_write_b128 v142, v[54:57] offset:4096
	ds_write_b128 v139, v[110:113] offset:8192
	ds_write_b128 v139, v[106:109] offset:12288
	ds_write_b128 v140, v[102:105] offset:8192
	ds_write_b128 v140, v[90:93] offset:12288
	ds_write_b128 v141, v[86:89] offset:8192
	ds_write_b128 v141, v[74:77] offset:12288
	ds_write_b128 v142, v[70:73] offset:8192
	ds_write_b128 v142, v[42:45] offset:12288
	s_waitcnt lgkmcnt(0)
	ds_read_b128 v[126:129], v143
	ds_read_b128 v[14:17], v143 offset:1024
	ds_read_b128 v[122:125], v143 offset:2048
	ds_read_b128 v[30:33], v143 offset:3072
	ds_read_b128 v[118:121], v143 offset:4096
	ds_read_b128 v[46:49], v143 offset:5120
	ds_read_b128 v[114:117], v143 offset:6144
	ds_read_b128 v[54:57], v143 offset:7168
	ds_read_b128 v[110:113], v143 offset:8192
	ds_read_b128 v[106:109], v143 offset:9216
	ds_read_b128 v[102:105], v143 offset:10240
	ds_read_b128 v[90:93], v143 offset:11264
	ds_read_b128 v[86:89], v143 offset:12288
	ds_read_b128 v[74:77], v143 offset:13312
	ds_read_b128 v[70:73], v143 offset:14336
	ds_read_b128 v[42:45], v143 offset:15360
	s_waitcnt lgkmcnt(0)
	ds_write_b128 v139, v[50:53]
	ds_write_b128 v139, v[58:61] offset:4096
	ds_write_b128 v140, v[62:65]
	ds_write_b128 v140, v[66:69] offset:4096
	ds_write_b128 v141, v[78:81]
	ds_write_b128 v141, v[82:85] offset:4096
	ds_write_b128 v142, v[94:97]
	ds_write_b128 v142, v[98:101] offset:4096
	ds_write_b128 v139, v[38:41] offset:8192
	ds_write_b128 v139, v[34:37] offset:12288
	ds_write_b128 v140, v[26:29] offset:8192
	ds_write_b128 v140, v[22:25] offset:12288
	ds_write_b128 v141, v[18:21] offset:8192
	ds_write_b128 v141, v[10:13] offset:12288
	ds_write_b128 v142, v[6:9] offset:8192
	ds_write_b128 v142, v[2:5] offset:12288
	s_waitcnt vmcnt(15)
	v_pk_add_f32 v[166:167], v[166:167], v[126:127]
	v_pk_add_f32 v[168:169], v[168:169], v[128:129]
	v_add_u32_e32 v157, 0x0, v144
	v_cvt_pk_bf16_f32 v158, v166, v167
	v_cvt_pk_bf16_f32 v159, v168, v169
	global_store_dwordx4 v157, v[166:169], s[26:27] nt
	v_add_u32_e32 v126, 0x0, v146
	v_mul_f32_e32 v149, v166, v166
	global_store_dwordx2 v126, v[158:159], s[96:97]
	v_fmac_f32_e32 v149, v167, v167
	v_fmac_f32_e32 v149, v168, v168
	v_fmac_f32_e32 v149, v169, v169
	s_waitcnt vmcnt(16)
	v_pk_add_f32 v[170:171], v[170:171], v[14:15]
	v_pk_add_f32 v[172:173], v[172:173], v[16:17]
	v_add_u32_e32 v160, 0x8000, v145
	v_cvt_pk_bf16_f32 v164, v170, v171
	v_cvt_pk_bf16_f32 v165, v172, v173
	global_store_dwordx4 v160, v[170:173], s[26:27] nt
	v_add_u32_e32 v14, 0x4000, v147
	v_mul_f32_e32 v150, v170, v170
	global_store_dwordx2 v14, v[164:165], s[96:97]
	v_fmac_f32_e32 v150, v171, v171
	v_fmac_f32_e32 v150, v172, v172
	v_fmac_f32_e32 v150, v173, v173
	s_waitcnt vmcnt(17)
; template <int EPI, int NRM>
; DEVI void epilogue(acc_t& acc, int pn, int trow, const EpiArgs& e, const float* rl, bf16* shmx) {
;     ...
;       for (int bj = 0; bj < 2; ++bj)
; #pragma unroll
;         for (int m = 0; m < 4; ++m)
; #pragma unroll
;           for (int n = 0; n < 2; ++n) {
;             const int idx = (bj * 4 + m) * 2 + n;
;             const unsigned off = (unsigned)((tk0 + bj * 128 + n * 16) * DM + pn * 256 + ai * 128 + m * 16 + fl0);
;             const float4 xx = *reinterpret_cast<const float4*>(lbase + idx * 1024 + lane * 16);
;             float4 o;
;             o.x = xx.x + acc[ai][bj][m][n][0]; o.y = xx.y + acc[ai][bj][m][n][1];
;             o.z = xx.z + acc[ai][bj][m][n][2]; o.w = xx.w + acc[ai][bj][m][n][3];
;             *reinterpret_cast<float4*>(e.xout + off) = o;
;             uint2 ob; ob.x = pack2(o.x, o.y); ob.y = pack2(o.z, o.w);
;             *reinterpret_cast<uint2*>(e.o0 + off) = ob;
;             ss[bj][n] += o.x * o.x + o.y * o.y + o.z * o.z + o.w * o.w;
;           }
	v_pk_add_f32 v[174:175], v[174:175], v[122:123]
	v_pk_add_f32 v[176:177], v[176:177], v[124:125]
	v_add_u32_e32 v157, 0x10000, v144
	v_cvt_pk_bf16_f32 v158, v174, v175
	v_cvt_pk_bf16_f32 v159, v176, v177
	global_store_dwordx4 v157, v[174:177], s[26:27] nt
	v_add_u32_e32 v122, 0x8000, v146
	v_mul_f32_e32 v151, v174, v174
	global_store_dwordx2 v122, v[158:159], s[96:97]
	v_fmac_f32_e32 v151, v175, v175
	v_fmac_f32_e32 v151, v176, v176
	v_fmac_f32_e32 v151, v177, v177
	s_waitcnt vmcnt(18)
	v_pk_add_f32 v[178:179], v[178:179], v[30:31]
	v_pk_add_f32 v[180:181], v[180:181], v[32:33]
	v_add_u32_e32 v160, 0x18000, v145
	v_cvt_pk_bf16_f32 v164, v178, v179
	v_cvt_pk_bf16_f32 v165, v180, v181
	global_store_dwordx4 v160, v[178:181], s[26:27] nt
	v_add_u32_e32 v30, 0xc000, v147
	v_mul_f32_e32 v152, v178, v178
	global_store_dwordx2 v30, v[164:165], s[96:97]
	v_fmac_f32_e32 v152, v179, v179
	v_fmac_f32_e32 v152, v180, v180
	v_fmac_f32_e32 v152, v181, v181
	s_waitcnt vmcnt(19)
	v_pk_add_f32 v[182:183], v[182:183], v[118:119]
	v_pk_add_f32 v[184:185], v[184:185], v[120:121]
	v_add_u32_e32 v157, 0x20000, v144
	v_cvt_pk_bf16_f32 v158, v182, v183
	v_cvt_pk_bf16_f32 v159, v184, v185
	global_store_dwordx4 v157, v[182:185], s[26:27] nt
	v_add_u32_e32 v118, 0x10000, v146
	v_mul_f32_e32 v153, v182, v182
	global_store_dwordx2 v118, v[158:159], s[96:97]
	v_fmac_f32_e32 v153, v183, v183
	v_fmac_f32_e32 v153, v184, v184
	v_fmac_f32_e32 v153, v185, v185
	s_waitcnt vmcnt(20)
	v_pk_add_f32 v[186:187], v[186:187], v[46:47]
	v_pk_add_f32 v[188:189], v[188:189], v[48:49]
	v_add_u32_e32 v160, 0x28000, v145
	v_cvt_pk_bf16_f32 v164, v186, v187
	v_cvt_pk_bf16_f32 v165, v188, v189
	global_store_dwordx4 v160, v[186:189], s[26:27] nt
	v_add_u32_e32 v46, 0x14000, v147
	v_mul_f32_e32 v154, v186, v186
	global_store_dwordx2 v46, v[164:165], s[96:97]
	v_fmac_f32_e32 v154, v187, v187
	v_fmac_f32_e32 v154, v188, v188
	v_fmac_f32_e32 v154, v189, v189
	s_waitcnt vmcnt(21)
	v_pk_add_f32 v[190:191], v[190:191], v[114:115]
	v_pk_add_f32 v[192:193], v[192:193], v[116:117]
	v_add_u32_e32 v157, 0x30000, v144
	v_cvt_pk_bf16_f32 v158, v190, v191
	v_cvt_pk_bf16_f32 v159, v192, v193
	global_store_dwordx4 v157, v[190:193], s[26:27] nt
	v_add_u32_e32 v114, 0x18000, v146
	v_mul_f32_e32 v155, v190, v190
	global_store_dwordx2 v114, v[158:159], s[96:97]
	v_fmac_f32_e32 v155, v191, v191
	v_fmac_f32_e32 v155, v192, v192
	v_fmac_f32_e32 v155, v193, v193
	s_waitcnt vmcnt(22)
	v_pk_add_f32 v[194:195], v[194:195], v[54:55]
	v_pk_add_f32 v[196:197], v[196:197], v[56:57]
	v_add_u32_e32 v160, 0x38000, v145
	v_cvt_pk_bf16_f32 v164, v194, v195
	v_cvt_pk_bf16_f32 v165, v196, v197
	global_store_dwordx4 v160, v[194:197], s[26:27] nt
	v_add_u32_e32 v54, 0x1c000, v147
	v_mul_f32_e32 v156, v194, v194
	global_store_dwordx2 v54, v[164:165], s[96:97]
	v_fmac_f32_e32 v156, v195, v195
	v_fmac_f32_e32 v156, v196, v196
	v_fmac_f32_e32 v156, v197, v197
	v_add_u32_e32 v157, 0x100000, v144
	global_load_dwordx4 v[166:169], v157, s[4:5] nt
	v_add_u32_e32 v160, 0x108000, v145
	global_load_dwordx4 v[170:173], v160, s[4:5] nt
	v_add_u32_e32 v157, 0x110000, v144
	global_load_dwordx4 v[174:177], v157, s[4:5] nt
	v_add_u32_e32 v160, 0x118000, v145
	global_load_dwordx4 v[178:181], v160, s[4:5] nt
	v_add_u32_e32 v157, 0x120000, v144
	global_load_dwordx4 v[182:185], v157, s[4:5] nt
	v_add_u32_e32 v160, 0x128000, v145
	global_load_dwordx4 v[186:189], v160, s[4:5] nt
	v_add_u32_e32 v157, 0x130000, v144
	global_load_dwordx4 v[190:193], v157, s[4:5] nt
	v_add_u32_e32 v160, 0x138000, v145
	global_load_dwordx4 v[194:197], v160, s[4:5] nt
	s_waitcnt vmcnt(31)
	v_pk_add_f32 v[198:199], v[198:199], v[110:111]
	v_pk_add_f32 v[200:201], v[200:201], v[112:113]
	v_add_u32_e32 v157, 0x200, v144
	v_cvt_pk_bf16_f32 v158, v198, v199
	v_cvt_pk_bf16_f32 v159, v200, v201
	global_store_dwordx4 v157, v[198:201], s[26:27] nt
	v_add_u32_e32 v110, 0x100, v146
	v_fmac_f32_e32 v149, v198, v198
	global_store_dwordx2 v110, v[158:159], s[96:97]
	v_fmac_f32_e32 v149, v199, v199
	v_fmac_f32_e32 v149, v200, v200
	v_fmac_f32_e32 v149, v201, v201
	s_waitcnt vmcnt(32)
	v_pk_add_f32 v[202:203], v[202:203], v[106:107]
	v_pk_add_f32 v[204:205], v[204:205], v[108:109]
	v_add_u32_e32 v160, 0x8200, v145
	v_cvt_pk_bf16_f32 v164, v202, v203
	v_cvt_pk_bf16_f32 v165, v204, v205
	global_store_dwordx4 v160, v[202:205], s[26:27] nt
	v_add_u32_e32 v106, 0x4100, v147
	v_fmac_f32_e32 v150, v202, v202
	global_store_dwordx2 v106, v[164:165], s[96:97]
	v_fmac_f32_e32 v150, v203, v203
	v_fmac_f32_e32 v150, v204, v204
	v_fmac_f32_e32 v150, v205, v205
	s_waitcnt vmcnt(33)
	v_pk_add_f32 v[206:207], v[206:207], v[102:103]
	v_pk_add_f32 v[208:209], v[208:209], v[104:105]
	v_add_u32_e32 v157, 0x10200, v144
	v_cvt_pk_bf16_f32 v158, v206, v207
	v_cvt_pk_bf16_f32 v159, v208, v209
	global_store_dwordx4 v157, v[206:209], s[26:27] nt
	v_add_u32_e32 v102, 0x8100, v146
	v_fmac_f32_e32 v151, v206, v206
	global_store_dwordx2 v102, v[158:159], s[96:97]
	v_fmac_f32_e32 v151, v207, v207
	v_fmac_f32_e32 v151, v208, v208
	v_fmac_f32_e32 v151, v209, v209
	s_waitcnt vmcnt(34)
	v_pk_add_f32 v[210:211], v[210:211], v[90:91]
	v_pk_add_f32 v[212:213], v[212:213], v[92:93]
	v_add_u32_e32 v160, 0x18200, v145
	v_cvt_pk_bf16_f32 v164, v210, v211
	v_cvt_pk_bf16_f32 v165, v212, v213
	global_store_dwordx4 v160, v[210:213], s[26:27] nt
	v_add_u32_e32 v90, 0xc100, v147
	v_fmac_f32_e32 v152, v210, v210
	global_store_dwordx2 v90, v[164:165], s[96:97]
	v_fmac_f32_e32 v152, v211, v211
	v_fmac_f32_e32 v152, v212, v212
	v_fmac_f32_e32 v152, v213, v213
	s_waitcnt vmcnt(35)
; template <int EPI, int NRM>
; DEVI void epilogue(acc_t& acc, int pn, int trow, const EpiArgs& e, const float* rl, bf16* shmx) {
;     ...
;       for (int bj = 0; bj < 2; ++bj)
; #pragma unroll
;         for (int m = 0; m < 4; ++m)
; #pragma unroll
;           for (int n = 0; n < 2; ++n) {
;             const int idx = (bj * 4 + m) * 2 + n;
;             const unsigned off = (unsigned)((tk0 + bj * 128 + n * 16) * DM + pn * 256 + ai * 128 + m * 16 + fl0);
;             const float4 xx = *reinterpret_cast<const float4*>(lbase + idx * 1024 + lane * 16);
;             float4 o;
;             o.x = xx.x + acc[ai][bj][m][n][0]; o.y = xx.y + acc[ai][bj][m][n][1];
;             o.z = xx.z + acc[ai][bj][m][n][2]; o.w = xx.w + acc[ai][bj][m][n][3];
;             *reinterpret_cast<float4*>(e.xout + off) = o;
;             uint2 ob; ob.x = pack2(o.x, o.y); ob.y = pack2(o.z, o.w);
;             *reinterpret_cast<uint2*>(e.o0 + off) = ob;
;             ss[bj][n] += o.x * o.x + o.y * o.y + o.z * o.z + o.w * o.w;
;           }
;       asm volatile("s_waitcnt lgkmcnt(0)" ::: "memory");
;     }
; #pragma unroll
;     for (int bj = 0; bj < 2; ++bj)
; #pragma unroll
;       for (int n = 0; n < 2; ++n) {
;         float v = ss[bj][n];
;         v += __shfl_xor(v, 16); v += __shfl_xor(v, 32);
;         if (fq == 0) e.stw[(pn * 2 + wr) * TOK + tk0 + bj * 128 + n * 16] = v;
;       }
	v_pk_add_f32 v[214:215], v[214:215], v[86:87]
	v_pk_add_f32 v[216:217], v[216:217], v[88:89]
	v_add_u32_e32 v157, 0x20200, v144
	v_cvt_pk_bf16_f32 v158, v214, v215
	v_cvt_pk_bf16_f32 v159, v216, v217
	global_store_dwordx4 v157, v[214:217], s[26:27] nt
	v_add_u32_e32 v86, 0x10100, v146
	v_fmac_f32_e32 v153, v214, v214
	global_store_dwordx2 v86, v[158:159], s[96:97]
	v_fmac_f32_e32 v153, v215, v215
	v_fmac_f32_e32 v153, v216, v216
	v_fmac_f32_e32 v153, v217, v217
	s_waitcnt vmcnt(36)
	v_pk_add_f32 v[218:219], v[218:219], v[74:75]
	v_pk_add_f32 v[220:221], v[220:221], v[76:77]
	v_add_u32_e32 v160, 0x28200, v145
	v_cvt_pk_bf16_f32 v164, v218, v219
	v_cvt_pk_bf16_f32 v165, v220, v221
	global_store_dwordx4 v160, v[218:221], s[26:27] nt
	v_add_u32_e32 v74, 0x14100, v147
	v_fmac_f32_e32 v154, v218, v218
	global_store_dwordx2 v74, v[164:165], s[96:97]
	v_fmac_f32_e32 v154, v219, v219
	v_fmac_f32_e32 v154, v220, v220
	v_fmac_f32_e32 v154, v221, v221
	s_waitcnt vmcnt(37)
	v_pk_add_f32 v[222:223], v[222:223], v[70:71]
	v_pk_add_f32 v[224:225], v[224:225], v[72:73]
	v_add_u32_e32 v157, 0x30200, v144
	v_cvt_pk_bf16_f32 v158, v222, v223
	v_cvt_pk_bf16_f32 v159, v224, v225
	global_store_dwordx4 v157, v[222:225], s[26:27] nt
	v_add_u32_e32 v70, 0x18100, v146
	v_fmac_f32_e32 v155, v222, v222
	global_store_dwordx2 v70, v[158:159], s[96:97]
	v_fmac_f32_e32 v155, v223, v223
	v_fmac_f32_e32 v155, v224, v224
	v_fmac_f32_e32 v155, v225, v225
	s_waitcnt vmcnt(38)
	v_pk_add_f32 v[226:227], v[226:227], v[42:43]
	v_pk_add_f32 v[228:229], v[228:229], v[44:45]
	v_add_u32_e32 v160, 0x38200, v145
	v_cvt_pk_bf16_f32 v164, v226, v227
	v_cvt_pk_bf16_f32 v165, v228, v229
	global_store_dwordx4 v160, v[226:229], s[26:27] nt
	v_add_u32_e32 v42, 0x1c100, v147
	v_fmac_f32_e32 v156, v226, v226
	global_store_dwordx2 v42, v[164:165], s[96:97]
	v_fmac_f32_e32 v156, v227, v227
	v_fmac_f32_e32 v156, v228, v228
	v_fmac_f32_e32 v156, v229, v229
	v_add_u32_e32 v157, 0x100200, v144
	global_load_dwordx4 v[198:201], v157, s[4:5] nt
	v_add_u32_e32 v160, 0x108200, v145
	global_load_dwordx4 v[202:205], v160, s[4:5] nt
	v_add_u32_e32 v157, 0x110200, v144
	global_load_dwordx4 v[206:209], v157, s[4:5] nt
	v_add_u32_e32 v160, 0x118200, v145
	global_load_dwordx4 v[210:213], v160, s[4:5] nt
	v_add_u32_e32 v157, 0x120200, v144
	global_load_dwordx4 v[214:217], v157, s[4:5] nt
	v_add_u32_e32 v160, 0x128200, v145
	global_load_dwordx4 v[218:221], v160, s[4:5] nt
	v_add_u32_e32 v157, 0x130200, v144
	global_load_dwordx4 v[222:225], v157, s[4:5] nt
	v_add_u32_e32 v160, 0x138200, v145
	global_load_dwordx4 v[226:229], v160, s[4:5] nt
	v_add_f32_dpp v149, v149, v149 row_shr:1 row_mask:0xf bank_mask:0xf bound_ctrl:0
	v_add_f32_dpp v150, v150, v150 row_shr:1 row_mask:0xf bank_mask:0xf bound_ctrl:0
	v_add_f32_dpp v151, v151, v151 row_shr:1 row_mask:0xf bank_mask:0xf bound_ctrl:0
	v_add_f32_dpp v152, v152, v152 row_shr:1 row_mask:0xf bank_mask:0xf bound_ctrl:0
	v_add_f32_dpp v153, v153, v153 row_shr:1 row_mask:0xf bank_mask:0xf bound_ctrl:0
	v_add_f32_dpp v154, v154, v154 row_shr:1 row_mask:0xf bank_mask:0xf bound_ctrl:0
	v_add_f32_dpp v155, v155, v155 row_shr:1 row_mask:0xf bank_mask:0xf bound_ctrl:0
	v_add_f32_dpp v156, v156, v156 row_shr:1 row_mask:0xf bank_mask:0xf bound_ctrl:0
	v_add_f32_dpp v149, v149, v149 row_shr:2 row_mask:0xf bank_mask:0xf bound_ctrl:0
	v_add_f32_dpp v150, v150, v150 row_shr:2 row_mask:0xf bank_mask:0xf bound_ctrl:0
	v_add_f32_dpp v151, v151, v151 row_shr:2 row_mask:0xf bank_mask:0xf bound_ctrl:0
	v_add_f32_dpp v152, v152, v152 row_shr:2 row_mask:0xf bank_mask:0xf bound_ctrl:0
	v_add_f32_dpp v153, v153, v153 row_shr:2 row_mask:0xf bank_mask:0xf bound_ctrl:0
	v_add_f32_dpp v154, v154, v154 row_shr:2 row_mask:0xf bank_mask:0xf bound_ctrl:0
	v_add_f32_dpp v155, v155, v155 row_shr:2 row_mask:0xf bank_mask:0xf bound_ctrl:0
	v_add_f32_dpp v156, v156, v156 row_shr:2 row_mask:0xf bank_mask:0xf bound_ctrl:0
	v_add_f32_dpp v149, v149, v149 row_shr:4 row_mask:0xf bank_mask:0xf bound_ctrl:0
	v_add_f32_dpp v150, v150, v150 row_shr:4 row_mask:0xf bank_mask:0xf bound_ctrl:0
	v_add_f32_dpp v151, v151, v151 row_shr:4 row_mask:0xf bank_mask:0xf bound_ctrl:0
	v_add_f32_dpp v152, v152, v152 row_shr:4 row_mask:0xf bank_mask:0xf bound_ctrl:0
	v_add_f32_dpp v153, v153, v153 row_shr:4 row_mask:0xf bank_mask:0xf bound_ctrl:0
	v_add_f32_dpp v154, v154, v154 row_shr:4 row_mask:0xf bank_mask:0xf bound_ctrl:0
	v_add_f32_dpp v155, v155, v155 row_shr:4 row_mask:0xf bank_mask:0xf bound_ctrl:0
	v_add_f32_dpp v156, v156, v156 row_shr:4 row_mask:0xf bank_mask:0xf bound_ctrl:0
	v_add_f32_dpp v149, v149, v149 row_shr:8 row_mask:0xf bank_mask:0xf bound_ctrl:0
	v_add_f32_dpp v150, v150, v150 row_shr:8 row_mask:0xf bank_mask:0xf bound_ctrl:0
	v_add_f32_dpp v151, v151, v151 row_shr:8 row_mask:0xf bank_mask:0xf bound_ctrl:0
	v_add_f32_dpp v152, v152, v152 row_shr:8 row_mask:0xf bank_mask:0xf bound_ctrl:0
	v_add_f32_dpp v153, v153, v153 row_shr:8 row_mask:0xf bank_mask:0xf bound_ctrl:0
	v_add_f32_dpp v154, v154, v154 row_shr:8 row_mask:0xf bank_mask:0xf bound_ctrl:0
	v_add_f32_dpp v155, v155, v155 row_shr:8 row_mask:0xf bank_mask:0xf bound_ctrl:0
	v_add_f32_dpp v156, v156, v156 row_shr:8 row_mask:0xf bank_mask:0xf bound_ctrl:0
	v_cmp_eq_u32_e32 vcc, 15, v138
	s_and_saveexec_b64 s[6:7], vcc
	global_store_dword v148, v149, s[94:95]
	global_store_dword v148, v150, s[94:95] offset:16
	global_store_dword v148, v151, s[94:95] offset:32
	global_store_dword v148, v152, s[94:95] offset:48
	global_store_dword v148, v153, s[94:95] offset:64
	global_store_dword v148, v154, s[94:95] offset:80
	global_store_dword v148, v155, s[94:95] offset:96
	global_store_dword v148, v156, s[94:95] offset:112
	s_or_b64 exec, exec, s[6:7]
	s_waitcnt lgkmcnt(0)
; template <int EPI, int NRM>
; DEVI void epilogue(acc_t& acc, int pn, int trow, const EpiArgs& e, const float* rl, bf16* shmx) {
;     ...
;       for (int bj = 0; bj < 2; ++bj)
; #pragma unroll
;         for (int m = 0; m < 4; ++m)
; #pragma unroll
;           for (int n = 0; n < 2; ++n) {
;             const int idx = (bj * 4 + m) * 2 + n;
;             const unsigned off = (unsigned)((tk0 + bj * 128 + n * 16) * DM + pn * 256 + ai * 128 + m * 16 + fl0);
;             const float4 xx = *reinterpret_cast<const float4*>(lbase + idx * 1024 + lane * 16);
;             float4 o;
;             o.x = xx.x + acc[ai][bj][m][n][0]; o.y = xx.y + acc[ai][bj][m][n][1];
;             o.z = xx.z + acc[ai][bj][m][n][2]; o.w = xx.w + acc[ai][bj][m][n][3];
;             *reinterpret_cast<float4*>(e.xout + off) = o;
;             uint2 ob; ob.x = pack2(o.x, o.y); ob.y = pack2(o.z, o.w);
;             *reinterpret_cast<uint2*>(e.o0 + off) = ob;
;             ss[bj][n] += o.x * o.x + o.y * o.y + o.z * o.z + o.w * o.w;
;           }
	ds_read_b128 v[50:53], v143
	ds_read_b128 v[58:61], v143 offset:1024
	ds_read_b128 v[62:65], v143 offset:2048
	ds_read_b128 v[66:69], v143 offset:3072
	ds_read_b128 v[78:81], v143 offset:4096
	ds_read_b128 v[82:85], v143 offset:5120
	ds_read_b128 v[94:97], v143 offset:6144
	ds_read_b128 v[98:101], v143 offset:7168
	ds_read_b128 v[38:41], v143 offset:8192
	ds_read_b128 v[34:37], v143 offset:9216
	ds_read_b128 v[26:29], v143 offset:10240
	ds_read_b128 v[22:25], v143 offset:11264
	ds_read_b128 v[18:21], v143 offset:12288
	ds_read_b128 v[10:13], v143 offset:13312
	ds_read_b128 v[6:9], v143 offset:14336
	ds_read_b128 v[2:5], v143 offset:15360
	s_waitcnt lgkmcnt(0)
	s_waitcnt vmcnt(39)
	v_pk_add_f32 v[166:167], v[166:167], v[50:51]
	v_pk_add_f32 v[168:169], v[168:169], v[52:53]
	v_add_u32_e32 v157, 0x100000, v144
	v_cvt_pk_bf16_f32 v158, v166, v167
	v_cvt_pk_bf16_f32 v159, v168, v169
	global_store_dwordx4 v157, v[166:169], s[26:27] nt
	v_add_u32_e32 v50, 0x80000, v146
	v_mul_f32_e32 v149, v166, v166
	global_store_dwordx2 v50, v[158:159], s[96:97]
	v_fmac_f32_e32 v149, v167, v167
	v_fmac_f32_e32 v149, v168, v168
	v_fmac_f32_e32 v149, v169, v169
	s_waitcnt vmcnt(40)
	v_pk_add_f32 v[170:171], v[170:171], v[58:59]
	v_pk_add_f32 v[172:173], v[172:173], v[60:61]
	v_add_u32_e32 v160, 0x108000, v145
	v_cvt_pk_bf16_f32 v164, v170, v171
	v_cvt_pk_bf16_f32 v165, v172, v173
	global_store_dwordx4 v160, v[170:173], s[26:27] nt
	v_add_u32_e32 v58, 0x84000, v147
	v_mul_f32_e32 v150, v170, v170
	global_store_dwordx2 v58, v[164:165], s[96:97]
	v_fmac_f32_e32 v150, v171, v171
	v_fmac_f32_e32 v150, v172, v172
	v_fmac_f32_e32 v150, v173, v173
	s_waitcnt vmcnt(41)
	v_pk_add_f32 v[174:175], v[174:175], v[62:63]
	v_pk_add_f32 v[176:177], v[176:177], v[64:65]
	v_add_u32_e32 v157, 0x110000, v144
	v_cvt_pk_bf16_f32 v158, v174, v175
	v_cvt_pk_bf16_f32 v159, v176, v177
	global_store_dwordx4 v157, v[174:177], s[26:27] nt
	v_add_u32_e32 v62, 0x88000, v146
	v_mul_f32_e32 v151, v174, v174
	global_store_dwordx2 v62, v[158:159], s[96:97]
	v_fmac_f32_e32 v151, v175, v175
	v_fmac_f32_e32 v151, v176, v176
	v_fmac_f32_e32 v151, v177, v177
	s_waitcnt vmcnt(42)
	v_pk_add_f32 v[178:179], v[178:179], v[66:67]
	v_pk_add_f32 v[180:181], v[180:181], v[68:69]
	v_add_u32_e32 v160, 0x118000, v145
	v_cvt_pk_bf16_f32 v164, v178, v179
	v_cvt_pk_bf16_f32 v165, v180, v181
	global_store_dwordx4 v160, v[178:181], s[26:27] nt
	v_add_u32_e32 v66, 0x8c000, v147
	v_mul_f32_e32 v152, v178, v178
	global_store_dwordx2 v66, v[164:165], s[96:97]
	v_fmac_f32_e32 v152, v179, v179
	v_fmac_f32_e32 v152, v180, v180
	v_fmac_f32_e32 v152, v181, v181
	s_waitcnt vmcnt(43)
	v_pk_add_f32 v[182:183], v[182:183], v[78:79]
	v_pk_add_f32 v[184:185], v[184:185], v[80:81]
	v_add_u32_e32 v157, 0x120000, v144
	v_cvt_pk_bf16_f32 v158, v182, v183
	v_cvt_pk_bf16_f32 v159, v184, v185
	global_store_dwordx4 v157, v[182:185], s[26:27] nt
	v_add_u32_e32 v78, 0x90000, v146
	v_mul_f32_e32 v153, v182, v182
	global_store_dwordx2 v78, v[158:159], s[96:97]
	v_fmac_f32_e32 v153, v183, v183
	v_fmac_f32_e32 v153, v184, v184
	v_fmac_f32_e32 v153, v185, v185
	s_waitcnt vmcnt(44)
	v_pk_add_f32 v[186:187], v[186:187], v[82:83]
	v_pk_add_f32 v[188:189], v[188:189], v[84:85]
	v_add_u32_e32 v160, 0x128000, v145
	v_cvt_pk_bf16_f32 v164, v186, v187
	v_cvt_pk_bf16_f32 v165, v188, v189
	global_store_dwordx4 v160, v[186:189], s[26:27] nt
	v_add_u32_e32 v82, 0x94000, v147
	v_mul_f32_e32 v154, v186, v186
	global_store_dwordx2 v82, v[164:165], s[96:97]
	v_fmac_f32_e32 v154, v187, v187
	v_fmac_f32_e32 v154, v188, v188
	v_fmac_f32_e32 v154, v189, v189
	s_waitcnt vmcnt(45)
	v_pk_add_f32 v[190:191], v[190:191], v[94:95]
	v_pk_add_f32 v[192:193], v[192:193], v[96:97]
	v_add_u32_e32 v157, 0x130000, v144
	v_cvt_pk_bf16_f32 v158, v190, v191
	v_cvt_pk_bf16_f32 v159, v192, v193
	global_store_dwordx4 v157, v[190:193], s[26:27] nt
	v_add_u32_e32 v94, 0x98000, v146
	v_mul_f32_e32 v155, v190, v190
	global_store_dwordx2 v94, v[158:159], s[96:97]
	v_fmac_f32_e32 v155, v191, v191
	v_fmac_f32_e32 v155, v192, v192
	v_fmac_f32_e32 v155, v193, v193
	s_waitcnt vmcnt(46)
	v_pk_add_f32 v[194:195], v[194:195], v[98:99]
	v_pk_add_f32 v[196:197], v[196:197], v[100:101]
	v_add_u32_e32 v160, 0x138000, v145
	v_cvt_pk_bf16_f32 v164, v194, v195
	v_cvt_pk_bf16_f32 v165, v196, v197
	global_store_dwordx4 v160, v[194:197], s[26:27] nt
	v_add_u32_e32 v98, 0x9c000, v147
	v_mul_f32_e32 v156, v194, v194
	global_store_dwordx2 v98, v[164:165], s[96:97]
	v_fmac_f32_e32 v156, v195, v195
	v_fmac_f32_e32 v156, v196, v196
	v_fmac_f32_e32 v156, v197, v197
	s_waitcnt vmcnt(31)
	v_pk_add_f32 v[198:199], v[198:199], v[38:39]
	v_pk_add_f32 v[200:201], v[200:201], v[40:41]
	v_add_u32_e32 v157, 0x100200, v144
	v_cvt_pk_bf16_f32 v158, v198, v199
	v_cvt_pk_bf16_f32 v159, v200, v201
	global_store_dwordx4 v157, v[198:201], s[26:27] nt
	v_add_u32_e32 v38, 0x80100, v146
	v_fmac_f32_e32 v149, v198, v198
	global_store_dwordx2 v38, v[158:159], s[96:97]
	v_fmac_f32_e32 v149, v199, v199
	v_fmac_f32_e32 v149, v200, v200
	v_fmac_f32_e32 v149, v201, v201
	s_waitcnt vmcnt(32)
	v_pk_add_f32 v[202:203], v[202:203], v[34:35]
	v_pk_add_f32 v[204:205], v[204:205], v[36:37]
	v_add_u32_e32 v160, 0x108200, v145
	v_cvt_pk_bf16_f32 v164, v202, v203
	v_cvt_pk_bf16_f32 v165, v204, v205
	global_store_dwordx4 v160, v[202:205], s[26:27] nt
	v_add_u32_e32 v34, 0x84100, v147
	v_fmac_f32_e32 v150, v202, v202
	global_store_dwordx2 v34, v[164:165], s[96:97]
	v_fmac_f32_e32 v150, v203, v203
	v_fmac_f32_e32 v150, v204, v204
	v_fmac_f32_e32 v150, v205, v205
	s_waitcnt vmcnt(33)
; template <int EPI, int NRM>
; DEVI void epilogue(acc_t& acc, int pn, int trow, const EpiArgs& e, const float* rl, bf16* shmx) {
;     ...
;       for (int bj = 0; bj < 2; ++bj)
; #pragma unroll
;         for (int m = 0; m < 4; ++m)
; #pragma unroll
;           for (int n = 0; n < 2; ++n) {
;             const int idx = (bj * 4 + m) * 2 + n;
;             const unsigned off = (unsigned)((tk0 + bj * 128 + n * 16) * DM + pn * 256 + ai * 128 + m * 16 + fl0);
;             const float4 xx = *reinterpret_cast<const float4*>(lbase + idx * 1024 + lane * 16);
;             float4 o;
;             o.x = xx.x + acc[ai][bj][m][n][0]; o.y = xx.y + acc[ai][bj][m][n][1];
;             o.z = xx.z + acc[ai][bj][m][n][2]; o.w = xx.w + acc[ai][bj][m][n][3];
;             *reinterpret_cast<float4*>(e.xout + off) = o;
;             uint2 ob; ob.x = pack2(o.x, o.y); ob.y = pack2(o.z, o.w);
;             *reinterpret_cast<uint2*>(e.o0 + off) = ob;
;             ss[bj][n] += o.x * o.x + o.y * o.y + o.z * o.z + o.w * o.w;
;           }
;       asm volatile("s_waitcnt lgkmcnt(0)" ::: "memory");
;     }
; #pragma unroll
;     for (int bj = 0; bj < 2; ++bj)
; #pragma unroll
;       for (int n = 0; n < 2; ++n) {
;         float v = ss[bj][n];
;         v += __shfl_xor(v, 16); v += __shfl_xor(v, 32);
;         if (fq == 0) e.stw[(pn * 2 + wr) * TOK + tk0 + bj * 128 + n * 16] = v;
;       }
;     asm volatile("s_waitcnt lgkmcnt(0)" ::: "memory");
;     __builtin_amdgcn_s_barrier();
	v_pk_add_f32 v[206:207], v[206:207], v[26:27]
	v_pk_add_f32 v[208:209], v[208:209], v[28:29]
	v_add_u32_e32 v157, 0x110200, v144
	v_cvt_pk_bf16_f32 v158, v206, v207
	v_cvt_pk_bf16_f32 v159, v208, v209
	global_store_dwordx4 v157, v[206:209], s[26:27] nt
	v_add_u32_e32 v26, 0x88100, v146
	v_fmac_f32_e32 v151, v206, v206
	global_store_dwordx2 v26, v[158:159], s[96:97]
	v_fmac_f32_e32 v151, v207, v207
	v_fmac_f32_e32 v151, v208, v208
	v_fmac_f32_e32 v151, v209, v209
	s_waitcnt vmcnt(34)
	v_pk_add_f32 v[210:211], v[210:211], v[22:23]
	v_pk_add_f32 v[212:213], v[212:213], v[24:25]
	v_add_u32_e32 v160, 0x118200, v145
	v_cvt_pk_bf16_f32 v164, v210, v211
	v_cvt_pk_bf16_f32 v165, v212, v213
	global_store_dwordx4 v160, v[210:213], s[26:27] nt
	v_add_u32_e32 v22, 0x8c100, v147
	v_fmac_f32_e32 v152, v210, v210
	global_store_dwordx2 v22, v[164:165], s[96:97]
	v_fmac_f32_e32 v152, v211, v211
	v_fmac_f32_e32 v152, v212, v212
	v_fmac_f32_e32 v152, v213, v213
	s_waitcnt vmcnt(35)
	v_pk_add_f32 v[214:215], v[214:215], v[18:19]
	v_pk_add_f32 v[216:217], v[216:217], v[20:21]
	v_add_u32_e32 v157, 0x120200, v144
	v_cvt_pk_bf16_f32 v158, v214, v215
	v_cvt_pk_bf16_f32 v159, v216, v217
	global_store_dwordx4 v157, v[214:217], s[26:27] nt
	v_add_u32_e32 v18, 0x90100, v146
	v_fmac_f32_e32 v153, v214, v214
	global_store_dwordx2 v18, v[158:159], s[96:97]
	v_fmac_f32_e32 v153, v215, v215
	v_fmac_f32_e32 v153, v216, v216
	v_fmac_f32_e32 v153, v217, v217
	s_waitcnt vmcnt(36)
	v_pk_add_f32 v[218:219], v[218:219], v[10:11]
	v_pk_add_f32 v[220:221], v[220:221], v[12:13]
	v_add_u32_e32 v160, 0x128200, v145
	v_cvt_pk_bf16_f32 v164, v218, v219
	v_cvt_pk_bf16_f32 v165, v220, v221
	global_store_dwordx4 v160, v[218:221], s[26:27] nt
	v_add_u32_e32 v10, 0x94100, v147
	v_fmac_f32_e32 v154, v218, v218
	global_store_dwordx2 v10, v[164:165], s[96:97]
	v_fmac_f32_e32 v154, v219, v219
	v_fmac_f32_e32 v154, v220, v220
	v_fmac_f32_e32 v154, v221, v221
	s_waitcnt vmcnt(37)
	v_pk_add_f32 v[222:223], v[222:223], v[6:7]
	v_pk_add_f32 v[224:225], v[224:225], v[8:9]
	v_add_u32_e32 v157, 0x130200, v144
	v_cvt_pk_bf16_f32 v158, v222, v223
	v_cvt_pk_bf16_f32 v159, v224, v225
	global_store_dwordx4 v157, v[222:225], s[26:27] nt
	v_add_u32_e32 v6, 0x98100, v146
	v_fmac_f32_e32 v155, v222, v222
	global_store_dwordx2 v6, v[158:159], s[96:97]
	v_fmac_f32_e32 v155, v223, v223
	v_fmac_f32_e32 v155, v224, v224
	v_fmac_f32_e32 v155, v225, v225
	s_waitcnt vmcnt(38)
	v_pk_add_f32 v[226:227], v[226:227], v[2:3]
	v_pk_add_f32 v[228:229], v[228:229], v[4:5]
	v_add_u32_e32 v160, 0x138200, v145
	v_cvt_pk_bf16_f32 v164, v226, v227
	v_cvt_pk_bf16_f32 v165, v228, v229
	global_store_dwordx4 v160, v[226:229], s[26:27] nt
	v_add_u32_e32 v2, 0x9c100, v147
	v_fmac_f32_e32 v156, v226, v226
	global_store_dwordx2 v2, v[164:165], s[96:97]
	v_fmac_f32_e32 v156, v227, v227
	v_fmac_f32_e32 v156, v228, v228
	v_fmac_f32_e32 v156, v229, v229
	v_add_f32_dpp v149, v149, v149 row_shr:1 row_mask:0xf bank_mask:0xf bound_ctrl:0
	v_add_f32_dpp v150, v150, v150 row_shr:1 row_mask:0xf bank_mask:0xf bound_ctrl:0
	v_add_f32_dpp v151, v151, v151 row_shr:1 row_mask:0xf bank_mask:0xf bound_ctrl:0
	v_add_f32_dpp v152, v152, v152 row_shr:1 row_mask:0xf bank_mask:0xf bound_ctrl:0
	v_add_f32_dpp v153, v153, v153 row_shr:1 row_mask:0xf bank_mask:0xf bound_ctrl:0
	v_add_f32_dpp v154, v154, v154 row_shr:1 row_mask:0xf bank_mask:0xf bound_ctrl:0
	v_add_f32_dpp v155, v155, v155 row_shr:1 row_mask:0xf bank_mask:0xf bound_ctrl:0
	v_add_f32_dpp v156, v156, v156 row_shr:1 row_mask:0xf bank_mask:0xf bound_ctrl:0
	v_add_f32_dpp v149, v149, v149 row_shr:2 row_mask:0xf bank_mask:0xf bound_ctrl:0
	v_add_f32_dpp v150, v150, v150 row_shr:2 row_mask:0xf bank_mask:0xf bound_ctrl:0
	v_add_f32_dpp v151, v151, v151 row_shr:2 row_mask:0xf bank_mask:0xf bound_ctrl:0
	v_add_f32_dpp v152, v152, v152 row_shr:2 row_mask:0xf bank_mask:0xf bound_ctrl:0
	v_add_f32_dpp v153, v153, v153 row_shr:2 row_mask:0xf bank_mask:0xf bound_ctrl:0
	v_add_f32_dpp v154, v154, v154 row_shr:2 row_mask:0xf bank_mask:0xf bound_ctrl:0
	v_add_f32_dpp v155, v155, v155 row_shr:2 row_mask:0xf bank_mask:0xf bound_ctrl:0
	v_add_f32_dpp v156, v156, v156 row_shr:2 row_mask:0xf bank_mask:0xf bound_ctrl:0
	v_add_f32_dpp v149, v149, v149 row_shr:4 row_mask:0xf bank_mask:0xf bound_ctrl:0
	v_add_f32_dpp v150, v150, v150 row_shr:4 row_mask:0xf bank_mask:0xf bound_ctrl:0
	v_add_f32_dpp v151, v151, v151 row_shr:4 row_mask:0xf bank_mask:0xf bound_ctrl:0
	v_add_f32_dpp v152, v152, v152 row_shr:4 row_mask:0xf bank_mask:0xf bound_ctrl:0
	v_add_f32_dpp v153, v153, v153 row_shr:4 row_mask:0xf bank_mask:0xf bound_ctrl:0
	v_add_f32_dpp v154, v154, v154 row_shr:4 row_mask:0xf bank_mask:0xf bound_ctrl:0
	v_add_f32_dpp v155, v155, v155 row_shr:4 row_mask:0xf bank_mask:0xf bound_ctrl:0
	v_add_f32_dpp v156, v156, v156 row_shr:4 row_mask:0xf bank_mask:0xf bound_ctrl:0
	v_add_f32_dpp v149, v149, v149 row_shr:8 row_mask:0xf bank_mask:0xf bound_ctrl:0
	v_add_f32_dpp v150, v150, v150 row_shr:8 row_mask:0xf bank_mask:0xf bound_ctrl:0
	v_add_f32_dpp v151, v151, v151 row_shr:8 row_mask:0xf bank_mask:0xf bound_ctrl:0
	v_add_f32_dpp v152, v152, v152 row_shr:8 row_mask:0xf bank_mask:0xf bound_ctrl:0
	v_add_f32_dpp v153, v153, v153 row_shr:8 row_mask:0xf bank_mask:0xf bound_ctrl:0
	v_add_f32_dpp v154, v154, v154 row_shr:8 row_mask:0xf bank_mask:0xf bound_ctrl:0
	v_add_f32_dpp v155, v155, v155 row_shr:8 row_mask:0xf bank_mask:0xf bound_ctrl:0
	v_add_f32_dpp v156, v156, v156 row_shr:8 row_mask:0xf bank_mask:0xf bound_ctrl:0
	v_cmp_eq_u32_e32 vcc, 15, v138
	s_and_saveexec_b64 s[6:7], vcc
	global_store_dword v148, v149, s[94:95] offset:512
	global_store_dword v148, v150, s[94:95] offset:528
	global_store_dword v148, v151, s[94:95] offset:544
	global_store_dword v148, v152, s[94:95] offset:560
	global_store_dword v148, v153, s[94:95] offset:576
	global_store_dword v148, v154, s[94:95] offset:592
	global_store_dword v148, v155, s[94:95] offset:608
	global_store_dword v148, v156, s[94:95] offset:624
	s_branch .LBB0_1175

; DEVI float silu(float x) { return x * __builtin_amdgcn_rcpf(1.f + __expf(-x)); }
; template <int EPI, int NRM>
; DEVI void epilogue(acc_t& acc, int pn, int trow, const EpiArgs& e, const float* rl, bf16* shmx) {
;     ...
;   if constexpr (NRM) {
; #pragma unroll
;     for (int bj = 0; bj < 2; ++bj)
; #pragma unroll
;       for (int n = 0; n < 2; ++n) rs[bj][n] = rl[wc * 32 + fr + bj * 128 + n * 16];
;     ...
;   } else if constexpr (EPI == EPI_SWIGLU) {
; #pragma unroll
;     for (int bj = 0; bj < 2; ++bj)
; #pragma unroll
;       for (int m = 0; m < 4; ++m)
; #pragma unroll
;         for (int n = 0; n < 2; ++n) {
;           float r[4];
; #pragma unroll
;           for (int j = 0; j < 4; ++j) r[j] = silu(acc[0][bj][m][n][j] * rs[bj][n]) * (acc[1][bj][m][n][j] * rs[bj][n]);
;           uint2 o; o.x = pack2(r[0], r[1]); o.y = pack2(r[2], r[3]);
;           const unsigned off = (unsigned)((tk0 + bj * 128 + n * 16) * DFF + pn * 128 + m * 16 + fl0);
;           *reinterpret_cast<uint2*>(e.o0 + off) = o;
;         }
.LBB0_1224:
	v_and_b32_e32 v170, 15, v136
	v_bfe_u32 v171, v136, 4, 2
	v_lshrrev_b32_e32 v172, 6, v136
	v_and_b32_e32 v173, 3, v172
	v_lshrrev_b32_e32 v174, 2, v172
	v_lshlrev_b32_e32 v175, 13, v173
	v_lshl_add_u32 v175, v174, 16, v175
	v_add_u32_e32 v175, 0x8000, v175
	v_lshl_add_u32 v176, v170, 7, v175
	v_and_b32_e32 v177, 1, v171
	v_lshl_add_u32 v176, v177, 3, v176
	v_lshrrev_b32_e32 v177, 1, v171
	v_and_b32_e32 v178, 7, v170
	v_add_u32_e32 v179, 0, v177
	v_xor_b32_e32 v179, v179, v178
	v_lshl_add_u32 v164, v179, 4, v176
	v_add_u32_e32 v179, 2, v177
	v_xor_b32_e32 v179, v179, v178
	v_lshl_add_u32 v165, v179, 4, v176
	v_add_u32_e32 v179, 4, v177
	v_xor_b32_e32 v179, v179, v178
	v_lshl_add_u32 v166, v179, 4, v176
	v_add_u32_e32 v179, 6, v177
	v_xor_b32_e32 v179, v179, v178
	v_lshl_add_u32 v167, v179, 4, v176
	v_and_b32_e32 v180, 63, v136
	v_lshl_add_u32 v168, v180, 4, v175
	v_lshrrev_b32_e32 v181, 3, v180
	v_and_b32_e32 v182, 7, v180
	v_xor_b32_e32 v182, v182, v181
	s_lshl_b32 s9, s12, 8
	v_lshl_add_u32 v183, v173, 5, v181
	v_add_u32_e32 v183, s9, v183
	v_mul_u32_u24_e32 v183, 0x1600, v183
	s_lshl_b32 s9, s14, 7
	v_lshl_add_u32 v179, v174, 6, s9
	v_lshl_add_u32 v179, v182, 3, v179
	v_add_lshl_u32 v169, v183, v179, 1
	v_mov_b32_e32 v130, v136
	s_lshl_b32 s11, s16, 10
	s_and_b32 s11, s11, 0x400
	v_and_b32_e32 v141, 15, v130
	v_ashrrev_i32_e32 v142, 2, v130
	v_lshrrev_b32_e32 v143, 2, v130
	v_lshrrev_b32_e32 v130, 1, v130
	s_add_i32 s11, s11, 0
	v_and_b32_e32 v130, 0x60, v130
	s_add_i32 s11, s11, 0x20000
	v_lshlrev_b32_e32 v132, 2, v130
	v_lshlrev_b32_e32 v133, 2, v141
	v_add3_u32 v132, s11, v132, v133
	ds_read2_b32 v[134:135], v132 offset1:16
	ds_read2_b32 v[132:133], v132 offset0:128 offset1:144
	s_lshl_b32 s9, s12, 8
	v_or3_b32 v130, v141, s9, v130
	s_lshl_b32 s9, s14, 7
	s_waitcnt lgkmcnt(1)
	v_pk_mul_f32 v[122:123], v[122:123], v[134:135] op_sel_hi:[1,0]
	v_and_or_b32 v141, v143, 12, s9
	v_mul_f32_e32 v143, 0xbfb8aa3b, v122
	v_mul_f32_e32 v144, 0xbfb8aa3b, v123
	v_exp_f32_e32 v143, v143
	v_exp_f32_e32 v144, v144
	v_and_b32_e32 v142, 0xffffffc0, v142
	v_pk_mul_f32 v[124:125], v[124:125], v[134:135] op_sel_hi:[1,0]
	v_add_u32_e32 v141, v141, v142
	v_add_f32_e32 v142, 1.0, v143
	v_add_f32_e32 v143, 1.0, v144
	v_mul_f32_e32 v144, 0xbfb8aa3b, v124
	v_mul_f32_e32 v145, 0xbfb8aa3b, v125
	v_rcp_f32_e32 v142, v142
	v_rcp_f32_e32 v143, v143
	v_exp_f32_e32 v144, v144
	v_exp_f32_e32 v145, v145
	v_pk_mul_f32 v[126:127], v[126:127], v[134:135] op_sel_hi:[1,0]
	v_pk_mul_f32 v[122:123], v[122:123], v[142:143]
	v_add_f32_e32 v142, 1.0, v144
	v_add_f32_e32 v143, 1.0, v145
	v_rcp_f32_e32 v142, v142
	v_rcp_f32_e32 v143, v143
	v_pk_mul_f32 v[122:123], v[126:127], v[122:123]
	v_pk_mul_f32 v[106:107], v[106:107], v[134:135] op_sel_hi:[1,0]
	v_cvt_pk_bf16_f32 v126, v122, v123
	v_pk_mul_f32 v[122:123], v[124:125], v[142:143]
	v_pk_mul_f32 v[124:125], v[128:129], v[134:135] op_sel_hi:[1,0]
	v_pk_mul_f32 v[108:109], v[108:109], v[134:135] op_sel_hi:[1,0]
	v_pk_mul_f32 v[122:123], v[124:125], v[122:123]
	v_pk_mul_f32 v[110:111], v[110:111], v[134:135] op_sel_hi:[1,0]
	v_cvt_pk_bf16_f32 v127, v122, v123
	v_mul_lo_u32 v123, v130, s41
	v_mov_b32_e32 v122, v135
	v_pk_mul_f32 v[114:115], v[114:115], v[122:123] op_sel_hi:[1,0]
	v_add_u32_e32 v130, v141, v123
	v_mul_f32_e32 v128, 0xbfb8aa3b, v114
	v_mul_f32_e32 v129, 0xbfb8aa3b, v115
	v_exp_f32_e32 v128, v128
	v_exp_f32_e32 v129, v129
	v_lshl_add_u64 v[124:125], v[130:131], 1, s[2:3]
	v_pk_mul_f32 v[116:117], v[116:117], v[122:123] op_sel_hi:[1,0]
	ds_write_b64 v164, v[126:127]
	v_add_f32_e32 v124, 1.0, v128
	v_add_f32_e32 v125, 1.0, v129
	v_mul_f32_e32 v126, 0xbfb8aa3b, v116
	v_mul_f32_e32 v127, 0xbfb8aa3b, v117
	v_rcp_f32_e32 v124, v124
	v_rcp_f32_e32 v125, v125
	v_exp_f32_e32 v126, v126
	v_exp_f32_e32 v127, v127
	v_pk_mul_f32 v[118:119], v[118:119], v[122:123] op_sel_hi:[1,0]
	v_pk_mul_f32 v[114:115], v[114:115], v[124:125]
	v_add_f32_e32 v124, 1.0, v126
	v_add_f32_e32 v125, 1.0, v127
	v_rcp_f32_e32 v124, v124
	v_rcp_f32_e32 v125, v125
	v_pk_mul_f32 v[114:115], v[118:119], v[114:115]
	v_pk_mul_f32 v[118:119], v[120:121], v[122:123] op_sel_hi:[1,0]
	v_cvt_pk_bf16_f32 v114, v114, v115
	v_pk_mul_f32 v[116:117], v[116:117], v[124:125]
	v_pk_mul_f32 v[98:99], v[98:99], v[122:123] op_sel_hi:[1,0]
	v_pk_mul_f32 v[116:117], v[118:119], v[116:117]
	v_add_u32_e32 v118, 0x16000, v123
	v_add_u32_e32 v130, v118, v141
	v_cvt_pk_bf16_f32 v115, v116, v117
	v_lshl_add_u64 v[116:117], v[130:131], 1, s[2:3]
	ds_write_b64 v164, v[114:115] offset:2048
	v_mul_f32_e32 v114, 0xbfb8aa3b, v106
	v_mul_f32_e32 v115, 0xbfb8aa3b, v107
	v_exp_f32_e32 v114, v114
	v_exp_f32_e32 v115, v115
	v_mul_f32_e32 v117, 0xbfb8aa3b, v108
	v_mul_f32_e32 v119, 0xbfb8aa3b, v109
	v_add_f32_e32 v114, 1.0, v114
	v_add_f32_e32 v115, 1.0, v115
	v_rcp_f32_e32 v114, v114
	v_rcp_f32_e32 v115, v115
	v_exp_f32_e32 v117, v117
	v_exp_f32_e32 v119, v119
	v_or_b32_e32 v116, 16, v141
	v_pk_mul_f32 v[106:107], v[106:107], v[114:115]
	v_add_f32_e32 v114, 1.0, v117
	v_add_f32_e32 v115, 1.0, v119
	v_rcp_f32_e32 v114, v114
	v_rcp_f32_e32 v115, v115
	v_pk_mul_f32 v[106:107], v[110:111], v[106:107]
	v_pk_mul_f32 v[110:111], v[112:113], v[134:135] op_sel_hi:[1,0]
	v_add_u32_e32 v130, v116, v123
	v_pk_mul_f32 v[108:109], v[108:109], v[114:115]
	v_cvt_pk_bf16_f32 v106, v106, v107
	v_pk_mul_f32 v[108:109], v[110:111], v[108:109]
	v_mul_f32_e32 v110, 0xbfb8aa3b, v98
	v_mul_f32_e32 v111, 0xbfb8aa3b, v99
	v_exp_f32_e32 v110, v110
	v_exp_f32_e32 v111, v111
	v_cvt_pk_bf16_f32 v107, v108, v109
	v_lshl_add_u64 v[108:109], v[130:131], 1, s[2:3]
	v_pk_mul_f32 v[100:101], v[100:101], v[122:123] op_sel_hi:[1,0]
; DEVI float silu(float x) { return x * __builtin_amdgcn_rcpf(1.f + __expf(-x)); }
; template <int EPI, int NRM>
; DEVI void epilogue(acc_t& acc, int pn, int trow, const EpiArgs& e, const float* rl, bf16* shmx) {
;     ...
;   } else if constexpr (EPI == EPI_SWIGLU) {
; #pragma unroll
;     for (int bj = 0; bj < 2; ++bj)
; #pragma unroll
;       for (int m = 0; m < 4; ++m)
; #pragma unroll
;         for (int n = 0; n < 2; ++n) {
;           float r[4];
; #pragma unroll
;           for (int j = 0; j < 4; ++j) r[j] = silu(acc[0][bj][m][n][j] * rs[bj][n]) * (acc[1][bj][m][n][j] * rs[bj][n]);
;           uint2 o; o.x = pack2(r[0], r[1]); o.y = pack2(r[2], r[3]);
;           const unsigned off = (unsigned)((tk0 + bj * 128 + n * 16) * DFF + pn * 128 + m * 16 + fl0);
;           *reinterpret_cast<uint2*>(e.o0 + off) = o;
;         }
	ds_write_b64 v165, v[106:107]
	v_add_f32_e32 v106, 1.0, v110
	v_add_f32_e32 v107, 1.0, v111
	v_mul_f32_e32 v108, 0xbfb8aa3b, v100
	v_mul_f32_e32 v109, 0xbfb8aa3b, v101
	v_rcp_f32_e32 v106, v106
	v_rcp_f32_e32 v107, v107
	v_exp_f32_e32 v108, v108
	v_exp_f32_e32 v109, v109
	v_pk_mul_f32 v[102:103], v[102:103], v[122:123] op_sel_hi:[1,0]
	v_pk_mul_f32 v[98:99], v[98:99], v[106:107]
	v_add_f32_e32 v106, 1.0, v108
	v_add_f32_e32 v107, 1.0, v109
	v_rcp_f32_e32 v106, v106
	v_rcp_f32_e32 v107, v107
	v_pk_mul_f32 v[98:99], v[102:103], v[98:99]
	v_pk_mul_f32 v[102:103], v[104:105], v[122:123] op_sel_hi:[1,0]
	v_add_u32_e32 v130, v116, v118
	v_pk_mul_f32 v[100:101], v[100:101], v[106:107]
	v_cvt_pk_bf16_f32 v98, v98, v99
	v_pk_mul_f32 v[100:101], v[102:103], v[100:101]
	v_pk_mul_f32 v[90:91], v[90:91], v[134:135] op_sel_hi:[1,0]
	v_cvt_pk_bf16_f32 v99, v100, v101
	v_lshl_add_u64 v[100:101], v[130:131], 1, s[2:3]
	ds_write_b64 v165, v[98:99] offset:2048
	v_mul_f32_e32 v98, 0xbfb8aa3b, v90
	v_mul_f32_e32 v99, 0xbfb8aa3b, v91
	v_exp_f32_e32 v98, v98
	v_exp_f32_e32 v99, v99
	v_pk_mul_f32 v[92:93], v[92:93], v[134:135] op_sel_hi:[1,0]
	v_pk_mul_f32 v[94:95], v[94:95], v[134:135] op_sel_hi:[1,0]
	v_add_f32_e32 v98, 1.0, v98
	v_add_f32_e32 v99, 1.0, v99
	v_mul_f32_e32 v101, 0xbfb8aa3b, v92
	v_mul_f32_e32 v102, 0xbfb8aa3b, v93
	v_rcp_f32_e32 v98, v98
	v_rcp_f32_e32 v99, v99
	v_exp_f32_e32 v101, v101
	v_exp_f32_e32 v102, v102
	v_pk_mul_f32 v[82:83], v[82:83], v[122:123] op_sel_hi:[1,0]
	v_pk_mul_f32 v[90:91], v[90:91], v[98:99]
	v_add_f32_e32 v98, 1.0, v101
	v_add_f32_e32 v99, 1.0, v102
	v_rcp_f32_e32 v98, v98
	v_rcp_f32_e32 v99, v99
	v_pk_mul_f32 v[90:91], v[94:95], v[90:91]
	v_pk_mul_f32 v[94:95], v[96:97], v[134:135] op_sel_hi:[1,0]
	v_or_b32_e32 v100, 32, v141
	v_pk_mul_f32 v[92:93], v[92:93], v[98:99]
	v_add_u32_e32 v130, v100, v123
	v_pk_mul_f32 v[92:93], v[94:95], v[92:93]
	v_mul_f32_e32 v94, 0xbfb8aa3b, v82
	v_mul_f32_e32 v95, 0xbfb8aa3b, v83
	v_exp_f32_e32 v94, v94
	v_exp_f32_e32 v95, v95
	v_cvt_pk_bf16_f32 v90, v90, v91
	v_cvt_pk_bf16_f32 v91, v92, v93
	v_lshl_add_u64 v[92:93], v[130:131], 1, s[2:3]
	v_pk_mul_f32 v[84:85], v[84:85], v[122:123] op_sel_hi:[1,0]
	ds_write_b64 v166, v[90:91]
	v_add_f32_e32 v90, 1.0, v94
	v_add_f32_e32 v91, 1.0, v95
	v_mul_f32_e32 v92, 0xbfb8aa3b, v84
	v_mul_f32_e32 v93, 0xbfb8aa3b, v85
	v_rcp_f32_e32 v90, v90
	v_rcp_f32_e32 v91, v91
	v_exp_f32_e32 v92, v92
	v_exp_f32_e32 v93, v93
	v_pk_mul_f32 v[86:87], v[86:87], v[122:123] op_sel_hi:[1,0]
	v_pk_mul_f32 v[82:83], v[82:83], v[90:91]
	v_add_f32_e32 v90, 1.0, v92
	v_add_f32_e32 v91, 1.0, v93
	v_rcp_f32_e32 v90, v90
	v_rcp_f32_e32 v91, v91
	v_pk_mul_f32 v[82:83], v[86:87], v[82:83]
	v_pk_mul_f32 v[86:87], v[88:89], v[122:123] op_sel_hi:[1,0]
	v_add_u32_e32 v130, v100, v118
	v_pk_mul_f32 v[84:85], v[84:85], v[90:91]
	v_cvt_pk_bf16_f32 v82, v82, v83
	v_pk_mul_f32 v[84:85], v[86:87], v[84:85]
	v_pk_mul_f32 v[74:75], v[74:75], v[134:135] op_sel_hi:[1,0]
	v_cvt_pk_bf16_f32 v83, v84, v85
	v_lshl_add_u64 v[84:85], v[130:131], 1, s[2:3]
	ds_write_b64 v166, v[82:83] offset:2048
	v_mul_f32_e32 v82, 0xbfb8aa3b, v74
	v_mul_f32_e32 v83, 0xbfb8aa3b, v75
	v_exp_f32_e32 v82, v82
	v_exp_f32_e32 v83, v83
	v_pk_mul_f32 v[76:77], v[76:77], v[134:135] op_sel_hi:[1,0]
	v_pk_mul_f32 v[78:79], v[78:79], v[134:135] op_sel_hi:[1,0]
	v_add_f32_e32 v82, 1.0, v82
	v_add_f32_e32 v83, 1.0, v83
	v_mul_f32_e32 v85, 0xbfb8aa3b, v76
	v_mul_f32_e32 v86, 0xbfb8aa3b, v77
	v_rcp_f32_e32 v82, v82
	v_rcp_f32_e32 v83, v83
	v_exp_f32_e32 v85, v85
	v_exp_f32_e32 v86, v86
	v_pk_mul_f32 v[66:67], v[66:67], v[122:123] op_sel_hi:[1,0]
	v_pk_mul_f32 v[74:75], v[74:75], v[82:83]
	v_add_f32_e32 v82, 1.0, v85
	v_add_f32_e32 v83, 1.0, v86
	v_rcp_f32_e32 v82, v82
	v_rcp_f32_e32 v83, v83
	v_pk_mul_f32 v[74:75], v[78:79], v[74:75]
	v_pk_mul_f32 v[78:79], v[80:81], v[134:135] op_sel_hi:[1,0]
	v_or_b32_e32 v84, 48, v141
	v_pk_mul_f32 v[76:77], v[76:77], v[82:83]
	v_add_u32_e32 v130, v84, v123
	v_pk_mul_f32 v[76:77], v[78:79], v[76:77]
	v_mul_f32_e32 v78, 0xbfb8aa3b, v66
	v_mul_f32_e32 v79, 0xbfb8aa3b, v67
	v_exp_f32_e32 v78, v78
	v_exp_f32_e32 v79, v79
	v_cvt_pk_bf16_f32 v74, v74, v75
	v_cvt_pk_bf16_f32 v75, v76, v77
	v_lshl_add_u64 v[76:77], v[130:131], 1, s[2:3]
	v_pk_mul_f32 v[68:69], v[68:69], v[122:123] op_sel_hi:[1,0]
	ds_write_b64 v167, v[74:75]
	v_add_f32_e32 v74, 1.0, v78
	v_add_f32_e32 v75, 1.0, v79
	v_mul_f32_e32 v76, 0xbfb8aa3b, v68
	v_mul_f32_e32 v77, 0xbfb8aa3b, v69
	v_rcp_f32_e32 v74, v74
	v_rcp_f32_e32 v75, v75
	v_exp_f32_e32 v76, v76
	v_exp_f32_e32 v77, v77
	v_pk_mul_f32 v[70:71], v[70:71], v[122:123] op_sel_hi:[1,0]
	v_pk_mul_f32 v[66:67], v[66:67], v[74:75]
	v_add_f32_e32 v74, 1.0, v76
	v_add_f32_e32 v75, 1.0, v77
	v_rcp_f32_e32 v74, v74
	v_rcp_f32_e32 v75, v75
	v_pk_mul_f32 v[66:67], v[70:71], v[66:67]
	v_pk_mul_f32 v[70:71], v[72:73], v[122:123] op_sel_hi:[1,0]
	s_waitcnt lgkmcnt(0)
; DEVI float silu(float x) { return x * __builtin_amdgcn_rcpf(1.f + __expf(-x)); }
; template <int EPI, int NRM>
; DEVI void epilogue(acc_t& acc, int pn, int trow, const EpiArgs& e, const float* rl, bf16* shmx) {
;     ...
;   } else if constexpr (EPI == EPI_SWIGLU) {
; #pragma unroll
;     for (int bj = 0; bj < 2; ++bj)
; #pragma unroll
;       for (int m = 0; m < 4; ++m)
; #pragma unroll
;         for (int n = 0; n < 2; ++n) {
;           float r[4];
; #pragma unroll
;           for (int j = 0; j < 4; ++j) r[j] = silu(acc[0][bj][m][n][j] * rs[bj][n]) * (acc[1][bj][m][n][j] * rs[bj][n]);
;           uint2 o; o.x = pack2(r[0], r[1]); o.y = pack2(r[2], r[3]);
;           const unsigned off = (unsigned)((tk0 + bj * 128 + n * 16) * DFF + pn * 128 + m * 16 + fl0);
;           *reinterpret_cast<uint2*>(e.o0 + off) = o;
;         }
	v_pk_mul_f32 v[58:59], v[58:59], v[132:133] op_sel_hi:[1,0]
	v_pk_mul_f32 v[68:69], v[68:69], v[74:75]
	v_add_u32_e32 v130, v84, v118
	v_pk_mul_f32 v[68:69], v[70:71], v[68:69]
	v_mul_f32_e32 v70, 0xbfb8aa3b, v58
	v_mul_f32_e32 v71, 0xbfb8aa3b, v59
	v_exp_f32_e32 v70, v70
	v_exp_f32_e32 v71, v71
	v_cvt_pk_bf16_f32 v66, v66, v67
	v_cvt_pk_bf16_f32 v67, v68, v69
	v_lshl_add_u64 v[68:69], v[130:131], 1, s[2:3]
	v_pk_mul_f32 v[60:61], v[60:61], v[132:133] op_sel_hi:[1,0]
	ds_write_b64 v167, v[66:67] offset:2048
	v_add_f32_e32 v66, 1.0, v70
	v_add_f32_e32 v67, 1.0, v71
	v_mul_f32_e32 v68, 0xbfb8aa3b, v60
	v_mul_f32_e32 v69, 0xbfb8aa3b, v61
	v_rcp_f32_e32 v66, v66
	v_rcp_f32_e32 v67, v67
	v_exp_f32_e32 v68, v68
	v_exp_f32_e32 v69, v69
	v_pk_mul_f32 v[62:63], v[62:63], v[132:133] op_sel_hi:[1,0]
	v_pk_mul_f32 v[58:59], v[58:59], v[66:67]
	v_add_f32_e32 v66, 1.0, v68
	v_add_f32_e32 v67, 1.0, v69
	v_rcp_f32_e32 v66, v66
	v_rcp_f32_e32 v67, v67
	v_pk_mul_f32 v[58:59], v[62:63], v[58:59]
	v_pk_mul_f32 v[42:43], v[42:43], v[132:133] op_sel_hi:[1,0]
	v_cvt_pk_bf16_f32 v62, v58, v59
	v_pk_mul_f32 v[58:59], v[60:61], v[66:67]
	v_pk_mul_f32 v[60:61], v[64:65], v[132:133] op_sel_hi:[1,0]
	v_pk_mul_f32 v[44:45], v[44:45], v[132:133] op_sel_hi:[1,0]
	v_pk_mul_f32 v[58:59], v[60:61], v[58:59]
	v_pk_mul_f32 v[46:47], v[46:47], v[132:133] op_sel_hi:[1,0]
	v_cvt_pk_bf16_f32 v63, v58, v59
	v_add_u32_e32 v59, 0xb0000, v123
	v_mov_b32_e32 v58, v133
	v_pk_mul_f32 v[50:51], v[50:51], v[58:59] op_sel_hi:[1,0]
	v_add_u32_e32 v130, v59, v141
	v_mul_f32_e32 v64, 0xbfb8aa3b, v50
	v_mul_f32_e32 v65, 0xbfb8aa3b, v51
	v_exp_f32_e32 v64, v64
	v_exp_f32_e32 v65, v65
	v_lshl_add_u64 v[60:61], v[130:131], 1, s[2:3]
	v_pk_mul_f32 v[52:53], v[52:53], v[58:59] op_sel_hi:[1,0]
	ds_write_b64 v164, v[62:63] offset:4096
	v_add_f32_e32 v60, 1.0, v64
	v_add_f32_e32 v61, 1.0, v65
	v_mul_f32_e32 v62, 0xbfb8aa3b, v52
	v_mul_f32_e32 v63, 0xbfb8aa3b, v53
	v_rcp_f32_e32 v60, v60
	v_rcp_f32_e32 v61, v61
	v_exp_f32_e32 v62, v62
	v_exp_f32_e32 v63, v63
	v_pk_mul_f32 v[54:55], v[54:55], v[58:59] op_sel_hi:[1,0]
	v_pk_mul_f32 v[50:51], v[50:51], v[60:61]
	v_add_f32_e32 v60, 1.0, v62
	v_add_f32_e32 v61, 1.0, v63
	v_rcp_f32_e32 v60, v60
	v_rcp_f32_e32 v61, v61
	v_pk_mul_f32 v[50:51], v[54:55], v[50:51]
	v_pk_mul_f32 v[54:55], v[56:57], v[58:59] op_sel_hi:[1,0]
	v_mul_f32_e32 v56, 0xbfb8aa3b, v43
	v_pk_mul_f32 v[52:53], v[52:53], v[60:61]
	v_exp_f32_e32 v56, v56
	v_pk_mul_f32 v[52:53], v[54:55], v[52:53]
	v_mul_f32_e32 v55, 0xbfb8aa3b, v42
	v_exp_f32_e32 v55, v55
	v_add_u32_e32 v54, 0xc6000, v123
	v_add_u32_e32 v130, v54, v141
	v_cvt_pk_bf16_f32 v50, v50, v51
	v_cvt_pk_bf16_f32 v51, v52, v53
	v_lshl_add_u64 v[52:53], v[130:131], 1, s[2:3]
	ds_write_b64 v164, v[50:51] offset:6144
	v_add_f32_e32 v50, 1.0, v55
	v_add_f32_e32 v51, 1.0, v56
	v_mul_f32_e32 v52, 0xbfb8aa3b, v44
	v_mul_f32_e32 v53, 0xbfb8aa3b, v45
	v_rcp_f32_e32 v50, v50
	v_rcp_f32_e32 v51, v51
	v_exp_f32_e32 v52, v52
	v_exp_f32_e32 v53, v53
	v_pk_mul_f32 v[34:35], v[34:35], v[58:59] op_sel_hi:[1,0]
	v_pk_mul_f32 v[42:43], v[42:43], v[50:51]
	v_add_f32_e32 v50, 1.0, v52
	v_add_f32_e32 v51, 1.0, v53
	v_rcp_f32_e32 v50, v50
	v_rcp_f32_e32 v51, v51
	v_pk_mul_f32 v[42:43], v[46:47], v[42:43]
	v_pk_mul_f32 v[46:47], v[48:49], v[132:133] op_sel_hi:[1,0]
	v_add_u32_e32 v130, v116, v59
	v_pk_mul_f32 v[44:45], v[44:45], v[50:51]
	v_cvt_pk_bf16_f32 v42, v42, v43
	v_pk_mul_f32 v[44:45], v[46:47], v[44:45]
	v_mul_f32_e32 v46, 0xbfb8aa3b, v34
	v_mul_f32_e32 v47, 0xbfb8aa3b, v35
	v_exp_f32_e32 v46, v46
	v_exp_f32_e32 v47, v47
	v_cvt_pk_bf16_f32 v43, v44, v45
	v_lshl_add_u64 v[44:45], v[130:131], 1, s[2:3]
	v_pk_mul_f32 v[36:37], v[36:37], v[58:59] op_sel_hi:[1,0]
	ds_write_b64 v165, v[42:43] offset:4096
	v_add_f32_e32 v42, 1.0, v46
	v_add_f32_e32 v43, 1.0, v47
	v_mul_f32_e32 v44, 0xbfb8aa3b, v36
	v_mul_f32_e32 v45, 0xbfb8aa3b, v37
	v_rcp_f32_e32 v42, v42
	v_rcp_f32_e32 v43, v43
	v_exp_f32_e32 v44, v44
	v_exp_f32_e32 v45, v45
	v_pk_mul_f32 v[38:39], v[38:39], v[58:59] op_sel_hi:[1,0]
	v_pk_mul_f32 v[34:35], v[34:35], v[42:43]
	v_add_f32_e32 v42, 1.0, v44
	v_add_f32_e32 v43, 1.0, v45
	v_rcp_f32_e32 v42, v42
	v_rcp_f32_e32 v43, v43
	v_pk_mul_f32 v[34:35], v[38:39], v[34:35]
	v_pk_mul_f32 v[38:39], v[40:41], v[58:59] op_sel_hi:[1,0]
	v_pk_mul_f32 v[26:27], v[26:27], v[132:133] op_sel_hi:[1,0]
	v_pk_mul_f32 v[36:37], v[36:37], v[42:43]
	v_add_u32_e32 v130, v116, v54
	v_pk_mul_f32 v[36:37], v[38:39], v[36:37]
	v_mul_f32_e32 v38, 0xbfb8aa3b, v26
	v_mul_f32_e32 v39, 0xbfb8aa3b, v27
	v_exp_f32_e32 v38, v38
	v_exp_f32_e32 v39, v39
	v_cvt_pk_bf16_f32 v34, v34, v35
	v_cvt_pk_bf16_f32 v35, v36, v37
	v_lshl_add_u64 v[36:37], v[130:131], 1, s[2:3]
	v_pk_mul_f32 v[28:29], v[28:29], v[132:133] op_sel_hi:[1,0]
	ds_write_b64 v165, v[34:35] offset:6144
	v_add_f32_e32 v34, 1.0, v38
	v_add_f32_e32 v35, 1.0, v39
	v_mul_f32_e32 v36, 0xbfb8aa3b, v28
	v_mul_f32_e32 v37, 0xbfb8aa3b, v29
	v_rcp_f32_e32 v34, v34
	v_rcp_f32_e32 v35, v35
	v_exp_f32_e32 v36, v36
; DEVI float silu(float x) { return x * __builtin_amdgcn_rcpf(1.f + __expf(-x)); }
; template <int EPI, int NRM>
; DEVI void epilogue(acc_t& acc, int pn, int trow, const EpiArgs& e, const float* rl, bf16* shmx) {
;     ...
;   } else if constexpr (EPI == EPI_SWIGLU) {
; #pragma unroll
;     for (int bj = 0; bj < 2; ++bj)
; #pragma unroll
;       for (int m = 0; m < 4; ++m)
; #pragma unroll
;         for (int n = 0; n < 2; ++n) {
;           float r[4];
; #pragma unroll
;           for (int j = 0; j < 4; ++j) r[j] = silu(acc[0][bj][m][n][j] * rs[bj][n]) * (acc[1][bj][m][n][j] * rs[bj][n]);
;           uint2 o; o.x = pack2(r[0], r[1]); o.y = pack2(r[2], r[3]);
;           const unsigned off = (unsigned)((tk0 + bj * 128 + n * 16) * DFF + pn * 128 + m * 16 + fl0);
;           *reinterpret_cast<uint2*>(e.o0 + off) = o;
;         }
	v_exp_f32_e32 v37, v37
	v_pk_mul_f32 v[30:31], v[30:31], v[132:133] op_sel_hi:[1,0]
	v_pk_mul_f32 v[26:27], v[26:27], v[34:35]
	v_add_f32_e32 v34, 1.0, v36
	v_add_f32_e32 v35, 1.0, v37
	v_rcp_f32_e32 v34, v34
	v_rcp_f32_e32 v35, v35
	v_pk_mul_f32 v[26:27], v[30:31], v[26:27]
	v_pk_mul_f32 v[30:31], v[32:33], v[132:133] op_sel_hi:[1,0]
	v_pk_mul_f32 v[18:19], v[18:19], v[58:59] op_sel_hi:[1,0]
	v_pk_mul_f32 v[28:29], v[28:29], v[34:35]
	v_add_u32_e32 v130, v100, v59
	v_pk_mul_f32 v[28:29], v[30:31], v[28:29]
	v_mul_f32_e32 v30, 0xbfb8aa3b, v18
	v_mul_f32_e32 v31, 0xbfb8aa3b, v19
	v_exp_f32_e32 v30, v30
	v_exp_f32_e32 v31, v31
	v_cvt_pk_bf16_f32 v26, v26, v27
	v_cvt_pk_bf16_f32 v27, v28, v29
	v_lshl_add_u64 v[28:29], v[130:131], 1, s[2:3]
	v_pk_mul_f32 v[20:21], v[20:21], v[58:59] op_sel_hi:[1,0]
	ds_write_b64 v166, v[26:27] offset:4096
	v_add_f32_e32 v26, 1.0, v30
	v_add_f32_e32 v27, 1.0, v31
	v_mul_f32_e32 v28, 0xbfb8aa3b, v20
	v_mul_f32_e32 v29, 0xbfb8aa3b, v21
	v_rcp_f32_e32 v26, v26
	v_rcp_f32_e32 v27, v27
	v_exp_f32_e32 v28, v28
	v_exp_f32_e32 v29, v29
	v_pk_mul_f32 v[22:23], v[22:23], v[58:59] op_sel_hi:[1,0]
	v_pk_mul_f32 v[18:19], v[18:19], v[26:27]
	v_add_f32_e32 v26, 1.0, v28
	v_add_f32_e32 v27, 1.0, v29
	v_rcp_f32_e32 v26, v26
	v_rcp_f32_e32 v27, v27
	v_pk_mul_f32 v[18:19], v[22:23], v[18:19]
	v_pk_mul_f32 v[22:23], v[24:25], v[58:59] op_sel_hi:[1,0]
	v_pk_mul_f32 v[10:11], v[10:11], v[132:133] op_sel_hi:[1,0]
	v_pk_mul_f32 v[20:21], v[20:21], v[26:27]
	v_add_u32_e32 v130, v100, v54
	v_pk_mul_f32 v[20:21], v[22:23], v[20:21]
	v_mul_f32_e32 v22, 0xbfb8aa3b, v10
	v_mul_f32_e32 v23, 0xbfb8aa3b, v11
	v_exp_f32_e32 v22, v22
	v_exp_f32_e32 v23, v23
	v_cvt_pk_bf16_f32 v18, v18, v19
	v_cvt_pk_bf16_f32 v19, v20, v21
	v_lshl_add_u64 v[20:21], v[130:131], 1, s[2:3]
	v_pk_mul_f32 v[12:13], v[12:13], v[132:133] op_sel_hi:[1,0]
	ds_write_b64 v166, v[18:19] offset:6144
	v_add_f32_e32 v18, 1.0, v22
	v_add_f32_e32 v19, 1.0, v23
	v_mul_f32_e32 v20, 0xbfb8aa3b, v12
	v_mul_f32_e32 v21, 0xbfb8aa3b, v13
	v_rcp_f32_e32 v18, v18
	v_rcp_f32_e32 v19, v19
	v_exp_f32_e32 v20, v20
	v_exp_f32_e32 v21, v21
	v_pk_mul_f32 v[14:15], v[14:15], v[132:133] op_sel_hi:[1,0]
	v_pk_mul_f32 v[10:11], v[10:11], v[18:19]
	v_add_f32_e32 v18, 1.0, v20
	v_add_f32_e32 v19, 1.0, v21
	v_rcp_f32_e32 v18, v18
	v_rcp_f32_e32 v19, v19
	v_pk_mul_f32 v[10:11], v[14:15], v[10:11]
	v_pk_mul_f32 v[14:15], v[16:17], v[132:133] op_sel_hi:[1,0]
	v_pk_mul_f32 v[2:3], v[2:3], v[58:59] op_sel_hi:[1,0]
	v_pk_mul_f32 v[12:13], v[12:13], v[18:19]
	v_add_u32_e32 v130, v84, v59
	v_pk_mul_f32 v[12:13], v[14:15], v[12:13]
	v_mul_f32_e32 v14, 0xbfb8aa3b, v2
	v_mul_f32_e32 v15, 0xbfb8aa3b, v3
	v_exp_f32_e32 v14, v14
	v_exp_f32_e32 v15, v15
	v_cvt_pk_bf16_f32 v10, v10, v11
	v_cvt_pk_bf16_f32 v11, v12, v13
	v_lshl_add_u64 v[12:13], v[130:131], 1, s[2:3]
	v_pk_mul_f32 v[4:5], v[4:5], v[58:59] op_sel_hi:[1,0]
	ds_write_b64 v167, v[10:11] offset:4096
	v_add_f32_e32 v10, 1.0, v14
	v_add_f32_e32 v11, 1.0, v15
	v_mul_f32_e32 v12, 0xbfb8aa3b, v4
	v_mul_f32_e32 v13, 0xbfb8aa3b, v5
	v_rcp_f32_e32 v10, v10
	v_rcp_f32_e32 v11, v11
	v_exp_f32_e32 v12, v12
	v_exp_f32_e32 v13, v13
	v_pk_mul_f32 v[6:7], v[6:7], v[58:59] op_sel_hi:[1,0]
	v_pk_mul_f32 v[2:3], v[2:3], v[10:11]
	v_add_f32_e32 v10, 1.0, v12
	v_add_f32_e32 v11, 1.0, v13
	v_rcp_f32_e32 v10, v10
	v_rcp_f32_e32 v11, v11
	v_pk_mul_f32 v[2:3], v[6:7], v[2:3]
	v_pk_mul_f32 v[6:7], v[8:9], v[58:59] op_sel_hi:[1,0]
	v_add_u32_e32 v130, v84, v54
	v_pk_mul_f32 v[4:5], v[4:5], v[10:11]
	v_cvt_pk_bf16_f32 v2, v2, v3
	v_pk_mul_f32 v[4:5], v[6:7], v[4:5]
	s_add_i32 s16, s16, 1
	v_cvt_pk_bf16_f32 v3, v4, v5
	v_lshl_add_u64 v[4:5], v[130:131], 1, s[2:3]
	s_andn2_b64 vcc, exec, s[4:5]
	s_mov_b32 s14, s8
	s_mov_b32 s12, s10
	ds_write_b64 v167, v[2:3] offset:6144
	s_waitcnt lgkmcnt(0)
	ds_read_b128 v[172:175], v168
	ds_read_b128 v[176:179], v168 offset:1024
	ds_read_b128 v[180:183], v168 offset:2048
	ds_read_b128 v[184:187], v168 offset:3072
	ds_read_b128 v[188:191], v168 offset:4096
	ds_read_b128 v[192:195], v168 offset:5120
	ds_read_b128 v[196:199], v168 offset:6144
	ds_read_b128 v[200:203], v168 offset:7168
	v_add_u32_e32 v204, 0x16000, v169
	v_add_u32_e32 v205, 0x2c000, v169
	v_add_u32_e32 v206, 0x42000, v169
	v_add_u32_e32 v207, 0x160000, v169
	v_add_u32_e32 v208, 0x176000, v169
	v_add_u32_e32 v209, 0x18c000, v169
	v_add_u32_e32 v210, 0x1a2000, v169
	s_waitcnt lgkmcnt(7)
	global_store_dwordx4 v169, v[172:175], s[2:3] nt
	s_waitcnt lgkmcnt(6)
	global_store_dwordx4 v204, v[176:179], s[2:3] nt
	s_waitcnt lgkmcnt(5)
	global_store_dwordx4 v205, v[180:183], s[2:3] nt
	s_waitcnt lgkmcnt(4)
	global_store_dwordx4 v206, v[184:187], s[2:3] nt
	s_waitcnt lgkmcnt(3)
	global_store_dwordx4 v207, v[188:191], s[2:3] nt
	s_waitcnt lgkmcnt(2)
	global_store_dwordx4 v208, v[192:195], s[2:3] nt
	s_waitcnt lgkmcnt(1)
	global_store_dwordx4 v209, v[196:199], s[2:3] nt
	s_waitcnt lgkmcnt(0)
	global_store_dwordx4 v210, v[200:203], s[2:3] nt
	s_cbranch_vccz .LBB0_1237

; template <int EPI, int NRM>
; DEVI void epilogue(acc_t& acc, int pn, int trow, const EpiArgs& e, const float* rl, bf16* shmx) {
;     ...
;   if constexpr (EPI == EPI_RESID) {
;     float ss[2][2] = {{0.f, 0.f}, {0.f, 0.f}};
;     __amdgpu_buffer_rsrc_t rsX = __builtin_amdgcn_make_buffer_rsrc((void*)e.xin, 0, 0x7fffffff, 0x00020000);
;     char* lbase = reinterpret_cast<char*>(shmx) + wid * 16384;
;     const int vx = ((tk0 * DM) + pn * 256 + fl0) * 4;
; #pragma unroll
;     for (int ai = 0; ai < 2; ++ai) {
; #pragma unroll
;       for (int bj = 0; bj < 2; ++bj)
; #pragma unroll
;         for (int m = 0; m < 4; ++m)
; #pragma unroll
;           for (int n = 0; n < 2; ++n) {
;             const int idx = (bj * 4 + m) * 2 + n;
;             const int so = ((bj * 128 + n * 16) * DM + ai * 128 + m * 16) * 4;
;             __builtin_amdgcn_raw_ptr_buffer_load_lds(rsX, (__attribute__((address_space(3))) unsigned*)(lbase + idx * 1024 + lane * 16), 16, vx, so, 0, 0);
;           }
;       asm volatile("s_waitcnt vmcnt(0)" ::: "memory");
; #pragma unroll
;       for (int bj = 0; bj < 2; ++bj)
; #pragma unroll
;         for (int m = 0; m < 4; ++m)
; #pragma unroll
;           for (int n = 0; n < 2; ++n) {
;             const int idx = (bj * 4 + m) * 2 + n;
;             const unsigned off = (unsigned)((tk0 + bj * 128 + n * 16) * DM + pn * 256 + ai * 128 + m * 16 + fl0);
;             const float4 xx = *reinterpret_cast<const float4*>(lbase + idx * 1024 + lane * 16);
;             float4 o;
;             o.x = xx.x + acc[ai][bj][m][n][0]; o.y = xx.y + acc[ai][bj][m][n][1];
;             o.z = xx.z + acc[ai][bj][m][n][2]; o.w = xx.w + acc[ai][bj][m][n][3];
;             *reinterpret_cast<float4*>(e.xout + off) = o;
;             uint2 ob; ob.x = pack2(o.x, o.y); ob.y = pack2(o.z, o.w);
;             *reinterpret_cast<uint2*>(e.o0 + off) = ob;
;             ss[bj][n] += o.x * o.x + o.y * o.y + o.z * o.z + o.w * o.w;
;           }
.LBB0_1279:
	v_and_b32_e32 v138, 15, v134
	v_bfe_u32 v198, v134, 4, 2
	v_lshrrev_b32_e32 v199, 6, v134
	v_and_b32_e32 v200, 3, v199
	v_lshrrev_b32_e32 v201, 2, v199
	v_lshlrev_b32_e32 v202, 14, v199
	v_and_b32_e32 v203, 63, v134
	v_lshl_add_u32 v143, v203, 4, v202
	v_lshl_add_u32 v202, v138, 8, v202
	v_and_b32_e32 v203, 7, v138
	v_add_u32_e32 v204, 0, v198
	v_xor_b32_e32 v204, v204, v203
	v_lshl_add_u32 v139, v204, 4, v202
	v_add_u32_e32 v204, 4, v198
	v_xor_b32_e32 v204, v204, v203
	v_lshl_add_u32 v140, v204, 4, v202
	v_add_u32_e32 v204, 8, v198
	v_xor_b32_e32 v204, v204, v203
	v_lshl_add_u32 v141, v204, 4, v202
	v_add_u32_e32 v204, 12, v198
	v_xor_b32_e32 v204, v204, v203
	v_lshl_add_u32 v142, v204, 4, v202
	s_lshl_b32 s6, s39, 8
	v_lshl_add_u32 v202, v200, 5, v198
	v_add_u32_e32 v202, s6, v202
	s_lshl_b32 s6, s38, 1
	v_add_u32_e32 v204, s6, v201
	v_lshl_add_u32 v204, v204, 15, v202
	v_lshlrev_b32_e32 v148, 2, v204
	v_lshlrev_b32_e32 v202, 11, v202
	s_lshl_b32 s6, s38, 8
	v_lshl_add_u32 v204, v201, 6, s6
	v_add_u32_e32 v202, v202, v204
	v_add_u32_e32 v203, 0, v198
	v_xor_b32_e32 v203, v203, v138
	v_lshl_add_u32 v203, v203, 2, v202
	v_lshlrev_b32_e32 v144, 2, v203
	v_lshlrev_b32_e32 v146, 1, v203
	v_add_u32_e32 v203, 4, v198
	v_xor_b32_e32 v203, v203, v138
	v_lshl_add_u32 v203, v203, 2, v202
	v_lshlrev_b32_e32 v145, 2, v203
	v_lshlrev_b32_e32 v147, 1, v203
	v_add_u32_e32 v157, 0x0, v144
	global_load_dwordx4 v[166:169], v157, s[4:5] nt
	v_add_u32_e32 v160, 0x8000, v145
	global_load_dwordx4 v[170:173], v160, s[4:5] nt
	v_add_u32_e32 v157, 0x10000, v144
	global_load_dwordx4 v[174:177], v157, s[4:5] nt
	v_add_u32_e32 v160, 0x18000, v145
	global_load_dwordx4 v[178:181], v160, s[4:5] nt
	v_add_u32_e32 v157, 0x20000, v144
	global_load_dwordx4 v[182:185], v157, s[4:5] nt
	v_add_u32_e32 v160, 0x28000, v145
	global_load_dwordx4 v[186:189], v160, s[4:5] nt
	v_add_u32_e32 v157, 0x30000, v144
	global_load_dwordx4 v[190:193], v157, s[4:5] nt
	v_add_u32_e32 v160, 0x38000, v145
	global_load_dwordx4 v[194:197], v160, s[4:5] nt
	v_add_u32_e32 v157, 0x200, v144
	global_load_dwordx4 v[198:201], v157, s[4:5] nt
	v_add_u32_e32 v160, 0x8200, v145
	global_load_dwordx4 v[202:205], v160, s[4:5] nt
	v_add_u32_e32 v157, 0x10200, v144
	global_load_dwordx4 v[206:209], v157, s[4:5] nt
	v_add_u32_e32 v160, 0x18200, v145
	global_load_dwordx4 v[210:213], v160, s[4:5] nt
	v_add_u32_e32 v157, 0x20200, v144
	global_load_dwordx4 v[214:217], v157, s[4:5] nt
	v_add_u32_e32 v160, 0x28200, v145
	global_load_dwordx4 v[218:221], v160, s[4:5] nt
	v_add_u32_e32 v157, 0x30200, v144
	global_load_dwordx4 v[222:225], v157, s[4:5] nt
	v_add_u32_e32 v160, 0x38200, v145
	global_load_dwordx4 v[226:229], v160, s[4:5] nt
	ds_write_b128 v139, v[126:129]
	ds_write_b128 v139, v[14:17] offset:4096
	ds_write_b128 v140, v[122:125]
	ds_write_b128 v140, v[30:33] offset:4096
	ds_write_b128 v141, v[118:121]
	ds_write_b128 v141, v[46:49] offset:4096
	ds_write_b128 v142, v[114:117]
	ds_write_b128 v142, v[54:57] offset:4096
	ds_write_b128 v139, v[110:113] offset:8192
	ds_write_b128 v139, v[106:109] offset:12288
	ds_write_b128 v140, v[102:105] offset:8192
	ds_write_b128 v140, v[90:93] offset:12288
	ds_write_b128 v141, v[86:89] offset:8192
	ds_write_b128 v141, v[74:77] offset:12288
	ds_write_b128 v142, v[70:73] offset:8192
	ds_write_b128 v142, v[42:45] offset:12288
	s_waitcnt lgkmcnt(0)
	ds_read_b128 v[126:129], v143
	ds_read_b128 v[14:17], v143 offset:1024
	ds_read_b128 v[122:125], v143 offset:2048
	ds_read_b128 v[30:33], v143 offset:3072
	ds_read_b128 v[118:121], v143 offset:4096
	ds_read_b128 v[46:49], v143 offset:5120
	ds_read_b128 v[114:117], v143 offset:6144
	ds_read_b128 v[54:57], v143 offset:7168
	ds_read_b128 v[110:113], v143 offset:8192
	ds_read_b128 v[106:109], v143 offset:9216
	ds_read_b128 v[102:105], v143 offset:10240
	ds_read_b128 v[90:93], v143 offset:11264
	ds_read_b128 v[86:89], v143 offset:12288
	ds_read_b128 v[74:77], v143 offset:13312
	ds_read_b128 v[70:73], v143 offset:14336
	ds_read_b128 v[42:45], v143 offset:15360
	s_waitcnt lgkmcnt(0)
	ds_write_b128 v139, v[50:53]
	ds_write_b128 v139, v[58:61] offset:4096
	ds_write_b128 v140, v[62:65]
	ds_write_b128 v140, v[66:69] offset:4096
	ds_write_b128 v141, v[78:81]
	ds_write_b128 v141, v[82:85] offset:4096
	ds_write_b128 v142, v[94:97]
	ds_write_b128 v142, v[98:101] offset:4096
	ds_write_b128 v139, v[38:41] offset:8192
	ds_write_b128 v139, v[34:37] offset:12288
	ds_write_b128 v140, v[26:29] offset:8192
	ds_write_b128 v140, v[22:25] offset:12288
	ds_write_b128 v141, v[18:21] offset:8192
	ds_write_b128 v141, v[10:13] offset:12288
	ds_write_b128 v142, v[6:9] offset:8192
	ds_write_b128 v142, v[2:5] offset:12288
	s_waitcnt vmcnt(15)
	v_pk_add_f32 v[166:167], v[166:167], v[126:127]
	v_pk_add_f32 v[168:169], v[168:169], v[128:129]
	v_add_u32_e32 v157, 0x0, v144
	v_cvt_pk_bf16_f32 v158, v166, v167
	v_cvt_pk_bf16_f32 v159, v168, v169
	global_store_dwordx4 v157, v[166:169], s[26:27] nt
	v_add_u32_e32 v126, 0x0, v146
	v_mul_f32_e32 v149, v166, v166
	global_store_dwordx2 v126, v[158:159], s[96:97]
	v_fmac_f32_e32 v149, v167, v167
	v_fmac_f32_e32 v149, v168, v168
	v_fmac_f32_e32 v149, v169, v169
	s_waitcnt vmcnt(16)
	v_pk_add_f32 v[170:171], v[170:171], v[14:15]
	v_pk_add_f32 v[172:173], v[172:173], v[16:17]
	v_add_u32_e32 v160, 0x8000, v145
	v_cvt_pk_bf16_f32 v164, v170, v171
	v_cvt_pk_bf16_f32 v165, v172, v173
	global_store_dwordx4 v160, v[170:173], s[26:27] nt
	v_add_u32_e32 v14, 0x4000, v147
	v_mul_f32_e32 v150, v170, v170
	global_store_dwordx2 v14, v[164:165], s[96:97]
	v_fmac_f32_e32 v150, v171, v171
	v_fmac_f32_e32 v150, v172, v172
	v_fmac_f32_e32 v150, v173, v173
	s_waitcnt vmcnt(17)
; template <int EPI, int NRM>
; DEVI void epilogue(acc_t& acc, int pn, int trow, const EpiArgs& e, const float* rl, bf16* shmx) {
;     ...
;       for (int bj = 0; bj < 2; ++bj)
; #pragma unroll
;         for (int m = 0; m < 4; ++m)
; #pragma unroll
;           for (int n = 0; n < 2; ++n) {
;             const int idx = (bj * 4 + m) * 2 + n;
;             const unsigned off = (unsigned)((tk0 + bj * 128 + n * 16) * DM + pn * 256 + ai * 128 + m * 16 + fl0);
;             const float4 xx = *reinterpret_cast<const float4*>(lbase + idx * 1024 + lane * 16);
;             float4 o;
;             o.x = xx.x + acc[ai][bj][m][n][0]; o.y = xx.y + acc[ai][bj][m][n][1];
;             o.z = xx.z + acc[ai][bj][m][n][2]; o.w = xx.w + acc[ai][bj][m][n][3];
;             *reinterpret_cast<float4*>(e.xout + off) = o;
;             uint2 ob; ob.x = pack2(o.x, o.y); ob.y = pack2(o.z, o.w);
;             *reinterpret_cast<uint2*>(e.o0 + off) = ob;
;             ss[bj][n] += o.x * o.x + o.y * o.y + o.z * o.z + o.w * o.w;
;           }
	v_pk_add_f32 v[174:175], v[174:175], v[122:123]
	v_pk_add_f32 v[176:177], v[176:177], v[124:125]
	v_add_u32_e32 v157, 0x10000, v144
	v_cvt_pk_bf16_f32 v158, v174, v175
	v_cvt_pk_bf16_f32 v159, v176, v177
	global_store_dwordx4 v157, v[174:177], s[26:27] nt
	v_add_u32_e32 v122, 0x8000, v146
	v_mul_f32_e32 v151, v174, v174
	global_store_dwordx2 v122, v[158:159], s[96:97]
	v_fmac_f32_e32 v151, v175, v175
	v_fmac_f32_e32 v151, v176, v176
	v_fmac_f32_e32 v151, v177, v177
	s_waitcnt vmcnt(18)
	v_pk_add_f32 v[178:179], v[178:179], v[30:31]
	v_pk_add_f32 v[180:181], v[180:181], v[32:33]
	v_add_u32_e32 v160, 0x18000, v145
	v_cvt_pk_bf16_f32 v164, v178, v179
	v_cvt_pk_bf16_f32 v165, v180, v181
	global_store_dwordx4 v160, v[178:181], s[26:27] nt
	v_add_u32_e32 v30, 0xc000, v147
	v_mul_f32_e32 v152, v178, v178
	global_store_dwordx2 v30, v[164:165], s[96:97]
	v_fmac_f32_e32 v152, v179, v179
	v_fmac_f32_e32 v152, v180, v180
	v_fmac_f32_e32 v152, v181, v181
	s_waitcnt vmcnt(19)
	v_pk_add_f32 v[182:183], v[182:183], v[118:119]
	v_pk_add_f32 v[184:185], v[184:185], v[120:121]
	v_add_u32_e32 v157, 0x20000, v144
	v_cvt_pk_bf16_f32 v158, v182, v183
	v_cvt_pk_bf16_f32 v159, v184, v185
	global_store_dwordx4 v157, v[182:185], s[26:27] nt
	v_add_u32_e32 v118, 0x10000, v146
	v_mul_f32_e32 v153, v182, v182
	global_store_dwordx2 v118, v[158:159], s[96:97]
	v_fmac_f32_e32 v153, v183, v183
	v_fmac_f32_e32 v153, v184, v184
	v_fmac_f32_e32 v153, v185, v185
	s_waitcnt vmcnt(20)
	v_pk_add_f32 v[186:187], v[186:187], v[46:47]
	v_pk_add_f32 v[188:189], v[188:189], v[48:49]
	v_add_u32_e32 v160, 0x28000, v145
	v_cvt_pk_bf16_f32 v164, v186, v187
	v_cvt_pk_bf16_f32 v165, v188, v189
	global_store_dwordx4 v160, v[186:189], s[26:27] nt
	v_add_u32_e32 v46, 0x14000, v147
	v_mul_f32_e32 v154, v186, v186
	global_store_dwordx2 v46, v[164:165], s[96:97]
	v_fmac_f32_e32 v154, v187, v187
	v_fmac_f32_e32 v154, v188, v188
	v_fmac_f32_e32 v154, v189, v189
	s_waitcnt vmcnt(21)
	v_pk_add_f32 v[190:191], v[190:191], v[114:115]
	v_pk_add_f32 v[192:193], v[192:193], v[116:117]
	v_add_u32_e32 v157, 0x30000, v144
	v_cvt_pk_bf16_f32 v158, v190, v191
	v_cvt_pk_bf16_f32 v159, v192, v193
	global_store_dwordx4 v157, v[190:193], s[26:27] nt
	v_add_u32_e32 v114, 0x18000, v146
	v_mul_f32_e32 v155, v190, v190
	global_store_dwordx2 v114, v[158:159], s[96:97]
	v_fmac_f32_e32 v155, v191, v191
	v_fmac_f32_e32 v155, v192, v192
	v_fmac_f32_e32 v155, v193, v193
	s_waitcnt vmcnt(22)
	v_pk_add_f32 v[194:195], v[194:195], v[54:55]
	v_pk_add_f32 v[196:197], v[196:197], v[56:57]
	v_add_u32_e32 v160, 0x38000, v145
	v_cvt_pk_bf16_f32 v164, v194, v195
	v_cvt_pk_bf16_f32 v165, v196, v197
	global_store_dwordx4 v160, v[194:197], s[26:27] nt
	v_add_u32_e32 v54, 0x1c000, v147
	v_mul_f32_e32 v156, v194, v194
	global_store_dwordx2 v54, v[164:165], s[96:97]
	v_fmac_f32_e32 v156, v195, v195
	v_fmac_f32_e32 v156, v196, v196
	v_fmac_f32_e32 v156, v197, v197
	v_add_u32_e32 v157, 0x100000, v144
	global_load_dwordx4 v[166:169], v157, s[4:5] nt
	v_add_u32_e32 v160, 0x108000, v145
	global_load_dwordx4 v[170:173], v160, s[4:5] nt
	v_add_u32_e32 v157, 0x110000, v144
	global_load_dwordx4 v[174:177], v157, s[4:5] nt
	v_add_u32_e32 v160, 0x118000, v145
	global_load_dwordx4 v[178:181], v160, s[4:5] nt
	v_add_u32_e32 v157, 0x120000, v144
	global_load_dwordx4 v[182:185], v157, s[4:5] nt
	v_add_u32_e32 v160, 0x128000, v145
	global_load_dwordx4 v[186:189], v160, s[4:5] nt
	v_add_u32_e32 v157, 0x130000, v144
	global_load_dwordx4 v[190:193], v157, s[4:5] nt
	v_add_u32_e32 v160, 0x138000, v145
	global_load_dwordx4 v[194:197], v160, s[4:5] nt
	s_waitcnt vmcnt(31)
	v_pk_add_f32 v[198:199], v[198:199], v[110:111]
	v_pk_add_f32 v[200:201], v[200:201], v[112:113]
	v_add_u32_e32 v157, 0x200, v144
	v_cvt_pk_bf16_f32 v158, v198, v199
	v_cvt_pk_bf16_f32 v159, v200, v201
	global_store_dwordx4 v157, v[198:201], s[26:27] nt
	v_add_u32_e32 v110, 0x100, v146
	v_fmac_f32_e32 v149, v198, v198
	global_store_dwordx2 v110, v[158:159], s[96:97]
	v_fmac_f32_e32 v149, v199, v199
	v_fmac_f32_e32 v149, v200, v200
	v_fmac_f32_e32 v149, v201, v201
	s_waitcnt vmcnt(32)
	v_pk_add_f32 v[202:203], v[202:203], v[106:107]
	v_pk_add_f32 v[204:205], v[204:205], v[108:109]
	v_add_u32_e32 v160, 0x8200, v145
	v_cvt_pk_bf16_f32 v164, v202, v203
	v_cvt_pk_bf16_f32 v165, v204, v205
	global_store_dwordx4 v160, v[202:205], s[26:27] nt
	v_add_u32_e32 v106, 0x4100, v147
	v_fmac_f32_e32 v150, v202, v202
	global_store_dwordx2 v106, v[164:165], s[96:97]
	v_fmac_f32_e32 v150, v203, v203
	v_fmac_f32_e32 v150, v204, v204
	v_fmac_f32_e32 v150, v205, v205
	s_waitcnt vmcnt(33)
	v_pk_add_f32 v[206:207], v[206:207], v[102:103]
	v_pk_add_f32 v[208:209], v[208:209], v[104:105]
	v_add_u32_e32 v157, 0x10200, v144
	v_cvt_pk_bf16_f32 v158, v206, v207
	v_cvt_pk_bf16_f32 v159, v208, v209
	global_store_dwordx4 v157, v[206:209], s[26:27] nt
	v_add_u32_e32 v102, 0x8100, v146
	v_fmac_f32_e32 v151, v206, v206
	global_store_dwordx2 v102, v[158:159], s[96:97]
	v_fmac_f32_e32 v151, v207, v207
	v_fmac_f32_e32 v151, v208, v208
	v_fmac_f32_e32 v151, v209, v209
	s_waitcnt vmcnt(34)
	v_pk_add_f32 v[210:211], v[210:211], v[90:91]
	v_pk_add_f32 v[212:213], v[212:213], v[92:93]
	v_add_u32_e32 v160, 0x18200, v145
	v_cvt_pk_bf16_f32 v164, v210, v211
	v_cvt_pk_bf16_f32 v165, v212, v213
	global_store_dwordx4 v160, v[210:213], s[26:27] nt
	v_add_u32_e32 v90, 0xc100, v147
	v_fmac_f32_e32 v152, v210, v210
	global_store_dwordx2 v90, v[164:165], s[96:97]
	v_fmac_f32_e32 v152, v211, v211
	v_fmac_f32_e32 v152, v212, v212
	v_fmac_f32_e32 v152, v213, v213
	s_waitcnt vmcnt(35)
; template <int EPI, int NRM>
; DEVI void epilogue(acc_t& acc, int pn, int trow, const EpiArgs& e, const float* rl, bf16* shmx) {
;     ...
;       for (int bj = 0; bj < 2; ++bj)
; #pragma unroll
;         for (int m = 0; m < 4; ++m)
; #pragma unroll
;           for (int n = 0; n < 2; ++n) {
;             const int idx = (bj * 4 + m) * 2 + n;
;             const unsigned off = (unsigned)((tk0 + bj * 128 + n * 16) * DM + pn * 256 + ai * 128 + m * 16 + fl0);
;             const float4 xx = *reinterpret_cast<const float4*>(lbase + idx * 1024 + lane * 16);
;             float4 o;
;             o.x = xx.x + acc[ai][bj][m][n][0]; o.y = xx.y + acc[ai][bj][m][n][1];
;             o.z = xx.z + acc[ai][bj][m][n][2]; o.w = xx.w + acc[ai][bj][m][n][3];
;             *reinterpret_cast<float4*>(e.xout + off) = o;
;             uint2 ob; ob.x = pack2(o.x, o.y); ob.y = pack2(o.z, o.w);
;             *reinterpret_cast<uint2*>(e.o0 + off) = ob;
;             ss[bj][n] += o.x * o.x + o.y * o.y + o.z * o.z + o.w * o.w;
;           }
;       asm volatile("s_waitcnt lgkmcnt(0)" ::: "memory");
;     }
; #pragma unroll
;     for (int bj = 0; bj < 2; ++bj)
; #pragma unroll
;       for (int n = 0; n < 2; ++n) {
;         float v = ss[bj][n];
;         v += __shfl_xor(v, 16); v += __shfl_xor(v, 32);
;         if (fq == 0) e.stw[(pn * 2 + wr) * TOK + tk0 + bj * 128 + n * 16] = v;
;       }
	v_pk_add_f32 v[214:215], v[214:215], v[86:87]
	v_pk_add_f32 v[216:217], v[216:217], v[88:89]
	v_add_u32_e32 v157, 0x20200, v144
	v_cvt_pk_bf16_f32 v158, v214, v215
	v_cvt_pk_bf16_f32 v159, v216, v217
	global_store_dwordx4 v157, v[214:217], s[26:27] nt
	v_add_u32_e32 v86, 0x10100, v146
	v_fmac_f32_e32 v153, v214, v214
	global_store_dwordx2 v86, v[158:159], s[96:97]
	v_fmac_f32_e32 v153, v215, v215
	v_fmac_f32_e32 v153, v216, v216
	v_fmac_f32_e32 v153, v217, v217
	s_waitcnt vmcnt(36)
	v_pk_add_f32 v[218:219], v[218:219], v[74:75]
	v_pk_add_f32 v[220:221], v[220:221], v[76:77]
	v_add_u32_e32 v160, 0x28200, v145
	v_cvt_pk_bf16_f32 v164, v218, v219
	v_cvt_pk_bf16_f32 v165, v220, v221
	global_store_dwordx4 v160, v[218:221], s[26:27] nt
	v_add_u32_e32 v74, 0x14100, v147
	v_fmac_f32_e32 v154, v218, v218
	global_store_dwordx2 v74, v[164:165], s[96:97]
	v_fmac_f32_e32 v154, v219, v219
	v_fmac_f32_e32 v154, v220, v220
	v_fmac_f32_e32 v154, v221, v221
	s_waitcnt vmcnt(37)
	v_pk_add_f32 v[222:223], v[222:223], v[70:71]
	v_pk_add_f32 v[224:225], v[224:225], v[72:73]
	v_add_u32_e32 v157, 0x30200, v144
	v_cvt_pk_bf16_f32 v158, v222, v223
	v_cvt_pk_bf16_f32 v159, v224, v225
	global_store_dwordx4 v157, v[222:225], s[26:27] nt
	v_add_u32_e32 v70, 0x18100, v146
	v_fmac_f32_e32 v155, v222, v222
	global_store_dwordx2 v70, v[158:159], s[96:97]
	v_fmac_f32_e32 v155, v223, v223
	v_fmac_f32_e32 v155, v224, v224
	v_fmac_f32_e32 v155, v225, v225
	s_waitcnt vmcnt(38)
	v_pk_add_f32 v[226:227], v[226:227], v[42:43]
	v_pk_add_f32 v[228:229], v[228:229], v[44:45]
	v_add_u32_e32 v160, 0x38200, v145
	v_cvt_pk_bf16_f32 v164, v226, v227
	v_cvt_pk_bf16_f32 v165, v228, v229
	global_store_dwordx4 v160, v[226:229], s[26:27] nt
	v_add_u32_e32 v42, 0x1c100, v147
	v_fmac_f32_e32 v156, v226, v226
	global_store_dwordx2 v42, v[164:165], s[96:97]
	v_fmac_f32_e32 v156, v227, v227
	v_fmac_f32_e32 v156, v228, v228
	v_fmac_f32_e32 v156, v229, v229
	v_add_u32_e32 v157, 0x100200, v144
	global_load_dwordx4 v[198:201], v157, s[4:5] nt
	v_add_u32_e32 v160, 0x108200, v145
	global_load_dwordx4 v[202:205], v160, s[4:5] nt
	v_add_u32_e32 v157, 0x110200, v144
	global_load_dwordx4 v[206:209], v157, s[4:5] nt
	v_add_u32_e32 v160, 0x118200, v145
	global_load_dwordx4 v[210:213], v160, s[4:5] nt
	v_add_u32_e32 v157, 0x120200, v144
	global_load_dwordx4 v[214:217], v157, s[4:5] nt
	v_add_u32_e32 v160, 0x128200, v145
	global_load_dwordx4 v[218:221], v160, s[4:5] nt
	v_add_u32_e32 v157, 0x130200, v144
	global_load_dwordx4 v[222:225], v157, s[4:5] nt
	v_add_u32_e32 v160, 0x138200, v145
	global_load_dwordx4 v[226:229], v160, s[4:5] nt
	v_add_f32_dpp v149, v149, v149 row_shr:1 row_mask:0xf bank_mask:0xf bound_ctrl:0
	v_add_f32_dpp v150, v150, v150 row_shr:1 row_mask:0xf bank_mask:0xf bound_ctrl:0
	v_add_f32_dpp v151, v151, v151 row_shr:1 row_mask:0xf bank_mask:0xf bound_ctrl:0
	v_add_f32_dpp v152, v152, v152 row_shr:1 row_mask:0xf bank_mask:0xf bound_ctrl:0
	v_add_f32_dpp v153, v153, v153 row_shr:1 row_mask:0xf bank_mask:0xf bound_ctrl:0
	v_add_f32_dpp v154, v154, v154 row_shr:1 row_mask:0xf bank_mask:0xf bound_ctrl:0
	v_add_f32_dpp v155, v155, v155 row_shr:1 row_mask:0xf bank_mask:0xf bound_ctrl:0
	v_add_f32_dpp v156, v156, v156 row_shr:1 row_mask:0xf bank_mask:0xf bound_ctrl:0
	v_add_f32_dpp v149, v149, v149 row_shr:2 row_mask:0xf bank_mask:0xf bound_ctrl:0
	v_add_f32_dpp v150, v150, v150 row_shr:2 row_mask:0xf bank_mask:0xf bound_ctrl:0
	v_add_f32_dpp v151, v151, v151 row_shr:2 row_mask:0xf bank_mask:0xf bound_ctrl:0
	v_add_f32_dpp v152, v152, v152 row_shr:2 row_mask:0xf bank_mask:0xf bound_ctrl:0
	v_add_f32_dpp v153, v153, v153 row_shr:2 row_mask:0xf bank_mask:0xf bound_ctrl:0
	v_add_f32_dpp v154, v154, v154 row_shr:2 row_mask:0xf bank_mask:0xf bound_ctrl:0
	v_add_f32_dpp v155, v155, v155 row_shr:2 row_mask:0xf bank_mask:0xf bound_ctrl:0
	v_add_f32_dpp v156, v156, v156 row_shr:2 row_mask:0xf bank_mask:0xf bound_ctrl:0
	v_add_f32_dpp v149, v149, v149 row_shr:4 row_mask:0xf bank_mask:0xf bound_ctrl:0
	v_add_f32_dpp v150, v150, v150 row_shr:4 row_mask:0xf bank_mask:0xf bound_ctrl:0
	v_add_f32_dpp v151, v151, v151 row_shr:4 row_mask:0xf bank_mask:0xf bound_ctrl:0
	v_add_f32_dpp v152, v152, v152 row_shr:4 row_mask:0xf bank_mask:0xf bound_ctrl:0
	v_add_f32_dpp v153, v153, v153 row_shr:4 row_mask:0xf bank_mask:0xf bound_ctrl:0
	v_add_f32_dpp v154, v154, v154 row_shr:4 row_mask:0xf bank_mask:0xf bound_ctrl:0
	v_add_f32_dpp v155, v155, v155 row_shr:4 row_mask:0xf bank_mask:0xf bound_ctrl:0
	v_add_f32_dpp v156, v156, v156 row_shr:4 row_mask:0xf bank_mask:0xf bound_ctrl:0
	v_add_f32_dpp v149, v149, v149 row_shr:8 row_mask:0xf bank_mask:0xf bound_ctrl:0
	v_add_f32_dpp v150, v150, v150 row_shr:8 row_mask:0xf bank_mask:0xf bound_ctrl:0
	v_add_f32_dpp v151, v151, v151 row_shr:8 row_mask:0xf bank_mask:0xf bound_ctrl:0
	v_add_f32_dpp v152, v152, v152 row_shr:8 row_mask:0xf bank_mask:0xf bound_ctrl:0
	v_add_f32_dpp v153, v153, v153 row_shr:8 row_mask:0xf bank_mask:0xf bound_ctrl:0
	v_add_f32_dpp v154, v154, v154 row_shr:8 row_mask:0xf bank_mask:0xf bound_ctrl:0
	v_add_f32_dpp v155, v155, v155 row_shr:8 row_mask:0xf bank_mask:0xf bound_ctrl:0
	v_add_f32_dpp v156, v156, v156 row_shr:8 row_mask:0xf bank_mask:0xf bound_ctrl:0
	v_cmp_eq_u32_e32 vcc, 15, v138
	s_and_saveexec_b64 s[6:7], vcc
	global_store_dword v148, v149, s[88:89]
	global_store_dword v148, v150, s[88:89] offset:16
	global_store_dword v148, v151, s[88:89] offset:32
	global_store_dword v148, v152, s[88:89] offset:48
	global_store_dword v148, v153, s[88:89] offset:64
	global_store_dword v148, v154, s[88:89] offset:80
	global_store_dword v148, v155, s[88:89] offset:96
	global_store_dword v148, v156, s[88:89] offset:112
	s_or_b64 exec, exec, s[6:7]
	s_waitcnt lgkmcnt(0)
; template <int EPI, int NRM>
; DEVI void epilogue(acc_t& acc, int pn, int trow, const EpiArgs& e, const float* rl, bf16* shmx) {
;     ...
;       for (int bj = 0; bj < 2; ++bj)
; #pragma unroll
;         for (int m = 0; m < 4; ++m)
; #pragma unroll
;           for (int n = 0; n < 2; ++n) {
;             const int idx = (bj * 4 + m) * 2 + n;
;             const unsigned off = (unsigned)((tk0 + bj * 128 + n * 16) * DM + pn * 256 + ai * 128 + m * 16 + fl0);
;             const float4 xx = *reinterpret_cast<const float4*>(lbase + idx * 1024 + lane * 16);
;             float4 o;
;             o.x = xx.x + acc[ai][bj][m][n][0]; o.y = xx.y + acc[ai][bj][m][n][1];
;             o.z = xx.z + acc[ai][bj][m][n][2]; o.w = xx.w + acc[ai][bj][m][n][3];
;             *reinterpret_cast<float4*>(e.xout + off) = o;
;             uint2 ob; ob.x = pack2(o.x, o.y); ob.y = pack2(o.z, o.w);
;             *reinterpret_cast<uint2*>(e.o0 + off) = ob;
;             ss[bj][n] += o.x * o.x + o.y * o.y + o.z * o.z + o.w * o.w;
;           }
	ds_read_b128 v[50:53], v143
	ds_read_b128 v[58:61], v143 offset:1024
	ds_read_b128 v[62:65], v143 offset:2048
	ds_read_b128 v[66:69], v143 offset:3072
	ds_read_b128 v[78:81], v143 offset:4096
	ds_read_b128 v[82:85], v143 offset:5120
	ds_read_b128 v[94:97], v143 offset:6144
	ds_read_b128 v[98:101], v143 offset:7168
	ds_read_b128 v[38:41], v143 offset:8192
	ds_read_b128 v[34:37], v143 offset:9216
	ds_read_b128 v[26:29], v143 offset:10240
	ds_read_b128 v[22:25], v143 offset:11264
	ds_read_b128 v[18:21], v143 offset:12288
	ds_read_b128 v[10:13], v143 offset:13312
	ds_read_b128 v[6:9], v143 offset:14336
	ds_read_b128 v[2:5], v143 offset:15360
	s_waitcnt lgkmcnt(0)
	s_waitcnt vmcnt(39)
	v_pk_add_f32 v[166:167], v[166:167], v[50:51]
	v_pk_add_f32 v[168:169], v[168:169], v[52:53]
	v_add_u32_e32 v157, 0x100000, v144
	v_cvt_pk_bf16_f32 v158, v166, v167
	v_cvt_pk_bf16_f32 v159, v168, v169
	global_store_dwordx4 v157, v[166:169], s[26:27] nt
	v_add_u32_e32 v50, 0x80000, v146
	v_mul_f32_e32 v149, v166, v166
	global_store_dwordx2 v50, v[158:159], s[96:97]
	v_fmac_f32_e32 v149, v167, v167
	v_fmac_f32_e32 v149, v168, v168
	v_fmac_f32_e32 v149, v169, v169
	s_waitcnt vmcnt(40)
	v_pk_add_f32 v[170:171], v[170:171], v[58:59]
	v_pk_add_f32 v[172:173], v[172:173], v[60:61]
	v_add_u32_e32 v160, 0x108000, v145
	v_cvt_pk_bf16_f32 v164, v170, v171
	v_cvt_pk_bf16_f32 v165, v172, v173
	global_store_dwordx4 v160, v[170:173], s[26:27] nt
	v_add_u32_e32 v58, 0x84000, v147
	v_mul_f32_e32 v150, v170, v170
	global_store_dwordx2 v58, v[164:165], s[96:97]
	v_fmac_f32_e32 v150, v171, v171
	v_fmac_f32_e32 v150, v172, v172
	v_fmac_f32_e32 v150, v173, v173
	s_waitcnt vmcnt(41)
	v_pk_add_f32 v[174:175], v[174:175], v[62:63]
	v_pk_add_f32 v[176:177], v[176:177], v[64:65]
	v_add_u32_e32 v157, 0x110000, v144
	v_cvt_pk_bf16_f32 v158, v174, v175
	v_cvt_pk_bf16_f32 v159, v176, v177
	global_store_dwordx4 v157, v[174:177], s[26:27] nt
	v_add_u32_e32 v62, 0x88000, v146
	v_mul_f32_e32 v151, v174, v174
	global_store_dwordx2 v62, v[158:159], s[96:97]
	v_fmac_f32_e32 v151, v175, v175
	v_fmac_f32_e32 v151, v176, v176
	v_fmac_f32_e32 v151, v177, v177
	s_waitcnt vmcnt(42)
	v_pk_add_f32 v[178:179], v[178:179], v[66:67]
	v_pk_add_f32 v[180:181], v[180:181], v[68:69]
	v_add_u32_e32 v160, 0x118000, v145
	v_cvt_pk_bf16_f32 v164, v178, v179
	v_cvt_pk_bf16_f32 v165, v180, v181
	global_store_dwordx4 v160, v[178:181], s[26:27] nt
	v_add_u32_e32 v66, 0x8c000, v147
	v_mul_f32_e32 v152, v178, v178
	global_store_dwordx2 v66, v[164:165], s[96:97]
	v_fmac_f32_e32 v152, v179, v179
	v_fmac_f32_e32 v152, v180, v180
	v_fmac_f32_e32 v152, v181, v181
	s_waitcnt vmcnt(43)
	v_pk_add_f32 v[182:183], v[182:183], v[78:79]
	v_pk_add_f32 v[184:185], v[184:185], v[80:81]
	v_add_u32_e32 v157, 0x120000, v144
	v_cvt_pk_bf16_f32 v158, v182, v183
	v_cvt_pk_bf16_f32 v159, v184, v185
	global_store_dwordx4 v157, v[182:185], s[26:27] nt
	v_add_u32_e32 v78, 0x90000, v146
	v_mul_f32_e32 v153, v182, v182
	global_store_dwordx2 v78, v[158:159], s[96:97]
	v_fmac_f32_e32 v153, v183, v183
	v_fmac_f32_e32 v153, v184, v184
	v_fmac_f32_e32 v153, v185, v185
	s_waitcnt vmcnt(44)
	v_pk_add_f32 v[186:187], v[186:187], v[82:83]
	v_pk_add_f32 v[188:189], v[188:189], v[84:85]
	v_add_u32_e32 v160, 0x128000, v145
	v_cvt_pk_bf16_f32 v164, v186, v187
	v_cvt_pk_bf16_f32 v165, v188, v189
	global_store_dwordx4 v160, v[186:189], s[26:27] nt
	v_add_u32_e32 v82, 0x94000, v147
	v_mul_f32_e32 v154, v186, v186
	global_store_dwordx2 v82, v[164:165], s[96:97]
	v_fmac_f32_e32 v154, v187, v187
	v_fmac_f32_e32 v154, v188, v188
	v_fmac_f32_e32 v154, v189, v189
	s_waitcnt vmcnt(45)
	v_pk_add_f32 v[190:191], v[190:191], v[94:95]
	v_pk_add_f32 v[192:193], v[192:193], v[96:97]
	v_add_u32_e32 v157, 0x130000, v144
	v_cvt_pk_bf16_f32 v158, v190, v191
	v_cvt_pk_bf16_f32 v159, v192, v193
	global_store_dwordx4 v157, v[190:193], s[26:27] nt
	v_add_u32_e32 v94, 0x98000, v146
	v_mul_f32_e32 v155, v190, v190
	global_store_dwordx2 v94, v[158:159], s[96:97]
	v_fmac_f32_e32 v155, v191, v191
	v_fmac_f32_e32 v155, v192, v192
	v_fmac_f32_e32 v155, v193, v193
	s_waitcnt vmcnt(46)
	v_pk_add_f32 v[194:195], v[194:195], v[98:99]
	v_pk_add_f32 v[196:197], v[196:197], v[100:101]
	v_add_u32_e32 v160, 0x138000, v145
	v_cvt_pk_bf16_f32 v164, v194, v195
	v_cvt_pk_bf16_f32 v165, v196, v197
	global_store_dwordx4 v160, v[194:197], s[26:27] nt
	v_add_u32_e32 v98, 0x9c000, v147
	v_mul_f32_e32 v156, v194, v194
	global_store_dwordx2 v98, v[164:165], s[96:97]
	v_fmac_f32_e32 v156, v195, v195
	v_fmac_f32_e32 v156, v196, v196
	v_fmac_f32_e32 v156, v197, v197
	s_waitcnt vmcnt(31)
	v_pk_add_f32 v[198:199], v[198:199], v[38:39]
	v_pk_add_f32 v[200:201], v[200:201], v[40:41]
	v_add_u32_e32 v157, 0x100200, v144
	v_cvt_pk_bf16_f32 v158, v198, v199
	v_cvt_pk_bf16_f32 v159, v200, v201
	global_store_dwordx4 v157, v[198:201], s[26:27] nt
	v_add_u32_e32 v38, 0x80100, v146
	v_fmac_f32_e32 v149, v198, v198
	global_store_dwordx2 v38, v[158:159], s[96:97]
	v_fmac_f32_e32 v149, v199, v199
	v_fmac_f32_e32 v149, v200, v200
	v_fmac_f32_e32 v149, v201, v201
	s_waitcnt vmcnt(32)
	v_pk_add_f32 v[202:203], v[202:203], v[34:35]
	v_pk_add_f32 v[204:205], v[204:205], v[36:37]
	v_add_u32_e32 v160, 0x108200, v145
	v_cvt_pk_bf16_f32 v164, v202, v203
	v_cvt_pk_bf16_f32 v165, v204, v205
	global_store_dwordx4 v160, v[202:205], s[26:27] nt
	v_add_u32_e32 v34, 0x84100, v147
	v_fmac_f32_e32 v150, v202, v202
	global_store_dwordx2 v34, v[164:165], s[96:97]
	v_fmac_f32_e32 v150, v203, v203
	v_fmac_f32_e32 v150, v204, v204
	v_fmac_f32_e32 v150, v205, v205
	s_waitcnt vmcnt(33)
; template <int EPI, int NRM>
; DEVI void epilogue(acc_t& acc, int pn, int trow, const EpiArgs& e, const float* rl, bf16* shmx) {
;     ...
;       for (int bj = 0; bj < 2; ++bj)
; #pragma unroll
;         for (int m = 0; m < 4; ++m)
; #pragma unroll
;           for (int n = 0; n < 2; ++n) {
;             const int idx = (bj * 4 + m) * 2 + n;
;             const unsigned off = (unsigned)((tk0 + bj * 128 + n * 16) * DM + pn * 256 + ai * 128 + m * 16 + fl0);
;             const float4 xx = *reinterpret_cast<const float4*>(lbase + idx * 1024 + lane * 16);
;             float4 o;
;             o.x = xx.x + acc[ai][bj][m][n][0]; o.y = xx.y + acc[ai][bj][m][n][1];
;             o.z = xx.z + acc[ai][bj][m][n][2]; o.w = xx.w + acc[ai][bj][m][n][3];
;             *reinterpret_cast<float4*>(e.xout + off) = o;
;             uint2 ob; ob.x = pack2(o.x, o.y); ob.y = pack2(o.z, o.w);
;             *reinterpret_cast<uint2*>(e.o0 + off) = ob;
;             ss[bj][n] += o.x * o.x + o.y * o.y + o.z * o.z + o.w * o.w;
;           }
;       asm volatile("s_waitcnt lgkmcnt(0)" ::: "memory");
;     }
; #pragma unroll
;     for (int bj = 0; bj < 2; ++bj)
; #pragma unroll
;       for (int n = 0; n < 2; ++n) {
;         float v = ss[bj][n];
;         v += __shfl_xor(v, 16); v += __shfl_xor(v, 32);
;         if (fq == 0) e.stw[(pn * 2 + wr) * TOK + tk0 + bj * 128 + n * 16] = v;
;       }
;     asm volatile("s_waitcnt lgkmcnt(0)" ::: "memory");
;     __builtin_amdgcn_s_barrier();
	v_pk_add_f32 v[206:207], v[206:207], v[26:27]
	v_pk_add_f32 v[208:209], v[208:209], v[28:29]
	v_add_u32_e32 v157, 0x110200, v144
	v_cvt_pk_bf16_f32 v158, v206, v207
	v_cvt_pk_bf16_f32 v159, v208, v209
	global_store_dwordx4 v157, v[206:209], s[26:27] nt
	v_add_u32_e32 v26, 0x88100, v146
	v_fmac_f32_e32 v151, v206, v206
	global_store_dwordx2 v26, v[158:159], s[96:97]
	v_fmac_f32_e32 v151, v207, v207
	v_fmac_f32_e32 v151, v208, v208
	v_fmac_f32_e32 v151, v209, v209
	s_waitcnt vmcnt(34)
	v_pk_add_f32 v[210:211], v[210:211], v[22:23]
	v_pk_add_f32 v[212:213], v[212:213], v[24:25]
	v_add_u32_e32 v160, 0x118200, v145
	v_cvt_pk_bf16_f32 v164, v210, v211
	v_cvt_pk_bf16_f32 v165, v212, v213
	global_store_dwordx4 v160, v[210:213], s[26:27] nt
	v_add_u32_e32 v22, 0x8c100, v147
	v_fmac_f32_e32 v152, v210, v210
	global_store_dwordx2 v22, v[164:165], s[96:97]
	v_fmac_f32_e32 v152, v211, v211
	v_fmac_f32_e32 v152, v212, v212
	v_fmac_f32_e32 v152, v213, v213
	s_waitcnt vmcnt(35)
	v_pk_add_f32 v[214:215], v[214:215], v[18:19]
	v_pk_add_f32 v[216:217], v[216:217], v[20:21]
	v_add_u32_e32 v157, 0x120200, v144
	v_cvt_pk_bf16_f32 v158, v214, v215
	v_cvt_pk_bf16_f32 v159, v216, v217
	global_store_dwordx4 v157, v[214:217], s[26:27] nt
	v_add_u32_e32 v18, 0x90100, v146
	v_fmac_f32_e32 v153, v214, v214
	global_store_dwordx2 v18, v[158:159], s[96:97]
	v_fmac_f32_e32 v153, v215, v215
	v_fmac_f32_e32 v153, v216, v216
	v_fmac_f32_e32 v153, v217, v217
	s_waitcnt vmcnt(36)
	v_pk_add_f32 v[218:219], v[218:219], v[10:11]
	v_pk_add_f32 v[220:221], v[220:221], v[12:13]
	v_add_u32_e32 v160, 0x128200, v145
	v_cvt_pk_bf16_f32 v164, v218, v219
	v_cvt_pk_bf16_f32 v165, v220, v221
	global_store_dwordx4 v160, v[218:221], s[26:27] nt
	v_add_u32_e32 v10, 0x94100, v147
	v_fmac_f32_e32 v154, v218, v218
	global_store_dwordx2 v10, v[164:165], s[96:97]
	v_fmac_f32_e32 v154, v219, v219
	v_fmac_f32_e32 v154, v220, v220
	v_fmac_f32_e32 v154, v221, v221
	s_waitcnt vmcnt(37)
	v_pk_add_f32 v[222:223], v[222:223], v[6:7]
	v_pk_add_f32 v[224:225], v[224:225], v[8:9]
	v_add_u32_e32 v157, 0x130200, v144
	v_cvt_pk_bf16_f32 v158, v222, v223
	v_cvt_pk_bf16_f32 v159, v224, v225
	global_store_dwordx4 v157, v[222:225], s[26:27] nt
	v_add_u32_e32 v6, 0x98100, v146
	v_fmac_f32_e32 v155, v222, v222
	global_store_dwordx2 v6, v[158:159], s[96:97]
	v_fmac_f32_e32 v155, v223, v223
	v_fmac_f32_e32 v155, v224, v224
	v_fmac_f32_e32 v155, v225, v225
	s_waitcnt vmcnt(38)
	v_pk_add_f32 v[226:227], v[226:227], v[2:3]
	v_pk_add_f32 v[228:229], v[228:229], v[4:5]
	v_add_u32_e32 v160, 0x138200, v145
	v_cvt_pk_bf16_f32 v164, v226, v227
	v_cvt_pk_bf16_f32 v165, v228, v229
	global_store_dwordx4 v160, v[226:229], s[26:27] nt
	v_add_u32_e32 v2, 0x9c100, v147
	v_fmac_f32_e32 v156, v226, v226
	global_store_dwordx2 v2, v[164:165], s[96:97]
	v_fmac_f32_e32 v156, v227, v227
	v_fmac_f32_e32 v156, v228, v228
	v_fmac_f32_e32 v156, v229, v229
	v_add_f32_dpp v149, v149, v149 row_shr:1 row_mask:0xf bank_mask:0xf bound_ctrl:0
	v_add_f32_dpp v150, v150, v150 row_shr:1 row_mask:0xf bank_mask:0xf bound_ctrl:0
	v_add_f32_dpp v151, v151, v151 row_shr:1 row_mask:0xf bank_mask:0xf bound_ctrl:0
	v_add_f32_dpp v152, v152, v152 row_shr:1 row_mask:0xf bank_mask:0xf bound_ctrl:0
	v_add_f32_dpp v153, v153, v153 row_shr:1 row_mask:0xf bank_mask:0xf bound_ctrl:0
	v_add_f32_dpp v154, v154, v154 row_shr:1 row_mask:0xf bank_mask:0xf bound_ctrl:0
	v_add_f32_dpp v155, v155, v155 row_shr:1 row_mask:0xf bank_mask:0xf bound_ctrl:0
	v_add_f32_dpp v156, v156, v156 row_shr:1 row_mask:0xf bank_mask:0xf bound_ctrl:0
	v_add_f32_dpp v149, v149, v149 row_shr:2 row_mask:0xf bank_mask:0xf bound_ctrl:0
	v_add_f32_dpp v150, v150, v150 row_shr:2 row_mask:0xf bank_mask:0xf bound_ctrl:0
	v_add_f32_dpp v151, v151, v151 row_shr:2 row_mask:0xf bank_mask:0xf bound_ctrl:0
	v_add_f32_dpp v152, v152, v152 row_shr:2 row_mask:0xf bank_mask:0xf bound_ctrl:0
	v_add_f32_dpp v153, v153, v153 row_shr:2 row_mask:0xf bank_mask:0xf bound_ctrl:0
	v_add_f32_dpp v154, v154, v154 row_shr:2 row_mask:0xf bank_mask:0xf bound_ctrl:0
	v_add_f32_dpp v155, v155, v155 row_shr:2 row_mask:0xf bank_mask:0xf bound_ctrl:0
	v_add_f32_dpp v156, v156, v156 row_shr:2 row_mask:0xf bank_mask:0xf bound_ctrl:0
	v_add_f32_dpp v149, v149, v149 row_shr:4 row_mask:0xf bank_mask:0xf bound_ctrl:0
	v_add_f32_dpp v150, v150, v150 row_shr:4 row_mask:0xf bank_mask:0xf bound_ctrl:0
	v_add_f32_dpp v151, v151, v151 row_shr:4 row_mask:0xf bank_mask:0xf bound_ctrl:0
	v_add_f32_dpp v152, v152, v152 row_shr:4 row_mask:0xf bank_mask:0xf bound_ctrl:0
	v_add_f32_dpp v153, v153, v153 row_shr:4 row_mask:0xf bank_mask:0xf bound_ctrl:0
	v_add_f32_dpp v154, v154, v154 row_shr:4 row_mask:0xf bank_mask:0xf bound_ctrl:0
	v_add_f32_dpp v155, v155, v155 row_shr:4 row_mask:0xf bank_mask:0xf bound_ctrl:0
	v_add_f32_dpp v156, v156, v156 row_shr:4 row_mask:0xf bank_mask:0xf bound_ctrl:0
	v_add_f32_dpp v149, v149, v149 row_shr:8 row_mask:0xf bank_mask:0xf bound_ctrl:0
	v_add_f32_dpp v150, v150, v150 row_shr:8 row_mask:0xf bank_mask:0xf bound_ctrl:0
	v_add_f32_dpp v151, v151, v151 row_shr:8 row_mask:0xf bank_mask:0xf bound_ctrl:0
	v_add_f32_dpp v152, v152, v152 row_shr:8 row_mask:0xf bank_mask:0xf bound_ctrl:0
	v_add_f32_dpp v153, v153, v153 row_shr:8 row_mask:0xf bank_mask:0xf bound_ctrl:0
	v_add_f32_dpp v154, v154, v154 row_shr:8 row_mask:0xf bank_mask:0xf bound_ctrl:0
	v_add_f32_dpp v155, v155, v155 row_shr:8 row_mask:0xf bank_mask:0xf bound_ctrl:0
	v_add_f32_dpp v156, v156, v156 row_shr:8 row_mask:0xf bank_mask:0xf bound_ctrl:0
	v_cmp_eq_u32_e32 vcc, 15, v138
	s_and_saveexec_b64 s[6:7], vcc
	global_store_dword v148, v149, s[88:89] offset:512
	global_store_dword v148, v150, s[88:89] offset:528
	global_store_dword v148, v151, s[88:89] offset:544
	global_store_dword v148, v152, s[88:89] offset:560
	global_store_dword v148, v153, s[88:89] offset:576
	global_store_dword v148, v154, s[88:89] offset:592
	global_store_dword v148, v155, s[88:89] offset:608
	global_store_dword v148, v156, s[88:89] offset:624
	s_branch .LBB0_1266

; DEVI void convT(const float* __restrict__ src, int K, int N, bf16* __restrict__ dst, int ldd, int blk, int blk_stride,
;                 int row_off, const float* __restrict__ nscale, const float* __restrict__ kscale, float* lds) {
;   const int tid = threadIdx.x;
;   const int tilesN = (N + 63) / 64, tilesK = K / 64;
;   const int ntl = tilesN * tilesK;
;   const int lk = tid / 16, ln = (tid % 16) * 4;
;   int tile = blockIdx.x;
;   float4 c0 = make_float4(0.f, 0.f, 0.f, 0.f), c1 = c0;
;   if (tile < ntl) {
;     const int n0 = (tile % tilesN) * 64, k0 = (tile / tilesN) * 64;
;     if (n0 + ln < N) {
;       c0 = *reinterpret_cast<const float4*>(src + (long)(k0 + lk) * N + n0 + ln);
;       c1 = *reinterpret_cast<const float4*>(src + (long)(k0 + lk + 32) * N + n0 + ln);
;     }
.LBB0_1309:
	s_cmp_gt_i32 s30, 13
	s_cselect_b64 s[0:1], -1, 0
	s_cmp_lt_i32 s31, 14
	s_cselect_b64 s[2:3], -1, 0
	s_or_b64 s[0:1], s[0:1], s[2:3]
	s_and_b64 vcc, exec, s[0:1]
	s_cbranch_vccnz .LBB0_1435
	v_and_b32_e32 v30, 0x3ff, v0
	v_lshlrev_b32_e32 v2, 2, v30
	v_and_b32_e32 v28, 60, v2
	v_mul_u32_u24_e32 v2, 0x41, v1
	v_lshlrev_b32_e32 v18, 2, v28
	v_lshlrev_b32_e32 v2, 2, v2
	v_add3_u32 v31, 0, v18, v2
	v_add3_u32 v32, 0, v2, v18
	v_lshlrev_b32_e32 v2, 3, v30
	v_and_b32_e32 v33, 56, v2
	s_cmpk_gt_i32 s92, 0xc1f
	v_mov_b32_e32 v10, 0
	v_mul_u32_u24_e32 v35, 0x104, v33
	s_cbranch_scc1 .LBB0_1337
	s_mul_hi_i32 s0, s92, 0x151d07eb
	s_lshr_b32 s1, s0, 31
	s_ashr_i32 s3, s0, 3
	s_add_i32 s3, s3, s1
	s_mul_i32 s0, s3, 0x61
	s_sub_i32 s0, s92, s0
	s_lshl_b32 s2, s0, 6
	v_or_b32_e32 v2, s2, v28
	s_movk_i32 s8, 0x1810
	v_cmp_gt_i32_e32 vcc, s8, v2
	v_mov_b32_e32 v11, 0
	v_mov_b32_e32 v12, 0
	v_mov_b32_e32 v13, 0
	v_mov_b32_e32 v14, 0
	v_mov_b32_e32 v15, 0
	v_mov_b32_e32 v16, 0
	v_mov_b32_e32 v17, 0
	s_and_saveexec_b64 s[0:1], vcc
	s_cbranch_execz .LBB0_1313
	v_lshl_or_b32 v6, s3, 6, v1
	v_add_u32_e32 v4, 32, v6
	s_movk_i32 s6, 0x6040
	s_waitcnt lgkmcnt(0)
	v_mov_b64_e32 v[2:3], s[80:81]
	s_ashr_i32 s3, s2, 31
	v_mad_i64_i32 v[4:5], s[4:5], v4, s6, v[2:3]
	s_lshl_b64 s[2:3], s[2:3], 2
	v_mad_i64_i32 v[2:3], s[4:5], v6, s6, v[2:3]
	v_mov_b32_e32 v19, 0
	v_lshl_add_u64 v[2:3], v[2:3], 0, s[2:3]
	v_lshl_add_u64 v[4:5], v[4:5], 0, s[2:3]
	v_lshl_add_u64 v[2:3], v[2:3], 0, v[18:19]
	v_lshl_add_u64 v[4:5], v[4:5], 0, v[18:19]
	global_load_dwordx4 v[14:17], v[2:3], off nt
	global_load_dwordx4 v[10:13], v[4:5], off nt

; DEVI void convT(const float* __restrict__ src, int K, int N, bf16* __restrict__ dst, int ldd, int blk, int blk_stride,
;                 int row_off, const float* __restrict__ nscale, const float* __restrict__ kscale, float* lds) {
;     ...
;   while (tile < ntl) {
;     const int n0 = (tile % tilesN) * 64, k0 = (tile / tilesN) * 64;
;     const int nxt = tile + gridDim.x;
;     float4 d0 = make_float4(0.f, 0.f, 0.f, 0.f), d1 = d0;
;     if (nxt < ntl) {
;       const int n2 = (nxt % tilesN) * 64, k2 = (nxt / tilesN) * 64;
;       if (n2 + ln < N) {
;         d0 = *reinterpret_cast<const float4*>(src + (long)(k2 + lk) * N + n2 + ln);
;         d1 = *reinterpret_cast<const float4*>(src + (long)(k2 + lk + 32) * N + n2 + ln);
;       }
.LBB0_1316:
	s_add_i32 s14, s10, s6
	s_cmpk_gt_i32 s14, 0xc1f
	s_cselect_b64 s[2:3], -1, 0
	s_and_b64 vcc, exec, s[2:3]
	v_mov_b32_e32 v2, 0
	v_mov_b32_e32 v3, 0
	v_mov_b32_e32 v4, 0
	v_mov_b32_e32 v5, 0
	v_mov_b32_e32 v6, 0
	v_mov_b32_e32 v7, 0
	v_mov_b32_e32 v8, 0
	v_mov_b32_e32 v9, 0
	s_cbranch_vccnz .LBB0_1320
	s_mul_hi_i32 s4, s14, 0x151d07eb
	s_lshr_b32 s5, s4, 31
	s_ashr_i32 s7, s4, 3
	s_add_i32 s7, s7, s5
	s_mul_i32 s15, s7, 0xffffe7c0
	s_add_i32 s4, s15, s11
	v_add_u32_e32 v2, s4, v22
	v_cmp_gt_i32_e32 vcc, s8, v2
	v_mov_b32_e32 v9, 0
	v_mov_b32_e32 v8, 0
	v_mov_b32_e32 v7, 0
	v_mov_b32_e32 v6, 0
	v_mov_b32_e32 v5, 0
	v_mov_b32_e32 v4, 0
	v_mov_b32_e32 v3, 0
	v_mov_b32_e32 v2, 0
	s_and_saveexec_b64 s[4:5], vcc
	s_cbranch_execz .LBB0_1319
	s_add_i32 s16, s12, s11
	s_add_i32 s16, s16, s15
	v_lshl_or_b32 v6, s7, 6, v1
	v_mov_b64_e32 v[2:3], s[80:81]
	v_mad_i64_i32 v[4:5], s[18:19], v6, s9, v[2:3]
	s_ashr_i32 s17, s16, 31
	v_add_u32_e32 v6, 32, v6
	s_lshl_b64 s[16:17], s[16:17], 2
	v_mad_i64_i32 v[2:3], s[18:19], v6, s9, v[2:3]
	v_lshl_add_u64 v[4:5], v[4:5], 0, s[16:17]
	v_mov_b32_e32 v19, v21
	v_lshl_add_u64 v[2:3], v[2:3], 0, s[16:17]
	v_lshl_add_u64 v[4:5], v[4:5], 0, v[18:19]
	v_lshl_add_u64 v[2:3], v[2:3], 0, v[18:19]
	global_load_dwordx4 v[6:9], v[4:5], off nt
	s_nop 0
	global_load_dwordx4 v[2:5], v[2:3], off nt

; DEVI void convT(const float* __restrict__ src, int K, int N, bf16* __restrict__ dst, int ldd, int blk, int blk_stride,
;                 int row_off, const float* __restrict__ nscale, const float* __restrict__ kscale, float* lds) {
;   const int tid = threadIdx.x;
;   const int tilesN = (N + 63) / 64, tilesK = K / 64;
;   const int ntl = tilesN * tilesK;
;   const int lk = tid / 16, ln = (tid % 16) * 4;
;   int tile = blockIdx.x;
;   float4 c0 = make_float4(0.f, 0.f, 0.f, 0.f), c1 = c0;
;   if (tile < ntl) {
;     const int n0 = (tile % tilesN) * 64, k0 = (tile / tilesN) * 64;
;     if (n0 + ln < N) {
;       c0 = *reinterpret_cast<const float4*>(src + (long)(k0 + lk) * N + n0 + ln);
;       c1 = *reinterpret_cast<const float4*>(src + (long)(k0 + lk + 32) * N + n0 + ln);
;     }
.LBB0_1337:
	s_ashr_i32 s0, s92, 31
	s_lshr_b32 s0, s0, 27
	s_add_i32 s0, s92, s0
	s_and_b32 s1, s0, 0x3ffffe0
	s_sub_i32 s1, s92, s1
	s_lshl_b32 s6, s1, 6
	s_lshl_b32 s0, s0, 1
	s_and_b32 s2, s0, 0xffffffc0
	v_or_b32_e32 v2, s6, v28
	s_movk_i32 s0, 0x800
	v_cmp_gt_i32_e64 s[0:1], s0, v2
	v_or_b32_e32 v2, s2, v1
	s_waitcnt lgkmcnt(0)
	v_ashrrev_i32_e32 v3, 31, v2
	s_ashr_i32 s7, s6, 31
	v_lshlrev_b64 v[20:21], 13, v[2:3]
	s_mov_b64 s[2:3], 0x40000
	s_cmpk_gt_i32 s92, 0x3ff
	v_lshl_add_u64 v[22:23], v[20:21], 0, s[2:3]
	s_cbranch_scc1 .LBB0_1348
	v_mov_b32_e32 v19, 0
	v_mov_b32_e32 v2, v19
	v_mov_b32_e32 v3, v19
	v_mov_b32_e32 v4, v19
	v_mov_b32_e32 v5, v19
	v_mov_b32_e32 v6, v19
	v_mov_b32_e32 v7, v19
	v_mov_b32_e32 v8, v19
	v_mov_b32_e32 v9, v19
	s_and_saveexec_b64 s[2:3], s[0:1]
	s_cbranch_execz .LBB0_1340
	v_lshl_add_u64 v[2:3], s[56:57], 0, v[22:23]
	s_lshl_b64 s[4:5], s[6:7], 2
	v_lshl_add_u64 v[6:7], s[56:57], 0, v[20:21]
	v_lshl_add_u64 v[2:3], v[2:3], 0, s[4:5]
	v_mov_b32_e32 v5, 0
	v_mov_b32_e32 v4, v18
	v_lshl_add_u64 v[6:7], v[6:7], 0, s[4:5]
	v_lshl_add_u64 v[2:3], v[2:3], 0, v[4:5]
	v_lshl_add_u64 v[4:5], v[6:7], 0, v[4:5]
	global_load_dwordx4 v[6:9], v[4:5], off nt
	s_nop 0
	global_load_dwordx4 v[2:5], v[2:3], off nt

; DEVI void convT(const float* __restrict__ src, int K, int N, bf16* __restrict__ dst, int ldd, int blk, int blk_stride,
;                 int row_off, const float* __restrict__ nscale, const float* __restrict__ kscale, float* lds) {
;     ...
;   while (tile < ntl) {
;     const int n0 = (tile % tilesN) * 64, k0 = (tile / tilesN) * 64;
;     const int nxt = tile + gridDim.x;
;     float4 d0 = make_float4(0.f, 0.f, 0.f, 0.f), d1 = d0;
;     if (nxt < ntl) {
;       const int n2 = (nxt % tilesN) * 64, k2 = (nxt / tilesN) * 64;
;       if (n2 + ln < N) {
;         d0 = *reinterpret_cast<const float4*>(src + (long)(k2 + lk) * N + n2 + ln);
;         d1 = *reinterpret_cast<const float4*>(src + (long)(k2 + lk + 32) * N + n2 + ln);
;       }
.LBB0_1342:
	s_add_i32 s14, s11, s15
	s_cmpk_gt_i32 s14, 0x3ff
	s_cselect_b64 s[4:5], -1, 0
	v_mov_b32_e32 v10, 0
	s_and_b64 vcc, exec, s[4:5]
	v_mov_b32_e32 v11, 0
	v_mov_b32_e32 v12, 0
	v_mov_b32_e32 v13, 0
	v_mov_b32_e32 v14, 0
	v_mov_b32_e32 v15, 0
	v_mov_b32_e32 v16, 0
	v_mov_b32_e32 v17, 0
	s_cbranch_vccnz .LBB0_1346
	s_ashr_i32 s8, s14, 31
	s_lshr_b32 s8, s8, 27
	s_add_i32 s8, s14, s8
	s_ashr_i32 s16, s8, 5
	s_lshl_b32 s17, s16, 11
	s_sub_i32 s8, s12, s17
	v_add_u32_e32 v10, s8, v26
	v_cmp_gt_i32_e32 vcc, s10, v10
	v_mov_b32_e32 v17, 0
	v_mov_b32_e32 v16, 0
	v_mov_b32_e32 v15, 0
	v_mov_b32_e32 v14, 0
	v_mov_b32_e32 v13, 0
	v_mov_b32_e32 v12, 0
	v_mov_b32_e32 v11, 0
	v_mov_b32_e32 v10, 0
	s_and_saveexec_b64 s[8:9], vcc
	s_cbranch_execz .LBB0_1345
	v_lshl_or_b32 v10, s16, 6, v1
	s_sub_i32 s17, 0, s17
	s_add_i32 s18, s13, s12
	v_ashrrev_i32_e32 v11, 31, v10
	s_add_i32 s18, s18, s17
	v_lshlrev_b64 v[10:11], 13, v[10:11]
	v_lshl_add_u64 v[10:11], s[56:57], 0, v[10:11]
	s_ashr_i32 s19, s18, 31
	v_lshl_add_u64 v[10:11], s[18:19], 2, v[10:11]
	v_lshl_add_u64 v[10:11], v[10:11], 0, v[18:19]
	v_add_co_u32_e32 v12, vcc, 0x40000, v10
	s_nop 1
	v_addc_co_u32_e32 v13, vcc, 0, v11, vcc
	global_load_dwordx4 v[14:17], v[10:11], off nt
	s_nop 0
	global_load_dwordx4 v[10:13], v[12:13], off nt

; DEVI void convT(const float* __restrict__ src, int K, int N, bf16* __restrict__ dst, int ldd, int blk, int blk_stride,
;                 int row_off, const float* __restrict__ nscale, const float* __restrict__ kscale, float* lds) {
;   const int tid = threadIdx.x;
;   const int tilesN = (N + 63) / 64, tilesK = K / 64;
;   const int ntl = tilesN * tilesK;
;   const int lk = tid / 16, ln = (tid % 16) * 4;
;   int tile = blockIdx.x;
;   float4 c0 = make_float4(0.f, 0.f, 0.f, 0.f), c1 = c0;
;   if (tile < ntl) {
;     const int n0 = (tile % tilesN) * 64, k0 = (tile / tilesN) * 64;
;     if (n0 + ln < N) {
;       c0 = *reinterpret_cast<const float4*>(src + (long)(k0 + lk) * N + n0 + ln);
;       c1 = *reinterpret_cast<const float4*>(src + (long)(k0 + lk + 32) * N + n0 + ln);
;     }
; DEVI void convert_ffn(const Params& p, int ig, bf16* shm) {
;     ...
;   convT(p.in[ig], DM, DFF, (bf16*)(p.ws + W_GU), DM, 128, 256, 0, nullptr, p.in[ig - 1], lds);
.LBB0_1350:
	s_andn2_b64 vcc, exec, s[2:3]
	s_cbranch_vccnz .LBB0_1413
	s_mul_hi_i32 s2, s92, 0x2e8ba2e9
	s_lshr_b32 s3, s2, 31
	s_ashr_i32 s2, s2, 4
	s_add_i32 s2, s2, s3
	s_mul_i32 s3, s2, 0x58
	s_sub_i32 s3, s92, s3
	s_lshl_b32 s10, s3, 6
	v_or_b32_e32 v2, s10, v28
	s_movk_i32 s21, 0x1600
	v_cmp_gt_i32_e64 s[4:5], s21, v2
	v_lshl_or_b32 v2, s2, 6, v1
	s_movk_i32 s22, 0x5800
	v_mad_i64_i32 v[24:25], s[2:3], v2, s22, 0
	v_add_u32_e32 v2, 32, v2
	s_ashr_i32 s11, s10, 31
	v_mad_i64_i32 v[26:27], s[2:3], v2, s22, 0
	v_mov_b32_e32 v29, 0
	v_mov_b32_e32 v10, 0
	v_mov_b32_e32 v11, 0
	v_mov_b32_e32 v12, 0
	v_mov_b32_e32 v13, 0
	v_mov_b32_e32 v14, 0
	v_mov_b32_e32 v15, 0
	v_mov_b32_e32 v16, 0
	v_mov_b32_e32 v17, 0
	s_and_saveexec_b64 s[2:3], s[4:5]
	s_cbranch_execz .LBB0_1353
	s_lshl_b64 s[8:9], s[10:11], 2
	v_lshl_add_u64 v[4:5], s[60:61], 0, v[24:25]
	v_lshl_add_u64 v[2:3], s[60:61], 0, v[26:27]
	v_mov_b32_e32 v19, 0
	v_lshl_add_u64 v[4:5], v[4:5], 0, s[8:9]
	v_lshl_add_u64 v[2:3], v[2:3], 0, s[8:9]
	v_lshl_add_u64 v[4:5], v[4:5], 0, v[18:19]
	v_lshl_add_u64 v[2:3], v[2:3], 0, v[18:19]
	global_load_dwordx4 v[14:17], v[4:5], off nt
	global_load_dwordx4 v[10:13], v[2:3], off nt

; DEVI void convT(const float* __restrict__ src, int K, int N, bf16* __restrict__ dst, int ldd, int blk, int blk_stride,
;                 int row_off, const float* __restrict__ nscale, const float* __restrict__ kscale, float* lds) {
;     ...
;   while (tile < ntl) {
;     const int n0 = (tile % tilesN) * 64, k0 = (tile / tilesN) * 64;
;     const int nxt = tile + gridDim.x;
;     float4 d0 = make_float4(0.f, 0.f, 0.f, 0.f), d1 = d0;
;     if (nxt < ntl) {
;       const int n2 = (nxt % tilesN) * 64, k2 = (nxt / tilesN) * 64;
;       if (n2 + ln < N) {
;         d0 = *reinterpret_cast<const float4*>(src + (long)(k2 + lk) * N + n2 + ln);
;         d1 = *reinterpret_cast<const float4*>(src + (long)(k2 + lk + 32) * N + n2 + ln);
;       }
; DEVI void convert_ffn(const Params& p, int ig, bf16* shm) {
;     ...
;   convT(p.in[ig], DM, DFF, (bf16*)(p.ws + W_GU), DM, 128, 256, 0, nullptr, p.in[ig - 1], lds);
.LBB0_1356:
	s_add_i32 s34, s18, s16
	s_cmpk_gt_i32 s34, 0xaff
	s_cselect_b64 s[12:13], -1, 0
	v_mov_b32_e32 v2, 0
	s_and_b64 vcc, exec, s[12:13]
	v_mov_b32_e32 v3, 0
	v_mov_b32_e32 v4, 0
	v_mov_b32_e32 v5, 0
	v_mov_b32_e32 v6, 0
	v_mov_b32_e32 v7, 0
	v_mov_b32_e32 v8, 0
	v_mov_b32_e32 v9, 0
	s_cbranch_vccnz .LBB0_1360
	s_mul_hi_i32 s14, s34, 0x2e8ba2e9
	s_lshr_b32 s15, s14, 31
	s_ashr_i32 s17, s14, 4
	s_add_i32 s17, s17, s15
	s_mul_i32 s35, s17, 0xffffea00
	s_add_i32 s14, s35, s23
	v_add_u32_e32 v2, s14, v34
	v_cmp_gt_i32_e32 vcc, s21, v2
	v_mov_b32_e32 v9, 0
	v_mov_b32_e32 v8, 0
	v_mov_b32_e32 v7, 0
	v_mov_b32_e32 v6, 0
	v_mov_b32_e32 v5, 0
	v_mov_b32_e32 v4, 0
	v_mov_b32_e32 v3, 0
	v_mov_b32_e32 v2, 0
	s_and_saveexec_b64 s[14:15], vcc
	s_cbranch_execz .LBB0_1359
	s_add_i32 s36, s20, s23
	s_add_i32 s36, s36, s35
	v_lshl_or_b32 v6, s17, 6, v1
	v_mov_b64_e32 v[2:3], s[60:61]
	v_mad_i64_i32 v[4:5], s[38:39], v6, s22, v[2:3]
	s_ashr_i32 s37, s36, 31
	v_add_u32_e32 v6, 32, v6
	s_lshl_b64 s[36:37], s[36:37], 2
	v_mad_i64_i32 v[2:3], s[38:39], v6, s22, v[2:3]
	v_lshl_add_u64 v[4:5], v[4:5], 0, s[36:37]
	v_mov_b32_e32 v19, v29
	v_lshl_add_u64 v[2:3], v[2:3], 0, s[36:37]
	v_lshl_add_u64 v[4:5], v[4:5], 0, v[18:19]
	v_lshl_add_u64 v[2:3], v[2:3], 0, v[18:19]
	global_load_dwordx4 v[6:9], v[4:5], off nt
	s_nop 0
	global_load_dwordx4 v[2:5], v[2:3], off nt

; DEVI void convT(const float* __restrict__ src, int K, int N, bf16* __restrict__ dst, int ldd, int blk, int blk_stride,
;                 int row_off, const float* __restrict__ nscale, const float* __restrict__ kscale, float* lds) {
;   const int tid = threadIdx.x;
;   const int tilesN = (N + 63) / 64, tilesK = K / 64;
;   const int ntl = tilesN * tilesK;
;   const int lk = tid / 16, ln = (tid % 16) * 4;
;   int tile = blockIdx.x;
;   float4 c0 = make_float4(0.f, 0.f, 0.f, 0.f), c1 = c0;
;   if (tile < ntl) {
;     const int n0 = (tile % tilesN) * 64, k0 = (tile / tilesN) * 64;
;     if (n0 + ln < N) {
;       c0 = *reinterpret_cast<const float4*>(src + (long)(k0 + lk) * N + n0 + ln);
;       c1 = *reinterpret_cast<const float4*>(src + (long)(k0 + lk + 32) * N + n0 + ln);
;     }
; DEVI void convert_ffn(const Params& p, int ig, bf16* shm) {
;     ...
;   convT(p.in[ig + 1], DM, DFF, (bf16*)(p.ws + W_GU), DM, 128, 256, 128, nullptr, p.in[ig - 1], lds);
.LBB0_1377:
	v_mov_b32_e32 v29, 0
	v_mov_b32_e32 v10, 0
	v_mov_b32_e32 v11, 0
	v_mov_b32_e32 v12, 0
	v_mov_b32_e32 v13, 0
	v_mov_b32_e32 v14, 0
	v_mov_b32_e32 v15, 0
	v_mov_b32_e32 v16, 0
	v_mov_b32_e32 v17, 0
	s_and_saveexec_b64 s[12:13], s[4:5]
	s_cbranch_execz .LBB0_1379
	s_lshl_b64 s[4:5], s[10:11], 2
	v_lshl_add_u64 v[4:5], s[62:63], 0, v[24:25]
	v_lshl_add_u64 v[2:3], s[62:63], 0, v[26:27]
	v_mov_b32_e32 v19, 0
	v_lshl_add_u64 v[4:5], v[4:5], 0, s[4:5]
	v_lshl_add_u64 v[2:3], v[2:3], 0, s[4:5]
	v_lshl_add_u64 v[4:5], v[4:5], 0, v[18:19]
	v_lshl_add_u64 v[2:3], v[2:3], 0, v[18:19]
	global_load_dwordx4 v[10:13], v[4:5], off nt
	global_load_dwordx4 v[14:17], v[2:3], off nt

; DEVI void convT(const float* __restrict__ src, int K, int N, bf16* __restrict__ dst, int ldd, int blk, int blk_stride,
;                 int row_off, const float* __restrict__ nscale, const float* __restrict__ kscale, float* lds) {
;     ...
;   while (tile < ntl) {
;     const int n0 = (tile % tilesN) * 64, k0 = (tile / tilesN) * 64;
;     const int nxt = tile + gridDim.x;
;     float4 d0 = make_float4(0.f, 0.f, 0.f, 0.f), d1 = d0;
;     if (nxt < ntl) {
;       const int n2 = (nxt % tilesN) * 64, k2 = (nxt / tilesN) * 64;
;       if (n2 + ln < N) {
;         d0 = *reinterpret_cast<const float4*>(src + (long)(k2 + lk) * N + n2 + ln);
;         d1 = *reinterpret_cast<const float4*>(src + (long)(k2 + lk + 32) * N + n2 + ln);
;       }
; DEVI void convert_ffn(const Params& p, int ig, bf16* shm) {
;     ...
;   convT(p.in[ig + 1], DM, DFF, (bf16*)(p.ws + W_GU), DM, 128, 256, 128, nullptr, p.in[ig - 1], lds);
.LBB0_1382:
	s_add_i32 s17, s12, s18
	s_cmpk_gt_i32 s17, 0xaff
	s_cselect_b64 s[4:5], -1, 0
	v_mov_b32_e32 v2, 0
	s_and_b64 vcc, exec, s[4:5]
	v_mov_b32_e32 v3, 0
	v_mov_b32_e32 v4, 0
	v_mov_b32_e32 v5, 0
	v_mov_b32_e32 v6, 0
	v_mov_b32_e32 v7, 0
	v_mov_b32_e32 v8, 0
	v_mov_b32_e32 v9, 0
	s_cbranch_vccnz .LBB0_1386
	s_mul_hi_i32 s10, s17, 0x2e8ba2e9
	s_lshr_b32 s11, s10, 31
	s_ashr_i32 s13, s10, 4
	s_add_i32 s13, s13, s11
	s_mul_i32 s21, s13, 0xffffea00
	s_add_i32 s10, s21, s16
	v_add_u32_e32 v2, s10, v34
	v_cmp_gt_i32_e32 vcc, s14, v2
	v_mov_b32_e32 v9, 0
	v_mov_b32_e32 v8, 0
	v_mov_b32_e32 v7, 0
	v_mov_b32_e32 v6, 0
	v_mov_b32_e32 v5, 0
	v_mov_b32_e32 v4, 0
	v_mov_b32_e32 v3, 0
	v_mov_b32_e32 v2, 0
	s_and_saveexec_b64 s[10:11], vcc
	s_cbranch_execz .LBB0_1385
	s_add_i32 s22, s20, s16
	s_add_i32 s22, s22, s21
	v_lshl_or_b32 v6, s13, 6, v1
	v_mov_b64_e32 v[2:3], s[62:63]
	v_mad_i64_i32 v[4:5], s[34:35], v6, s15, v[2:3]
	s_ashr_i32 s23, s22, 31
	v_add_u32_e32 v6, 32, v6
	s_lshl_b64 s[22:23], s[22:23], 2
	v_mad_i64_i32 v[2:3], s[34:35], v6, s15, v[2:3]
	v_lshl_add_u64 v[4:5], v[4:5], 0, s[22:23]
	v_mov_b32_e32 v19, v29
	v_lshl_add_u64 v[2:3], v[2:3], 0, s[22:23]
	v_lshl_add_u64 v[4:5], v[4:5], 0, v[18:19]
	v_lshl_add_u64 v[2:3], v[2:3], 0, v[18:19]
	global_load_dwordx4 v[6:9], v[4:5], off nt
	s_nop 0
	global_load_dwordx4 v[2:5], v[2:3], off nt

; DEVI void convT(const float* __restrict__ src, int K, int N, bf16* __restrict__ dst, int ldd, int blk, int blk_stride,
;                 int row_off, const float* __restrict__ nscale, const float* __restrict__ kscale, float* lds) {
;   const int tid = threadIdx.x;
;   const int tilesN = (N + 63) / 64, tilesK = K / 64;
;   const int ntl = tilesN * tilesK;
;   const int lk = tid / 16, ln = (tid % 16) * 4;
;   int tile = blockIdx.x;
;   float4 c0 = make_float4(0.f, 0.f, 0.f, 0.f), c1 = c0;
;   if (tile < ntl) {
;     const int n0 = (tile % tilesN) * 64, k0 = (tile / tilesN) * 64;
;     if (n0 + ln < N) {
;       c0 = *reinterpret_cast<const float4*>(src + (long)(k0 + lk) * N + n0 + ln);
;       c1 = *reinterpret_cast<const float4*>(src + (long)(k0 + lk + 32) * N + n0 + ln);
;     }
; DEVI void convert_ffn(const Params& p, int ig, bf16* shm) {
;     ...
;   convT(p.in[ig + 2], DFF, DM, (bf16*)(p.ws + W_DN), DFF, DM, 0, 0, nullptr, nullptr, lds);
.LBB0_1403:
	v_mov_b32_e32 v19, 0
	v_mov_b32_e32 v2, v19
	v_mov_b32_e32 v3, v19
	v_mov_b32_e32 v4, v19
	v_mov_b32_e32 v5, v19
	v_mov_b32_e32 v6, v19
	v_mov_b32_e32 v7, v19
	v_mov_b32_e32 v8, v19
	v_mov_b32_e32 v9, v19
	s_and_saveexec_b64 s[2:3], s[0:1]
	s_cbranch_execz .LBB0_1405
	v_lshl_add_u64 v[2:3], s[64:65], 0, v[22:23]
	s_lshl_b64 s[0:1], s[6:7], 2
	v_lshl_add_u64 v[2:3], v[2:3], 0, s[0:1]
	v_mov_b32_e32 v5, 0
	v_mov_b32_e32 v4, v18
	v_lshl_add_u64 v[6:7], v[2:3], 0, v[4:5]
	v_lshl_add_u64 v[2:3], s[64:65], 0, v[20:21]
	v_lshl_add_u64 v[2:3], v[2:3], 0, s[0:1]
	v_lshl_add_u64 v[2:3], v[2:3], 0, v[4:5]
	global_load_dwordx4 v[2:5], v[2:3], off nt
	s_nop 0
	global_load_dwordx4 v[6:9], v[6:7], off nt

; DEVI void convT(const float* __restrict__ src, int K, int N, bf16* __restrict__ dst, int ldd, int blk, int blk_stride,
;                 int row_off, const float* __restrict__ nscale, const float* __restrict__ kscale, float* lds) {
;     ...
;   while (tile < ntl) {
;     const int n0 = (tile % tilesN) * 64, k0 = (tile / tilesN) * 64;
;     const int nxt = tile + gridDim.x;
;     float4 d0 = make_float4(0.f, 0.f, 0.f, 0.f), d1 = d0;
;     if (nxt < ntl) {
;       const int n2 = (nxt % tilesN) * 64, k2 = (nxt / tilesN) * 64;
;       if (n2 + ln < N) {
;         d0 = *reinterpret_cast<const float4*>(src + (long)(k2 + lk) * N + n2 + ln);
;         d1 = *reinterpret_cast<const float4*>(src + (long)(k2 + lk + 32) * N + n2 + ln);
;       }
; DEVI void convert_ffn(const Params& p, int ig, bf16* shm) {
;     ...
;   convT(p.in[ig + 2], DFF, DM, (bf16*)(p.ws + W_DN), DFF, DM, 0, 0, nullptr, nullptr, lds);
.LBB0_1407:
	s_add_i32 s7, s8, s18
	s_cmpk_gt_i32 s7, 0xaff
	s_cselect_b64 s[2:3], -1, 0
	v_mov_b32_e32 v10, 0
	s_and_b64 vcc, exec, s[2:3]
	v_mov_b32_e32 v11, 0
	v_mov_b32_e32 v12, 0
	v_mov_b32_e32 v13, 0
	v_mov_b32_e32 v14, 0
	v_mov_b32_e32 v15, 0
	v_mov_b32_e32 v16, 0
	v_mov_b32_e32 v17, 0
	s_cbranch_vccnz .LBB0_1411
	s_ashr_i32 s4, s7, 31
	s_lshr_b32 s4, s4, 27
	s_add_i32 s4, s7, s4
	s_ashr_i32 s9, s4, 5
	s_lshl_b32 s10, s9, 11
	s_sub_i32 s4, s19, s10
	v_add_u32_e32 v10, s4, v34
	v_cmp_gt_i32_e32 vcc, s6, v10
	v_mov_b32_e32 v17, 0
	v_mov_b32_e32 v16, 0
	v_mov_b32_e32 v15, 0
	v_mov_b32_e32 v14, 0
	v_mov_b32_e32 v13, 0
	v_mov_b32_e32 v12, 0
	v_mov_b32_e32 v11, 0
	v_mov_b32_e32 v10, 0
	s_and_saveexec_b64 s[4:5], vcc
	s_cbranch_execz .LBB0_1410
	v_lshl_or_b32 v10, s9, 6, v1
	s_sub_i32 s10, 0, s10
	s_add_i32 s11, s20, s19
	v_ashrrev_i32_e32 v11, 31, v10
	s_add_i32 s10, s11, s10
	v_lshlrev_b64 v[10:11], 13, v[10:11]
	v_lshl_add_u64 v[10:11], s[64:65], 0, v[10:11]
	s_ashr_i32 s11, s10, 31
	v_lshl_add_u64 v[10:11], s[10:11], 2, v[10:11]
	v_lshl_add_u64 v[10:11], v[10:11], 0, v[18:19]
	v_add_co_u32_e32 v12, vcc, 0x40000, v10
	s_nop 1
	v_addc_co_u32_e32 v13, vcc, 0, v11, vcc
	global_load_dwordx4 v[14:17], v[10:11], off nt
	s_nop 0
	global_load_dwordx4 v[10:13], v[12:13], off nt

; template <int EPI, int NRM>
; DEVI void epilogue(acc_t& acc, int pn, int trow, const EpiArgs& e, const float* rl, bf16* shmx) {
;     ...
;   if constexpr (EPI == EPI_RESID) {
;     float ss[2][2] = {{0.f, 0.f}, {0.f, 0.f}};
;     __amdgpu_buffer_rsrc_t rsX = __builtin_amdgcn_make_buffer_rsrc((void*)e.xin, 0, 0x7fffffff, 0x00020000);
;     char* lbase = reinterpret_cast<char*>(shmx) + wid * 16384;
;     const int vx = ((tk0 * DM) + pn * 256 + fl0) * 4;
; #pragma unroll
;     for (int ai = 0; ai < 2; ++ai) {
; #pragma unroll
;       for (int bj = 0; bj < 2; ++bj)
; #pragma unroll
;         for (int m = 0; m < 4; ++m)
; #pragma unroll
;           for (int n = 0; n < 2; ++n) {
;             const int idx = (bj * 4 + m) * 2 + n;
;             const int so = ((bj * 128 + n * 16) * DM + ai * 128 + m * 16) * 4;
;             __builtin_amdgcn_raw_ptr_buffer_load_lds(rsX, (__attribute__((address_space(3))) unsigned*)(lbase + idx * 1024 + lane * 16), 16, vx, so, 0, 0);
;           }
;       asm volatile("s_waitcnt vmcnt(0)" ::: "memory");
; #pragma unroll
;       for (int bj = 0; bj < 2; ++bj)
; #pragma unroll
;         for (int m = 0; m < 4; ++m)
; #pragma unroll
;           for (int n = 0; n < 2; ++n) {
;             const int idx = (bj * 4 + m) * 2 + n;
;             const unsigned off = (unsigned)((tk0 + bj * 128 + n * 16) * DM + pn * 256 + ai * 128 + m * 16 + fl0);
;             const float4 xx = *reinterpret_cast<const float4*>(lbase + idx * 1024 + lane * 16);
;             float4 o;
;             o.x = xx.x + acc[ai][bj][m][n][0]; o.y = xx.y + acc[ai][bj][m][n][1];
;             o.z = xx.z + acc[ai][bj][m][n][2]; o.w = xx.w + acc[ai][bj][m][n][3];
;             *reinterpret_cast<float4*>(e.xout + off) = o;
;             uint2 ob; ob.x = pack2(o.x, o.y); ob.y = pack2(o.z, o.w);
;             *reinterpret_cast<uint2*>(e.o0 + off) = ob;
;             ss[bj][n] += o.x * o.x + o.y * o.y + o.z * o.z + o.w * o.w;
;           }
.LBB0_1619:
	v_and_b32_e32 v138, 15, v131
	v_bfe_u32 v198, v131, 4, 2
	v_lshrrev_b32_e32 v199, 6, v131
	v_and_b32_e32 v200, 3, v199
	v_lshrrev_b32_e32 v201, 2, v199
	v_lshlrev_b32_e32 v202, 14, v199
	v_and_b32_e32 v203, 63, v131
	v_lshl_add_u32 v143, v203, 4, v202
	v_lshl_add_u32 v202, v138, 8, v202
	v_and_b32_e32 v203, 7, v138
	v_add_u32_e32 v204, 0, v198
	v_xor_b32_e32 v204, v204, v203
	v_lshl_add_u32 v139, v204, 4, v202
	v_add_u32_e32 v204, 4, v198
	v_xor_b32_e32 v204, v204, v203
	v_lshl_add_u32 v140, v204, 4, v202
	v_add_u32_e32 v204, 8, v198
	v_xor_b32_e32 v204, v204, v203
	v_lshl_add_u32 v141, v204, 4, v202
	v_add_u32_e32 v204, 12, v198
	v_xor_b32_e32 v204, v204, v203
	v_lshl_add_u32 v142, v204, 4, v202
	s_lshl_b32 s6, s6, 8
	v_lshl_add_u32 v202, v200, 5, v198
	v_add_u32_e32 v202, s6, v202
	s_lshl_b32 s6, s12, 1
	v_add_u32_e32 v204, s6, v201
	v_lshl_add_u32 v204, v204, 15, v202
	v_lshlrev_b32_e32 v148, 2, v204
	v_lshlrev_b32_e32 v202, 11, v202
	s_lshl_b32 s6, s12, 8
	v_lshl_add_u32 v204, v201, 6, s6
	v_add_u32_e32 v202, v202, v204
	v_add_u32_e32 v203, 0, v198
	v_xor_b32_e32 v203, v203, v138
	v_lshl_add_u32 v203, v203, 2, v202
	v_lshlrev_b32_e32 v144, 2, v203
	v_lshlrev_b32_e32 v146, 1, v203
	v_add_u32_e32 v203, 4, v198
	v_xor_b32_e32 v203, v203, v138
	v_lshl_add_u32 v203, v203, 2, v202
	v_lshlrev_b32_e32 v145, 2, v203
	v_lshlrev_b32_e32 v147, 1, v203
	v_add_u32_e32 v157, 0x0, v144
	global_load_dwordx4 v[166:169], v157, s[4:5] nt
	v_add_u32_e32 v160, 0x8000, v145
	global_load_dwordx4 v[170:173], v160, s[4:5] nt
	v_add_u32_e32 v157, 0x10000, v144
	global_load_dwordx4 v[174:177], v157, s[4:5] nt
	v_add_u32_e32 v160, 0x18000, v145
	global_load_dwordx4 v[178:181], v160, s[4:5] nt
	v_add_u32_e32 v157, 0x20000, v144
	global_load_dwordx4 v[182:185], v157, s[4:5] nt
	v_add_u32_e32 v160, 0x28000, v145
	global_load_dwordx4 v[186:189], v160, s[4:5] nt
	v_add_u32_e32 v157, 0x30000, v144
	global_load_dwordx4 v[190:193], v157, s[4:5] nt
	v_add_u32_e32 v160, 0x38000, v145
	global_load_dwordx4 v[194:197], v160, s[4:5] nt
	v_add_u32_e32 v157, 0x200, v144
	global_load_dwordx4 v[198:201], v157, s[4:5] nt
	v_add_u32_e32 v160, 0x8200, v145
	global_load_dwordx4 v[202:205], v160, s[4:5] nt
	v_add_u32_e32 v157, 0x10200, v144
	global_load_dwordx4 v[206:209], v157, s[4:5] nt
	v_add_u32_e32 v160, 0x18200, v145
	global_load_dwordx4 v[210:213], v160, s[4:5] nt
	v_add_u32_e32 v157, 0x20200, v144
	global_load_dwordx4 v[214:217], v157, s[4:5] nt
	v_add_u32_e32 v160, 0x28200, v145
	global_load_dwordx4 v[218:221], v160, s[4:5] nt
	v_add_u32_e32 v157, 0x30200, v144
	global_load_dwordx4 v[222:225], v157, s[4:5] nt
	v_add_u32_e32 v160, 0x38200, v145
	global_load_dwordx4 v[226:229], v160, s[4:5] nt
	ds_write_b128 v139, v[126:129]
	ds_write_b128 v139, v[14:17] offset:4096
	ds_write_b128 v140, v[122:125]
	ds_write_b128 v140, v[26:29] offset:4096
	ds_write_b128 v141, v[118:121]
	ds_write_b128 v141, v[42:45] offset:4096
	ds_write_b128 v142, v[114:117]
	ds_write_b128 v142, v[54:57] offset:4096
	ds_write_b128 v139, v[110:113] offset:8192
	ds_write_b128 v139, v[106:109] offset:12288
	ds_write_b128 v140, v[102:105] offset:8192
	ds_write_b128 v140, v[94:97] offset:12288
	ds_write_b128 v141, v[86:89] offset:8192
	ds_write_b128 v141, v[78:81] offset:12288
	ds_write_b128 v142, v[70:73] offset:8192
	ds_write_b128 v142, v[46:49] offset:12288
	s_waitcnt lgkmcnt(0)
	ds_read_b128 v[126:129], v143
	ds_read_b128 v[14:17], v143 offset:1024
	ds_read_b128 v[122:125], v143 offset:2048
	ds_read_b128 v[26:29], v143 offset:3072
	ds_read_b128 v[118:121], v143 offset:4096
	ds_read_b128 v[42:45], v143 offset:5120
	ds_read_b128 v[114:117], v143 offset:6144
	ds_read_b128 v[54:57], v143 offset:7168
	ds_read_b128 v[110:113], v143 offset:8192
	ds_read_b128 v[106:109], v143 offset:9216
	ds_read_b128 v[102:105], v143 offset:10240
	ds_read_b128 v[94:97], v143 offset:11264
	ds_read_b128 v[86:89], v143 offset:12288
	ds_read_b128 v[78:81], v143 offset:13312
	ds_read_b128 v[70:73], v143 offset:14336
	ds_read_b128 v[46:49], v143 offset:15360
	s_waitcnt lgkmcnt(0)
	ds_write_b128 v139, v[50:53]
	ds_write_b128 v139, v[58:61] offset:4096
	ds_write_b128 v140, v[62:65]
	ds_write_b128 v140, v[66:69] offset:4096
	ds_write_b128 v141, v[74:77]
	ds_write_b128 v141, v[82:85] offset:4096
	ds_write_b128 v142, v[90:93]
	ds_write_b128 v142, v[98:101] offset:4096
	ds_write_b128 v139, v[38:41] offset:8192
	ds_write_b128 v139, v[34:37] offset:12288
	ds_write_b128 v140, v[30:33] offset:8192
	ds_write_b128 v140, v[22:25] offset:12288
	ds_write_b128 v141, v[18:21] offset:8192
	ds_write_b128 v141, v[10:13] offset:12288
	ds_write_b128 v142, v[6:9] offset:8192
	ds_write_b128 v142, v[2:5] offset:12288
	s_waitcnt vmcnt(15)
	v_pk_add_f32 v[166:167], v[166:167], v[126:127]
	v_pk_add_f32 v[168:169], v[168:169], v[128:129]
	v_add_u32_e32 v157, 0x0, v144
	v_cvt_pk_bf16_f32 v158, v166, v167
	v_cvt_pk_bf16_f32 v159, v168, v169
	global_store_dwordx4 v157, v[166:169], s[26:27] nt
	v_add_u32_e32 v126, 0x0, v146
	v_mul_f32_e32 v149, v166, v166
	global_store_dwordx2 v126, v[158:159], s[96:97]
	v_fmac_f32_e32 v149, v167, v167
	v_fmac_f32_e32 v149, v168, v168
	v_fmac_f32_e32 v149, v169, v169
	s_waitcnt vmcnt(16)
	v_pk_add_f32 v[170:171], v[170:171], v[14:15]
	v_pk_add_f32 v[172:173], v[172:173], v[16:17]
	v_add_u32_e32 v160, 0x8000, v145
	v_cvt_pk_bf16_f32 v164, v170, v171
	v_cvt_pk_bf16_f32 v165, v172, v173
	global_store_dwordx4 v160, v[170:173], s[26:27] nt
	v_add_u32_e32 v14, 0x4000, v147
	v_mul_f32_e32 v150, v170, v170
	global_store_dwordx2 v14, v[164:165], s[96:97]
	v_fmac_f32_e32 v150, v171, v171
	v_fmac_f32_e32 v150, v172, v172
	v_fmac_f32_e32 v150, v173, v173
	s_waitcnt vmcnt(17)
; template <int EPI, int NRM>
; DEVI void epilogue(acc_t& acc, int pn, int trow, const EpiArgs& e, const float* rl, bf16* shmx) {
;     ...
;             const unsigned off = (unsigned)((tk0 + bj * 128 + n * 16) * DM + pn * 256 + ai * 128 + m * 16 + fl0);
;             const float4 xx = *reinterpret_cast<const float4*>(lbase + idx * 1024 + lane * 16);
;             float4 o;
;             o.x = xx.x + acc[ai][bj][m][n][0]; o.y = xx.y + acc[ai][bj][m][n][1];
;             o.z = xx.z + acc[ai][bj][m][n][2]; o.w = xx.w + acc[ai][bj][m][n][3];
;             *reinterpret_cast<float4*>(e.xout + off) = o;
;             uint2 ob; ob.x = pack2(o.x, o.y); ob.y = pack2(o.z, o.w);
;             *reinterpret_cast<uint2*>(e.o0 + off) = ob;
;             ss[bj][n] += o.x * o.x + o.y * o.y + o.z * o.z + o.w * o.w;
	v_pk_add_f32 v[174:175], v[174:175], v[122:123]
	v_pk_add_f32 v[176:177], v[176:177], v[124:125]
	v_add_u32_e32 v157, 0x10000, v144
	v_cvt_pk_bf16_f32 v158, v174, v175
	v_cvt_pk_bf16_f32 v159, v176, v177
	global_store_dwordx4 v157, v[174:177], s[26:27] nt
	v_add_u32_e32 v122, 0x8000, v146
	v_mul_f32_e32 v151, v174, v174
	global_store_dwordx2 v122, v[158:159], s[96:97]
	v_fmac_f32_e32 v151, v175, v175
	v_fmac_f32_e32 v151, v176, v176
	v_fmac_f32_e32 v151, v177, v177
	s_waitcnt vmcnt(18)
	v_pk_add_f32 v[178:179], v[178:179], v[26:27]
	v_pk_add_f32 v[180:181], v[180:181], v[28:29]
	v_add_u32_e32 v160, 0x18000, v145
	v_cvt_pk_bf16_f32 v164, v178, v179
	v_cvt_pk_bf16_f32 v165, v180, v181
	global_store_dwordx4 v160, v[178:181], s[26:27] nt
	v_add_u32_e32 v26, 0xc000, v147
	v_mul_f32_e32 v152, v178, v178
	global_store_dwordx2 v26, v[164:165], s[96:97]
	v_fmac_f32_e32 v152, v179, v179
	v_fmac_f32_e32 v152, v180, v180
	v_fmac_f32_e32 v152, v181, v181
	s_waitcnt vmcnt(19)
	v_pk_add_f32 v[182:183], v[182:183], v[118:119]
	v_pk_add_f32 v[184:185], v[184:185], v[120:121]
	v_add_u32_e32 v157, 0x20000, v144
	v_cvt_pk_bf16_f32 v158, v182, v183
	v_cvt_pk_bf16_f32 v159, v184, v185
	global_store_dwordx4 v157, v[182:185], s[26:27] nt
	v_add_u32_e32 v118, 0x10000, v146
	v_mul_f32_e32 v153, v182, v182
	global_store_dwordx2 v118, v[158:159], s[96:97]
	v_fmac_f32_e32 v153, v183, v183
	v_fmac_f32_e32 v153, v184, v184
	v_fmac_f32_e32 v153, v185, v185
	s_waitcnt vmcnt(20)
	v_pk_add_f32 v[186:187], v[186:187], v[42:43]
	v_pk_add_f32 v[188:189], v[188:189], v[44:45]
	v_add_u32_e32 v160, 0x28000, v145
	v_cvt_pk_bf16_f32 v164, v186, v187
	v_cvt_pk_bf16_f32 v165, v188, v189
	global_store_dwordx4 v160, v[186:189], s[26:27] nt
	v_add_u32_e32 v42, 0x14000, v147
	v_mul_f32_e32 v154, v186, v186
	global_store_dwordx2 v42, v[164:165], s[96:97]
	v_fmac_f32_e32 v154, v187, v187
	v_fmac_f32_e32 v154, v188, v188
	v_fmac_f32_e32 v154, v189, v189
	s_waitcnt vmcnt(21)
	v_pk_add_f32 v[190:191], v[190:191], v[114:115]
	v_pk_add_f32 v[192:193], v[192:193], v[116:117]
	v_add_u32_e32 v157, 0x30000, v144
	v_cvt_pk_bf16_f32 v158, v190, v191
	v_cvt_pk_bf16_f32 v159, v192, v193
	global_store_dwordx4 v157, v[190:193], s[26:27] nt
	v_add_u32_e32 v114, 0x18000, v146
	v_mul_f32_e32 v155, v190, v190
	global_store_dwordx2 v114, v[158:159], s[96:97]
	v_fmac_f32_e32 v155, v191, v191
	v_fmac_f32_e32 v155, v192, v192
	v_fmac_f32_e32 v155, v193, v193
	s_waitcnt vmcnt(22)
	v_pk_add_f32 v[194:195], v[194:195], v[54:55]
	v_pk_add_f32 v[196:197], v[196:197], v[56:57]
	v_add_u32_e32 v160, 0x38000, v145
	v_cvt_pk_bf16_f32 v164, v194, v195
	v_cvt_pk_bf16_f32 v165, v196, v197
	global_store_dwordx4 v160, v[194:197], s[26:27] nt
	v_add_u32_e32 v54, 0x1c000, v147
	v_mul_f32_e32 v156, v194, v194
	global_store_dwordx2 v54, v[164:165], s[96:97]
	v_fmac_f32_e32 v156, v195, v195
	v_fmac_f32_e32 v156, v196, v196
	v_fmac_f32_e32 v156, v197, v197
	v_add_u32_e32 v157, 0x100000, v144
	global_load_dwordx4 v[166:169], v157, s[4:5] nt
	v_add_u32_e32 v160, 0x108000, v145
	global_load_dwordx4 v[170:173], v160, s[4:5] nt
	v_add_u32_e32 v157, 0x110000, v144
	global_load_dwordx4 v[174:177], v157, s[4:5] nt
	v_add_u32_e32 v160, 0x118000, v145
	global_load_dwordx4 v[178:181], v160, s[4:5] nt
	v_add_u32_e32 v157, 0x120000, v144
	global_load_dwordx4 v[182:185], v157, s[4:5] nt
	v_add_u32_e32 v160, 0x128000, v145
	global_load_dwordx4 v[186:189], v160, s[4:5] nt
	v_add_u32_e32 v157, 0x130000, v144
	global_load_dwordx4 v[190:193], v157, s[4:5] nt
	v_add_u32_e32 v160, 0x138000, v145
	global_load_dwordx4 v[194:197], v160, s[4:5] nt
	s_waitcnt vmcnt(31)
	v_pk_add_f32 v[198:199], v[198:199], v[110:111]
	v_pk_add_f32 v[200:201], v[200:201], v[112:113]
	v_add_u32_e32 v157, 0x200, v144
	v_cvt_pk_bf16_f32 v158, v198, v199
	v_cvt_pk_bf16_f32 v159, v200, v201
	global_store_dwordx4 v157, v[198:201], s[26:27] nt
	v_add_u32_e32 v110, 0x100, v146
	v_fmac_f32_e32 v149, v198, v198
	global_store_dwordx2 v110, v[158:159], s[96:97]
	v_fmac_f32_e32 v149, v199, v199
	v_fmac_f32_e32 v149, v200, v200
	v_fmac_f32_e32 v149, v201, v201
	s_waitcnt vmcnt(32)
	v_pk_add_f32 v[202:203], v[202:203], v[106:107]
	v_pk_add_f32 v[204:205], v[204:205], v[108:109]
	v_add_u32_e32 v160, 0x8200, v145
	v_cvt_pk_bf16_f32 v164, v202, v203
	v_cvt_pk_bf16_f32 v165, v204, v205
	global_store_dwordx4 v160, v[202:205], s[26:27] nt
	v_add_u32_e32 v106, 0x4100, v147
	v_fmac_f32_e32 v150, v202, v202
	global_store_dwordx2 v106, v[164:165], s[96:97]
	v_fmac_f32_e32 v150, v203, v203
	v_fmac_f32_e32 v150, v204, v204
	v_fmac_f32_e32 v150, v205, v205
	s_waitcnt vmcnt(33)
	v_pk_add_f32 v[206:207], v[206:207], v[102:103]
	v_pk_add_f32 v[208:209], v[208:209], v[104:105]
	v_add_u32_e32 v157, 0x10200, v144
	v_cvt_pk_bf16_f32 v158, v206, v207
	v_cvt_pk_bf16_f32 v159, v208, v209
	global_store_dwordx4 v157, v[206:209], s[26:27] nt
	v_add_u32_e32 v102, 0x8100, v146
	v_fmac_f32_e32 v151, v206, v206
	global_store_dwordx2 v102, v[158:159], s[96:97]
	v_fmac_f32_e32 v151, v207, v207
	v_fmac_f32_e32 v151, v208, v208
	v_fmac_f32_e32 v151, v209, v209
	s_waitcnt vmcnt(34)
	v_pk_add_f32 v[210:211], v[210:211], v[94:95]
	v_pk_add_f32 v[212:213], v[212:213], v[96:97]
	v_add_u32_e32 v160, 0x18200, v145
	v_cvt_pk_bf16_f32 v164, v210, v211
	v_cvt_pk_bf16_f32 v165, v212, v213
	global_store_dwordx4 v160, v[210:213], s[26:27] nt
	v_add_u32_e32 v94, 0xc100, v147
	v_fmac_f32_e32 v152, v210, v210
	global_store_dwordx2 v94, v[164:165], s[96:97]
	v_fmac_f32_e32 v152, v211, v211
	v_fmac_f32_e32 v152, v212, v212
	v_fmac_f32_e32 v152, v213, v213
	s_waitcnt vmcnt(35)
; template <int EPI, int NRM>
; DEVI void epilogue(acc_t& acc, int pn, int trow, const EpiArgs& e, const float* rl, bf16* shmx) {
;     ...
;             const unsigned off = (unsigned)((tk0 + bj * 128 + n * 16) * DM + pn * 256 + ai * 128 + m * 16 + fl0);
;             const float4 xx = *reinterpret_cast<const float4*>(lbase + idx * 1024 + lane * 16);
;             float4 o;
;             o.x = xx.x + acc[ai][bj][m][n][0]; o.y = xx.y + acc[ai][bj][m][n][1];
;             o.z = xx.z + acc[ai][bj][m][n][2]; o.w = xx.w + acc[ai][bj][m][n][3];
;             *reinterpret_cast<float4*>(e.xout + off) = o;
;             uint2 ob; ob.x = pack2(o.x, o.y); ob.y = pack2(o.z, o.w);
;             *reinterpret_cast<uint2*>(e.o0 + off) = ob;
;             ss[bj][n] += o.x * o.x + o.y * o.y + o.z * o.z + o.w * o.w;
;           }
;       asm volatile("s_waitcnt lgkmcnt(0)" ::: "memory");
;     }
; #pragma unroll
;     for (int bj = 0; bj < 2; ++bj)
; #pragma unroll
;       for (int n = 0; n < 2; ++n) {
;         float v = ss[bj][n];
;         v += __shfl_xor(v, 16); v += __shfl_xor(v, 32);
;         if (fq == 0) e.stw[(pn * 2 + wr) * TOK + tk0 + bj * 128 + n * 16] = v;
	v_pk_add_f32 v[214:215], v[214:215], v[86:87]
	v_pk_add_f32 v[216:217], v[216:217], v[88:89]
	v_add_u32_e32 v157, 0x20200, v144
	v_cvt_pk_bf16_f32 v158, v214, v215
	v_cvt_pk_bf16_f32 v159, v216, v217
	global_store_dwordx4 v157, v[214:217], s[26:27] nt
	v_add_u32_e32 v86, 0x10100, v146
	v_fmac_f32_e32 v153, v214, v214
	global_store_dwordx2 v86, v[158:159], s[96:97]
	v_fmac_f32_e32 v153, v215, v215
	v_fmac_f32_e32 v153, v216, v216
	v_fmac_f32_e32 v153, v217, v217
	s_waitcnt vmcnt(36)
	v_pk_add_f32 v[218:219], v[218:219], v[78:79]
	v_pk_add_f32 v[220:221], v[220:221], v[80:81]
	v_add_u32_e32 v160, 0x28200, v145
	v_cvt_pk_bf16_f32 v164, v218, v219
	v_cvt_pk_bf16_f32 v165, v220, v221
	global_store_dwordx4 v160, v[218:221], s[26:27] nt
	v_add_u32_e32 v78, 0x14100, v147
	v_fmac_f32_e32 v154, v218, v218
	global_store_dwordx2 v78, v[164:165], s[96:97]
	v_fmac_f32_e32 v154, v219, v219
	v_fmac_f32_e32 v154, v220, v220
	v_fmac_f32_e32 v154, v221, v221
	s_waitcnt vmcnt(37)
	v_pk_add_f32 v[222:223], v[222:223], v[70:71]
	v_pk_add_f32 v[224:225], v[224:225], v[72:73]
	v_add_u32_e32 v157, 0x30200, v144
	v_cvt_pk_bf16_f32 v158, v222, v223
	v_cvt_pk_bf16_f32 v159, v224, v225
	global_store_dwordx4 v157, v[222:225], s[26:27] nt
	v_add_u32_e32 v70, 0x18100, v146
	v_fmac_f32_e32 v155, v222, v222
	global_store_dwordx2 v70, v[158:159], s[96:97]
	v_fmac_f32_e32 v155, v223, v223
	v_fmac_f32_e32 v155, v224, v224
	v_fmac_f32_e32 v155, v225, v225
	s_waitcnt vmcnt(38)
	v_pk_add_f32 v[226:227], v[226:227], v[46:47]
	v_pk_add_f32 v[228:229], v[228:229], v[48:49]
	v_add_u32_e32 v160, 0x38200, v145
	v_cvt_pk_bf16_f32 v164, v226, v227
	v_cvt_pk_bf16_f32 v165, v228, v229
	global_store_dwordx4 v160, v[226:229], s[26:27] nt
	v_add_u32_e32 v46, 0x1c100, v147
	v_fmac_f32_e32 v156, v226, v226
	global_store_dwordx2 v46, v[164:165], s[96:97]
	v_fmac_f32_e32 v156, v227, v227
	v_fmac_f32_e32 v156, v228, v228
	v_fmac_f32_e32 v156, v229, v229
	v_add_u32_e32 v157, 0x100200, v144
	global_load_dwordx4 v[198:201], v157, s[4:5] nt
	v_add_u32_e32 v160, 0x108200, v145
	global_load_dwordx4 v[202:205], v160, s[4:5] nt
	v_add_u32_e32 v157, 0x110200, v144
	global_load_dwordx4 v[206:209], v157, s[4:5] nt
	v_add_u32_e32 v160, 0x118200, v145
	global_load_dwordx4 v[210:213], v160, s[4:5] nt
	v_add_u32_e32 v157, 0x120200, v144
	global_load_dwordx4 v[214:217], v157, s[4:5] nt
	v_add_u32_e32 v160, 0x128200, v145
	global_load_dwordx4 v[218:221], v160, s[4:5] nt
	v_add_u32_e32 v157, 0x130200, v144
	global_load_dwordx4 v[222:225], v157, s[4:5] nt
	v_add_u32_e32 v160, 0x138200, v145
	global_load_dwordx4 v[226:229], v160, s[4:5] nt
	v_add_f32_dpp v149, v149, v149 row_shr:1 row_mask:0xf bank_mask:0xf bound_ctrl:0
	v_add_f32_dpp v150, v150, v150 row_shr:1 row_mask:0xf bank_mask:0xf bound_ctrl:0
	v_add_f32_dpp v151, v151, v151 row_shr:1 row_mask:0xf bank_mask:0xf bound_ctrl:0
	v_add_f32_dpp v152, v152, v152 row_shr:1 row_mask:0xf bank_mask:0xf bound_ctrl:0
	v_add_f32_dpp v153, v153, v153 row_shr:1 row_mask:0xf bank_mask:0xf bound_ctrl:0
	v_add_f32_dpp v154, v154, v154 row_shr:1 row_mask:0xf bank_mask:0xf bound_ctrl:0
	v_add_f32_dpp v155, v155, v155 row_shr:1 row_mask:0xf bank_mask:0xf bound_ctrl:0
	v_add_f32_dpp v156, v156, v156 row_shr:1 row_mask:0xf bank_mask:0xf bound_ctrl:0
	v_add_f32_dpp v149, v149, v149 row_shr:2 row_mask:0xf bank_mask:0xf bound_ctrl:0
	v_add_f32_dpp v150, v150, v150 row_shr:2 row_mask:0xf bank_mask:0xf bound_ctrl:0
	v_add_f32_dpp v151, v151, v151 row_shr:2 row_mask:0xf bank_mask:0xf bound_ctrl:0
	v_add_f32_dpp v152, v152, v152 row_shr:2 row_mask:0xf bank_mask:0xf bound_ctrl:0
	v_add_f32_dpp v153, v153, v153 row_shr:2 row_mask:0xf bank_mask:0xf bound_ctrl:0
	v_add_f32_dpp v154, v154, v154 row_shr:2 row_mask:0xf bank_mask:0xf bound_ctrl:0
	v_add_f32_dpp v155, v155, v155 row_shr:2 row_mask:0xf bank_mask:0xf bound_ctrl:0
	v_add_f32_dpp v156, v156, v156 row_shr:2 row_mask:0xf bank_mask:0xf bound_ctrl:0
	v_add_f32_dpp v149, v149, v149 row_shr:4 row_mask:0xf bank_mask:0xf bound_ctrl:0
	v_add_f32_dpp v150, v150, v150 row_shr:4 row_mask:0xf bank_mask:0xf bound_ctrl:0
	v_add_f32_dpp v151, v151, v151 row_shr:4 row_mask:0xf bank_mask:0xf bound_ctrl:0
	v_add_f32_dpp v152, v152, v152 row_shr:4 row_mask:0xf bank_mask:0xf bound_ctrl:0
	v_add_f32_dpp v153, v153, v153 row_shr:4 row_mask:0xf bank_mask:0xf bound_ctrl:0
	v_add_f32_dpp v154, v154, v154 row_shr:4 row_mask:0xf bank_mask:0xf bound_ctrl:0
	v_add_f32_dpp v155, v155, v155 row_shr:4 row_mask:0xf bank_mask:0xf bound_ctrl:0
	v_add_f32_dpp v156, v156, v156 row_shr:4 row_mask:0xf bank_mask:0xf bound_ctrl:0
	v_add_f32_dpp v149, v149, v149 row_shr:8 row_mask:0xf bank_mask:0xf bound_ctrl:0
	v_add_f32_dpp v150, v150, v150 row_shr:8 row_mask:0xf bank_mask:0xf bound_ctrl:0
	v_add_f32_dpp v151, v151, v151 row_shr:8 row_mask:0xf bank_mask:0xf bound_ctrl:0
	v_add_f32_dpp v152, v152, v152 row_shr:8 row_mask:0xf bank_mask:0xf bound_ctrl:0
	v_add_f32_dpp v153, v153, v153 row_shr:8 row_mask:0xf bank_mask:0xf bound_ctrl:0
	v_add_f32_dpp v154, v154, v154 row_shr:8 row_mask:0xf bank_mask:0xf bound_ctrl:0
	v_add_f32_dpp v155, v155, v155 row_shr:8 row_mask:0xf bank_mask:0xf bound_ctrl:0
	v_add_f32_dpp v156, v156, v156 row_shr:8 row_mask:0xf bank_mask:0xf bound_ctrl:0
	v_cmp_eq_u32_e32 vcc, 15, v138
	s_and_saveexec_b64 s[6:7], vcc
	global_store_dword v148, v149, s[94:95]
	global_store_dword v148, v150, s[94:95] offset:16
	global_store_dword v148, v151, s[94:95] offset:32
	global_store_dword v148, v152, s[94:95] offset:48
	global_store_dword v148, v153, s[94:95] offset:64
	global_store_dword v148, v154, s[94:95] offset:80
	global_store_dword v148, v155, s[94:95] offset:96
	global_store_dword v148, v156, s[94:95] offset:112
	s_or_b64 exec, exec, s[6:7]
	s_waitcnt lgkmcnt(0)
; template <int EPI, int NRM>
; DEVI void epilogue(acc_t& acc, int pn, int trow, const EpiArgs& e, const float* rl, bf16* shmx) {
;     ...
;             const unsigned off = (unsigned)((tk0 + bj * 128 + n * 16) * DM + pn * 256 + ai * 128 + m * 16 + fl0);
;             const float4 xx = *reinterpret_cast<const float4*>(lbase + idx * 1024 + lane * 16);
;             float4 o;
;             o.x = xx.x + acc[ai][bj][m][n][0]; o.y = xx.y + acc[ai][bj][m][n][1];
;             o.z = xx.z + acc[ai][bj][m][n][2]; o.w = xx.w + acc[ai][bj][m][n][3];
;             *reinterpret_cast<float4*>(e.xout + off) = o;
;             uint2 ob; ob.x = pack2(o.x, o.y); ob.y = pack2(o.z, o.w);
;             *reinterpret_cast<uint2*>(e.o0 + off) = ob;
;             ss[bj][n] += o.x * o.x + o.y * o.y + o.z * o.z + o.w * o.w;
	ds_read_b128 v[50:53], v143
	ds_read_b128 v[58:61], v143 offset:1024
	ds_read_b128 v[62:65], v143 offset:2048
	ds_read_b128 v[66:69], v143 offset:3072
	ds_read_b128 v[74:77], v143 offset:4096
	ds_read_b128 v[82:85], v143 offset:5120
	ds_read_b128 v[90:93], v143 offset:6144
	ds_read_b128 v[98:101], v143 offset:7168
	ds_read_b128 v[38:41], v143 offset:8192
	ds_read_b128 v[34:37], v143 offset:9216
	ds_read_b128 v[30:33], v143 offset:10240
	ds_read_b128 v[22:25], v143 offset:11264
	ds_read_b128 v[18:21], v143 offset:12288
	ds_read_b128 v[10:13], v143 offset:13312
	ds_read_b128 v[6:9], v143 offset:14336
	ds_read_b128 v[2:5], v143 offset:15360
	s_waitcnt lgkmcnt(0)
	s_waitcnt vmcnt(39)
	v_pk_add_f32 v[166:167], v[166:167], v[50:51]
	v_pk_add_f32 v[168:169], v[168:169], v[52:53]
	v_add_u32_e32 v157, 0x100000, v144
	v_cvt_pk_bf16_f32 v158, v166, v167
	v_cvt_pk_bf16_f32 v159, v168, v169
	global_store_dwordx4 v157, v[166:169], s[26:27] nt
	v_add_u32_e32 v50, 0x80000, v146
	v_mul_f32_e32 v149, v166, v166
	global_store_dwordx2 v50, v[158:159], s[96:97]
	v_fmac_f32_e32 v149, v167, v167
	v_fmac_f32_e32 v149, v168, v168
	v_fmac_f32_e32 v149, v169, v169
	s_waitcnt vmcnt(40)
	v_pk_add_f32 v[170:171], v[170:171], v[58:59]
	v_pk_add_f32 v[172:173], v[172:173], v[60:61]
	v_add_u32_e32 v160, 0x108000, v145
	v_cvt_pk_bf16_f32 v164, v170, v171
	v_cvt_pk_bf16_f32 v165, v172, v173
	global_store_dwordx4 v160, v[170:173], s[26:27] nt
	v_add_u32_e32 v58, 0x84000, v147
	v_mul_f32_e32 v150, v170, v170
	global_store_dwordx2 v58, v[164:165], s[96:97]
	v_fmac_f32_e32 v150, v171, v171
	v_fmac_f32_e32 v150, v172, v172
	v_fmac_f32_e32 v150, v173, v173
	s_waitcnt vmcnt(41)
	v_pk_add_f32 v[174:175], v[174:175], v[62:63]
	v_pk_add_f32 v[176:177], v[176:177], v[64:65]
	v_add_u32_e32 v157, 0x110000, v144
	v_cvt_pk_bf16_f32 v158, v174, v175
	v_cvt_pk_bf16_f32 v159, v176, v177
	global_store_dwordx4 v157, v[174:177], s[26:27] nt
	v_add_u32_e32 v62, 0x88000, v146
	v_mul_f32_e32 v151, v174, v174
	global_store_dwordx2 v62, v[158:159], s[96:97]
	v_fmac_f32_e32 v151, v175, v175
	v_fmac_f32_e32 v151, v176, v176
	v_fmac_f32_e32 v151, v177, v177
	s_waitcnt vmcnt(42)
	v_pk_add_f32 v[178:179], v[178:179], v[66:67]
	v_pk_add_f32 v[180:181], v[180:181], v[68:69]
	v_add_u32_e32 v160, 0x118000, v145
	v_cvt_pk_bf16_f32 v164, v178, v179
	v_cvt_pk_bf16_f32 v165, v180, v181
	global_store_dwordx4 v160, v[178:181], s[26:27] nt
	v_add_u32_e32 v66, 0x8c000, v147
	v_mul_f32_e32 v152, v178, v178
	global_store_dwordx2 v66, v[164:165], s[96:97]
	v_fmac_f32_e32 v152, v179, v179
	v_fmac_f32_e32 v152, v180, v180
	v_fmac_f32_e32 v152, v181, v181
	s_waitcnt vmcnt(43)
	v_pk_add_f32 v[182:183], v[182:183], v[74:75]
	v_pk_add_f32 v[184:185], v[184:185], v[76:77]
	v_add_u32_e32 v157, 0x120000, v144
	v_cvt_pk_bf16_f32 v158, v182, v183
	v_cvt_pk_bf16_f32 v159, v184, v185
	global_store_dwordx4 v157, v[182:185], s[26:27] nt
	v_add_u32_e32 v74, 0x90000, v146
	v_mul_f32_e32 v153, v182, v182
	global_store_dwordx2 v74, v[158:159], s[96:97]
	v_fmac_f32_e32 v153, v183, v183
	v_fmac_f32_e32 v153, v184, v184
	v_fmac_f32_e32 v153, v185, v185
	s_waitcnt vmcnt(44)
	v_pk_add_f32 v[186:187], v[186:187], v[82:83]
	v_pk_add_f32 v[188:189], v[188:189], v[84:85]
	v_add_u32_e32 v160, 0x128000, v145
	v_cvt_pk_bf16_f32 v164, v186, v187
	v_cvt_pk_bf16_f32 v165, v188, v189
	global_store_dwordx4 v160, v[186:189], s[26:27] nt
	v_add_u32_e32 v82, 0x94000, v147
	v_mul_f32_e32 v154, v186, v186
	global_store_dwordx2 v82, v[164:165], s[96:97]
	v_fmac_f32_e32 v154, v187, v187
	v_fmac_f32_e32 v154, v188, v188
	v_fmac_f32_e32 v154, v189, v189
	s_waitcnt vmcnt(45)
	v_pk_add_f32 v[190:191], v[190:191], v[90:91]
	v_pk_add_f32 v[192:193], v[192:193], v[92:93]
	v_add_u32_e32 v157, 0x130000, v144
	v_cvt_pk_bf16_f32 v158, v190, v191
	v_cvt_pk_bf16_f32 v159, v192, v193
	global_store_dwordx4 v157, v[190:193], s[26:27] nt
	v_add_u32_e32 v90, 0x98000, v146
	v_mul_f32_e32 v155, v190, v190
	global_store_dwordx2 v90, v[158:159], s[96:97]
	v_fmac_f32_e32 v155, v191, v191
	v_fmac_f32_e32 v155, v192, v192
	v_fmac_f32_e32 v155, v193, v193
	s_waitcnt vmcnt(46)
	v_pk_add_f32 v[194:195], v[194:195], v[98:99]
	v_pk_add_f32 v[196:197], v[196:197], v[100:101]
	v_add_u32_e32 v160, 0x138000, v145
	v_cvt_pk_bf16_f32 v164, v194, v195
	v_cvt_pk_bf16_f32 v165, v196, v197
	global_store_dwordx4 v160, v[194:197], s[26:27] nt
	v_add_u32_e32 v98, 0x9c000, v147
	v_mul_f32_e32 v156, v194, v194
	global_store_dwordx2 v98, v[164:165], s[96:97]
	v_fmac_f32_e32 v156, v195, v195
	v_fmac_f32_e32 v156, v196, v196
	v_fmac_f32_e32 v156, v197, v197
	s_waitcnt vmcnt(31)
	v_pk_add_f32 v[198:199], v[198:199], v[38:39]
	v_pk_add_f32 v[200:201], v[200:201], v[40:41]
	v_add_u32_e32 v157, 0x100200, v144
	v_cvt_pk_bf16_f32 v158, v198, v199
	v_cvt_pk_bf16_f32 v159, v200, v201
	global_store_dwordx4 v157, v[198:201], s[26:27] nt
	v_add_u32_e32 v38, 0x80100, v146
	v_fmac_f32_e32 v149, v198, v198
	global_store_dwordx2 v38, v[158:159], s[96:97]
	v_fmac_f32_e32 v149, v199, v199
	v_fmac_f32_e32 v149, v200, v200
	v_fmac_f32_e32 v149, v201, v201
	s_waitcnt vmcnt(32)
	v_pk_add_f32 v[202:203], v[202:203], v[34:35]
	v_pk_add_f32 v[204:205], v[204:205], v[36:37]
	v_add_u32_e32 v160, 0x108200, v145
	v_cvt_pk_bf16_f32 v164, v202, v203
	v_cvt_pk_bf16_f32 v165, v204, v205
	global_store_dwordx4 v160, v[202:205], s[26:27] nt
	v_add_u32_e32 v34, 0x84100, v147
	v_fmac_f32_e32 v150, v202, v202
	global_store_dwordx2 v34, v[164:165], s[96:97]
	v_fmac_f32_e32 v150, v203, v203
	v_fmac_f32_e32 v150, v204, v204
	v_fmac_f32_e32 v150, v205, v205
	s_waitcnt vmcnt(33)
; template <int EPI, int NRM>
; DEVI void epilogue(acc_t& acc, int pn, int trow, const EpiArgs& e, const float* rl, bf16* shmx) {
;     ...
;             const unsigned off = (unsigned)((tk0 + bj * 128 + n * 16) * DM + pn * 256 + ai * 128 + m * 16 + fl0);
;             const float4 xx = *reinterpret_cast<const float4*>(lbase + idx * 1024 + lane * 16);
;             float4 o;
;             o.x = xx.x + acc[ai][bj][m][n][0]; o.y = xx.y + acc[ai][bj][m][n][1];
;             o.z = xx.z + acc[ai][bj][m][n][2]; o.w = xx.w + acc[ai][bj][m][n][3];
;             *reinterpret_cast<float4*>(e.xout + off) = o;
;             uint2 ob; ob.x = pack2(o.x, o.y); ob.y = pack2(o.z, o.w);
;             *reinterpret_cast<uint2*>(e.o0 + off) = ob;
;             ss[bj][n] += o.x * o.x + o.y * o.y + o.z * o.z + o.w * o.w;
;           }
;       asm volatile("s_waitcnt lgkmcnt(0)" ::: "memory");
;     }
; #pragma unroll
;     for (int bj = 0; bj < 2; ++bj)
; #pragma unroll
;       for (int n = 0; n < 2; ++n) {
;         float v = ss[bj][n];
;         v += __shfl_xor(v, 16); v += __shfl_xor(v, 32);
;         if (fq == 0) e.stw[(pn * 2 + wr) * TOK + tk0 + bj * 128 + n * 16] = v;
;       }
	v_pk_add_f32 v[206:207], v[206:207], v[30:31]
	v_pk_add_f32 v[208:209], v[208:209], v[32:33]
	v_add_u32_e32 v157, 0x110200, v144
	v_cvt_pk_bf16_f32 v158, v206, v207
	v_cvt_pk_bf16_f32 v159, v208, v209
	global_store_dwordx4 v157, v[206:209], s[26:27] nt
	v_add_u32_e32 v30, 0x88100, v146
	v_fmac_f32_e32 v151, v206, v206
	global_store_dwordx2 v30, v[158:159], s[96:97]
	v_fmac_f32_e32 v151, v207, v207
	v_fmac_f32_e32 v151, v208, v208
	v_fmac_f32_e32 v151, v209, v209
	s_waitcnt vmcnt(34)
	v_pk_add_f32 v[210:211], v[210:211], v[22:23]
	v_pk_add_f32 v[212:213], v[212:213], v[24:25]
	v_add_u32_e32 v160, 0x118200, v145
	v_cvt_pk_bf16_f32 v164, v210, v211
	v_cvt_pk_bf16_f32 v165, v212, v213
	global_store_dwordx4 v160, v[210:213], s[26:27] nt
	v_add_u32_e32 v22, 0x8c100, v147
	v_fmac_f32_e32 v152, v210, v210
	global_store_dwordx2 v22, v[164:165], s[96:97]
	v_fmac_f32_e32 v152, v211, v211
	v_fmac_f32_e32 v152, v212, v212
	v_fmac_f32_e32 v152, v213, v213
	s_waitcnt vmcnt(35)
	v_pk_add_f32 v[214:215], v[214:215], v[18:19]
	v_pk_add_f32 v[216:217], v[216:217], v[20:21]
	v_add_u32_e32 v157, 0x120200, v144
	v_cvt_pk_bf16_f32 v158, v214, v215
	v_cvt_pk_bf16_f32 v159, v216, v217
	global_store_dwordx4 v157, v[214:217], s[26:27] nt
	v_add_u32_e32 v18, 0x90100, v146
	v_fmac_f32_e32 v153, v214, v214
	global_store_dwordx2 v18, v[158:159], s[96:97]
	v_fmac_f32_e32 v153, v215, v215
	v_fmac_f32_e32 v153, v216, v216
	v_fmac_f32_e32 v153, v217, v217
	s_waitcnt vmcnt(36)
	v_pk_add_f32 v[218:219], v[218:219], v[10:11]
	v_pk_add_f32 v[220:221], v[220:221], v[12:13]
	v_add_u32_e32 v160, 0x128200, v145
	v_cvt_pk_bf16_f32 v164, v218, v219
	v_cvt_pk_bf16_f32 v165, v220, v221
	global_store_dwordx4 v160, v[218:221], s[26:27] nt
	v_add_u32_e32 v10, 0x94100, v147
	v_fmac_f32_e32 v154, v218, v218
	global_store_dwordx2 v10, v[164:165], s[96:97]
	v_fmac_f32_e32 v154, v219, v219
	v_fmac_f32_e32 v154, v220, v220
	v_fmac_f32_e32 v154, v221, v221
	s_waitcnt vmcnt(37)
	v_pk_add_f32 v[222:223], v[222:223], v[6:7]
	v_pk_add_f32 v[224:225], v[224:225], v[8:9]
	v_add_u32_e32 v157, 0x130200, v144
	v_cvt_pk_bf16_f32 v158, v222, v223
	v_cvt_pk_bf16_f32 v159, v224, v225
	global_store_dwordx4 v157, v[222:225], s[26:27] nt
	v_add_u32_e32 v6, 0x98100, v146
	v_fmac_f32_e32 v155, v222, v222
	global_store_dwordx2 v6, v[158:159], s[96:97]
	v_fmac_f32_e32 v155, v223, v223
	v_fmac_f32_e32 v155, v224, v224
	v_fmac_f32_e32 v155, v225, v225
	s_waitcnt vmcnt(38)
	v_pk_add_f32 v[226:227], v[226:227], v[2:3]
	v_pk_add_f32 v[228:229], v[228:229], v[4:5]
	v_add_u32_e32 v160, 0x138200, v145
	v_cvt_pk_bf16_f32 v164, v226, v227
	v_cvt_pk_bf16_f32 v165, v228, v229
	global_store_dwordx4 v160, v[226:229], s[26:27] nt
	v_add_u32_e32 v2, 0x9c100, v147
	v_fmac_f32_e32 v156, v226, v226
	global_store_dwordx2 v2, v[164:165], s[96:97]
	v_fmac_f32_e32 v156, v227, v227
	v_fmac_f32_e32 v156, v228, v228
	v_fmac_f32_e32 v156, v229, v229
	v_add_f32_dpp v149, v149, v149 row_shr:1 row_mask:0xf bank_mask:0xf bound_ctrl:0
	v_add_f32_dpp v150, v150, v150 row_shr:1 row_mask:0xf bank_mask:0xf bound_ctrl:0
	v_add_f32_dpp v151, v151, v151 row_shr:1 row_mask:0xf bank_mask:0xf bound_ctrl:0
	v_add_f32_dpp v152, v152, v152 row_shr:1 row_mask:0xf bank_mask:0xf bound_ctrl:0
	v_add_f32_dpp v153, v153, v153 row_shr:1 row_mask:0xf bank_mask:0xf bound_ctrl:0
	v_add_f32_dpp v154, v154, v154 row_shr:1 row_mask:0xf bank_mask:0xf bound_ctrl:0
	v_add_f32_dpp v155, v155, v155 row_shr:1 row_mask:0xf bank_mask:0xf bound_ctrl:0
	v_add_f32_dpp v156, v156, v156 row_shr:1 row_mask:0xf bank_mask:0xf bound_ctrl:0
	v_add_f32_dpp v149, v149, v149 row_shr:2 row_mask:0xf bank_mask:0xf bound_ctrl:0
	v_add_f32_dpp v150, v150, v150 row_shr:2 row_mask:0xf bank_mask:0xf bound_ctrl:0
	v_add_f32_dpp v151, v151, v151 row_shr:2 row_mask:0xf bank_mask:0xf bound_ctrl:0
	v_add_f32_dpp v152, v152, v152 row_shr:2 row_mask:0xf bank_mask:0xf bound_ctrl:0
	v_add_f32_dpp v153, v153, v153 row_shr:2 row_mask:0xf bank_mask:0xf bound_ctrl:0
	v_add_f32_dpp v154, v154, v154 row_shr:2 row_mask:0xf bank_mask:0xf bound_ctrl:0
	v_add_f32_dpp v155, v155, v155 row_shr:2 row_mask:0xf bank_mask:0xf bound_ctrl:0
	v_add_f32_dpp v156, v156, v156 row_shr:2 row_mask:0xf bank_mask:0xf bound_ctrl:0
	v_add_f32_dpp v149, v149, v149 row_shr:4 row_mask:0xf bank_mask:0xf bound_ctrl:0
	v_add_f32_dpp v150, v150, v150 row_shr:4 row_mask:0xf bank_mask:0xf bound_ctrl:0
	v_add_f32_dpp v151, v151, v151 row_shr:4 row_mask:0xf bank_mask:0xf bound_ctrl:0
	v_add_f32_dpp v152, v152, v152 row_shr:4 row_mask:0xf bank_mask:0xf bound_ctrl:0
	v_add_f32_dpp v153, v153, v153 row_shr:4 row_mask:0xf bank_mask:0xf bound_ctrl:0
	v_add_f32_dpp v154, v154, v154 row_shr:4 row_mask:0xf bank_mask:0xf bound_ctrl:0
	v_add_f32_dpp v155, v155, v155 row_shr:4 row_mask:0xf bank_mask:0xf bound_ctrl:0
	v_add_f32_dpp v156, v156, v156 row_shr:4 row_mask:0xf bank_mask:0xf bound_ctrl:0
	v_add_f32_dpp v149, v149, v149 row_shr:8 row_mask:0xf bank_mask:0xf bound_ctrl:0
	v_add_f32_dpp v150, v150, v150 row_shr:8 row_mask:0xf bank_mask:0xf bound_ctrl:0
	v_add_f32_dpp v151, v151, v151 row_shr:8 row_mask:0xf bank_mask:0xf bound_ctrl:0
	v_add_f32_dpp v152, v152, v152 row_shr:8 row_mask:0xf bank_mask:0xf bound_ctrl:0
	v_add_f32_dpp v153, v153, v153 row_shr:8 row_mask:0xf bank_mask:0xf bound_ctrl:0
	v_add_f32_dpp v154, v154, v154 row_shr:8 row_mask:0xf bank_mask:0xf bound_ctrl:0
	v_add_f32_dpp v155, v155, v155 row_shr:8 row_mask:0xf bank_mask:0xf bound_ctrl:0
	v_add_f32_dpp v156, v156, v156 row_shr:8 row_mask:0xf bank_mask:0xf bound_ctrl:0
	v_cmp_eq_u32_e32 vcc, 15, v138
	s_and_saveexec_b64 s[6:7], vcc
	global_store_dword v148, v149, s[94:95] offset:512
	global_store_dword v148, v150, s[94:95] offset:528
	global_store_dword v148, v151, s[94:95] offset:544
	global_store_dword v148, v152, s[94:95] offset:560
	global_store_dword v148, v153, s[94:95] offset:576
	global_store_dword v148, v154, s[94:95] offset:592
	global_store_dword v148, v155, s[94:95] offset:608
	global_store_dword v148, v156, s[94:95] offset:624
	s_branch .LBB0_1606

; DEVI float silu(float x) { return x * __builtin_amdgcn_rcpf(1.f + __expf(-x)); }
; template <int EPI, int NRM>
; DEVI void epilogue(acc_t& acc, int pn, int trow, const EpiArgs& e, const float* rl, bf16* shmx) {
;     ...
;   if constexpr (NRM) {
; #pragma unroll
;     for (int bj = 0; bj < 2; ++bj)
; #pragma unroll
;       for (int n = 0; n < 2; ++n) rs[bj][n] = rl[wc * 32 + fr + bj * 128 + n * 16];
;     ...
;   } else if constexpr (EPI == EPI_SWIGLU) {
; #pragma unroll
;     for (int bj = 0; bj < 2; ++bj)
; #pragma unroll
;       for (int m = 0; m < 4; ++m)
; #pragma unroll
;         for (int n = 0; n < 2; ++n) {
;           float r[4];
; #pragma unroll
;           for (int j = 0; j < 4; ++j) r[j] = silu(acc[0][bj][m][n][j] * rs[bj][n]) * (acc[1][bj][m][n][j] * rs[bj][n]);
;           uint2 o; o.x = pack2(r[0], r[1]); o.y = pack2(r[2], r[3]);
;           const unsigned off = (unsigned)((tk0 + bj * 128 + n * 16) * DFF + pn * 128 + m * 16 + fl0);
;           *reinterpret_cast<uint2*>(e.o0 + off) = o;
;         }
.LBB0_1655:
	v_and_b32_e32 v170, 15, v131
	v_bfe_u32 v171, v131, 4, 2
	v_lshrrev_b32_e32 v172, 6, v131
	v_and_b32_e32 v173, 3, v172
	v_lshrrev_b32_e32 v174, 2, v172
	v_lshlrev_b32_e32 v175, 13, v173
	v_lshl_add_u32 v175, v174, 16, v175
	v_add_u32_e32 v175, 0x8000, v175
	v_lshl_add_u32 v176, v170, 7, v175
	v_and_b32_e32 v177, 1, v171
	v_lshl_add_u32 v176, v177, 3, v176
	v_lshrrev_b32_e32 v177, 1, v171
	v_and_b32_e32 v178, 7, v170
	v_add_u32_e32 v179, 0, v177
	v_xor_b32_e32 v179, v179, v178
	v_lshl_add_u32 v164, v179, 4, v176
	v_add_u32_e32 v179, 2, v177
	v_xor_b32_e32 v179, v179, v178
	v_lshl_add_u32 v165, v179, 4, v176
	v_add_u32_e32 v179, 4, v177
	v_xor_b32_e32 v179, v179, v178
	v_lshl_add_u32 v166, v179, 4, v176
	v_add_u32_e32 v179, 6, v177
	v_xor_b32_e32 v179, v179, v178
	v_lshl_add_u32 v167, v179, 4, v176
	v_and_b32_e32 v180, 63, v131
	v_lshl_add_u32 v168, v180, 4, v175
	v_lshrrev_b32_e32 v181, 3, v180
	v_and_b32_e32 v182, 7, v180
	v_xor_b32_e32 v182, v182, v181
	s_lshl_b32 s9, s12, 8
	v_lshl_add_u32 v183, v173, 5, v181
	v_add_u32_e32 v183, s9, v183
	v_mul_u32_u24_e32 v183, 0x1600, v183
	s_lshl_b32 s9, s14, 7
	v_lshl_add_u32 v179, v174, 6, s9
	v_lshl_add_u32 v179, v182, 3, v179
	v_add_lshl_u32 v169, v183, v179, 1
	v_mov_b32_e32 v132, v131
	s_lshl_b32 s11, s16, 10
	s_and_b32 s11, s11, 0x400
	v_and_b32_e32 v142, 15, v132
	v_ashrrev_i32_e32 v143, 2, v132
	v_lshrrev_b32_e32 v144, 2, v132
	v_lshrrev_b32_e32 v132, 1, v132
	s_add_i32 s11, s11, 0
	v_and_b32_e32 v132, 0x60, v132
	s_add_i32 s11, s11, 0x20000
	v_lshlrev_b32_e32 v134, 2, v132
	v_lshlrev_b32_e32 v135, 2, v142
	v_add3_u32 v134, s11, v134, v135
	ds_read2_b32 v[136:137], v134 offset1:16
	ds_read2_b32 v[134:135], v134 offset0:128 offset1:144
	s_lshl_b32 s9, s12, 8
	v_or3_b32 v132, v142, s9, v132
	s_lshl_b32 s9, s14, 7
	s_waitcnt lgkmcnt(1)
	v_pk_mul_f32 v[122:123], v[122:123], v[136:137] op_sel_hi:[1,0]
	v_and_or_b32 v142, v144, 12, s9
	v_mul_f32_e32 v144, 0xbfb8aa3b, v122
	v_mul_f32_e32 v145, 0xbfb8aa3b, v123
	v_exp_f32_e32 v144, v144
	v_exp_f32_e32 v145, v145
	v_and_b32_e32 v143, 0xffffffc0, v143
	v_pk_mul_f32 v[124:125], v[124:125], v[136:137] op_sel_hi:[1,0]
	v_add_u32_e32 v146, v142, v143
	v_add_f32_e32 v142, 1.0, v144
	v_add_f32_e32 v143, 1.0, v145
	v_mul_f32_e32 v144, 0xbfb8aa3b, v124
	v_mul_f32_e32 v145, 0xbfb8aa3b, v125
	v_rcp_f32_e32 v142, v142
	v_rcp_f32_e32 v143, v143
	v_exp_f32_e32 v144, v144
	v_exp_f32_e32 v145, v145
	v_pk_mul_f32 v[126:127], v[126:127], v[136:137] op_sel_hi:[1,0]
	v_pk_mul_f32 v[122:123], v[122:123], v[142:143]
	v_add_f32_e32 v142, 1.0, v144
	v_add_f32_e32 v143, 1.0, v145
	v_rcp_f32_e32 v142, v142
	v_rcp_f32_e32 v143, v143
	v_pk_mul_f32 v[122:123], v[126:127], v[122:123]
	v_pk_mul_f32 v[106:107], v[106:107], v[136:137] op_sel_hi:[1,0]
	v_cvt_pk_bf16_f32 v126, v122, v123
	v_pk_mul_f32 v[122:123], v[124:125], v[142:143]
	v_pk_mul_f32 v[124:125], v[128:129], v[136:137] op_sel_hi:[1,0]
	v_pk_mul_f32 v[108:109], v[108:109], v[136:137] op_sel_hi:[1,0]
	v_pk_mul_f32 v[122:123], v[124:125], v[122:123]
	v_pk_mul_f32 v[110:111], v[110:111], v[136:137] op_sel_hi:[1,0]
	v_cvt_pk_bf16_f32 v127, v122, v123
	v_mul_lo_u32 v123, v132, s41
	v_mov_b32_e32 v122, v137
	v_pk_mul_f32 v[114:115], v[114:115], v[122:123] op_sel_hi:[1,0]
	v_add_u32_e32 v132, v146, v123
	v_mul_f32_e32 v128, 0xbfb8aa3b, v114
	v_mul_f32_e32 v129, 0xbfb8aa3b, v115
	v_exp_f32_e32 v128, v128
	v_exp_f32_e32 v129, v129
	v_lshl_add_u64 v[124:125], v[132:133], 1, s[2:3]
	v_pk_mul_f32 v[116:117], v[116:117], v[122:123] op_sel_hi:[1,0]
	ds_write_b64 v164, v[126:127]
	v_add_f32_e32 v124, 1.0, v128
	v_add_f32_e32 v125, 1.0, v129
	v_mul_f32_e32 v126, 0xbfb8aa3b, v116
	v_mul_f32_e32 v127, 0xbfb8aa3b, v117
	v_rcp_f32_e32 v124, v124
	v_rcp_f32_e32 v125, v125
	v_exp_f32_e32 v126, v126
	v_exp_f32_e32 v127, v127
	v_pk_mul_f32 v[118:119], v[118:119], v[122:123] op_sel_hi:[1,0]
	v_pk_mul_f32 v[114:115], v[114:115], v[124:125]
	v_add_f32_e32 v124, 1.0, v126
	v_add_f32_e32 v125, 1.0, v127
	v_rcp_f32_e32 v124, v124
	v_rcp_f32_e32 v125, v125
	v_pk_mul_f32 v[114:115], v[118:119], v[114:115]
	v_pk_mul_f32 v[118:119], v[120:121], v[122:123] op_sel_hi:[1,0]
	v_cvt_pk_bf16_f32 v114, v114, v115
	v_pk_mul_f32 v[116:117], v[116:117], v[124:125]
	v_pk_mul_f32 v[98:99], v[98:99], v[122:123] op_sel_hi:[1,0]
	v_pk_mul_f32 v[116:117], v[118:119], v[116:117]
	v_add_u32_e32 v118, 0x16000, v123
	v_add_u32_e32 v132, v118, v146
	v_cvt_pk_bf16_f32 v115, v116, v117
	v_lshl_add_u64 v[116:117], v[132:133], 1, s[2:3]
	ds_write_b64 v164, v[114:115] offset:2048
	v_mul_f32_e32 v114, 0xbfb8aa3b, v106
	v_mul_f32_e32 v115, 0xbfb8aa3b, v107
	v_exp_f32_e32 v114, v114
	v_exp_f32_e32 v115, v115
	v_mul_f32_e32 v117, 0xbfb8aa3b, v108
	v_mul_f32_e32 v119, 0xbfb8aa3b, v109
	v_add_f32_e32 v114, 1.0, v114
	v_add_f32_e32 v115, 1.0, v115
	v_rcp_f32_e32 v114, v114
	v_rcp_f32_e32 v115, v115
	v_exp_f32_e32 v117, v117
	v_exp_f32_e32 v119, v119
	v_or_b32_e32 v116, 16, v146
	v_pk_mul_f32 v[106:107], v[106:107], v[114:115]
	v_add_f32_e32 v114, 1.0, v117
	v_add_f32_e32 v115, 1.0, v119
	v_rcp_f32_e32 v114, v114
	v_rcp_f32_e32 v115, v115
	v_pk_mul_f32 v[106:107], v[110:111], v[106:107]
	v_pk_mul_f32 v[110:111], v[112:113], v[136:137] op_sel_hi:[1,0]
	v_add_u32_e32 v132, v116, v123
	v_pk_mul_f32 v[108:109], v[108:109], v[114:115]
	v_cvt_pk_bf16_f32 v106, v106, v107
	v_pk_mul_f32 v[108:109], v[110:111], v[108:109]
	v_mul_f32_e32 v110, 0xbfb8aa3b, v98
	v_mul_f32_e32 v111, 0xbfb8aa3b, v99
	v_exp_f32_e32 v110, v110
	v_exp_f32_e32 v111, v111
	v_cvt_pk_bf16_f32 v107, v108, v109
	v_lshl_add_u64 v[108:109], v[132:133], 1, s[2:3]
	v_pk_mul_f32 v[100:101], v[100:101], v[122:123] op_sel_hi:[1,0]
; DEVI float silu(float x) { return x * __builtin_amdgcn_rcpf(1.f + __expf(-x)); }
; template <int EPI, int NRM>
; DEVI void epilogue(acc_t& acc, int pn, int trow, const EpiArgs& e, const float* rl, bf16* shmx) {
;     ...
;   } else if constexpr (EPI == EPI_SWIGLU) {
; #pragma unroll
;     for (int bj = 0; bj < 2; ++bj)
; #pragma unroll
;       for (int m = 0; m < 4; ++m)
; #pragma unroll
;         for (int n = 0; n < 2; ++n) {
;           float r[4];
; #pragma unroll
;           for (int j = 0; j < 4; ++j) r[j] = silu(acc[0][bj][m][n][j] * rs[bj][n]) * (acc[1][bj][m][n][j] * rs[bj][n]);
;           uint2 o; o.x = pack2(r[0], r[1]); o.y = pack2(r[2], r[3]);
;           const unsigned off = (unsigned)((tk0 + bj * 128 + n * 16) * DFF + pn * 128 + m * 16 + fl0);
;           *reinterpret_cast<uint2*>(e.o0 + off) = o;
;         }
	ds_write_b64 v165, v[106:107]
	v_add_f32_e32 v106, 1.0, v110
	v_add_f32_e32 v107, 1.0, v111
	v_mul_f32_e32 v108, 0xbfb8aa3b, v100
	v_mul_f32_e32 v109, 0xbfb8aa3b, v101
	v_rcp_f32_e32 v106, v106
	v_rcp_f32_e32 v107, v107
	v_exp_f32_e32 v108, v108
	v_exp_f32_e32 v109, v109
	v_pk_mul_f32 v[102:103], v[102:103], v[122:123] op_sel_hi:[1,0]
	v_pk_mul_f32 v[98:99], v[98:99], v[106:107]
	v_add_f32_e32 v106, 1.0, v108
	v_add_f32_e32 v107, 1.0, v109
	v_rcp_f32_e32 v106, v106
	v_rcp_f32_e32 v107, v107
	v_pk_mul_f32 v[98:99], v[102:103], v[98:99]
	v_pk_mul_f32 v[102:103], v[104:105], v[122:123] op_sel_hi:[1,0]
	v_add_u32_e32 v132, v116, v118
	v_pk_mul_f32 v[100:101], v[100:101], v[106:107]
	v_cvt_pk_bf16_f32 v98, v98, v99
	v_pk_mul_f32 v[100:101], v[102:103], v[100:101]
	v_pk_mul_f32 v[90:91], v[90:91], v[136:137] op_sel_hi:[1,0]
	v_cvt_pk_bf16_f32 v99, v100, v101
	v_lshl_add_u64 v[100:101], v[132:133], 1, s[2:3]
	ds_write_b64 v165, v[98:99] offset:2048
	v_mul_f32_e32 v98, 0xbfb8aa3b, v90
	v_mul_f32_e32 v99, 0xbfb8aa3b, v91
	v_exp_f32_e32 v98, v98
	v_exp_f32_e32 v99, v99
	v_pk_mul_f32 v[92:93], v[92:93], v[136:137] op_sel_hi:[1,0]
	v_pk_mul_f32 v[94:95], v[94:95], v[136:137] op_sel_hi:[1,0]
	v_add_f32_e32 v98, 1.0, v98
	v_add_f32_e32 v99, 1.0, v99
	v_mul_f32_e32 v101, 0xbfb8aa3b, v92
	v_mul_f32_e32 v102, 0xbfb8aa3b, v93
	v_rcp_f32_e32 v98, v98
	v_rcp_f32_e32 v99, v99
	v_exp_f32_e32 v101, v101
	v_exp_f32_e32 v102, v102
	v_pk_mul_f32 v[82:83], v[82:83], v[122:123] op_sel_hi:[1,0]
	v_pk_mul_f32 v[90:91], v[90:91], v[98:99]
	v_add_f32_e32 v98, 1.0, v101
	v_add_f32_e32 v99, 1.0, v102
	v_rcp_f32_e32 v98, v98
	v_rcp_f32_e32 v99, v99
	v_pk_mul_f32 v[90:91], v[94:95], v[90:91]
	v_pk_mul_f32 v[94:95], v[96:97], v[136:137] op_sel_hi:[1,0]
	v_or_b32_e32 v100, 32, v146
	v_pk_mul_f32 v[92:93], v[92:93], v[98:99]
	v_add_u32_e32 v132, v100, v123
	v_pk_mul_f32 v[92:93], v[94:95], v[92:93]
	v_mul_f32_e32 v94, 0xbfb8aa3b, v82
	v_mul_f32_e32 v95, 0xbfb8aa3b, v83
	v_exp_f32_e32 v94, v94
	v_exp_f32_e32 v95, v95
	v_cvt_pk_bf16_f32 v90, v90, v91
	v_cvt_pk_bf16_f32 v91, v92, v93
	v_lshl_add_u64 v[92:93], v[132:133], 1, s[2:3]
	v_pk_mul_f32 v[84:85], v[84:85], v[122:123] op_sel_hi:[1,0]
	ds_write_b64 v166, v[90:91]
	v_add_f32_e32 v90, 1.0, v94
	v_add_f32_e32 v91, 1.0, v95
	v_mul_f32_e32 v92, 0xbfb8aa3b, v84
	v_mul_f32_e32 v93, 0xbfb8aa3b, v85
	v_rcp_f32_e32 v90, v90
	v_rcp_f32_e32 v91, v91
	v_exp_f32_e32 v92, v92
	v_exp_f32_e32 v93, v93
	v_pk_mul_f32 v[86:87], v[86:87], v[122:123] op_sel_hi:[1,0]
	v_pk_mul_f32 v[82:83], v[82:83], v[90:91]
	v_add_f32_e32 v90, 1.0, v92
	v_add_f32_e32 v91, 1.0, v93
	v_rcp_f32_e32 v90, v90
	v_rcp_f32_e32 v91, v91
	v_pk_mul_f32 v[82:83], v[86:87], v[82:83]
	v_pk_mul_f32 v[86:87], v[88:89], v[122:123] op_sel_hi:[1,0]
	v_add_u32_e32 v132, v100, v118
	v_pk_mul_f32 v[84:85], v[84:85], v[90:91]
	v_cvt_pk_bf16_f32 v82, v82, v83
	v_pk_mul_f32 v[84:85], v[86:87], v[84:85]
	v_pk_mul_f32 v[74:75], v[74:75], v[136:137] op_sel_hi:[1,0]
	v_cvt_pk_bf16_f32 v83, v84, v85
	v_lshl_add_u64 v[84:85], v[132:133], 1, s[2:3]
	ds_write_b64 v166, v[82:83] offset:2048
	v_mul_f32_e32 v82, 0xbfb8aa3b, v74
	v_mul_f32_e32 v83, 0xbfb8aa3b, v75
	v_exp_f32_e32 v82, v82
	v_exp_f32_e32 v83, v83
	v_pk_mul_f32 v[76:77], v[76:77], v[136:137] op_sel_hi:[1,0]
	v_pk_mul_f32 v[78:79], v[78:79], v[136:137] op_sel_hi:[1,0]
	v_add_f32_e32 v82, 1.0, v82
	v_add_f32_e32 v83, 1.0, v83
	v_mul_f32_e32 v85, 0xbfb8aa3b, v76
	v_mul_f32_e32 v86, 0xbfb8aa3b, v77
	v_rcp_f32_e32 v82, v82
	v_rcp_f32_e32 v83, v83
	v_exp_f32_e32 v85, v85
	v_exp_f32_e32 v86, v86
	v_pk_mul_f32 v[66:67], v[66:67], v[122:123] op_sel_hi:[1,0]
	v_pk_mul_f32 v[74:75], v[74:75], v[82:83]
	v_add_f32_e32 v82, 1.0, v85
	v_add_f32_e32 v83, 1.0, v86
	v_rcp_f32_e32 v82, v82
	v_rcp_f32_e32 v83, v83
	v_pk_mul_f32 v[74:75], v[78:79], v[74:75]
	v_pk_mul_f32 v[78:79], v[80:81], v[136:137] op_sel_hi:[1,0]
	v_or_b32_e32 v84, 48, v146
	v_pk_mul_f32 v[76:77], v[76:77], v[82:83]
	v_add_u32_e32 v132, v84, v123
	v_pk_mul_f32 v[76:77], v[78:79], v[76:77]
	v_mul_f32_e32 v78, 0xbfb8aa3b, v66
	v_mul_f32_e32 v79, 0xbfb8aa3b, v67
	v_exp_f32_e32 v78, v78
	v_exp_f32_e32 v79, v79
	v_cvt_pk_bf16_f32 v74, v74, v75
	v_cvt_pk_bf16_f32 v75, v76, v77
	v_lshl_add_u64 v[76:77], v[132:133], 1, s[2:3]
	v_pk_mul_f32 v[68:69], v[68:69], v[122:123] op_sel_hi:[1,0]
	ds_write_b64 v167, v[74:75]
	v_add_f32_e32 v74, 1.0, v78
	v_add_f32_e32 v75, 1.0, v79
	v_mul_f32_e32 v76, 0xbfb8aa3b, v68
	v_mul_f32_e32 v77, 0xbfb8aa3b, v69
	v_rcp_f32_e32 v74, v74
	v_rcp_f32_e32 v75, v75
	v_exp_f32_e32 v76, v76
	v_exp_f32_e32 v77, v77
	v_pk_mul_f32 v[70:71], v[70:71], v[122:123] op_sel_hi:[1,0]
	v_pk_mul_f32 v[66:67], v[66:67], v[74:75]
	v_add_f32_e32 v74, 1.0, v76
	v_add_f32_e32 v75, 1.0, v77
	v_rcp_f32_e32 v74, v74
	v_rcp_f32_e32 v75, v75
	v_pk_mul_f32 v[66:67], v[70:71], v[66:67]
	v_pk_mul_f32 v[70:71], v[72:73], v[122:123] op_sel_hi:[1,0]
	s_waitcnt lgkmcnt(0)
; DEVI float silu(float x) { return x * __builtin_amdgcn_rcpf(1.f + __expf(-x)); }
; template <int EPI, int NRM>
; DEVI void epilogue(acc_t& acc, int pn, int trow, const EpiArgs& e, const float* rl, bf16* shmx) {
;     ...
;   } else if constexpr (EPI == EPI_SWIGLU) {
; #pragma unroll
;     for (int bj = 0; bj < 2; ++bj)
; #pragma unroll
;       for (int m = 0; m < 4; ++m)
; #pragma unroll
;         for (int n = 0; n < 2; ++n) {
;           float r[4];
; #pragma unroll
;           for (int j = 0; j < 4; ++j) r[j] = silu(acc[0][bj][m][n][j] * rs[bj][n]) * (acc[1][bj][m][n][j] * rs[bj][n]);
;           uint2 o; o.x = pack2(r[0], r[1]); o.y = pack2(r[2], r[3]);
;           const unsigned off = (unsigned)((tk0 + bj * 128 + n * 16) * DFF + pn * 128 + m * 16 + fl0);
;           *reinterpret_cast<uint2*>(e.o0 + off) = o;
;         }
	v_pk_mul_f32 v[58:59], v[58:59], v[134:135] op_sel_hi:[1,0]
	v_pk_mul_f32 v[68:69], v[68:69], v[74:75]
	v_add_u32_e32 v132, v84, v118
	v_pk_mul_f32 v[68:69], v[70:71], v[68:69]
	v_mul_f32_e32 v70, 0xbfb8aa3b, v58
	v_mul_f32_e32 v71, 0xbfb8aa3b, v59
	v_exp_f32_e32 v70, v70
	v_exp_f32_e32 v71, v71
	v_cvt_pk_bf16_f32 v66, v66, v67
	v_cvt_pk_bf16_f32 v67, v68, v69
	v_lshl_add_u64 v[68:69], v[132:133], 1, s[2:3]
	v_pk_mul_f32 v[60:61], v[60:61], v[134:135] op_sel_hi:[1,0]
	ds_write_b64 v167, v[66:67] offset:2048
	v_add_f32_e32 v66, 1.0, v70
	v_add_f32_e32 v67, 1.0, v71
	v_mul_f32_e32 v68, 0xbfb8aa3b, v60
	v_mul_f32_e32 v69, 0xbfb8aa3b, v61
	v_rcp_f32_e32 v66, v66
	v_rcp_f32_e32 v67, v67
	v_exp_f32_e32 v68, v68
	v_exp_f32_e32 v69, v69
	v_pk_mul_f32 v[62:63], v[62:63], v[134:135] op_sel_hi:[1,0]
	v_pk_mul_f32 v[58:59], v[58:59], v[66:67]
	v_add_f32_e32 v66, 1.0, v68
	v_add_f32_e32 v67, 1.0, v69
	v_rcp_f32_e32 v66, v66
	v_rcp_f32_e32 v67, v67
	v_pk_mul_f32 v[58:59], v[62:63], v[58:59]
	v_pk_mul_f32 v[42:43], v[42:43], v[134:135] op_sel_hi:[1,0]
	v_cvt_pk_bf16_f32 v62, v58, v59
	v_pk_mul_f32 v[58:59], v[60:61], v[66:67]
	v_pk_mul_f32 v[60:61], v[64:65], v[134:135] op_sel_hi:[1,0]
	v_pk_mul_f32 v[44:45], v[44:45], v[134:135] op_sel_hi:[1,0]
	v_pk_mul_f32 v[58:59], v[60:61], v[58:59]
	v_pk_mul_f32 v[46:47], v[46:47], v[134:135] op_sel_hi:[1,0]
	v_cvt_pk_bf16_f32 v63, v58, v59
	v_add_u32_e32 v59, 0xb0000, v123
	v_mov_b32_e32 v58, v135
	v_pk_mul_f32 v[50:51], v[50:51], v[58:59] op_sel_hi:[1,0]
	v_add_u32_e32 v132, v59, v146
	v_mul_f32_e32 v64, 0xbfb8aa3b, v50
	v_mul_f32_e32 v65, 0xbfb8aa3b, v51
	v_exp_f32_e32 v64, v64
	v_exp_f32_e32 v65, v65
	v_lshl_add_u64 v[60:61], v[132:133], 1, s[2:3]
	v_pk_mul_f32 v[52:53], v[52:53], v[58:59] op_sel_hi:[1,0]
	ds_write_b64 v164, v[62:63] offset:4096
	v_add_f32_e32 v60, 1.0, v64
	v_add_f32_e32 v61, 1.0, v65
	v_mul_f32_e32 v62, 0xbfb8aa3b, v52
	v_mul_f32_e32 v63, 0xbfb8aa3b, v53
	v_rcp_f32_e32 v60, v60
	v_rcp_f32_e32 v61, v61
	v_exp_f32_e32 v62, v62
	v_exp_f32_e32 v63, v63
	v_pk_mul_f32 v[54:55], v[54:55], v[58:59] op_sel_hi:[1,0]
	v_pk_mul_f32 v[50:51], v[50:51], v[60:61]
	v_add_f32_e32 v60, 1.0, v62
	v_add_f32_e32 v61, 1.0, v63
	v_rcp_f32_e32 v60, v60
	v_rcp_f32_e32 v61, v61
	v_pk_mul_f32 v[50:51], v[54:55], v[50:51]
	v_pk_mul_f32 v[54:55], v[56:57], v[58:59] op_sel_hi:[1,0]
	v_mul_f32_e32 v56, 0xbfb8aa3b, v43
	v_pk_mul_f32 v[52:53], v[52:53], v[60:61]
	v_exp_f32_e32 v56, v56
	v_pk_mul_f32 v[52:53], v[54:55], v[52:53]
	v_mul_f32_e32 v55, 0xbfb8aa3b, v42
	v_exp_f32_e32 v55, v55
	v_add_u32_e32 v54, 0xc6000, v123
	v_add_u32_e32 v132, v54, v146
	v_cvt_pk_bf16_f32 v50, v50, v51
	v_cvt_pk_bf16_f32 v51, v52, v53
	v_lshl_add_u64 v[52:53], v[132:133], 1, s[2:3]
	ds_write_b64 v164, v[50:51] offset:6144
	v_add_f32_e32 v50, 1.0, v55
	v_add_f32_e32 v51, 1.0, v56
	v_mul_f32_e32 v52, 0xbfb8aa3b, v44
	v_mul_f32_e32 v53, 0xbfb8aa3b, v45
	v_rcp_f32_e32 v50, v50
	v_rcp_f32_e32 v51, v51
	v_exp_f32_e32 v52, v52
	v_exp_f32_e32 v53, v53
	v_pk_mul_f32 v[34:35], v[34:35], v[58:59] op_sel_hi:[1,0]
	v_pk_mul_f32 v[42:43], v[42:43], v[50:51]
	v_add_f32_e32 v50, 1.0, v52
	v_add_f32_e32 v51, 1.0, v53
	v_rcp_f32_e32 v50, v50
	v_rcp_f32_e32 v51, v51
	v_pk_mul_f32 v[42:43], v[46:47], v[42:43]
	v_pk_mul_f32 v[46:47], v[48:49], v[134:135] op_sel_hi:[1,0]
	v_add_u32_e32 v132, v116, v59
	v_pk_mul_f32 v[44:45], v[44:45], v[50:51]
	v_cvt_pk_bf16_f32 v42, v42, v43
	v_pk_mul_f32 v[44:45], v[46:47], v[44:45]
	v_mul_f32_e32 v46, 0xbfb8aa3b, v34
	v_mul_f32_e32 v47, 0xbfb8aa3b, v35
	v_exp_f32_e32 v46, v46
	v_exp_f32_e32 v47, v47
	v_cvt_pk_bf16_f32 v43, v44, v45
	v_lshl_add_u64 v[44:45], v[132:133], 1, s[2:3]
	v_pk_mul_f32 v[36:37], v[36:37], v[58:59] op_sel_hi:[1,0]
	ds_write_b64 v165, v[42:43] offset:4096
	v_add_f32_e32 v42, 1.0, v46
	v_add_f32_e32 v43, 1.0, v47
	v_mul_f32_e32 v44, 0xbfb8aa3b, v36
	v_mul_f32_e32 v45, 0xbfb8aa3b, v37
	v_rcp_f32_e32 v42, v42
	v_rcp_f32_e32 v43, v43
	v_exp_f32_e32 v44, v44
	v_exp_f32_e32 v45, v45
	v_pk_mul_f32 v[38:39], v[38:39], v[58:59] op_sel_hi:[1,0]
	v_pk_mul_f32 v[34:35], v[34:35], v[42:43]
	v_add_f32_e32 v42, 1.0, v44
	v_add_f32_e32 v43, 1.0, v45
	v_rcp_f32_e32 v42, v42
	v_rcp_f32_e32 v43, v43
	v_pk_mul_f32 v[34:35], v[38:39], v[34:35]
	v_pk_mul_f32 v[38:39], v[40:41], v[58:59] op_sel_hi:[1,0]
	v_pk_mul_f32 v[26:27], v[26:27], v[134:135] op_sel_hi:[1,0]
	v_pk_mul_f32 v[36:37], v[36:37], v[42:43]
	v_add_u32_e32 v132, v116, v54
	v_pk_mul_f32 v[36:37], v[38:39], v[36:37]
	v_mul_f32_e32 v38, 0xbfb8aa3b, v26
	v_mul_f32_e32 v39, 0xbfb8aa3b, v27
	v_exp_f32_e32 v38, v38
	v_exp_f32_e32 v39, v39
	v_cvt_pk_bf16_f32 v34, v34, v35
	v_cvt_pk_bf16_f32 v35, v36, v37
	v_lshl_add_u64 v[36:37], v[132:133], 1, s[2:3]
	v_pk_mul_f32 v[28:29], v[28:29], v[134:135] op_sel_hi:[1,0]
	ds_write_b64 v165, v[34:35] offset:6144
	v_add_f32_e32 v34, 1.0, v38
	v_add_f32_e32 v35, 1.0, v39
	v_mul_f32_e32 v36, 0xbfb8aa3b, v28
	v_mul_f32_e32 v37, 0xbfb8aa3b, v29
	v_rcp_f32_e32 v34, v34
	v_rcp_f32_e32 v35, v35
	v_exp_f32_e32 v36, v36
; DEVI float silu(float x) { return x * __builtin_amdgcn_rcpf(1.f + __expf(-x)); }
; template <int EPI, int NRM>
; DEVI void epilogue(acc_t& acc, int pn, int trow, const EpiArgs& e, const float* rl, bf16* shmx) {
;     ...
;   } else if constexpr (EPI == EPI_SWIGLU) {
; #pragma unroll
;     for (int bj = 0; bj < 2; ++bj)
; #pragma unroll
;       for (int m = 0; m < 4; ++m)
; #pragma unroll
;         for (int n = 0; n < 2; ++n) {
;           float r[4];
; #pragma unroll
;           for (int j = 0; j < 4; ++j) r[j] = silu(acc[0][bj][m][n][j] * rs[bj][n]) * (acc[1][bj][m][n][j] * rs[bj][n]);
;           uint2 o; o.x = pack2(r[0], r[1]); o.y = pack2(r[2], r[3]);
;           const unsigned off = (unsigned)((tk0 + bj * 128 + n * 16) * DFF + pn * 128 + m * 16 + fl0);
;           *reinterpret_cast<uint2*>(e.o0 + off) = o;
;         }
; template <int K, int LDA, int LDB, int EPI, int GRP, int NRM, int nTk = TOK / 256>
; DEVI void gemm_phase(const bf16* W, const bf16* X, int nF, const EpiArgs& e, bf16* shm) {
;     ...
;     epilogue<EPI, NRM>(acc, pn, pm * 256, e, rsl + (it & 1) * 256, shm);
;     t = tn; pm = pm2; pn = pn2; ++it;
	v_exp_f32_e32 v37, v37
	v_pk_mul_f32 v[30:31], v[30:31], v[134:135] op_sel_hi:[1,0]
	v_pk_mul_f32 v[26:27], v[26:27], v[34:35]
	v_add_f32_e32 v34, 1.0, v36
	v_add_f32_e32 v35, 1.0, v37
	v_rcp_f32_e32 v34, v34
	v_rcp_f32_e32 v35, v35
	v_pk_mul_f32 v[26:27], v[30:31], v[26:27]
	v_pk_mul_f32 v[30:31], v[32:33], v[134:135] op_sel_hi:[1,0]
	v_pk_mul_f32 v[18:19], v[18:19], v[58:59] op_sel_hi:[1,0]
	v_pk_mul_f32 v[28:29], v[28:29], v[34:35]
	v_add_u32_e32 v132, v100, v59
	v_pk_mul_f32 v[28:29], v[30:31], v[28:29]
	v_mul_f32_e32 v30, 0xbfb8aa3b, v18
	v_mul_f32_e32 v31, 0xbfb8aa3b, v19
	v_exp_f32_e32 v30, v30
	v_exp_f32_e32 v31, v31
	v_cvt_pk_bf16_f32 v26, v26, v27
	v_cvt_pk_bf16_f32 v27, v28, v29
	v_lshl_add_u64 v[28:29], v[132:133], 1, s[2:3]
	v_pk_mul_f32 v[20:21], v[20:21], v[58:59] op_sel_hi:[1,0]
	ds_write_b64 v166, v[26:27] offset:4096
	v_add_f32_e32 v26, 1.0, v30
	v_add_f32_e32 v27, 1.0, v31
	v_mul_f32_e32 v28, 0xbfb8aa3b, v20
	v_mul_f32_e32 v29, 0xbfb8aa3b, v21
	v_rcp_f32_e32 v26, v26
	v_rcp_f32_e32 v27, v27
	v_exp_f32_e32 v28, v28
	v_exp_f32_e32 v29, v29
	v_pk_mul_f32 v[22:23], v[22:23], v[58:59] op_sel_hi:[1,0]
	v_pk_mul_f32 v[18:19], v[18:19], v[26:27]
	v_add_f32_e32 v26, 1.0, v28
	v_add_f32_e32 v27, 1.0, v29
	v_rcp_f32_e32 v26, v26
	v_rcp_f32_e32 v27, v27
	v_pk_mul_f32 v[18:19], v[22:23], v[18:19]
	v_pk_mul_f32 v[22:23], v[24:25], v[58:59] op_sel_hi:[1,0]
	v_pk_mul_f32 v[10:11], v[10:11], v[134:135] op_sel_hi:[1,0]
	v_pk_mul_f32 v[20:21], v[20:21], v[26:27]
	v_add_u32_e32 v132, v100, v54
	v_pk_mul_f32 v[20:21], v[22:23], v[20:21]
	v_mul_f32_e32 v22, 0xbfb8aa3b, v10
	v_mul_f32_e32 v23, 0xbfb8aa3b, v11
	v_exp_f32_e32 v22, v22
	v_exp_f32_e32 v23, v23
	v_cvt_pk_bf16_f32 v18, v18, v19
	v_cvt_pk_bf16_f32 v19, v20, v21
	v_lshl_add_u64 v[20:21], v[132:133], 1, s[2:3]
	v_pk_mul_f32 v[12:13], v[12:13], v[134:135] op_sel_hi:[1,0]
	ds_write_b64 v166, v[18:19] offset:6144
	v_add_f32_e32 v18, 1.0, v22
	v_add_f32_e32 v19, 1.0, v23
	v_mul_f32_e32 v20, 0xbfb8aa3b, v12
	v_mul_f32_e32 v21, 0xbfb8aa3b, v13
	v_rcp_f32_e32 v18, v18
	v_rcp_f32_e32 v19, v19
	v_exp_f32_e32 v20, v20
	v_exp_f32_e32 v21, v21
	v_pk_mul_f32 v[14:15], v[14:15], v[134:135] op_sel_hi:[1,0]
	v_pk_mul_f32 v[10:11], v[10:11], v[18:19]
	v_add_f32_e32 v18, 1.0, v20
	v_add_f32_e32 v19, 1.0, v21
	v_rcp_f32_e32 v18, v18
	v_rcp_f32_e32 v19, v19
	v_pk_mul_f32 v[10:11], v[14:15], v[10:11]
	v_pk_mul_f32 v[14:15], v[16:17], v[134:135] op_sel_hi:[1,0]
	v_pk_mul_f32 v[2:3], v[2:3], v[58:59] op_sel_hi:[1,0]
	v_pk_mul_f32 v[12:13], v[12:13], v[18:19]
	v_add_u32_e32 v132, v84, v59
	v_pk_mul_f32 v[12:13], v[14:15], v[12:13]
	v_mul_f32_e32 v14, 0xbfb8aa3b, v2
	v_mul_f32_e32 v15, 0xbfb8aa3b, v3
	v_exp_f32_e32 v14, v14
	v_exp_f32_e32 v15, v15
	v_cvt_pk_bf16_f32 v10, v10, v11
	v_cvt_pk_bf16_f32 v11, v12, v13
	v_lshl_add_u64 v[12:13], v[132:133], 1, s[2:3]
	v_pk_mul_f32 v[4:5], v[4:5], v[58:59] op_sel_hi:[1,0]
	ds_write_b64 v167, v[10:11] offset:4096
	v_add_f32_e32 v10, 1.0, v14
	v_add_f32_e32 v11, 1.0, v15
	v_mul_f32_e32 v12, 0xbfb8aa3b, v4
	v_mul_f32_e32 v13, 0xbfb8aa3b, v5
	v_rcp_f32_e32 v10, v10
	v_rcp_f32_e32 v11, v11
	v_exp_f32_e32 v12, v12
	v_exp_f32_e32 v13, v13
	v_pk_mul_f32 v[6:7], v[6:7], v[58:59] op_sel_hi:[1,0]
	v_pk_mul_f32 v[2:3], v[2:3], v[10:11]
	v_add_f32_e32 v10, 1.0, v12
	v_add_f32_e32 v11, 1.0, v13
	v_rcp_f32_e32 v10, v10
	v_rcp_f32_e32 v11, v11
	v_pk_mul_f32 v[2:3], v[6:7], v[2:3]
	v_pk_mul_f32 v[6:7], v[8:9], v[58:59] op_sel_hi:[1,0]
	v_add_u32_e32 v132, v84, v54
	v_pk_mul_f32 v[4:5], v[4:5], v[10:11]
	v_cvt_pk_bf16_f32 v2, v2, v3
	v_pk_mul_f32 v[4:5], v[6:7], v[4:5]
	s_add_i32 s16, s16, 1
	v_cvt_pk_bf16_f32 v3, v4, v5
	v_lshl_add_u64 v[4:5], v[132:133], 1, s[2:3]
	s_andn2_b64 vcc, exec, s[4:5]
	s_mov_b32 s14, s8
	s_mov_b32 s12, s10
	ds_write_b64 v167, v[2:3] offset:6144
	s_waitcnt lgkmcnt(0)
	ds_read_b128 v[172:175], v168
	ds_read_b128 v[176:179], v168 offset:1024
	ds_read_b128 v[180:183], v168 offset:2048
	ds_read_b128 v[184:187], v168 offset:3072
	ds_read_b128 v[188:191], v168 offset:4096
	ds_read_b128 v[192:195], v168 offset:5120
	ds_read_b128 v[196:199], v168 offset:6144
	ds_read_b128 v[200:203], v168 offset:7168
	v_add_u32_e32 v204, 0x16000, v169
	v_add_u32_e32 v205, 0x2c000, v169
	v_add_u32_e32 v206, 0x42000, v169
	v_add_u32_e32 v207, 0x160000, v169
	v_add_u32_e32 v208, 0x176000, v169
	v_add_u32_e32 v209, 0x18c000, v169
	v_add_u32_e32 v210, 0x1a2000, v169
	s_waitcnt lgkmcnt(7)
	global_store_dwordx4 v169, v[172:175], s[2:3] nt
	s_waitcnt lgkmcnt(6)
	global_store_dwordx4 v204, v[176:179], s[2:3] nt
	s_waitcnt lgkmcnt(5)
	global_store_dwordx4 v205, v[180:183], s[2:3] nt
	s_waitcnt lgkmcnt(4)
	global_store_dwordx4 v206, v[184:187], s[2:3] nt
	s_waitcnt lgkmcnt(3)
	global_store_dwordx4 v207, v[188:191], s[2:3] nt
	s_waitcnt lgkmcnt(2)
	global_store_dwordx4 v208, v[192:195], s[2:3] nt
	s_waitcnt lgkmcnt(1)
	global_store_dwordx4 v209, v[196:199], s[2:3] nt
	s_waitcnt lgkmcnt(0)
	global_store_dwordx4 v210, v[200:203], s[2:3] nt
	s_cbranch_vccz .LBB0_1668

; template <int EPI, int NRM>
; DEVI void epilogue(acc_t& acc, int pn, int trow, const EpiArgs& e, const float* rl, bf16* shmx) {
;     ...
;     __amdgpu_buffer_rsrc_t rsX = __builtin_amdgcn_make_buffer_rsrc((void*)e.xin, 0, 0x7fffffff, 0x00020000);
;     char* lbase = reinterpret_cast<char*>(shmx) + wid * 16384;
;     const int vx = ((tk0 * DM) + pn * 256 + fl0) * 4;
; #pragma unroll
;     for (int ai = 0; ai < 2; ++ai) {
; #pragma unroll
;       for (int bj = 0; bj < 2; ++bj)
; #pragma unroll
;         for (int m = 0; m < 4; ++m)
; #pragma unroll
;           for (int n = 0; n < 2; ++n) {
;             const int idx = (bj * 4 + m) * 2 + n;
;             const int so = ((bj * 128 + n * 16) * DM + ai * 128 + m * 16) * 4;
;             __builtin_amdgcn_raw_ptr_buffer_load_lds(rsX, (__attribute__((address_space(3))) unsigned*)(lbase + idx * 1024 + lane * 16), 16, vx, so, 0, 0);
;           }
;       asm volatile("s_waitcnt vmcnt(0)" ::: "memory");
; #pragma unroll
;       for (int bj = 0; bj < 2; ++bj)
; #pragma unroll
;         for (int m = 0; m < 4; ++m)
; #pragma unroll
;           for (int n = 0; n < 2; ++n) {
;             const int idx = (bj * 4 + m) * 2 + n;
;             const unsigned off = (unsigned)((tk0 + bj * 128 + n * 16) * DM + pn * 256 + ai * 128 + m * 16 + fl0);
;             const float4 xx = *reinterpret_cast<const float4*>(lbase + idx * 1024 + lane * 16);
;             float4 o;
;             o.x = xx.x + acc[ai][bj][m][n][0]; o.y = xx.y + acc[ai][bj][m][n][1];
;             o.z = xx.z + acc[ai][bj][m][n][2]; o.w = xx.w + acc[ai][bj][m][n][3];
;             *reinterpret_cast<float4*>(e.xout + off) = o;
;             uint2 ob; ob.x = pack2(o.x, o.y); ob.y = pack2(o.z, o.w);
;             *reinterpret_cast<uint2*>(e.o0 + off) = ob;
;             ss[bj][n] += o.x * o.x + o.y * o.y + o.z * o.z + o.w * o.w;
.LBB0_1710:
	v_and_b32_e32 v138, 15, v131
	v_bfe_u32 v198, v131, 4, 2
	v_lshrrev_b32_e32 v199, 6, v131
	v_and_b32_e32 v200, 3, v199
	v_lshrrev_b32_e32 v201, 2, v199
	v_lshlrev_b32_e32 v202, 14, v199
	v_and_b32_e32 v203, 63, v131
	v_lshl_add_u32 v143, v203, 4, v202
	v_lshl_add_u32 v202, v138, 8, v202
	v_and_b32_e32 v203, 7, v138
	v_add_u32_e32 v204, 0, v198
	v_xor_b32_e32 v204, v204, v203
	v_lshl_add_u32 v139, v204, 4, v202
	v_add_u32_e32 v204, 4, v198
	v_xor_b32_e32 v204, v204, v203
	v_lshl_add_u32 v140, v204, 4, v202
	v_add_u32_e32 v204, 8, v198
	v_xor_b32_e32 v204, v204, v203
	v_lshl_add_u32 v141, v204, 4, v202
	v_add_u32_e32 v204, 12, v198
	v_xor_b32_e32 v204, v204, v203
	v_lshl_add_u32 v142, v204, 4, v202
	s_lshl_b32 s6, s59, 8
	v_lshl_add_u32 v202, v200, 5, v198
	v_add_u32_e32 v202, s6, v202
	s_lshl_b32 s6, s58, 1
	v_add_u32_e32 v204, s6, v201
	v_lshl_add_u32 v204, v204, 15, v202
	v_lshlrev_b32_e32 v148, 2, v204
	v_lshlrev_b32_e32 v202, 11, v202
	s_lshl_b32 s6, s58, 8
	v_lshl_add_u32 v204, v201, 6, s6
	v_add_u32_e32 v202, v202, v204
	v_add_u32_e32 v203, 0, v198
	v_xor_b32_e32 v203, v203, v138
	v_lshl_add_u32 v203, v203, 2, v202
	v_lshlrev_b32_e32 v144, 2, v203
	v_lshlrev_b32_e32 v146, 1, v203
	v_add_u32_e32 v203, 4, v198
	v_xor_b32_e32 v203, v203, v138
	v_lshl_add_u32 v203, v203, 2, v202
	v_lshlrev_b32_e32 v145, 2, v203
	v_lshlrev_b32_e32 v147, 1, v203
	v_add_u32_e32 v157, 0x0, v144
	global_load_dwordx4 v[166:169], v157, s[4:5] nt
	v_add_u32_e32 v160, 0x8000, v145
	global_load_dwordx4 v[170:173], v160, s[4:5] nt
	v_add_u32_e32 v157, 0x10000, v144
	global_load_dwordx4 v[174:177], v157, s[4:5] nt
	v_add_u32_e32 v160, 0x18000, v145
	global_load_dwordx4 v[178:181], v160, s[4:5] nt
	v_add_u32_e32 v157, 0x20000, v144
	global_load_dwordx4 v[182:185], v157, s[4:5] nt
	v_add_u32_e32 v160, 0x28000, v145
	global_load_dwordx4 v[186:189], v160, s[4:5] nt
	v_add_u32_e32 v157, 0x30000, v144
	global_load_dwordx4 v[190:193], v157, s[4:5] nt
	v_add_u32_e32 v160, 0x38000, v145
	global_load_dwordx4 v[194:197], v160, s[4:5] nt
	v_add_u32_e32 v157, 0x200, v144
	global_load_dwordx4 v[198:201], v157, s[4:5] nt
	v_add_u32_e32 v160, 0x8200, v145
	global_load_dwordx4 v[202:205], v160, s[4:5] nt
	v_add_u32_e32 v157, 0x10200, v144
	global_load_dwordx4 v[206:209], v157, s[4:5] nt
	v_add_u32_e32 v160, 0x18200, v145
	global_load_dwordx4 v[210:213], v160, s[4:5] nt
	v_add_u32_e32 v157, 0x20200, v144
	global_load_dwordx4 v[214:217], v157, s[4:5] nt
	v_add_u32_e32 v160, 0x28200, v145
	global_load_dwordx4 v[218:221], v160, s[4:5] nt
	v_add_u32_e32 v157, 0x30200, v144
	global_load_dwordx4 v[222:225], v157, s[4:5] nt
	v_add_u32_e32 v160, 0x38200, v145
	global_load_dwordx4 v[226:229], v160, s[4:5] nt
	ds_write_b128 v139, v[126:129]
	ds_write_b128 v139, v[14:17] offset:4096
	ds_write_b128 v140, v[122:125]
	ds_write_b128 v140, v[26:29] offset:4096
	ds_write_b128 v141, v[118:121]
	ds_write_b128 v141, v[42:45] offset:4096
	ds_write_b128 v142, v[114:117]
	ds_write_b128 v142, v[54:57] offset:4096
	ds_write_b128 v139, v[110:113] offset:8192
	ds_write_b128 v139, v[106:109] offset:12288
	ds_write_b128 v140, v[102:105] offset:8192
	ds_write_b128 v140, v[94:97] offset:12288
	ds_write_b128 v141, v[86:89] offset:8192
	ds_write_b128 v141, v[78:81] offset:12288
	ds_write_b128 v142, v[70:73] offset:8192
	ds_write_b128 v142, v[46:49] offset:12288
	s_waitcnt lgkmcnt(0)
	ds_read_b128 v[126:129], v143
	ds_read_b128 v[14:17], v143 offset:1024
	ds_read_b128 v[122:125], v143 offset:2048
	ds_read_b128 v[26:29], v143 offset:3072
	ds_read_b128 v[118:121], v143 offset:4096
	ds_read_b128 v[42:45], v143 offset:5120
	ds_read_b128 v[114:117], v143 offset:6144
	ds_read_b128 v[54:57], v143 offset:7168
	ds_read_b128 v[110:113], v143 offset:8192
	ds_read_b128 v[106:109], v143 offset:9216
	ds_read_b128 v[102:105], v143 offset:10240
	ds_read_b128 v[94:97], v143 offset:11264
	ds_read_b128 v[86:89], v143 offset:12288
	ds_read_b128 v[78:81], v143 offset:13312
	ds_read_b128 v[70:73], v143 offset:14336
	ds_read_b128 v[46:49], v143 offset:15360
	s_waitcnt lgkmcnt(0)
	ds_write_b128 v139, v[50:53]
	ds_write_b128 v139, v[58:61] offset:4096
	ds_write_b128 v140, v[62:65]
	ds_write_b128 v140, v[66:69] offset:4096
	ds_write_b128 v141, v[74:77]
	ds_write_b128 v141, v[82:85] offset:4096
	ds_write_b128 v142, v[90:93]
	ds_write_b128 v142, v[98:101] offset:4096
	ds_write_b128 v139, v[38:41] offset:8192
	ds_write_b128 v139, v[34:37] offset:12288
	ds_write_b128 v140, v[30:33] offset:8192
	ds_write_b128 v140, v[22:25] offset:12288
	ds_write_b128 v141, v[18:21] offset:8192
	ds_write_b128 v141, v[10:13] offset:12288
	ds_write_b128 v142, v[6:9] offset:8192
	ds_write_b128 v142, v[2:5] offset:12288
	s_waitcnt vmcnt(15)
	v_pk_add_f32 v[166:167], v[166:167], v[126:127]
	v_pk_add_f32 v[168:169], v[168:169], v[128:129]
	v_add_u32_e32 v157, 0x0, v144
	v_cvt_pk_bf16_f32 v158, v166, v167
	v_cvt_pk_bf16_f32 v159, v168, v169
	global_store_dwordx4 v157, v[166:169], s[26:27] nt
	v_add_u32_e32 v126, 0x0, v146
	v_mul_f32_e32 v149, v166, v166
	global_store_dwordx2 v126, v[158:159], s[96:97]
	v_fmac_f32_e32 v149, v167, v167
	v_fmac_f32_e32 v149, v168, v168
	v_fmac_f32_e32 v149, v169, v169
	s_waitcnt vmcnt(16)
	v_pk_add_f32 v[170:171], v[170:171], v[14:15]
	v_pk_add_f32 v[172:173], v[172:173], v[16:17]
	v_add_u32_e32 v160, 0x8000, v145
	v_cvt_pk_bf16_f32 v164, v170, v171
	v_cvt_pk_bf16_f32 v165, v172, v173
	global_store_dwordx4 v160, v[170:173], s[26:27] nt
	v_add_u32_e32 v14, 0x4000, v147
	v_mul_f32_e32 v150, v170, v170
	global_store_dwordx2 v14, v[164:165], s[96:97]
	v_fmac_f32_e32 v150, v171, v171
	v_fmac_f32_e32 v150, v172, v172
	v_fmac_f32_e32 v150, v173, v173
	s_waitcnt vmcnt(17)
; template <int EPI, int NRM>
; DEVI void epilogue(acc_t& acc, int pn, int trow, const EpiArgs& e, const float* rl, bf16* shmx) {
;     ...
;             const unsigned off = (unsigned)((tk0 + bj * 128 + n * 16) * DM + pn * 256 + ai * 128 + m * 16 + fl0);
;             const float4 xx = *reinterpret_cast<const float4*>(lbase + idx * 1024 + lane * 16);
;             float4 o;
;             o.x = xx.x + acc[ai][bj][m][n][0]; o.y = xx.y + acc[ai][bj][m][n][1];
;             o.z = xx.z + acc[ai][bj][m][n][2]; o.w = xx.w + acc[ai][bj][m][n][3];
;             *reinterpret_cast<float4*>(e.xout + off) = o;
;             uint2 ob; ob.x = pack2(o.x, o.y); ob.y = pack2(o.z, o.w);
;             *reinterpret_cast<uint2*>(e.o0 + off) = ob;
;             ss[bj][n] += o.x * o.x + o.y * o.y + o.z * o.z + o.w * o.w;
	v_pk_add_f32 v[174:175], v[174:175], v[122:123]
	v_pk_add_f32 v[176:177], v[176:177], v[124:125]
	v_add_u32_e32 v157, 0x10000, v144
	v_cvt_pk_bf16_f32 v158, v174, v175
	v_cvt_pk_bf16_f32 v159, v176, v177
	global_store_dwordx4 v157, v[174:177], s[26:27] nt
	v_add_u32_e32 v122, 0x8000, v146
	v_mul_f32_e32 v151, v174, v174
	global_store_dwordx2 v122, v[158:159], s[96:97]
	v_fmac_f32_e32 v151, v175, v175
	v_fmac_f32_e32 v151, v176, v176
	v_fmac_f32_e32 v151, v177, v177
	s_waitcnt vmcnt(18)
	v_pk_add_f32 v[178:179], v[178:179], v[26:27]
	v_pk_add_f32 v[180:181], v[180:181], v[28:29]
	v_add_u32_e32 v160, 0x18000, v145
	v_cvt_pk_bf16_f32 v164, v178, v179
	v_cvt_pk_bf16_f32 v165, v180, v181
	global_store_dwordx4 v160, v[178:181], s[26:27] nt
	v_add_u32_e32 v26, 0xc000, v147
	v_mul_f32_e32 v152, v178, v178
	global_store_dwordx2 v26, v[164:165], s[96:97]
	v_fmac_f32_e32 v152, v179, v179
	v_fmac_f32_e32 v152, v180, v180
	v_fmac_f32_e32 v152, v181, v181
	s_waitcnt vmcnt(19)
	v_pk_add_f32 v[182:183], v[182:183], v[118:119]
	v_pk_add_f32 v[184:185], v[184:185], v[120:121]
	v_add_u32_e32 v157, 0x20000, v144
	v_cvt_pk_bf16_f32 v158, v182, v183
	v_cvt_pk_bf16_f32 v159, v184, v185
	global_store_dwordx4 v157, v[182:185], s[26:27] nt
	v_add_u32_e32 v118, 0x10000, v146
	v_mul_f32_e32 v153, v182, v182
	global_store_dwordx2 v118, v[158:159], s[96:97]
	v_fmac_f32_e32 v153, v183, v183
	v_fmac_f32_e32 v153, v184, v184
	v_fmac_f32_e32 v153, v185, v185
	s_waitcnt vmcnt(20)
	v_pk_add_f32 v[186:187], v[186:187], v[42:43]
	v_pk_add_f32 v[188:189], v[188:189], v[44:45]
	v_add_u32_e32 v160, 0x28000, v145
	v_cvt_pk_bf16_f32 v164, v186, v187
	v_cvt_pk_bf16_f32 v165, v188, v189
	global_store_dwordx4 v160, v[186:189], s[26:27] nt
	v_add_u32_e32 v42, 0x14000, v147
	v_mul_f32_e32 v154, v186, v186
	global_store_dwordx2 v42, v[164:165], s[96:97]
	v_fmac_f32_e32 v154, v187, v187
	v_fmac_f32_e32 v154, v188, v188
	v_fmac_f32_e32 v154, v189, v189
	s_waitcnt vmcnt(21)
	v_pk_add_f32 v[190:191], v[190:191], v[114:115]
	v_pk_add_f32 v[192:193], v[192:193], v[116:117]
	v_add_u32_e32 v157, 0x30000, v144
	v_cvt_pk_bf16_f32 v158, v190, v191
	v_cvt_pk_bf16_f32 v159, v192, v193
	global_store_dwordx4 v157, v[190:193], s[26:27] nt
	v_add_u32_e32 v114, 0x18000, v146
	v_mul_f32_e32 v155, v190, v190
	global_store_dwordx2 v114, v[158:159], s[96:97]
	v_fmac_f32_e32 v155, v191, v191
	v_fmac_f32_e32 v155, v192, v192
	v_fmac_f32_e32 v155, v193, v193
	s_waitcnt vmcnt(22)
	v_pk_add_f32 v[194:195], v[194:195], v[54:55]
	v_pk_add_f32 v[196:197], v[196:197], v[56:57]
	v_add_u32_e32 v160, 0x38000, v145
	v_cvt_pk_bf16_f32 v164, v194, v195
	v_cvt_pk_bf16_f32 v165, v196, v197
	global_store_dwordx4 v160, v[194:197], s[26:27] nt
	v_add_u32_e32 v54, 0x1c000, v147
	v_mul_f32_e32 v156, v194, v194
	global_store_dwordx2 v54, v[164:165], s[96:97]
	v_fmac_f32_e32 v156, v195, v195
	v_fmac_f32_e32 v156, v196, v196
	v_fmac_f32_e32 v156, v197, v197
	v_add_u32_e32 v157, 0x100000, v144
	global_load_dwordx4 v[166:169], v157, s[4:5] nt
	v_add_u32_e32 v160, 0x108000, v145
	global_load_dwordx4 v[170:173], v160, s[4:5] nt
	v_add_u32_e32 v157, 0x110000, v144
	global_load_dwordx4 v[174:177], v157, s[4:5] nt
	v_add_u32_e32 v160, 0x118000, v145
	global_load_dwordx4 v[178:181], v160, s[4:5] nt
	v_add_u32_e32 v157, 0x120000, v144
	global_load_dwordx4 v[182:185], v157, s[4:5] nt
	v_add_u32_e32 v160, 0x128000, v145
	global_load_dwordx4 v[186:189], v160, s[4:5] nt
	v_add_u32_e32 v157, 0x130000, v144
	global_load_dwordx4 v[190:193], v157, s[4:5] nt
	v_add_u32_e32 v160, 0x138000, v145
	global_load_dwordx4 v[194:197], v160, s[4:5] nt
	s_waitcnt vmcnt(31)
	v_pk_add_f32 v[198:199], v[198:199], v[110:111]
	v_pk_add_f32 v[200:201], v[200:201], v[112:113]
	v_add_u32_e32 v157, 0x200, v144
	v_cvt_pk_bf16_f32 v158, v198, v199
	v_cvt_pk_bf16_f32 v159, v200, v201
	global_store_dwordx4 v157, v[198:201], s[26:27] nt
	v_add_u32_e32 v110, 0x100, v146
	v_fmac_f32_e32 v149, v198, v198
	global_store_dwordx2 v110, v[158:159], s[96:97]
	v_fmac_f32_e32 v149, v199, v199
	v_fmac_f32_e32 v149, v200, v200
	v_fmac_f32_e32 v149, v201, v201
	s_waitcnt vmcnt(32)
	v_pk_add_f32 v[202:203], v[202:203], v[106:107]
	v_pk_add_f32 v[204:205], v[204:205], v[108:109]
	v_add_u32_e32 v160, 0x8200, v145
	v_cvt_pk_bf16_f32 v164, v202, v203
	v_cvt_pk_bf16_f32 v165, v204, v205
	global_store_dwordx4 v160, v[202:205], s[26:27] nt
	v_add_u32_e32 v106, 0x4100, v147
	v_fmac_f32_e32 v150, v202, v202
	global_store_dwordx2 v106, v[164:165], s[96:97]
	v_fmac_f32_e32 v150, v203, v203
	v_fmac_f32_e32 v150, v204, v204
	v_fmac_f32_e32 v150, v205, v205
	s_waitcnt vmcnt(33)
	v_pk_add_f32 v[206:207], v[206:207], v[102:103]
	v_pk_add_f32 v[208:209], v[208:209], v[104:105]
	v_add_u32_e32 v157, 0x10200, v144
	v_cvt_pk_bf16_f32 v158, v206, v207
	v_cvt_pk_bf16_f32 v159, v208, v209
	global_store_dwordx4 v157, v[206:209], s[26:27] nt
	v_add_u32_e32 v102, 0x8100, v146
	v_fmac_f32_e32 v151, v206, v206
	global_store_dwordx2 v102, v[158:159], s[96:97]
	v_fmac_f32_e32 v151, v207, v207
	v_fmac_f32_e32 v151, v208, v208
	v_fmac_f32_e32 v151, v209, v209
	s_waitcnt vmcnt(34)
	v_pk_add_f32 v[210:211], v[210:211], v[94:95]
	v_pk_add_f32 v[212:213], v[212:213], v[96:97]
	v_add_u32_e32 v160, 0x18200, v145
	v_cvt_pk_bf16_f32 v164, v210, v211
	v_cvt_pk_bf16_f32 v165, v212, v213
	global_store_dwordx4 v160, v[210:213], s[26:27] nt
	v_add_u32_e32 v94, 0xc100, v147
	v_fmac_f32_e32 v152, v210, v210
	global_store_dwordx2 v94, v[164:165], s[96:97]
	v_fmac_f32_e32 v152, v211, v211
	v_fmac_f32_e32 v152, v212, v212
	v_fmac_f32_e32 v152, v213, v213
	s_waitcnt vmcnt(35)
; template <int EPI, int NRM>
; DEVI void epilogue(acc_t& acc, int pn, int trow, const EpiArgs& e, const float* rl, bf16* shmx) {
;     ...
;             const unsigned off = (unsigned)((tk0 + bj * 128 + n * 16) * DM + pn * 256 + ai * 128 + m * 16 + fl0);
;             const float4 xx = *reinterpret_cast<const float4*>(lbase + idx * 1024 + lane * 16);
;             float4 o;
;             o.x = xx.x + acc[ai][bj][m][n][0]; o.y = xx.y + acc[ai][bj][m][n][1];
;             o.z = xx.z + acc[ai][bj][m][n][2]; o.w = xx.w + acc[ai][bj][m][n][3];
;             *reinterpret_cast<float4*>(e.xout + off) = o;
;             uint2 ob; ob.x = pack2(o.x, o.y); ob.y = pack2(o.z, o.w);
;             *reinterpret_cast<uint2*>(e.o0 + off) = ob;
;             ss[bj][n] += o.x * o.x + o.y * o.y + o.z * o.z + o.w * o.w;
;           }
;       asm volatile("s_waitcnt lgkmcnt(0)" ::: "memory");
;     }
; #pragma unroll
;     for (int bj = 0; bj < 2; ++bj)
; #pragma unroll
;       for (int n = 0; n < 2; ++n) {
;         float v = ss[bj][n];
;         v += __shfl_xor(v, 16); v += __shfl_xor(v, 32);
;         if (fq == 0) e.stw[(pn * 2 + wr) * TOK + tk0 + bj * 128 + n * 16] = v;
	v_pk_add_f32 v[214:215], v[214:215], v[86:87]
	v_pk_add_f32 v[216:217], v[216:217], v[88:89]
	v_add_u32_e32 v157, 0x20200, v144
	v_cvt_pk_bf16_f32 v158, v214, v215
	v_cvt_pk_bf16_f32 v159, v216, v217
	global_store_dwordx4 v157, v[214:217], s[26:27] nt
	v_add_u32_e32 v86, 0x10100, v146
	v_fmac_f32_e32 v153, v214, v214
	global_store_dwordx2 v86, v[158:159], s[96:97]
	v_fmac_f32_e32 v153, v215, v215
	v_fmac_f32_e32 v153, v216, v216
	v_fmac_f32_e32 v153, v217, v217
	s_waitcnt vmcnt(36)
	v_pk_add_f32 v[218:219], v[218:219], v[78:79]
	v_pk_add_f32 v[220:221], v[220:221], v[80:81]
	v_add_u32_e32 v160, 0x28200, v145
	v_cvt_pk_bf16_f32 v164, v218, v219
	v_cvt_pk_bf16_f32 v165, v220, v221
	global_store_dwordx4 v160, v[218:221], s[26:27] nt
	v_add_u32_e32 v78, 0x14100, v147
	v_fmac_f32_e32 v154, v218, v218
	global_store_dwordx2 v78, v[164:165], s[96:97]
	v_fmac_f32_e32 v154, v219, v219
	v_fmac_f32_e32 v154, v220, v220
	v_fmac_f32_e32 v154, v221, v221
	s_waitcnt vmcnt(37)
	v_pk_add_f32 v[222:223], v[222:223], v[70:71]
	v_pk_add_f32 v[224:225], v[224:225], v[72:73]
	v_add_u32_e32 v157, 0x30200, v144
	v_cvt_pk_bf16_f32 v158, v222, v223
	v_cvt_pk_bf16_f32 v159, v224, v225
	global_store_dwordx4 v157, v[222:225], s[26:27] nt
	v_add_u32_e32 v70, 0x18100, v146
	v_fmac_f32_e32 v155, v222, v222
	global_store_dwordx2 v70, v[158:159], s[96:97]
	v_fmac_f32_e32 v155, v223, v223
	v_fmac_f32_e32 v155, v224, v224
	v_fmac_f32_e32 v155, v225, v225
	s_waitcnt vmcnt(38)
	v_pk_add_f32 v[226:227], v[226:227], v[46:47]
	v_pk_add_f32 v[228:229], v[228:229], v[48:49]
	v_add_u32_e32 v160, 0x38200, v145
	v_cvt_pk_bf16_f32 v164, v226, v227
	v_cvt_pk_bf16_f32 v165, v228, v229
	global_store_dwordx4 v160, v[226:229], s[26:27] nt
	v_add_u32_e32 v46, 0x1c100, v147
	v_fmac_f32_e32 v156, v226, v226
	global_store_dwordx2 v46, v[164:165], s[96:97]
	v_fmac_f32_e32 v156, v227, v227
	v_fmac_f32_e32 v156, v228, v228
	v_fmac_f32_e32 v156, v229, v229
	v_add_u32_e32 v157, 0x100200, v144
	global_load_dwordx4 v[198:201], v157, s[4:5] nt
	v_add_u32_e32 v160, 0x108200, v145
	global_load_dwordx4 v[202:205], v160, s[4:5] nt
	v_add_u32_e32 v157, 0x110200, v144
	global_load_dwordx4 v[206:209], v157, s[4:5] nt
	v_add_u32_e32 v160, 0x118200, v145
	global_load_dwordx4 v[210:213], v160, s[4:5] nt
	v_add_u32_e32 v157, 0x120200, v144
	global_load_dwordx4 v[214:217], v157, s[4:5] nt
	v_add_u32_e32 v160, 0x128200, v145
	global_load_dwordx4 v[218:221], v160, s[4:5] nt
	v_add_u32_e32 v157, 0x130200, v144
	global_load_dwordx4 v[222:225], v157, s[4:5] nt
	v_add_u32_e32 v160, 0x138200, v145
	global_load_dwordx4 v[226:229], v160, s[4:5] nt
	v_add_f32_dpp v149, v149, v149 row_shr:1 row_mask:0xf bank_mask:0xf bound_ctrl:0
	v_add_f32_dpp v150, v150, v150 row_shr:1 row_mask:0xf bank_mask:0xf bound_ctrl:0
	v_add_f32_dpp v151, v151, v151 row_shr:1 row_mask:0xf bank_mask:0xf bound_ctrl:0
	v_add_f32_dpp v152, v152, v152 row_shr:1 row_mask:0xf bank_mask:0xf bound_ctrl:0
	v_add_f32_dpp v153, v153, v153 row_shr:1 row_mask:0xf bank_mask:0xf bound_ctrl:0
	v_add_f32_dpp v154, v154, v154 row_shr:1 row_mask:0xf bank_mask:0xf bound_ctrl:0
	v_add_f32_dpp v155, v155, v155 row_shr:1 row_mask:0xf bank_mask:0xf bound_ctrl:0
	v_add_f32_dpp v156, v156, v156 row_shr:1 row_mask:0xf bank_mask:0xf bound_ctrl:0
	v_add_f32_dpp v149, v149, v149 row_shr:2 row_mask:0xf bank_mask:0xf bound_ctrl:0
	v_add_f32_dpp v150, v150, v150 row_shr:2 row_mask:0xf bank_mask:0xf bound_ctrl:0
	v_add_f32_dpp v151, v151, v151 row_shr:2 row_mask:0xf bank_mask:0xf bound_ctrl:0
	v_add_f32_dpp v152, v152, v152 row_shr:2 row_mask:0xf bank_mask:0xf bound_ctrl:0
	v_add_f32_dpp v153, v153, v153 row_shr:2 row_mask:0xf bank_mask:0xf bound_ctrl:0
	v_add_f32_dpp v154, v154, v154 row_shr:2 row_mask:0xf bank_mask:0xf bound_ctrl:0
	v_add_f32_dpp v155, v155, v155 row_shr:2 row_mask:0xf bank_mask:0xf bound_ctrl:0
	v_add_f32_dpp v156, v156, v156 row_shr:2 row_mask:0xf bank_mask:0xf bound_ctrl:0
	v_add_f32_dpp v149, v149, v149 row_shr:4 row_mask:0xf bank_mask:0xf bound_ctrl:0
	v_add_f32_dpp v150, v150, v150 row_shr:4 row_mask:0xf bank_mask:0xf bound_ctrl:0
	v_add_f32_dpp v151, v151, v151 row_shr:4 row_mask:0xf bank_mask:0xf bound_ctrl:0
	v_add_f32_dpp v152, v152, v152 row_shr:4 row_mask:0xf bank_mask:0xf bound_ctrl:0
	v_add_f32_dpp v153, v153, v153 row_shr:4 row_mask:0xf bank_mask:0xf bound_ctrl:0
	v_add_f32_dpp v154, v154, v154 row_shr:4 row_mask:0xf bank_mask:0xf bound_ctrl:0
	v_add_f32_dpp v155, v155, v155 row_shr:4 row_mask:0xf bank_mask:0xf bound_ctrl:0
	v_add_f32_dpp v156, v156, v156 row_shr:4 row_mask:0xf bank_mask:0xf bound_ctrl:0
	v_add_f32_dpp v149, v149, v149 row_shr:8 row_mask:0xf bank_mask:0xf bound_ctrl:0
	v_add_f32_dpp v150, v150, v150 row_shr:8 row_mask:0xf bank_mask:0xf bound_ctrl:0
	v_add_f32_dpp v151, v151, v151 row_shr:8 row_mask:0xf bank_mask:0xf bound_ctrl:0
	v_add_f32_dpp v152, v152, v152 row_shr:8 row_mask:0xf bank_mask:0xf bound_ctrl:0
	v_add_f32_dpp v153, v153, v153 row_shr:8 row_mask:0xf bank_mask:0xf bound_ctrl:0
	v_add_f32_dpp v154, v154, v154 row_shr:8 row_mask:0xf bank_mask:0xf bound_ctrl:0
	v_add_f32_dpp v155, v155, v155 row_shr:8 row_mask:0xf bank_mask:0xf bound_ctrl:0
	v_add_f32_dpp v156, v156, v156 row_shr:8 row_mask:0xf bank_mask:0xf bound_ctrl:0
	v_cmp_eq_u32_e32 vcc, 15, v138
	s_and_saveexec_b64 s[6:7], vcc
	global_store_dword v148, v149, s[88:89]
	global_store_dword v148, v150, s[88:89] offset:16
	global_store_dword v148, v151, s[88:89] offset:32
	global_store_dword v148, v152, s[88:89] offset:48
	global_store_dword v148, v153, s[88:89] offset:64
	global_store_dword v148, v154, s[88:89] offset:80
	global_store_dword v148, v155, s[88:89] offset:96
	global_store_dword v148, v156, s[88:89] offset:112
	s_or_b64 exec, exec, s[6:7]
	s_waitcnt lgkmcnt(0)
; template <int EPI, int NRM>
; DEVI void epilogue(acc_t& acc, int pn, int trow, const EpiArgs& e, const float* rl, bf16* shmx) {
;     ...
;             const unsigned off = (unsigned)((tk0 + bj * 128 + n * 16) * DM + pn * 256 + ai * 128 + m * 16 + fl0);
;             const float4 xx = *reinterpret_cast<const float4*>(lbase + idx * 1024 + lane * 16);
;             float4 o;
;             o.x = xx.x + acc[ai][bj][m][n][0]; o.y = xx.y + acc[ai][bj][m][n][1];
;             o.z = xx.z + acc[ai][bj][m][n][2]; o.w = xx.w + acc[ai][bj][m][n][3];
;             *reinterpret_cast<float4*>(e.xout + off) = o;
;             uint2 ob; ob.x = pack2(o.x, o.y); ob.y = pack2(o.z, o.w);
;             *reinterpret_cast<uint2*>(e.o0 + off) = ob;
;             ss[bj][n] += o.x * o.x + o.y * o.y + o.z * o.z + o.w * o.w;
	ds_read_b128 v[50:53], v143
	ds_read_b128 v[58:61], v143 offset:1024
	ds_read_b128 v[62:65], v143 offset:2048
	ds_read_b128 v[66:69], v143 offset:3072
	ds_read_b128 v[74:77], v143 offset:4096
	ds_read_b128 v[82:85], v143 offset:5120
	ds_read_b128 v[90:93], v143 offset:6144
	ds_read_b128 v[98:101], v143 offset:7168
	ds_read_b128 v[38:41], v143 offset:8192
	ds_read_b128 v[34:37], v143 offset:9216
	ds_read_b128 v[30:33], v143 offset:10240
	ds_read_b128 v[22:25], v143 offset:11264
	ds_read_b128 v[18:21], v143 offset:12288
	ds_read_b128 v[10:13], v143 offset:13312
	ds_read_b128 v[6:9], v143 offset:14336
	ds_read_b128 v[2:5], v143 offset:15360
	s_waitcnt lgkmcnt(0)
	s_waitcnt vmcnt(39)
	v_pk_add_f32 v[166:167], v[166:167], v[50:51]
	v_pk_add_f32 v[168:169], v[168:169], v[52:53]
	v_add_u32_e32 v157, 0x100000, v144
	v_cvt_pk_bf16_f32 v158, v166, v167
	v_cvt_pk_bf16_f32 v159, v168, v169
	global_store_dwordx4 v157, v[166:169], s[26:27] nt
	v_add_u32_e32 v50, 0x80000, v146
	v_mul_f32_e32 v149, v166, v166
	global_store_dwordx2 v50, v[158:159], s[96:97]
	v_fmac_f32_e32 v149, v167, v167
	v_fmac_f32_e32 v149, v168, v168
	v_fmac_f32_e32 v149, v169, v169
	s_waitcnt vmcnt(40)
	v_pk_add_f32 v[170:171], v[170:171], v[58:59]
	v_pk_add_f32 v[172:173], v[172:173], v[60:61]
	v_add_u32_e32 v160, 0x108000, v145
	v_cvt_pk_bf16_f32 v164, v170, v171
	v_cvt_pk_bf16_f32 v165, v172, v173
	global_store_dwordx4 v160, v[170:173], s[26:27] nt
	v_add_u32_e32 v58, 0x84000, v147
	v_mul_f32_e32 v150, v170, v170
	global_store_dwordx2 v58, v[164:165], s[96:97]
	v_fmac_f32_e32 v150, v171, v171
	v_fmac_f32_e32 v150, v172, v172
	v_fmac_f32_e32 v150, v173, v173
	s_waitcnt vmcnt(41)
	v_pk_add_f32 v[174:175], v[174:175], v[62:63]
	v_pk_add_f32 v[176:177], v[176:177], v[64:65]
	v_add_u32_e32 v157, 0x110000, v144
	v_cvt_pk_bf16_f32 v158, v174, v175
	v_cvt_pk_bf16_f32 v159, v176, v177
	global_store_dwordx4 v157, v[174:177], s[26:27] nt
	v_add_u32_e32 v62, 0x88000, v146
	v_mul_f32_e32 v151, v174, v174
	global_store_dwordx2 v62, v[158:159], s[96:97]
	v_fmac_f32_e32 v151, v175, v175
	v_fmac_f32_e32 v151, v176, v176
	v_fmac_f32_e32 v151, v177, v177
	s_waitcnt vmcnt(42)
	v_pk_add_f32 v[178:179], v[178:179], v[66:67]
	v_pk_add_f32 v[180:181], v[180:181], v[68:69]
	v_add_u32_e32 v160, 0x118000, v145
	v_cvt_pk_bf16_f32 v164, v178, v179
	v_cvt_pk_bf16_f32 v165, v180, v181
	global_store_dwordx4 v160, v[178:181], s[26:27] nt
	v_add_u32_e32 v66, 0x8c000, v147
	v_mul_f32_e32 v152, v178, v178
	global_store_dwordx2 v66, v[164:165], s[96:97]
	v_fmac_f32_e32 v152, v179, v179
	v_fmac_f32_e32 v152, v180, v180
	v_fmac_f32_e32 v152, v181, v181
	s_waitcnt vmcnt(43)
	v_pk_add_f32 v[182:183], v[182:183], v[74:75]
	v_pk_add_f32 v[184:185], v[184:185], v[76:77]
	v_add_u32_e32 v157, 0x120000, v144
	v_cvt_pk_bf16_f32 v158, v182, v183
	v_cvt_pk_bf16_f32 v159, v184, v185
	global_store_dwordx4 v157, v[182:185], s[26:27] nt
	v_add_u32_e32 v74, 0x90000, v146
	v_mul_f32_e32 v153, v182, v182
	global_store_dwordx2 v74, v[158:159], s[96:97]
	v_fmac_f32_e32 v153, v183, v183
	v_fmac_f32_e32 v153, v184, v184
	v_fmac_f32_e32 v153, v185, v185
	s_waitcnt vmcnt(44)
	v_pk_add_f32 v[186:187], v[186:187], v[82:83]
	v_pk_add_f32 v[188:189], v[188:189], v[84:85]
	v_add_u32_e32 v160, 0x128000, v145
	v_cvt_pk_bf16_f32 v164, v186, v187
	v_cvt_pk_bf16_f32 v165, v188, v189
	global_store_dwordx4 v160, v[186:189], s[26:27] nt
	v_add_u32_e32 v82, 0x94000, v147
	v_mul_f32_e32 v154, v186, v186
	global_store_dwordx2 v82, v[164:165], s[96:97]
	v_fmac_f32_e32 v154, v187, v187
	v_fmac_f32_e32 v154, v188, v188
	v_fmac_f32_e32 v154, v189, v189
	s_waitcnt vmcnt(45)
	v_pk_add_f32 v[190:191], v[190:191], v[90:91]
	v_pk_add_f32 v[192:193], v[192:193], v[92:93]
	v_add_u32_e32 v157, 0x130000, v144
	v_cvt_pk_bf16_f32 v158, v190, v191
	v_cvt_pk_bf16_f32 v159, v192, v193
	global_store_dwordx4 v157, v[190:193], s[26:27] nt
	v_add_u32_e32 v90, 0x98000, v146
	v_mul_f32_e32 v155, v190, v190
	global_store_dwordx2 v90, v[158:159], s[96:97]
	v_fmac_f32_e32 v155, v191, v191
	v_fmac_f32_e32 v155, v192, v192
	v_fmac_f32_e32 v155, v193, v193
	s_waitcnt vmcnt(46)
	v_pk_add_f32 v[194:195], v[194:195], v[98:99]
	v_pk_add_f32 v[196:197], v[196:197], v[100:101]
	v_add_u32_e32 v160, 0x138000, v145
	v_cvt_pk_bf16_f32 v164, v194, v195
	v_cvt_pk_bf16_f32 v165, v196, v197
	global_store_dwordx4 v160, v[194:197], s[26:27] nt
	v_add_u32_e32 v98, 0x9c000, v147
	v_mul_f32_e32 v156, v194, v194
	global_store_dwordx2 v98, v[164:165], s[96:97]
	v_fmac_f32_e32 v156, v195, v195
	v_fmac_f32_e32 v156, v196, v196
	v_fmac_f32_e32 v156, v197, v197
	s_waitcnt vmcnt(31)
	v_pk_add_f32 v[198:199], v[198:199], v[38:39]
	v_pk_add_f32 v[200:201], v[200:201], v[40:41]
	v_add_u32_e32 v157, 0x100200, v144
	v_cvt_pk_bf16_f32 v158, v198, v199
	v_cvt_pk_bf16_f32 v159, v200, v201
	global_store_dwordx4 v157, v[198:201], s[26:27] nt
	v_add_u32_e32 v38, 0x80100, v146
	v_fmac_f32_e32 v149, v198, v198
	global_store_dwordx2 v38, v[158:159], s[96:97]
	v_fmac_f32_e32 v149, v199, v199
	v_fmac_f32_e32 v149, v200, v200
	v_fmac_f32_e32 v149, v201, v201
	s_waitcnt vmcnt(32)
	v_pk_add_f32 v[202:203], v[202:203], v[34:35]
	v_pk_add_f32 v[204:205], v[204:205], v[36:37]
	v_add_u32_e32 v160, 0x108200, v145
	v_cvt_pk_bf16_f32 v164, v202, v203
	v_cvt_pk_bf16_f32 v165, v204, v205
	global_store_dwordx4 v160, v[202:205], s[26:27] nt
	v_add_u32_e32 v34, 0x84100, v147
	v_fmac_f32_e32 v150, v202, v202
	global_store_dwordx2 v34, v[164:165], s[96:97]
	v_fmac_f32_e32 v150, v203, v203
	v_fmac_f32_e32 v150, v204, v204
	v_fmac_f32_e32 v150, v205, v205
	s_waitcnt vmcnt(33)
; template <int EPI, int NRM>
; DEVI void epilogue(acc_t& acc, int pn, int trow, const EpiArgs& e, const float* rl, bf16* shmx) {
;     ...
;             const unsigned off = (unsigned)((tk0 + bj * 128 + n * 16) * DM + pn * 256 + ai * 128 + m * 16 + fl0);
;             const float4 xx = *reinterpret_cast<const float4*>(lbase + idx * 1024 + lane * 16);
;             float4 o;
;             o.x = xx.x + acc[ai][bj][m][n][0]; o.y = xx.y + acc[ai][bj][m][n][1];
;             o.z = xx.z + acc[ai][bj][m][n][2]; o.w = xx.w + acc[ai][bj][m][n][3];
;             *reinterpret_cast<float4*>(e.xout + off) = o;
;             uint2 ob; ob.x = pack2(o.x, o.y); ob.y = pack2(o.z, o.w);
;             *reinterpret_cast<uint2*>(e.o0 + off) = ob;
;             ss[bj][n] += o.x * o.x + o.y * o.y + o.z * o.z + o.w * o.w;
;           }
;       asm volatile("s_waitcnt lgkmcnt(0)" ::: "memory");
;     }
; #pragma unroll
;     for (int bj = 0; bj < 2; ++bj)
; #pragma unroll
;       for (int n = 0; n < 2; ++n) {
;         float v = ss[bj][n];
;         v += __shfl_xor(v, 16); v += __shfl_xor(v, 32);
;         if (fq == 0) e.stw[(pn * 2 + wr) * TOK + tk0 + bj * 128 + n * 16] = v;
;       }
	v_pk_add_f32 v[206:207], v[206:207], v[30:31]
	v_pk_add_f32 v[208:209], v[208:209], v[32:33]
	v_add_u32_e32 v157, 0x110200, v144
	v_cvt_pk_bf16_f32 v158, v206, v207
	v_cvt_pk_bf16_f32 v159, v208, v209
	global_store_dwordx4 v157, v[206:209], s[26:27] nt
	v_add_u32_e32 v30, 0x88100, v146
	v_fmac_f32_e32 v151, v206, v206
	global_store_dwordx2 v30, v[158:159], s[96:97]
	v_fmac_f32_e32 v151, v207, v207
	v_fmac_f32_e32 v151, v208, v208
	v_fmac_f32_e32 v151, v209, v209
	s_waitcnt vmcnt(34)
	v_pk_add_f32 v[210:211], v[210:211], v[22:23]
	v_pk_add_f32 v[212:213], v[212:213], v[24:25]
	v_add_u32_e32 v160, 0x118200, v145
	v_cvt_pk_bf16_f32 v164, v210, v211
	v_cvt_pk_bf16_f32 v165, v212, v213
	global_store_dwordx4 v160, v[210:213], s[26:27] nt
	v_add_u32_e32 v22, 0x8c100, v147
	v_fmac_f32_e32 v152, v210, v210
	global_store_dwordx2 v22, v[164:165], s[96:97]
	v_fmac_f32_e32 v152, v211, v211
	v_fmac_f32_e32 v152, v212, v212
	v_fmac_f32_e32 v152, v213, v213
	s_waitcnt vmcnt(35)
	v_pk_add_f32 v[214:215], v[214:215], v[18:19]
	v_pk_add_f32 v[216:217], v[216:217], v[20:21]
	v_add_u32_e32 v157, 0x120200, v144
	v_cvt_pk_bf16_f32 v158, v214, v215
	v_cvt_pk_bf16_f32 v159, v216, v217
	global_store_dwordx4 v157, v[214:217], s[26:27] nt
	v_add_u32_e32 v18, 0x90100, v146
	v_fmac_f32_e32 v153, v214, v214
	global_store_dwordx2 v18, v[158:159], s[96:97]
	v_fmac_f32_e32 v153, v215, v215
	v_fmac_f32_e32 v153, v216, v216
	v_fmac_f32_e32 v153, v217, v217
	s_waitcnt vmcnt(36)
	v_pk_add_f32 v[218:219], v[218:219], v[10:11]
	v_pk_add_f32 v[220:221], v[220:221], v[12:13]
	v_add_u32_e32 v160, 0x128200, v145
	v_cvt_pk_bf16_f32 v164, v218, v219
	v_cvt_pk_bf16_f32 v165, v220, v221
	global_store_dwordx4 v160, v[218:221], s[26:27] nt
	v_add_u32_e32 v10, 0x94100, v147
	v_fmac_f32_e32 v154, v218, v218
	global_store_dwordx2 v10, v[164:165], s[96:97]
	v_fmac_f32_e32 v154, v219, v219
	v_fmac_f32_e32 v154, v220, v220
	v_fmac_f32_e32 v154, v221, v221
	s_waitcnt vmcnt(37)
	v_pk_add_f32 v[222:223], v[222:223], v[6:7]
	v_pk_add_f32 v[224:225], v[224:225], v[8:9]
	v_add_u32_e32 v157, 0x130200, v144
	v_cvt_pk_bf16_f32 v158, v222, v223
	v_cvt_pk_bf16_f32 v159, v224, v225
	global_store_dwordx4 v157, v[222:225], s[26:27] nt
	v_add_u32_e32 v6, 0x98100, v146
	v_fmac_f32_e32 v155, v222, v222
	global_store_dwordx2 v6, v[158:159], s[96:97]
	v_fmac_f32_e32 v155, v223, v223
	v_fmac_f32_e32 v155, v224, v224
	v_fmac_f32_e32 v155, v225, v225
	s_waitcnt vmcnt(38)
	v_pk_add_f32 v[226:227], v[226:227], v[2:3]
	v_pk_add_f32 v[228:229], v[228:229], v[4:5]
	v_add_u32_e32 v160, 0x138200, v145
	v_cvt_pk_bf16_f32 v164, v226, v227
	v_cvt_pk_bf16_f32 v165, v228, v229
	global_store_dwordx4 v160, v[226:229], s[26:27] nt
	v_add_u32_e32 v2, 0x9c100, v147
	v_fmac_f32_e32 v156, v226, v226
	global_store_dwordx2 v2, v[164:165], s[96:97]
	v_fmac_f32_e32 v156, v227, v227
	v_fmac_f32_e32 v156, v228, v228
	v_fmac_f32_e32 v156, v229, v229
	v_add_f32_dpp v149, v149, v149 row_shr:1 row_mask:0xf bank_mask:0xf bound_ctrl:0
	v_add_f32_dpp v150, v150, v150 row_shr:1 row_mask:0xf bank_mask:0xf bound_ctrl:0
	v_add_f32_dpp v151, v151, v151 row_shr:1 row_mask:0xf bank_mask:0xf bound_ctrl:0
	v_add_f32_dpp v152, v152, v152 row_shr:1 row_mask:0xf bank_mask:0xf bound_ctrl:0
	v_add_f32_dpp v153, v153, v153 row_shr:1 row_mask:0xf bank_mask:0xf bound_ctrl:0
	v_add_f32_dpp v154, v154, v154 row_shr:1 row_mask:0xf bank_mask:0xf bound_ctrl:0
	v_add_f32_dpp v155, v155, v155 row_shr:1 row_mask:0xf bank_mask:0xf bound_ctrl:0
	v_add_f32_dpp v156, v156, v156 row_shr:1 row_mask:0xf bank_mask:0xf bound_ctrl:0
	v_add_f32_dpp v149, v149, v149 row_shr:2 row_mask:0xf bank_mask:0xf bound_ctrl:0
	v_add_f32_dpp v150, v150, v150 row_shr:2 row_mask:0xf bank_mask:0xf bound_ctrl:0
	v_add_f32_dpp v151, v151, v151 row_shr:2 row_mask:0xf bank_mask:0xf bound_ctrl:0
	v_add_f32_dpp v152, v152, v152 row_shr:2 row_mask:0xf bank_mask:0xf bound_ctrl:0
	v_add_f32_dpp v153, v153, v153 row_shr:2 row_mask:0xf bank_mask:0xf bound_ctrl:0
	v_add_f32_dpp v154, v154, v154 row_shr:2 row_mask:0xf bank_mask:0xf bound_ctrl:0
	v_add_f32_dpp v155, v155, v155 row_shr:2 row_mask:0xf bank_mask:0xf bound_ctrl:0
	v_add_f32_dpp v156, v156, v156 row_shr:2 row_mask:0xf bank_mask:0xf bound_ctrl:0
	v_add_f32_dpp v149, v149, v149 row_shr:4 row_mask:0xf bank_mask:0xf bound_ctrl:0
	v_add_f32_dpp v150, v150, v150 row_shr:4 row_mask:0xf bank_mask:0xf bound_ctrl:0
	v_add_f32_dpp v151, v151, v151 row_shr:4 row_mask:0xf bank_mask:0xf bound_ctrl:0
	v_add_f32_dpp v152, v152, v152 row_shr:4 row_mask:0xf bank_mask:0xf bound_ctrl:0
	v_add_f32_dpp v153, v153, v153 row_shr:4 row_mask:0xf bank_mask:0xf bound_ctrl:0
	v_add_f32_dpp v154, v154, v154 row_shr:4 row_mask:0xf bank_mask:0xf bound_ctrl:0
	v_add_f32_dpp v155, v155, v155 row_shr:4 row_mask:0xf bank_mask:0xf bound_ctrl:0
	v_add_f32_dpp v156, v156, v156 row_shr:4 row_mask:0xf bank_mask:0xf bound_ctrl:0
	v_add_f32_dpp v149, v149, v149 row_shr:8 row_mask:0xf bank_mask:0xf bound_ctrl:0
	v_add_f32_dpp v150, v150, v150 row_shr:8 row_mask:0xf bank_mask:0xf bound_ctrl:0
	v_add_f32_dpp v151, v151, v151 row_shr:8 row_mask:0xf bank_mask:0xf bound_ctrl:0
	v_add_f32_dpp v152, v152, v152 row_shr:8 row_mask:0xf bank_mask:0xf bound_ctrl:0
	v_add_f32_dpp v153, v153, v153 row_shr:8 row_mask:0xf bank_mask:0xf bound_ctrl:0
	v_add_f32_dpp v154, v154, v154 row_shr:8 row_mask:0xf bank_mask:0xf bound_ctrl:0
	v_add_f32_dpp v155, v155, v155 row_shr:8 row_mask:0xf bank_mask:0xf bound_ctrl:0
	v_add_f32_dpp v156, v156, v156 row_shr:8 row_mask:0xf bank_mask:0xf bound_ctrl:0
	v_cmp_eq_u32_e32 vcc, 15, v138
	s_and_saveexec_b64 s[6:7], vcc
	global_store_dword v148, v149, s[88:89] offset:512
	global_store_dword v148, v150, s[88:89] offset:528
	global_store_dword v148, v151, s[88:89] offset:544
	global_store_dword v148, v152, s[88:89] offset:560
	global_store_dword v148, v153, s[88:89] offset:576
	global_store_dword v148, v154, s[88:89] offset:592
	global_store_dword v148, v155, s[88:89] offset:608
	global_store_dword v148, v156, s[88:89] offset:624
	s_branch .LBB0_1697

; #define RS for (int rep_ = 0; rep_ < REPS; ++rep_)
; #define PH_BEGIN if (ph >= lo && ph < hi) {
; DEVI void convT(const float* __restrict__ src, int K, int N, bf16* __restrict__ dst, int ldd, int blk, int blk_stride,
;                 int row_off, const float* __restrict__ nscale, const float* __restrict__ kscale, float* lds) {
;   const int tid = threadIdx.x;
;   const int tilesN = (N + 63) / 64, tilesK = K / 64;
;   const int ntl = tilesN * tilesK;
;   const int lk = tid / 16, ln = (tid % 16) * 4;
;   int tile = blockIdx.x;
;   float4 c0 = make_float4(0.f, 0.f, 0.f, 0.f), c1 = c0;
;   if (tile < ntl) {
;     const int n0 = (tile % tilesN) * 64, k0 = (tile / tilesN) * 64;
;     if (n0 + ln < N) {
;       c0 = *reinterpret_cast<const float4*>(src + (long)(k0 + lk) * N + n0 + ln);
;       c1 = *reinterpret_cast<const float4*>(src + (long)(k0 + lk + 32) * N + n0 + ln);
;     }
;   }
; template <int L>
; DEVI void run_layer(const Params& p, const int lo, const int hi, int& ph, unsigned& nbar, cg::grid_group& grid, bf16* shm) {
;     ...
;   PH_BEGIN
;    RS {
;     if constexpr (type == 0) {
;       convT(p.in[base + 1], DM, DM, (bf16*)(ws + W_IN), DM, DM, 0, 0, nullptr, p.in[base], lds);
.LBB0_1740:
	s_cmp_gt_i32 s30, 21
	s_cselect_b64 s[0:1], -1, 0
	s_cmp_lt_i32 s31, 22
	s_cselect_b64 s[2:3], -1, 0
	s_or_b64 s[0:1], s[0:1], s[2:3]
	s_and_b64 vcc, exec, s[0:1]
	s_cbranch_vccnz .LBB0_1885
	s_cmpk_lt_i32 s92, 0x400
	s_cselect_b64 s[4:5], -1, 0
	s_ashr_i32 s0, s92, 31
	s_lshr_b32 s0, s0, 27
	s_add_i32 s0, s92, s0
	v_and_b32_e32 v30, 0x3ff, v0
	s_and_b32 s1, s0, 0x3ffffe0
	s_lshl_b32 s0, s0, 1
	v_lshlrev_b32_e32 v2, 2, v30
	s_andn2_b32 s0, s0, 63
	v_and_b32_e32 v28, 60, v2
	v_or_b32_e32 v2, s0, v1
	s_waitcnt lgkmcnt(0)
	v_ashrrev_i32_e32 v3, 31, v2
	v_lshlrev_b64 v[20:21], 13, v[2:3]
	v_mul_u32_u24_e32 v2, 0x41, v1
	s_sub_i32 s1, s92, s1
	v_lshlrev_b32_e32 v18, 2, v28
	v_lshlrev_b32_e32 v2, 2, v2
	s_lshl_b32 s6, s1, 6
	v_add3_u32 v31, 0, v18, v2
	v_add3_u32 v32, 0, v2, v18
	v_lshlrev_b32_e32 v2, 3, v30
	s_ashr_i32 s7, s6, 31
	v_and_b32_e32 v33, 56, v2
	v_or_b32_e32 v2, s6, v28
	s_movk_i32 s0, 0x800
	s_cmpk_gt_i32 s92, 0x3ff
	v_mov_b32_e32 v10, 0
	v_or_b32_e32 v22, 0x40000, v20
	v_mov_b32_e32 v23, v21
	s_waitcnt vmcnt(4)
	v_mul_u32_u24_e32 v34, 0x104, v33
	v_cmp_gt_i32_e64 s[0:1], s0, v2
	s_cbranch_scc1 .LBB0_1768
	v_mov_b32_e32 v11, 0
	v_mov_b32_e32 v12, 0
	v_mov_b32_e32 v13, 0
	v_mov_b32_e32 v14, 0
	v_mov_b32_e32 v15, 0
	v_mov_b32_e32 v16, 0
	v_mov_b32_e32 v17, 0
	s_and_saveexec_b64 s[2:3], s[0:1]
	s_cbranch_execz .LBB0_1744
	s_lshl_b64 s[8:9], s[6:7], 2
	v_lshl_add_u64 v[4:5], s[68:69], 0, v[20:21]
	v_lshl_add_u64 v[2:3], s[68:69], 0, v[22:23]
	v_mov_b32_e32 v19, 0
	v_lshl_add_u64 v[4:5], v[4:5], 0, s[8:9]
	v_lshl_add_u64 v[2:3], v[2:3], 0, s[8:9]
	v_lshl_add_u64 v[4:5], v[4:5], 0, v[18:19]
	v_lshl_add_u64 v[2:3], v[2:3], 0, v[18:19]
	global_load_dwordx4 v[14:17], v[4:5], off nt
	global_load_dwordx4 v[10:13], v[2:3], off nt

; DEVI void convT(const float* __restrict__ src, int K, int N, bf16* __restrict__ dst, int ldd, int blk, int blk_stride,
;                 int row_off, const float* __restrict__ nscale, const float* __restrict__ kscale, float* lds) {
;     ...
;   while (tile < ntl) {
;     const int n0 = (tile % tilesN) * 64, k0 = (tile / tilesN) * 64;
;     const int nxt = tile + gridDim.x;
;     float4 d0 = make_float4(0.f, 0.f, 0.f, 0.f), d1 = d0;
;     if (nxt < ntl) {
;       const int n2 = (nxt % tilesN) * 64, k2 = (nxt / tilesN) * 64;
;       if (n2 + ln < N) {
;         d0 = *reinterpret_cast<const float4*>(src + (long)(k2 + lk) * N + n2 + ln);
;         d1 = *reinterpret_cast<const float4*>(src + (long)(k2 + lk + 32) * N + n2 + ln);
;       }
;     }
.LBB0_1747:
	s_add_i32 s18, s15, s12
	s_cmpk_gt_i32 s18, 0x3ff
	s_cselect_b64 s[8:9], -1, 0
	s_and_b64 vcc, exec, s[8:9]
	v_mov_b32_e32 v6, 0
	v_mov_b32_e32 v7, 0
	v_mov_b32_e32 v8, 0
	v_mov_b32_e32 v9, 0
	v_mov_b32_e32 v2, 0
	v_mov_b32_e32 v3, 0
	v_mov_b32_e32 v4, 0
	v_mov_b32_e32 v5, 0
	s_cbranch_vccnz .LBB0_1751
	s_ashr_i32 s10, s18, 31
	s_lshr_b32 s10, s10, 27
	s_add_i32 s10, s18, s10
	s_ashr_i32 s13, s10, 5
	s_lshl_b32 s19, s13, 11
	s_sub_i32 s10, s16, s19
	v_add_u32_e32 v2, s10, v26
	v_cmp_gt_i32_e32 vcc, s14, v2
	v_mov_b32_e32 v5, 0
	v_mov_b32_e32 v4, 0
	v_mov_b32_e32 v3, 0
	v_mov_b32_e32 v2, 0
	v_mov_b32_e32 v9, 0
	v_mov_b32_e32 v8, 0
	v_mov_b32_e32 v7, 0
	v_mov_b32_e32 v6, 0
	s_and_saveexec_b64 s[10:11], vcc
	s_cbranch_execz .LBB0_1750
	v_lshl_or_b32 v2, s13, 6, v1
	s_sub_i32 s19, 0, s19
	s_add_i32 s20, s17, s16
	v_ashrrev_i32_e32 v3, 31, v2
	s_add_i32 s20, s20, s19
	v_lshlrev_b64 v[2:3], 13, v[2:3]
	v_lshl_add_u64 v[2:3], s[68:69], 0, v[2:3]
	s_ashr_i32 s21, s20, 31
	v_lshl_add_u64 v[2:3], s[20:21], 2, v[2:3]
	v_mov_b32_e32 v19, v25
	v_lshl_add_u64 v[2:3], v[2:3], 0, v[18:19]
	v_add_co_u32_e32 v6, vcc, 0x40000, v2
	s_nop 1
	v_addc_co_u32_e32 v7, vcc, 0, v3, vcc
	global_load_dwordx4 v[2:5], v[2:3], off nt
	s_nop 0
	global_load_dwordx4 v[6:9], v[6:7], off nt

; DEVI void convT(const float* __restrict__ src, int K, int N, bf16* __restrict__ dst, int ldd, int blk, int blk_stride,
;                 int row_off, const float* __restrict__ nscale, const float* __restrict__ kscale, float* lds) {
;   const int tid = threadIdx.x;
;   const int tilesN = (N + 63) / 64, tilesK = K / 64;
;   const int ntl = tilesN * tilesK;
;   const int lk = tid / 16, ln = (tid % 16) * 4;
;   int tile = blockIdx.x;
;   float4 c0 = make_float4(0.f, 0.f, 0.f, 0.f), c1 = c0;
;   if (tile < ntl) {
;     const int n0 = (tile % tilesN) * 64, k0 = (tile / tilesN) * 64;
;     if (n0 + ln < N) {
;       c0 = *reinterpret_cast<const float4*>(src + (long)(k0 + lk) * N + n0 + ln);
;       c1 = *reinterpret_cast<const float4*>(src + (long)(k0 + lk + 32) * N + n0 + ln);
;     }
;   }
; template <int L>
; DEVI void run_layer(const Params& p, const int lo, const int hi, int& ph, unsigned& nbar, cg::grid_group& grid, bf16* shm) {
;     ...
;       convT(p.in[base + 4], DM, DM, (bf16*)(ws + W_OUT), DM, DM, 0, 0, nullptr, p.in[base + 3], lds);
.LBB0_1771:
	s_or_b64 exec, exec, s[2:3]
	s_andn2_b64 vcc, exec, s[4:5]
	s_cbranch_vccnz .LBB0_1798
	v_mov_b32_e32 v25, 0
	v_mov_b32_e32 v10, 0
	v_mov_b32_e32 v11, 0
	v_mov_b32_e32 v12, 0
	v_mov_b32_e32 v13, 0
	v_mov_b32_e32 v14, 0
	v_mov_b32_e32 v15, 0
	v_mov_b32_e32 v16, 0
	v_mov_b32_e32 v17, 0
	s_and_saveexec_b64 s[2:3], s[0:1]
	s_cbranch_execz .LBB0_1774
	s_lshl_b64 s[4:5], s[6:7], 2
	v_lshl_add_u64 v[4:5], s[74:75], 0, v[20:21]
	v_lshl_add_u64 v[2:3], s[74:75], 0, v[22:23]
	v_mov_b32_e32 v19, 0
	v_lshl_add_u64 v[4:5], v[4:5], 0, s[4:5]
	v_lshl_add_u64 v[2:3], v[2:3], 0, s[4:5]
	v_lshl_add_u64 v[4:5], v[4:5], 0, v[18:19]
	v_lshl_add_u64 v[2:3], v[2:3], 0, v[18:19]
	global_load_dwordx4 v[14:17], v[4:5], off nt
	global_load_dwordx4 v[10:13], v[2:3], off nt

; DEVI void convT(const float* __restrict__ src, int K, int N, bf16* __restrict__ dst, int ldd, int blk, int blk_stride,
;                 int row_off, const float* __restrict__ nscale, const float* __restrict__ kscale, float* lds) {
;     ...
;   while (tile < ntl) {
;     const int n0 = (tile % tilesN) * 64, k0 = (tile / tilesN) * 64;
;     const int nxt = tile + gridDim.x;
;     float4 d0 = make_float4(0.f, 0.f, 0.f, 0.f), d1 = d0;
;     if (nxt < ntl) {
;       const int n2 = (nxt % tilesN) * 64, k2 = (nxt / tilesN) * 64;
;       if (n2 + ln < N) {
;         d0 = *reinterpret_cast<const float4*>(src + (long)(k2 + lk) * N + n2 + ln);
;         d1 = *reinterpret_cast<const float4*>(src + (long)(k2 + lk + 32) * N + n2 + ln);
;       }
;     }
.LBB0_1777:
	s_add_i32 s18, s14, s12
	s_cmpk_gt_i32 s18, 0x3ff
	s_cselect_b64 s[8:9], -1, 0
	v_mov_b32_e32 v2, 0
	s_and_b64 vcc, exec, s[8:9]
	v_mov_b32_e32 v3, 0
	v_mov_b32_e32 v4, 0
	v_mov_b32_e32 v5, 0
	v_mov_b32_e32 v6, 0
	v_mov_b32_e32 v7, 0
	v_mov_b32_e32 v8, 0
	v_mov_b32_e32 v9, 0
	s_cbranch_vccnz .LBB0_1781
	s_ashr_i32 s10, s18, 31
	s_lshr_b32 s10, s10, 27
	s_add_i32 s10, s18, s10
	s_ashr_i32 s13, s10, 5
	s_lshl_b32 s19, s13, 11
	s_sub_i32 s10, s15, s19
	v_add_u32_e32 v2, s10, v26
	v_cmp_gt_i32_e32 vcc, s17, v2
	v_mov_b32_e32 v9, 0
	v_mov_b32_e32 v8, 0
	v_mov_b32_e32 v7, 0
	v_mov_b32_e32 v6, 0
	v_mov_b32_e32 v5, 0
	v_mov_b32_e32 v4, 0
	v_mov_b32_e32 v3, 0
	v_mov_b32_e32 v2, 0
	s_and_saveexec_b64 s[10:11], vcc
	s_cbranch_execz .LBB0_1780
	v_lshl_or_b32 v2, s13, 6, v1
	s_sub_i32 s19, 0, s19
	s_add_i32 s20, s16, s15
	v_ashrrev_i32_e32 v3, 31, v2
	s_add_i32 s20, s20, s19
	v_lshlrev_b64 v[2:3], 13, v[2:3]
	v_lshl_add_u64 v[2:3], s[74:75], 0, v[2:3]
	s_ashr_i32 s21, s20, 31
	v_lshl_add_u64 v[2:3], s[20:21], 2, v[2:3]
	v_mov_b32_e32 v19, v25
	v_lshl_add_u64 v[2:3], v[2:3], 0, v[18:19]
	v_add_co_u32_e32 v4, vcc, 0x40000, v2
	s_nop 1
	v_addc_co_u32_e32 v5, vcc, 0, v3, vcc
	global_load_dwordx4 v[6:9], v[2:3], off nt
	s_nop 0
	global_load_dwordx4 v[2:5], v[4:5], off nt

; DEVI void convT(const float* __restrict__ src, int K, int N, bf16* __restrict__ dst, int ldd, int blk, int blk_stride,
;                 int row_off, const float* __restrict__ nscale, const float* __restrict__ kscale, float* lds) {
;   const int tid = threadIdx.x;
;   const int tilesN = (N + 63) / 64, tilesK = K / 64;
;   const int ntl = tilesN * tilesK;
;   const int lk = tid / 16, ln = (tid % 16) * 4;
;   int tile = blockIdx.x;
;   float4 c0 = make_float4(0.f, 0.f, 0.f, 0.f), c1 = c0;
;   if (tile < ntl) {
;     const int n0 = (tile % tilesN) * 64, k0 = (tile / tilesN) * 64;
;     if (n0 + ln < N) {
;       c0 = *reinterpret_cast<const float4*>(src + (long)(k0 + lk) * N + n0 + ln);
;       c1 = *reinterpret_cast<const float4*>(src + (long)(k0 + lk + 32) * N + n0 + ln);
;     }
;   }
; DEVI void convert_ffn(const Params& p, int ig, bf16* shm) {
;     ...
;   convT(p.in[ig], DM, DFF, (bf16*)(p.ws + W_GU), DM, 128, 256, 0, nullptr, p.in[ig - 1], lds);
.LBB0_1800:
	s_andn2_b64 vcc, exec, s[2:3]
	s_cbranch_vccnz .LBB0_1863
	s_mul_hi_i32 s2, s92, 0x2e8ba2e9
	s_lshr_b32 s3, s2, 31
	s_ashr_i32 s2, s2, 4
	s_add_i32 s2, s2, s3
	s_mul_i32 s3, s2, 0x58
	s_sub_i32 s3, s92, s3
	s_lshl_b32 s10, s3, 6
	v_or_b32_e32 v2, s10, v28
	s_movk_i32 s21, 0x1600
	v_cmp_gt_i32_e64 s[4:5], s21, v2
	v_lshl_or_b32 v2, s2, 6, v1
	s_movk_i32 s22, 0x5800
	v_mad_i64_i32 v[24:25], s[2:3], v2, s22, 0
	v_add_u32_e32 v2, 32, v2
	s_ashr_i32 s11, s10, 31
	v_mad_i64_i32 v[26:27], s[2:3], v2, s22, 0
	v_mov_b32_e32 v29, 0
	v_mov_b32_e32 v10, 0
	v_mov_b32_e32 v11, 0
	v_mov_b32_e32 v12, 0
	v_mov_b32_e32 v13, 0
	v_mov_b32_e32 v14, 0
	v_mov_b32_e32 v15, 0
	v_mov_b32_e32 v16, 0
	v_mov_b32_e32 v17, 0
	s_and_saveexec_b64 s[2:3], s[4:5]
	s_cbranch_execz .LBB0_1803
	s_lshl_b64 s[8:9], s[10:11], 2
	v_lshl_add_u64 v[4:5], s[78:79], 0, v[24:25]
	v_lshl_add_u64 v[2:3], s[78:79], 0, v[26:27]
	v_mov_b32_e32 v19, 0
	v_lshl_add_u64 v[4:5], v[4:5], 0, s[8:9]
	v_lshl_add_u64 v[2:3], v[2:3], 0, s[8:9]
	v_lshl_add_u64 v[4:5], v[4:5], 0, v[18:19]
	v_lshl_add_u64 v[2:3], v[2:3], 0, v[18:19]
	global_load_dwordx4 v[14:17], v[4:5], off nt
	global_load_dwordx4 v[10:13], v[2:3], off nt

; DEVI void convT(const float* __restrict__ src, int K, int N, bf16* __restrict__ dst, int ldd, int blk, int blk_stride,
;                 int row_off, const float* __restrict__ nscale, const float* __restrict__ kscale, float* lds) {
;     ...
;   while (tile < ntl) {
;     const int n0 = (tile % tilesN) * 64, k0 = (tile / tilesN) * 64;
;     const int nxt = tile + gridDim.x;
;     float4 d0 = make_float4(0.f, 0.f, 0.f, 0.f), d1 = d0;
;     if (nxt < ntl) {
;       const int n2 = (nxt % tilesN) * 64, k2 = (nxt / tilesN) * 64;
;       if (n2 + ln < N) {
;         d0 = *reinterpret_cast<const float4*>(src + (long)(k2 + lk) * N + n2 + ln);
;         d1 = *reinterpret_cast<const float4*>(src + (long)(k2 + lk + 32) * N + n2 + ln);
;       }
;     }
; DEVI void convert_ffn(const Params& p, int ig, bf16* shm) {
;     ...
;   convT(p.in[ig], DM, DFF, (bf16*)(p.ws + W_GU), DM, 128, 256, 0, nullptr, p.in[ig - 1], lds);
.LBB0_1806:
	s_add_i32 s34, s18, s16
	s_cmpk_gt_i32 s34, 0xaff
	s_cselect_b64 s[12:13], -1, 0
	v_mov_b32_e32 v2, 0
	s_and_b64 vcc, exec, s[12:13]
	v_mov_b32_e32 v3, 0
	v_mov_b32_e32 v4, 0
	v_mov_b32_e32 v5, 0
	v_mov_b32_e32 v6, 0
	v_mov_b32_e32 v7, 0
	v_mov_b32_e32 v8, 0
	v_mov_b32_e32 v9, 0
	s_cbranch_vccnz .LBB0_1810
	s_mul_hi_i32 s14, s34, 0x2e8ba2e9
	s_lshr_b32 s15, s14, 31
	s_ashr_i32 s17, s14, 4
	s_add_i32 s17, s17, s15
	s_mul_i32 s35, s17, 0xffffea00
	s_add_i32 s14, s35, s23
	v_add_u32_e32 v2, s14, v35
	v_cmp_gt_i32_e32 vcc, s21, v2
	v_mov_b32_e32 v9, 0
	v_mov_b32_e32 v8, 0
	v_mov_b32_e32 v7, 0
	v_mov_b32_e32 v6, 0
	v_mov_b32_e32 v5, 0
	v_mov_b32_e32 v4, 0
	v_mov_b32_e32 v3, 0
	v_mov_b32_e32 v2, 0
	s_and_saveexec_b64 s[14:15], vcc
	s_cbranch_execz .LBB0_1809
	s_add_i32 s36, s20, s23
	s_add_i32 s36, s36, s35
	v_lshl_or_b32 v6, s17, 6, v1
	v_mov_b64_e32 v[2:3], s[78:79]
	v_mad_i64_i32 v[4:5], s[38:39], v6, s22, v[2:3]
	s_ashr_i32 s37, s36, 31
	v_add_u32_e32 v6, 32, v6
	s_lshl_b64 s[36:37], s[36:37], 2
	v_mad_i64_i32 v[2:3], s[38:39], v6, s22, v[2:3]
	v_lshl_add_u64 v[4:5], v[4:5], 0, s[36:37]
	v_mov_b32_e32 v19, v29
	v_lshl_add_u64 v[2:3], v[2:3], 0, s[36:37]
	v_lshl_add_u64 v[4:5], v[4:5], 0, v[18:19]
	v_lshl_add_u64 v[2:3], v[2:3], 0, v[18:19]
	global_load_dwordx4 v[6:9], v[4:5], off nt
	s_nop 0
	global_load_dwordx4 v[2:5], v[2:3], off nt

; DEVI void convT(const float* __restrict__ src, int K, int N, bf16* __restrict__ dst, int ldd, int blk, int blk_stride,
;                 int row_off, const float* __restrict__ nscale, const float* __restrict__ kscale, float* lds) {
;   const int tid = threadIdx.x;
;   const int tilesN = (N + 63) / 64, tilesK = K / 64;
;   const int ntl = tilesN * tilesK;
;   const int lk = tid / 16, ln = (tid % 16) * 4;
;   int tile = blockIdx.x;
;   float4 c0 = make_float4(0.f, 0.f, 0.f, 0.f), c1 = c0;
;   if (tile < ntl) {
;     const int n0 = (tile % tilesN) * 64, k0 = (tile / tilesN) * 64;
;     if (n0 + ln < N) {
;       c0 = *reinterpret_cast<const float4*>(src + (long)(k0 + lk) * N + n0 + ln);
;       c1 = *reinterpret_cast<const float4*>(src + (long)(k0 + lk + 32) * N + n0 + ln);
;     }
;   }
; DEVI void convert_ffn(const Params& p, int ig, bf16* shm) {
;     ...
;   convT(p.in[ig + 1], DM, DFF, (bf16*)(p.ws + W_GU), DM, 128, 256, 128, nullptr, p.in[ig - 1], lds);
.LBB0_1827:
	v_mov_b32_e32 v29, 0
	v_mov_b32_e32 v10, 0
	v_mov_b32_e32 v11, 0
	v_mov_b32_e32 v12, 0
	v_mov_b32_e32 v13, 0
	v_mov_b32_e32 v14, 0
	v_mov_b32_e32 v15, 0
	v_mov_b32_e32 v16, 0
	v_mov_b32_e32 v17, 0
	s_and_saveexec_b64 s[12:13], s[4:5]
	s_cbranch_execz .LBB0_1829
	s_lshl_b64 s[4:5], s[10:11], 2
	v_lshl_add_u64 v[4:5], s[80:81], 0, v[24:25]
	v_lshl_add_u64 v[2:3], s[80:81], 0, v[26:27]
	v_mov_b32_e32 v19, 0
	v_lshl_add_u64 v[4:5], v[4:5], 0, s[4:5]
	v_lshl_add_u64 v[2:3], v[2:3], 0, s[4:5]
	v_lshl_add_u64 v[4:5], v[4:5], 0, v[18:19]
	v_lshl_add_u64 v[2:3], v[2:3], 0, v[18:19]
	global_load_dwordx4 v[10:13], v[4:5], off nt
	global_load_dwordx4 v[14:17], v[2:3], off nt

; DEVI void convT(const float* __restrict__ src, int K, int N, bf16* __restrict__ dst, int ldd, int blk, int blk_stride,
;                 int row_off, const float* __restrict__ nscale, const float* __restrict__ kscale, float* lds) {
;     ...
;   while (tile < ntl) {
;     const int n0 = (tile % tilesN) * 64, k0 = (tile / tilesN) * 64;
;     const int nxt = tile + gridDim.x;
;     float4 d0 = make_float4(0.f, 0.f, 0.f, 0.f), d1 = d0;
;     if (nxt < ntl) {
;       const int n2 = (nxt % tilesN) * 64, k2 = (nxt / tilesN) * 64;
;       if (n2 + ln < N) {
;         d0 = *reinterpret_cast<const float4*>(src + (long)(k2 + lk) * N + n2 + ln);
;         d1 = *reinterpret_cast<const float4*>(src + (long)(k2 + lk + 32) * N + n2 + ln);
;       }
;     }
; DEVI void convert_ffn(const Params& p, int ig, bf16* shm) {
;     ...
;   convT(p.in[ig + 1], DM, DFF, (bf16*)(p.ws + W_GU), DM, 128, 256, 128, nullptr, p.in[ig - 1], lds);
.LBB0_1832:
	s_add_i32 s17, s12, s18
	s_cmpk_gt_i32 s17, 0xaff
	s_cselect_b64 s[4:5], -1, 0
	v_mov_b32_e32 v2, 0
	s_and_b64 vcc, exec, s[4:5]
	v_mov_b32_e32 v3, 0
	v_mov_b32_e32 v4, 0
	v_mov_b32_e32 v5, 0
	v_mov_b32_e32 v6, 0
	v_mov_b32_e32 v7, 0
	v_mov_b32_e32 v8, 0
	v_mov_b32_e32 v9, 0
	s_cbranch_vccnz .LBB0_1836
	s_mul_hi_i32 s10, s17, 0x2e8ba2e9
	s_lshr_b32 s11, s10, 31
	s_ashr_i32 s13, s10, 4
	s_add_i32 s13, s13, s11
	s_mul_i32 s21, s13, 0xffffea00
	s_add_i32 s10, s21, s16
	v_add_u32_e32 v2, s10, v35
	v_cmp_gt_i32_e32 vcc, s14, v2
	v_mov_b32_e32 v9, 0
	v_mov_b32_e32 v8, 0
	v_mov_b32_e32 v7, 0
	v_mov_b32_e32 v6, 0
	v_mov_b32_e32 v5, 0
	v_mov_b32_e32 v4, 0
	v_mov_b32_e32 v3, 0
	v_mov_b32_e32 v2, 0
	s_and_saveexec_b64 s[10:11], vcc
	s_cbranch_execz .LBB0_1835
	s_add_i32 s22, s20, s16
	s_add_i32 s22, s22, s21
	v_lshl_or_b32 v6, s13, 6, v1
	v_mov_b64_e32 v[2:3], s[80:81]
	s_ashr_i32 s23, s22, 31
	v_mad_i64_i32 v[4:5], s[34:35], v6, s15, v[2:3]
	s_lshl_b64 s[22:23], s[22:23], 2
	v_lshl_add_u64 v[4:5], v[4:5], 0, s[22:23]
	v_mov_b32_e32 v19, v29
	v_lshl_add_u64 v[26:27], v[4:5], 0, v[18:19]
	v_add_u32_e32 v4, 32, v6
	v_mad_i64_i32 v[2:3], s[34:35], v4, s15, v[2:3]
	v_lshl_add_u64 v[2:3], v[2:3], 0, s[22:23]
	v_lshl_add_u64 v[36:37], v[2:3], 0, v[18:19]
	global_load_dwordx4 v[6:9], v[26:27], off nt
	global_load_dwordx4 v[2:5], v[36:37], off nt

; DEVI void convT(const float* __restrict__ src, int K, int N, bf16* __restrict__ dst, int ldd, int blk, int blk_stride,
;                 int row_off, const float* __restrict__ nscale, const float* __restrict__ kscale, float* lds) {
;   const int tid = threadIdx.x;
;   const int tilesN = (N + 63) / 64, tilesK = K / 64;
;   const int ntl = tilesN * tilesK;
;   const int lk = tid / 16, ln = (tid % 16) * 4;
;   int tile = blockIdx.x;
;   float4 c0 = make_float4(0.f, 0.f, 0.f, 0.f), c1 = c0;
;   if (tile < ntl) {
;     const int n0 = (tile % tilesN) * 64, k0 = (tile / tilesN) * 64;
;     if (n0 + ln < N) {
;       c0 = *reinterpret_cast<const float4*>(src + (long)(k0 + lk) * N + n0 + ln);
;       c1 = *reinterpret_cast<const float4*>(src + (long)(k0 + lk + 32) * N + n0 + ln);
;     }
;   }
; DEVI void convert_ffn(const Params& p, int ig, bf16* shm) {
;     ...
;   convT(p.in[ig + 2], DFF, DM, (bf16*)(p.ws + W_DN), DFF, DM, 0, 0, nullptr, nullptr, lds);
.LBB0_1853:
	v_mov_b32_e32 v19, 0
	v_mov_b32_e32 v2, v19
	v_mov_b32_e32 v3, v19
	v_mov_b32_e32 v4, v19
	v_mov_b32_e32 v5, v19
	v_mov_b32_e32 v6, v19
	v_mov_b32_e32 v7, v19
	v_mov_b32_e32 v8, v19
	v_mov_b32_e32 v9, v19
	s_and_saveexec_b64 s[2:3], s[0:1]
	s_cbranch_execz .LBB0_1855
	v_lshl_add_u64 v[2:3], s[82:83], 0, v[22:23]
	s_lshl_b64 s[0:1], s[6:7], 2
	v_lshl_add_u64 v[2:3], v[2:3], 0, s[0:1]
	v_mov_b32_e32 v5, 0
	v_mov_b32_e32 v4, v18
	v_lshl_add_u64 v[10:11], v[2:3], 0, v[4:5]
	v_lshl_add_u64 v[2:3], s[82:83], 0, v[20:21]
	v_lshl_add_u64 v[2:3], v[2:3], 0, s[0:1]
	v_lshl_add_u64 v[12:13], v[2:3], 0, v[4:5]
	global_load_dwordx4 v[2:5], v[12:13], off nt
	global_load_dwordx4 v[6:9], v[10:11], off nt

; DEVI void convT(const float* __restrict__ src, int K, int N, bf16* __restrict__ dst, int ldd, int blk, int blk_stride,
;                 int row_off, const float* __restrict__ nscale, const float* __restrict__ kscale, float* lds) {
;     ...
;   while (tile < ntl) {
;     const int n0 = (tile % tilesN) * 64, k0 = (tile / tilesN) * 64;
;     const int nxt = tile + gridDim.x;
;     float4 d0 = make_float4(0.f, 0.f, 0.f, 0.f), d1 = d0;
;     if (nxt < ntl) {
;       const int n2 = (nxt % tilesN) * 64, k2 = (nxt / tilesN) * 64;
;       if (n2 + ln < N) {
;         d0 = *reinterpret_cast<const float4*>(src + (long)(k2 + lk) * N + n2 + ln);
;         d1 = *reinterpret_cast<const float4*>(src + (long)(k2 + lk + 32) * N + n2 + ln);
;       }
;     }
; DEVI void convert_ffn(const Params& p, int ig, bf16* shm) {
;     ...
;   convT(p.in[ig + 2], DFF, DM, (bf16*)(p.ws + W_DN), DFF, DM, 0, 0, nullptr, nullptr, lds);
.LBB0_1857:
	s_add_i32 s7, s8, s18
	s_cmpk_gt_i32 s7, 0xaff
	s_cselect_b64 s[2:3], -1, 0
	v_mov_b32_e32 v10, 0
	s_and_b64 vcc, exec, s[2:3]
	v_mov_b32_e32 v11, 0
	v_mov_b32_e32 v12, 0
	v_mov_b32_e32 v13, 0
	v_mov_b32_e32 v14, 0
	v_mov_b32_e32 v15, 0
	v_mov_b32_e32 v16, 0
	v_mov_b32_e32 v17, 0
	s_cbranch_vccnz .LBB0_1861
	s_ashr_i32 s4, s7, 31
	s_lshr_b32 s4, s4, 27
	s_add_i32 s4, s7, s4
	s_ashr_i32 s9, s4, 5
	s_lshl_b32 s10, s9, 11
	s_sub_i32 s4, s19, s10
	v_add_u32_e32 v10, s4, v35
	v_cmp_gt_i32_e32 vcc, s6, v10
	v_mov_b32_e32 v17, 0
	v_mov_b32_e32 v16, 0
	v_mov_b32_e32 v15, 0
	v_mov_b32_e32 v14, 0
	v_mov_b32_e32 v13, 0
	v_mov_b32_e32 v12, 0
	v_mov_b32_e32 v11, 0
	v_mov_b32_e32 v10, 0
	s_and_saveexec_b64 s[4:5], vcc
	s_cbranch_execz .LBB0_1860
	v_lshl_or_b32 v10, s9, 6, v1
	s_sub_i32 s10, 0, s10
	s_add_i32 s11, s20, s19
	v_ashrrev_i32_e32 v11, 31, v10
	s_add_i32 s10, s11, s10
	v_lshlrev_b64 v[10:11], 13, v[10:11]
	v_lshl_add_u64 v[10:11], s[82:83], 0, v[10:11]
	s_ashr_i32 s11, s10, 31
	v_lshl_add_u64 v[10:11], s[10:11], 2, v[10:11]
	v_lshl_add_u64 v[26:27], v[10:11], 0, v[18:19]
	v_add_co_u32_e32 v28, vcc, 0x40000, v26
	s_nop 1
	v_addc_co_u32_e32 v29, vcc, 0, v27, vcc
	global_load_dwordx4 v[14:17], v[26:27], off nt
	global_load_dwordx4 v[10:13], v[28:29], off nt

; template <int EPI, int NRM>
; DEVI void epilogue(acc_t& acc, int pn, int trow, const EpiArgs& e, const float* rl, bf16* shmx) {
;     ...
;     __amdgpu_buffer_rsrc_t rsX = __builtin_amdgcn_make_buffer_rsrc((void*)e.xin, 0, 0x7fffffff, 0x00020000);
;     char* lbase = reinterpret_cast<char*>(shmx) + wid * 16384;
;     const int vx = ((tk0 * DM) + pn * 256 + fl0) * 4;
; #pragma unroll
;     for (int ai = 0; ai < 2; ++ai) {
; #pragma unroll
;       for (int bj = 0; bj < 2; ++bj)
; #pragma unroll
;         for (int m = 0; m < 4; ++m)
; #pragma unroll
;           for (int n = 0; n < 2; ++n) {
;             const int idx = (bj * 4 + m) * 2 + n;
;             const int so = ((bj * 128 + n * 16) * DM + ai * 128 + m * 16) * 4;
;             __builtin_amdgcn_raw_ptr_buffer_load_lds(rsX, (__attribute__((address_space(3))) unsigned*)(lbase + idx * 1024 + lane * 16), 16, vx, so, 0, 0);
;           }
;       asm volatile("s_waitcnt vmcnt(0)" ::: "memory");
; #pragma unroll
;       for (int bj = 0; bj < 2; ++bj)
; #pragma unroll
;         for (int m = 0; m < 4; ++m)
; #pragma unroll
;           for (int n = 0; n < 2; ++n) {
;             const int idx = (bj * 4 + m) * 2 + n;
;             const unsigned off = (unsigned)((tk0 + bj * 128 + n * 16) * DM + pn * 256 + ai * 128 + m * 16 + fl0);
;             const float4 xx = *reinterpret_cast<const float4*>(lbase + idx * 1024 + lane * 16);
;             float4 o;
;             o.x = xx.x + acc[ai][bj][m][n][0]; o.y = xx.y + acc[ai][bj][m][n][1];
;             o.z = xx.z + acc[ai][bj][m][n][2]; o.w = xx.w + acc[ai][bj][m][n][3];
;             *reinterpret_cast<float4*>(e.xout + off) = o;
;             uint2 ob; ob.x = pack2(o.x, o.y); ob.y = pack2(o.z, o.w);
;             *reinterpret_cast<uint2*>(e.o0 + off) = ob;
;             ss[bj][n] += o.x * o.x + o.y * o.y + o.z * o.z + o.w * o.w;
.LBB0_2019:
	v_and_b32_e32 v138, 15, v1
	v_bfe_u32 v198, v1, 4, 2
	v_lshrrev_b32_e32 v199, 6, v1
	v_and_b32_e32 v200, 3, v199
	v_lshrrev_b32_e32 v201, 2, v199
	v_lshlrev_b32_e32 v202, 14, v199
	v_and_b32_e32 v203, 63, v1
	v_lshl_add_u32 v143, v203, 4, v202
	v_lshl_add_u32 v202, v138, 8, v202
	v_and_b32_e32 v203, 7, v138
	v_add_u32_e32 v204, 0, v198
	v_xor_b32_e32 v204, v204, v203
	v_lshl_add_u32 v139, v204, 4, v202
	v_add_u32_e32 v204, 4, v198
	v_xor_b32_e32 v204, v204, v203
	v_lshl_add_u32 v140, v204, 4, v202
	v_add_u32_e32 v204, 8, v198
	v_xor_b32_e32 v204, v204, v203
	v_lshl_add_u32 v141, v204, 4, v202
	v_add_u32_e32 v204, 12, v198
	v_xor_b32_e32 v204, v204, v203
	v_lshl_add_u32 v142, v204, 4, v202
	s_lshl_b32 s6, s6, 8
	v_lshl_add_u32 v202, v200, 5, v198
	v_add_u32_e32 v202, s6, v202
	s_lshl_b32 s6, s12, 1
	v_add_u32_e32 v204, s6, v201
	v_lshl_add_u32 v204, v204, 15, v202
	v_lshlrev_b32_e32 v148, 2, v204
	v_lshlrev_b32_e32 v202, 11, v202
	s_lshl_b32 s6, s12, 8
	v_lshl_add_u32 v204, v201, 6, s6
	v_add_u32_e32 v202, v202, v204
	v_add_u32_e32 v203, 0, v198
	v_xor_b32_e32 v203, v203, v138
	v_lshl_add_u32 v203, v203, 2, v202
	v_lshlrev_b32_e32 v144, 2, v203
	v_lshlrev_b32_e32 v146, 1, v203
	v_add_u32_e32 v203, 4, v198
	v_xor_b32_e32 v203, v203, v138
	v_lshl_add_u32 v203, v203, 2, v202
	v_lshlrev_b32_e32 v145, 2, v203
	v_lshlrev_b32_e32 v147, 1, v203
	v_add_u32_e32 v157, 0x0, v144
	global_load_dwordx4 v[166:169], v157, s[4:5] nt
	v_add_u32_e32 v160, 0x8000, v145
	global_load_dwordx4 v[170:173], v160, s[4:5] nt
	v_add_u32_e32 v157, 0x10000, v144
	global_load_dwordx4 v[174:177], v157, s[4:5] nt
	v_add_u32_e32 v160, 0x18000, v145
	global_load_dwordx4 v[178:181], v160, s[4:5] nt
	v_add_u32_e32 v157, 0x20000, v144
	global_load_dwordx4 v[182:185], v157, s[4:5] nt
	v_add_u32_e32 v160, 0x28000, v145
	global_load_dwordx4 v[186:189], v160, s[4:5] nt
	v_add_u32_e32 v157, 0x30000, v144
	global_load_dwordx4 v[190:193], v157, s[4:5] nt
	v_add_u32_e32 v160, 0x38000, v145
	global_load_dwordx4 v[194:197], v160, s[4:5] nt
	v_add_u32_e32 v157, 0x200, v144
	global_load_dwordx4 v[198:201], v157, s[4:5] nt
	v_add_u32_e32 v160, 0x8200, v145
	global_load_dwordx4 v[202:205], v160, s[4:5] nt
	v_add_u32_e32 v157, 0x10200, v144
	global_load_dwordx4 v[206:209], v157, s[4:5] nt
	v_add_u32_e32 v160, 0x18200, v145
	global_load_dwordx4 v[210:213], v160, s[4:5] nt
	v_add_u32_e32 v157, 0x20200, v144
	global_load_dwordx4 v[214:217], v157, s[4:5] nt
	v_add_u32_e32 v160, 0x28200, v145
	global_load_dwordx4 v[218:221], v160, s[4:5] nt
	v_add_u32_e32 v157, 0x30200, v144
	global_load_dwordx4 v[222:225], v157, s[4:5] nt
	v_add_u32_e32 v160, 0x38200, v145
	global_load_dwordx4 v[226:229], v160, s[4:5] nt
	ds_write_b128 v139, v[126:129]
	ds_write_b128 v139, v[34:37] offset:4096
	ds_write_b128 v140, v[122:125]
	ds_write_b128 v140, v[42:45] offset:4096
	ds_write_b128 v141, v[118:121]
	ds_write_b128 v141, v[54:57] offset:4096
	ds_write_b128 v142, v[114:117]
	ds_write_b128 v142, v[74:77] offset:4096
	ds_write_b128 v139, v[106:109] offset:8192
	ds_write_b128 v139, v[94:97] offset:12288
	ds_write_b128 v140, v[90:93] offset:8192
	ds_write_b128 v140, v[78:81] offset:12288
	ds_write_b128 v141, v[70:73] offset:8192
	ds_write_b128 v141, v[58:61] offset:12288
	ds_write_b128 v142, v[46:49] offset:8192
	ds_write_b128 v142, v[38:41] offset:12288
	s_waitcnt lgkmcnt(0)
	ds_read_b128 v[126:129], v143
	ds_read_b128 v[34:37], v143 offset:1024
	ds_read_b128 v[122:125], v143 offset:2048
	ds_read_b128 v[42:45], v143 offset:3072
	ds_read_b128 v[118:121], v143 offset:4096
	ds_read_b128 v[54:57], v143 offset:5120
	ds_read_b128 v[114:117], v143 offset:6144
	ds_read_b128 v[74:77], v143 offset:7168
	ds_read_b128 v[106:109], v143 offset:8192
	ds_read_b128 v[94:97], v143 offset:9216
	ds_read_b128 v[90:93], v143 offset:10240
	ds_read_b128 v[78:81], v143 offset:11264
	ds_read_b128 v[70:73], v143 offset:12288
	ds_read_b128 v[58:61], v143 offset:13312
	ds_read_b128 v[46:49], v143 offset:14336
	ds_read_b128 v[38:41], v143 offset:15360
	s_waitcnt lgkmcnt(0)
	ds_write_b128 v139, v[62:65]
	ds_write_b128 v139, v[50:53] offset:4096
	ds_write_b128 v140, v[82:85]
	ds_write_b128 v140, v[66:69] offset:4096
	ds_write_b128 v141, v[98:101]
	ds_write_b128 v141, v[86:89] offset:4096
	ds_write_b128 v142, v[110:113]
	ds_write_b128 v142, v[102:105] offset:4096
	ds_write_b128 v139, v[30:33] offset:8192
	ds_write_b128 v139, v[26:29] offset:12288
	ds_write_b128 v140, v[22:25] offset:8192
	ds_write_b128 v140, v[18:21] offset:12288
	ds_write_b128 v141, v[14:17] offset:8192
	ds_write_b128 v141, v[10:13] offset:12288
	ds_write_b128 v142, v[6:9] offset:8192
	ds_write_b128 v142, v[2:5] offset:12288
	s_waitcnt vmcnt(15)
	v_pk_add_f32 v[166:167], v[166:167], v[126:127]
	v_pk_add_f32 v[168:169], v[168:169], v[128:129]
	v_add_u32_e32 v157, 0x0, v144
	v_cvt_pk_bf16_f32 v158, v166, v167
	v_cvt_pk_bf16_f32 v159, v168, v169
	global_store_dwordx4 v157, v[166:169], s[26:27] nt
	v_add_u32_e32 v126, 0x0, v146
	v_mul_f32_e32 v149, v166, v166
	global_store_dwordx2 v126, v[158:159], s[96:97]
	v_fmac_f32_e32 v149, v167, v167
	v_fmac_f32_e32 v149, v168, v168
	v_fmac_f32_e32 v149, v169, v169
	s_waitcnt vmcnt(16)
	v_pk_add_f32 v[170:171], v[170:171], v[34:35]
	v_pk_add_f32 v[172:173], v[172:173], v[36:37]
	v_add_u32_e32 v160, 0x8000, v145
	v_cvt_pk_bf16_f32 v164, v170, v171
	v_cvt_pk_bf16_f32 v165, v172, v173
	global_store_dwordx4 v160, v[170:173], s[26:27] nt
	v_add_u32_e32 v34, 0x4000, v147
	v_mul_f32_e32 v150, v170, v170
	global_store_dwordx2 v34, v[164:165], s[96:97]
	v_fmac_f32_e32 v150, v171, v171
	v_fmac_f32_e32 v150, v172, v172
	v_fmac_f32_e32 v150, v173, v173
	s_waitcnt vmcnt(17)
; template <int EPI, int NRM>
; DEVI void epilogue(acc_t& acc, int pn, int trow, const EpiArgs& e, const float* rl, bf16* shmx) {
;     ...
;             const unsigned off = (unsigned)((tk0 + bj * 128 + n * 16) * DM + pn * 256 + ai * 128 + m * 16 + fl0);
;             const float4 xx = *reinterpret_cast<const float4*>(lbase + idx * 1024 + lane * 16);
;             float4 o;
;             o.x = xx.x + acc[ai][bj][m][n][0]; o.y = xx.y + acc[ai][bj][m][n][1];
;             o.z = xx.z + acc[ai][bj][m][n][2]; o.w = xx.w + acc[ai][bj][m][n][3];
;             *reinterpret_cast<float4*>(e.xout + off) = o;
;             uint2 ob; ob.x = pack2(o.x, o.y); ob.y = pack2(o.z, o.w);
;             *reinterpret_cast<uint2*>(e.o0 + off) = ob;
;             ss[bj][n] += o.x * o.x + o.y * o.y + o.z * o.z + o.w * o.w;
	v_pk_add_f32 v[174:175], v[174:175], v[122:123]
	v_pk_add_f32 v[176:177], v[176:177], v[124:125]
	v_add_u32_e32 v157, 0x10000, v144
	v_cvt_pk_bf16_f32 v158, v174, v175
	v_cvt_pk_bf16_f32 v159, v176, v177
	global_store_dwordx4 v157, v[174:177], s[26:27] nt
	v_add_u32_e32 v122, 0x8000, v146
	v_mul_f32_e32 v151, v174, v174
	global_store_dwordx2 v122, v[158:159], s[96:97]
	v_fmac_f32_e32 v151, v175, v175
	v_fmac_f32_e32 v151, v176, v176
	v_fmac_f32_e32 v151, v177, v177
	s_waitcnt vmcnt(18)
	v_pk_add_f32 v[178:179], v[178:179], v[42:43]
	v_pk_add_f32 v[180:181], v[180:181], v[44:45]
	v_add_u32_e32 v160, 0x18000, v145
	v_cvt_pk_bf16_f32 v164, v178, v179
	v_cvt_pk_bf16_f32 v165, v180, v181
	global_store_dwordx4 v160, v[178:181], s[26:27] nt
	v_add_u32_e32 v42, 0xc000, v147
	v_mul_f32_e32 v152, v178, v178
	global_store_dwordx2 v42, v[164:165], s[96:97]
	v_fmac_f32_e32 v152, v179, v179
	v_fmac_f32_e32 v152, v180, v180
	v_fmac_f32_e32 v152, v181, v181
	s_waitcnt vmcnt(19)
	v_pk_add_f32 v[182:183], v[182:183], v[118:119]
	v_pk_add_f32 v[184:185], v[184:185], v[120:121]
	v_add_u32_e32 v157, 0x20000, v144
	v_cvt_pk_bf16_f32 v158, v182, v183
	v_cvt_pk_bf16_f32 v159, v184, v185
	global_store_dwordx4 v157, v[182:185], s[26:27] nt
	v_add_u32_e32 v118, 0x10000, v146
	v_mul_f32_e32 v153, v182, v182
	global_store_dwordx2 v118, v[158:159], s[96:97]
	v_fmac_f32_e32 v153, v183, v183
	v_fmac_f32_e32 v153, v184, v184
	v_fmac_f32_e32 v153, v185, v185
	s_waitcnt vmcnt(20)
	v_pk_add_f32 v[186:187], v[186:187], v[54:55]
	v_pk_add_f32 v[188:189], v[188:189], v[56:57]
	v_add_u32_e32 v160, 0x28000, v145
	v_cvt_pk_bf16_f32 v164, v186, v187
	v_cvt_pk_bf16_f32 v165, v188, v189
	global_store_dwordx4 v160, v[186:189], s[26:27] nt
	v_add_u32_e32 v54, 0x14000, v147
	v_mul_f32_e32 v154, v186, v186
	global_store_dwordx2 v54, v[164:165], s[96:97]
	v_fmac_f32_e32 v154, v187, v187
	v_fmac_f32_e32 v154, v188, v188
	v_fmac_f32_e32 v154, v189, v189
	s_waitcnt vmcnt(21)
	v_pk_add_f32 v[190:191], v[190:191], v[114:115]
	v_pk_add_f32 v[192:193], v[192:193], v[116:117]
	v_add_u32_e32 v157, 0x30000, v144
	v_cvt_pk_bf16_f32 v158, v190, v191
	v_cvt_pk_bf16_f32 v159, v192, v193
	global_store_dwordx4 v157, v[190:193], s[26:27] nt
	v_add_u32_e32 v114, 0x18000, v146
	v_mul_f32_e32 v155, v190, v190
	global_store_dwordx2 v114, v[158:159], s[96:97]
	v_fmac_f32_e32 v155, v191, v191
	v_fmac_f32_e32 v155, v192, v192
	v_fmac_f32_e32 v155, v193, v193
	s_waitcnt vmcnt(22)
	v_pk_add_f32 v[194:195], v[194:195], v[74:75]
	v_pk_add_f32 v[196:197], v[196:197], v[76:77]
	v_add_u32_e32 v160, 0x38000, v145
	v_cvt_pk_bf16_f32 v164, v194, v195
	v_cvt_pk_bf16_f32 v165, v196, v197
	global_store_dwordx4 v160, v[194:197], s[26:27] nt
	v_add_u32_e32 v74, 0x1c000, v147
	v_mul_f32_e32 v156, v194, v194
	global_store_dwordx2 v74, v[164:165], s[96:97]
	v_fmac_f32_e32 v156, v195, v195
	v_fmac_f32_e32 v156, v196, v196
	v_fmac_f32_e32 v156, v197, v197
	v_add_u32_e32 v157, 0x100000, v144
	global_load_dwordx4 v[166:169], v157, s[4:5] nt
	v_add_u32_e32 v160, 0x108000, v145
	global_load_dwordx4 v[170:173], v160, s[4:5] nt
	v_add_u32_e32 v157, 0x110000, v144
	global_load_dwordx4 v[174:177], v157, s[4:5] nt
	v_add_u32_e32 v160, 0x118000, v145
	global_load_dwordx4 v[178:181], v160, s[4:5] nt
	v_add_u32_e32 v157, 0x120000, v144
	global_load_dwordx4 v[182:185], v157, s[4:5] nt
	v_add_u32_e32 v160, 0x128000, v145
	global_load_dwordx4 v[186:189], v160, s[4:5] nt
	v_add_u32_e32 v157, 0x130000, v144
	global_load_dwordx4 v[190:193], v157, s[4:5] nt
	v_add_u32_e32 v160, 0x138000, v145
	global_load_dwordx4 v[194:197], v160, s[4:5] nt
	s_waitcnt vmcnt(31)
	v_pk_add_f32 v[198:199], v[198:199], v[106:107]
	v_pk_add_f32 v[200:201], v[200:201], v[108:109]
	v_add_u32_e32 v157, 0x200, v144
	v_cvt_pk_bf16_f32 v158, v198, v199
	v_cvt_pk_bf16_f32 v159, v200, v201
	global_store_dwordx4 v157, v[198:201], s[26:27] nt
	v_add_u32_e32 v106, 0x100, v146
	v_fmac_f32_e32 v149, v198, v198
	global_store_dwordx2 v106, v[158:159], s[96:97]
	v_fmac_f32_e32 v149, v199, v199
	v_fmac_f32_e32 v149, v200, v200
	v_fmac_f32_e32 v149, v201, v201
	s_waitcnt vmcnt(32)
	v_pk_add_f32 v[202:203], v[202:203], v[94:95]
	v_pk_add_f32 v[204:205], v[204:205], v[96:97]
	v_add_u32_e32 v160, 0x8200, v145
	v_cvt_pk_bf16_f32 v164, v202, v203
	v_cvt_pk_bf16_f32 v165, v204, v205
	global_store_dwordx4 v160, v[202:205], s[26:27] nt
	v_add_u32_e32 v94, 0x4100, v147
	v_fmac_f32_e32 v150, v202, v202
	global_store_dwordx2 v94, v[164:165], s[96:97]
	v_fmac_f32_e32 v150, v203, v203
	v_fmac_f32_e32 v150, v204, v204
	v_fmac_f32_e32 v150, v205, v205
	s_waitcnt vmcnt(33)
	v_pk_add_f32 v[206:207], v[206:207], v[90:91]
	v_pk_add_f32 v[208:209], v[208:209], v[92:93]
	v_add_u32_e32 v157, 0x10200, v144
	v_cvt_pk_bf16_f32 v158, v206, v207
	v_cvt_pk_bf16_f32 v159, v208, v209
	global_store_dwordx4 v157, v[206:209], s[26:27] nt
	v_add_u32_e32 v90, 0x8100, v146
	v_fmac_f32_e32 v151, v206, v206
	global_store_dwordx2 v90, v[158:159], s[96:97]
	v_fmac_f32_e32 v151, v207, v207
	v_fmac_f32_e32 v151, v208, v208
	v_fmac_f32_e32 v151, v209, v209
	s_waitcnt vmcnt(34)
	v_pk_add_f32 v[210:211], v[210:211], v[78:79]
	v_pk_add_f32 v[212:213], v[212:213], v[80:81]
	v_add_u32_e32 v160, 0x18200, v145
	v_cvt_pk_bf16_f32 v164, v210, v211
	v_cvt_pk_bf16_f32 v165, v212, v213
	global_store_dwordx4 v160, v[210:213], s[26:27] nt
	v_add_u32_e32 v78, 0xc100, v147
	v_fmac_f32_e32 v152, v210, v210
	global_store_dwordx2 v78, v[164:165], s[96:97]
	v_fmac_f32_e32 v152, v211, v211
	v_fmac_f32_e32 v152, v212, v212
	v_fmac_f32_e32 v152, v213, v213
	s_waitcnt vmcnt(35)
; template <int EPI, int NRM>
; DEVI void epilogue(acc_t& acc, int pn, int trow, const EpiArgs& e, const float* rl, bf16* shmx) {
;     ...
;             const unsigned off = (unsigned)((tk0 + bj * 128 + n * 16) * DM + pn * 256 + ai * 128 + m * 16 + fl0);
;             const float4 xx = *reinterpret_cast<const float4*>(lbase + idx * 1024 + lane * 16);
;             float4 o;
;             o.x = xx.x + acc[ai][bj][m][n][0]; o.y = xx.y + acc[ai][bj][m][n][1];
;             o.z = xx.z + acc[ai][bj][m][n][2]; o.w = xx.w + acc[ai][bj][m][n][3];
;             *reinterpret_cast<float4*>(e.xout + off) = o;
;             uint2 ob; ob.x = pack2(o.x, o.y); ob.y = pack2(o.z, o.w);
;             *reinterpret_cast<uint2*>(e.o0 + off) = ob;
;             ss[bj][n] += o.x * o.x + o.y * o.y + o.z * o.z + o.w * o.w;
;           }
;       asm volatile("s_waitcnt lgkmcnt(0)" ::: "memory");
;     }
; #pragma unroll
;     for (int bj = 0; bj < 2; ++bj)
; #pragma unroll
;       for (int n = 0; n < 2; ++n) {
;         float v = ss[bj][n];
;         v += __shfl_xor(v, 16); v += __shfl_xor(v, 32);
;         if (fq == 0) e.stw[(pn * 2 + wr) * TOK + tk0 + bj * 128 + n * 16] = v;
	v_pk_add_f32 v[214:215], v[214:215], v[70:71]
	v_pk_add_f32 v[216:217], v[216:217], v[72:73]
	v_add_u32_e32 v157, 0x20200, v144
	v_cvt_pk_bf16_f32 v158, v214, v215
	v_cvt_pk_bf16_f32 v159, v216, v217
	global_store_dwordx4 v157, v[214:217], s[26:27] nt
	v_add_u32_e32 v70, 0x10100, v146
	v_fmac_f32_e32 v153, v214, v214
	global_store_dwordx2 v70, v[158:159], s[96:97]
	v_fmac_f32_e32 v153, v215, v215
	v_fmac_f32_e32 v153, v216, v216
	v_fmac_f32_e32 v153, v217, v217
	s_waitcnt vmcnt(36)
	v_pk_add_f32 v[218:219], v[218:219], v[58:59]
	v_pk_add_f32 v[220:221], v[220:221], v[60:61]
	v_add_u32_e32 v160, 0x28200, v145
	v_cvt_pk_bf16_f32 v164, v218, v219
	v_cvt_pk_bf16_f32 v165, v220, v221
	global_store_dwordx4 v160, v[218:221], s[26:27] nt
	v_add_u32_e32 v58, 0x14100, v147
	v_fmac_f32_e32 v154, v218, v218
	global_store_dwordx2 v58, v[164:165], s[96:97]
	v_fmac_f32_e32 v154, v219, v219
	v_fmac_f32_e32 v154, v220, v220
	v_fmac_f32_e32 v154, v221, v221
	s_waitcnt vmcnt(37)
	v_pk_add_f32 v[222:223], v[222:223], v[46:47]
	v_pk_add_f32 v[224:225], v[224:225], v[48:49]
	v_add_u32_e32 v157, 0x30200, v144
	v_cvt_pk_bf16_f32 v158, v222, v223
	v_cvt_pk_bf16_f32 v159, v224, v225
	global_store_dwordx4 v157, v[222:225], s[26:27] nt
	v_add_u32_e32 v46, 0x18100, v146
	v_fmac_f32_e32 v155, v222, v222
	global_store_dwordx2 v46, v[158:159], s[96:97]
	v_fmac_f32_e32 v155, v223, v223
	v_fmac_f32_e32 v155, v224, v224
	v_fmac_f32_e32 v155, v225, v225
	s_waitcnt vmcnt(38)
	v_pk_add_f32 v[226:227], v[226:227], v[38:39]
	v_pk_add_f32 v[228:229], v[228:229], v[40:41]
	v_add_u32_e32 v160, 0x38200, v145
	v_cvt_pk_bf16_f32 v164, v226, v227
	v_cvt_pk_bf16_f32 v165, v228, v229
	global_store_dwordx4 v160, v[226:229], s[26:27] nt
	v_add_u32_e32 v38, 0x1c100, v147
	v_fmac_f32_e32 v156, v226, v226
	global_store_dwordx2 v38, v[164:165], s[96:97]
	v_fmac_f32_e32 v156, v227, v227
	v_fmac_f32_e32 v156, v228, v228
	v_fmac_f32_e32 v156, v229, v229
	v_add_u32_e32 v157, 0x100200, v144
	global_load_dwordx4 v[198:201], v157, s[4:5] nt
	v_add_u32_e32 v160, 0x108200, v145
	global_load_dwordx4 v[202:205], v160, s[4:5] nt
	v_add_u32_e32 v157, 0x110200, v144
	global_load_dwordx4 v[206:209], v157, s[4:5] nt
	v_add_u32_e32 v160, 0x118200, v145
	global_load_dwordx4 v[210:213], v160, s[4:5] nt
	v_add_u32_e32 v157, 0x120200, v144
	global_load_dwordx4 v[214:217], v157, s[4:5] nt
	v_add_u32_e32 v160, 0x128200, v145
	global_load_dwordx4 v[218:221], v160, s[4:5] nt
	v_add_u32_e32 v157, 0x130200, v144
	global_load_dwordx4 v[222:225], v157, s[4:5] nt
	v_add_u32_e32 v160, 0x138200, v145
	global_load_dwordx4 v[226:229], v160, s[4:5] nt
	v_add_f32_dpp v149, v149, v149 row_shr:1 row_mask:0xf bank_mask:0xf bound_ctrl:0
	v_add_f32_dpp v150, v150, v150 row_shr:1 row_mask:0xf bank_mask:0xf bound_ctrl:0
	v_add_f32_dpp v151, v151, v151 row_shr:1 row_mask:0xf bank_mask:0xf bound_ctrl:0
	v_add_f32_dpp v152, v152, v152 row_shr:1 row_mask:0xf bank_mask:0xf bound_ctrl:0
	v_add_f32_dpp v153, v153, v153 row_shr:1 row_mask:0xf bank_mask:0xf bound_ctrl:0
	v_add_f32_dpp v154, v154, v154 row_shr:1 row_mask:0xf bank_mask:0xf bound_ctrl:0
	v_add_f32_dpp v155, v155, v155 row_shr:1 row_mask:0xf bank_mask:0xf bound_ctrl:0
	v_add_f32_dpp v156, v156, v156 row_shr:1 row_mask:0xf bank_mask:0xf bound_ctrl:0
	v_add_f32_dpp v149, v149, v149 row_shr:2 row_mask:0xf bank_mask:0xf bound_ctrl:0
	v_add_f32_dpp v150, v150, v150 row_shr:2 row_mask:0xf bank_mask:0xf bound_ctrl:0
	v_add_f32_dpp v151, v151, v151 row_shr:2 row_mask:0xf bank_mask:0xf bound_ctrl:0
	v_add_f32_dpp v152, v152, v152 row_shr:2 row_mask:0xf bank_mask:0xf bound_ctrl:0
	v_add_f32_dpp v153, v153, v153 row_shr:2 row_mask:0xf bank_mask:0xf bound_ctrl:0
	v_add_f32_dpp v154, v154, v154 row_shr:2 row_mask:0xf bank_mask:0xf bound_ctrl:0
	v_add_f32_dpp v155, v155, v155 row_shr:2 row_mask:0xf bank_mask:0xf bound_ctrl:0
	v_add_f32_dpp v156, v156, v156 row_shr:2 row_mask:0xf bank_mask:0xf bound_ctrl:0
	v_add_f32_dpp v149, v149, v149 row_shr:4 row_mask:0xf bank_mask:0xf bound_ctrl:0
	v_add_f32_dpp v150, v150, v150 row_shr:4 row_mask:0xf bank_mask:0xf bound_ctrl:0
	v_add_f32_dpp v151, v151, v151 row_shr:4 row_mask:0xf bank_mask:0xf bound_ctrl:0
	v_add_f32_dpp v152, v152, v152 row_shr:4 row_mask:0xf bank_mask:0xf bound_ctrl:0
	v_add_f32_dpp v153, v153, v153 row_shr:4 row_mask:0xf bank_mask:0xf bound_ctrl:0
	v_add_f32_dpp v154, v154, v154 row_shr:4 row_mask:0xf bank_mask:0xf bound_ctrl:0
	v_add_f32_dpp v155, v155, v155 row_shr:4 row_mask:0xf bank_mask:0xf bound_ctrl:0
	v_add_f32_dpp v156, v156, v156 row_shr:4 row_mask:0xf bank_mask:0xf bound_ctrl:0
	v_add_f32_dpp v149, v149, v149 row_shr:8 row_mask:0xf bank_mask:0xf bound_ctrl:0
	v_add_f32_dpp v150, v150, v150 row_shr:8 row_mask:0xf bank_mask:0xf bound_ctrl:0
	v_add_f32_dpp v151, v151, v151 row_shr:8 row_mask:0xf bank_mask:0xf bound_ctrl:0
	v_add_f32_dpp v152, v152, v152 row_shr:8 row_mask:0xf bank_mask:0xf bound_ctrl:0
	v_add_f32_dpp v153, v153, v153 row_shr:8 row_mask:0xf bank_mask:0xf bound_ctrl:0
	v_add_f32_dpp v154, v154, v154 row_shr:8 row_mask:0xf bank_mask:0xf bound_ctrl:0
	v_add_f32_dpp v155, v155, v155 row_shr:8 row_mask:0xf bank_mask:0xf bound_ctrl:0
	v_add_f32_dpp v156, v156, v156 row_shr:8 row_mask:0xf bank_mask:0xf bound_ctrl:0
	v_cmp_eq_u32_e32 vcc, 15, v138
	s_and_saveexec_b64 s[6:7], vcc
	global_store_dword v148, v149, s[94:95]
	global_store_dword v148, v150, s[94:95] offset:16
	global_store_dword v148, v151, s[94:95] offset:32
	global_store_dword v148, v152, s[94:95] offset:48
	global_store_dword v148, v153, s[94:95] offset:64
	global_store_dword v148, v154, s[94:95] offset:80
	global_store_dword v148, v155, s[94:95] offset:96
	global_store_dword v148, v156, s[94:95] offset:112
	s_or_b64 exec, exec, s[6:7]
	s_waitcnt lgkmcnt(0)
; template <int EPI, int NRM>
; DEVI void epilogue(acc_t& acc, int pn, int trow, const EpiArgs& e, const float* rl, bf16* shmx) {
;     ...
;             const unsigned off = (unsigned)((tk0 + bj * 128 + n * 16) * DM + pn * 256 + ai * 128 + m * 16 + fl0);
;             const float4 xx = *reinterpret_cast<const float4*>(lbase + idx * 1024 + lane * 16);
;             float4 o;
;             o.x = xx.x + acc[ai][bj][m][n][0]; o.y = xx.y + acc[ai][bj][m][n][1];
;             o.z = xx.z + acc[ai][bj][m][n][2]; o.w = xx.w + acc[ai][bj][m][n][3];
;             *reinterpret_cast<float4*>(e.xout + off) = o;
;             uint2 ob; ob.x = pack2(o.x, o.y); ob.y = pack2(o.z, o.w);
;             *reinterpret_cast<uint2*>(e.o0 + off) = ob;
;             ss[bj][n] += o.x * o.x + o.y * o.y + o.z * o.z + o.w * o.w;
	ds_read_b128 v[62:65], v143
	ds_read_b128 v[50:53], v143 offset:1024
	ds_read_b128 v[82:85], v143 offset:2048
	ds_read_b128 v[66:69], v143 offset:3072
	ds_read_b128 v[98:101], v143 offset:4096
	ds_read_b128 v[86:89], v143 offset:5120
	ds_read_b128 v[110:113], v143 offset:6144
	ds_read_b128 v[102:105], v143 offset:7168
	ds_read_b128 v[30:33], v143 offset:8192
	ds_read_b128 v[26:29], v143 offset:9216
	ds_read_b128 v[22:25], v143 offset:10240
	ds_read_b128 v[18:21], v143 offset:11264
	ds_read_b128 v[14:17], v143 offset:12288
	ds_read_b128 v[10:13], v143 offset:13312
	ds_read_b128 v[6:9], v143 offset:14336
	ds_read_b128 v[2:5], v143 offset:15360
	s_waitcnt lgkmcnt(0)
	s_waitcnt vmcnt(39)
	v_pk_add_f32 v[166:167], v[166:167], v[62:63]
	v_pk_add_f32 v[168:169], v[168:169], v[64:65]
	v_add_u32_e32 v157, 0x100000, v144
	v_cvt_pk_bf16_f32 v158, v166, v167
	v_cvt_pk_bf16_f32 v159, v168, v169
	global_store_dwordx4 v157, v[166:169], s[26:27] nt
	v_add_u32_e32 v62, 0x80000, v146
	v_mul_f32_e32 v149, v166, v166
	global_store_dwordx2 v62, v[158:159], s[96:97]
	v_fmac_f32_e32 v149, v167, v167
	v_fmac_f32_e32 v149, v168, v168
	v_fmac_f32_e32 v149, v169, v169
	s_waitcnt vmcnt(40)
	v_pk_add_f32 v[170:171], v[170:171], v[50:51]
	v_pk_add_f32 v[172:173], v[172:173], v[52:53]
	v_add_u32_e32 v160, 0x108000, v145
	v_cvt_pk_bf16_f32 v164, v170, v171
	v_cvt_pk_bf16_f32 v165, v172, v173
	global_store_dwordx4 v160, v[170:173], s[26:27] nt
	v_add_u32_e32 v50, 0x84000, v147
	v_mul_f32_e32 v150, v170, v170
	global_store_dwordx2 v50, v[164:165], s[96:97]
	v_fmac_f32_e32 v150, v171, v171
	v_fmac_f32_e32 v150, v172, v172
	v_fmac_f32_e32 v150, v173, v173
	s_waitcnt vmcnt(41)
	v_pk_add_f32 v[174:175], v[174:175], v[82:83]
	v_pk_add_f32 v[176:177], v[176:177], v[84:85]
	v_add_u32_e32 v157, 0x110000, v144
	v_cvt_pk_bf16_f32 v158, v174, v175
	v_cvt_pk_bf16_f32 v159, v176, v177
	global_store_dwordx4 v157, v[174:177], s[26:27] nt
	v_add_u32_e32 v82, 0x88000, v146
	v_mul_f32_e32 v151, v174, v174
	global_store_dwordx2 v82, v[158:159], s[96:97]
	v_fmac_f32_e32 v151, v175, v175
	v_fmac_f32_e32 v151, v176, v176
	v_fmac_f32_e32 v151, v177, v177
	s_waitcnt vmcnt(42)
	v_pk_add_f32 v[178:179], v[178:179], v[66:67]
	v_pk_add_f32 v[180:181], v[180:181], v[68:69]
	v_add_u32_e32 v160, 0x118000, v145
	v_cvt_pk_bf16_f32 v164, v178, v179
	v_cvt_pk_bf16_f32 v165, v180, v181
	global_store_dwordx4 v160, v[178:181], s[26:27] nt
	v_add_u32_e32 v66, 0x8c000, v147
	v_mul_f32_e32 v152, v178, v178
	global_store_dwordx2 v66, v[164:165], s[96:97]
	v_fmac_f32_e32 v152, v179, v179
	v_fmac_f32_e32 v152, v180, v180
	v_fmac_f32_e32 v152, v181, v181
	s_waitcnt vmcnt(43)
	v_pk_add_f32 v[182:183], v[182:183], v[98:99]
	v_pk_add_f32 v[184:185], v[184:185], v[100:101]
	v_add_u32_e32 v157, 0x120000, v144
	v_cvt_pk_bf16_f32 v158, v182, v183
	v_cvt_pk_bf16_f32 v159, v184, v185
	global_store_dwordx4 v157, v[182:185], s[26:27] nt
	v_add_u32_e32 v98, 0x90000, v146
	v_mul_f32_e32 v153, v182, v182
	global_store_dwordx2 v98, v[158:159], s[96:97]
	v_fmac_f32_e32 v153, v183, v183
	v_fmac_f32_e32 v153, v184, v184
	v_fmac_f32_e32 v153, v185, v185
	s_waitcnt vmcnt(44)
	v_pk_add_f32 v[186:187], v[186:187], v[86:87]
	v_pk_add_f32 v[188:189], v[188:189], v[88:89]
	v_add_u32_e32 v160, 0x128000, v145
	v_cvt_pk_bf16_f32 v164, v186, v187
	v_cvt_pk_bf16_f32 v165, v188, v189
	global_store_dwordx4 v160, v[186:189], s[26:27] nt
	v_add_u32_e32 v86, 0x94000, v147
	v_mul_f32_e32 v154, v186, v186
	global_store_dwordx2 v86, v[164:165], s[96:97]
	v_fmac_f32_e32 v154, v187, v187
	v_fmac_f32_e32 v154, v188, v188
	v_fmac_f32_e32 v154, v189, v189
	s_waitcnt vmcnt(45)
	v_pk_add_f32 v[190:191], v[190:191], v[110:111]
	v_pk_add_f32 v[192:193], v[192:193], v[112:113]
	v_add_u32_e32 v157, 0x130000, v144
	v_cvt_pk_bf16_f32 v158, v190, v191
	v_cvt_pk_bf16_f32 v159, v192, v193
	global_store_dwordx4 v157, v[190:193], s[26:27] nt
	v_add_u32_e32 v110, 0x98000, v146
	v_mul_f32_e32 v155, v190, v190
	global_store_dwordx2 v110, v[158:159], s[96:97]
	v_fmac_f32_e32 v155, v191, v191
	v_fmac_f32_e32 v155, v192, v192
	v_fmac_f32_e32 v155, v193, v193
	s_waitcnt vmcnt(46)
	v_pk_add_f32 v[194:195], v[194:195], v[102:103]
	v_pk_add_f32 v[196:197], v[196:197], v[104:105]
	v_add_u32_e32 v160, 0x138000, v145
	v_cvt_pk_bf16_f32 v164, v194, v195
	v_cvt_pk_bf16_f32 v165, v196, v197
	global_store_dwordx4 v160, v[194:197], s[26:27] nt
	v_add_u32_e32 v102, 0x9c000, v147
	v_mul_f32_e32 v156, v194, v194
	global_store_dwordx2 v102, v[164:165], s[96:97]
	v_fmac_f32_e32 v156, v195, v195
	v_fmac_f32_e32 v156, v196, v196
	v_fmac_f32_e32 v156, v197, v197
	s_waitcnt vmcnt(31)
	v_pk_add_f32 v[198:199], v[198:199], v[30:31]
	v_pk_add_f32 v[200:201], v[200:201], v[32:33]
	v_add_u32_e32 v157, 0x100200, v144
	v_cvt_pk_bf16_f32 v158, v198, v199
	v_cvt_pk_bf16_f32 v159, v200, v201
	global_store_dwordx4 v157, v[198:201], s[26:27] nt
	v_add_u32_e32 v30, 0x80100, v146
	v_fmac_f32_e32 v149, v198, v198
	global_store_dwordx2 v30, v[158:159], s[96:97]
	v_fmac_f32_e32 v149, v199, v199
	v_fmac_f32_e32 v149, v200, v200
	v_fmac_f32_e32 v149, v201, v201
	s_waitcnt vmcnt(32)
	v_pk_add_f32 v[202:203], v[202:203], v[26:27]
	v_pk_add_f32 v[204:205], v[204:205], v[28:29]
	v_add_u32_e32 v160, 0x108200, v145
	v_cvt_pk_bf16_f32 v164, v202, v203
	v_cvt_pk_bf16_f32 v165, v204, v205
	global_store_dwordx4 v160, v[202:205], s[26:27] nt
	v_add_u32_e32 v26, 0x84100, v147
	v_fmac_f32_e32 v150, v202, v202
	global_store_dwordx2 v26, v[164:165], s[96:97]
	v_fmac_f32_e32 v150, v203, v203
	v_fmac_f32_e32 v150, v204, v204
	v_fmac_f32_e32 v150, v205, v205
	s_waitcnt vmcnt(33)
; template <int EPI, int NRM>
; DEVI void epilogue(acc_t& acc, int pn, int trow, const EpiArgs& e, const float* rl, bf16* shmx) {
;     ...
;             const unsigned off = (unsigned)((tk0 + bj * 128 + n * 16) * DM + pn * 256 + ai * 128 + m * 16 + fl0);
;             const float4 xx = *reinterpret_cast<const float4*>(lbase + idx * 1024 + lane * 16);
;             float4 o;
;             o.x = xx.x + acc[ai][bj][m][n][0]; o.y = xx.y + acc[ai][bj][m][n][1];
;             o.z = xx.z + acc[ai][bj][m][n][2]; o.w = xx.w + acc[ai][bj][m][n][3];
;             *reinterpret_cast<float4*>(e.xout + off) = o;
;             uint2 ob; ob.x = pack2(o.x, o.y); ob.y = pack2(o.z, o.w);
;             *reinterpret_cast<uint2*>(e.o0 + off) = ob;
;             ss[bj][n] += o.x * o.x + o.y * o.y + o.z * o.z + o.w * o.w;
;           }
;       asm volatile("s_waitcnt lgkmcnt(0)" ::: "memory");
;     }
; #pragma unroll
;     for (int bj = 0; bj < 2; ++bj)
; #pragma unroll
;       for (int n = 0; n < 2; ++n) {
;         float v = ss[bj][n];
;         v += __shfl_xor(v, 16); v += __shfl_xor(v, 32);
;         if (fq == 0) e.stw[(pn * 2 + wr) * TOK + tk0 + bj * 128 + n * 16] = v;
;       }
	v_pk_add_f32 v[206:207], v[206:207], v[22:23]
	v_pk_add_f32 v[208:209], v[208:209], v[24:25]
	v_add_u32_e32 v157, 0x110200, v144
	v_cvt_pk_bf16_f32 v158, v206, v207
	v_cvt_pk_bf16_f32 v159, v208, v209
	global_store_dwordx4 v157, v[206:209], s[26:27] nt
	v_add_u32_e32 v22, 0x88100, v146
	v_fmac_f32_e32 v151, v206, v206
	global_store_dwordx2 v22, v[158:159], s[96:97]
	v_fmac_f32_e32 v151, v207, v207
	v_fmac_f32_e32 v151, v208, v208
	v_fmac_f32_e32 v151, v209, v209
	s_waitcnt vmcnt(34)
	v_pk_add_f32 v[210:211], v[210:211], v[18:19]
	v_pk_add_f32 v[212:213], v[212:213], v[20:21]
	v_add_u32_e32 v160, 0x118200, v145
	v_cvt_pk_bf16_f32 v164, v210, v211
	v_cvt_pk_bf16_f32 v165, v212, v213
	global_store_dwordx4 v160, v[210:213], s[26:27] nt
	v_add_u32_e32 v18, 0x8c100, v147
	v_fmac_f32_e32 v152, v210, v210
	global_store_dwordx2 v18, v[164:165], s[96:97]
	v_fmac_f32_e32 v152, v211, v211
	v_fmac_f32_e32 v152, v212, v212
	v_fmac_f32_e32 v152, v213, v213
	s_waitcnt vmcnt(35)
	v_pk_add_f32 v[214:215], v[214:215], v[14:15]
	v_pk_add_f32 v[216:217], v[216:217], v[16:17]
	v_add_u32_e32 v157, 0x120200, v144
	v_cvt_pk_bf16_f32 v158, v214, v215
	v_cvt_pk_bf16_f32 v159, v216, v217
	global_store_dwordx4 v157, v[214:217], s[26:27] nt
	v_add_u32_e32 v14, 0x90100, v146
	v_fmac_f32_e32 v153, v214, v214
	global_store_dwordx2 v14, v[158:159], s[96:97]
	v_fmac_f32_e32 v153, v215, v215
	v_fmac_f32_e32 v153, v216, v216
	v_fmac_f32_e32 v153, v217, v217
	s_waitcnt vmcnt(36)
	v_pk_add_f32 v[218:219], v[218:219], v[10:11]
	v_pk_add_f32 v[220:221], v[220:221], v[12:13]
	v_add_u32_e32 v160, 0x128200, v145
	v_cvt_pk_bf16_f32 v164, v218, v219
	v_cvt_pk_bf16_f32 v165, v220, v221
	global_store_dwordx4 v160, v[218:221], s[26:27] nt
	v_add_u32_e32 v10, 0x94100, v147
	v_fmac_f32_e32 v154, v218, v218
	global_store_dwordx2 v10, v[164:165], s[96:97]
	v_fmac_f32_e32 v154, v219, v219
	v_fmac_f32_e32 v154, v220, v220
	v_fmac_f32_e32 v154, v221, v221
	s_waitcnt vmcnt(37)
	v_pk_add_f32 v[222:223], v[222:223], v[6:7]
	v_pk_add_f32 v[224:225], v[224:225], v[8:9]
	v_add_u32_e32 v157, 0x130200, v144
	v_cvt_pk_bf16_f32 v158, v222, v223
	v_cvt_pk_bf16_f32 v159, v224, v225
	global_store_dwordx4 v157, v[222:225], s[26:27] nt
	v_add_u32_e32 v6, 0x98100, v146
	v_fmac_f32_e32 v155, v222, v222
	global_store_dwordx2 v6, v[158:159], s[96:97]
	v_fmac_f32_e32 v155, v223, v223
	v_fmac_f32_e32 v155, v224, v224
	v_fmac_f32_e32 v155, v225, v225
	s_waitcnt vmcnt(38)
	v_pk_add_f32 v[226:227], v[226:227], v[2:3]
	v_pk_add_f32 v[228:229], v[228:229], v[4:5]
	v_add_u32_e32 v160, 0x138200, v145
	v_cvt_pk_bf16_f32 v164, v226, v227
	v_cvt_pk_bf16_f32 v165, v228, v229
	global_store_dwordx4 v160, v[226:229], s[26:27] nt
	v_add_u32_e32 v2, 0x9c100, v147
	v_fmac_f32_e32 v156, v226, v226
	global_store_dwordx2 v2, v[164:165], s[96:97]
	v_fmac_f32_e32 v156, v227, v227
	v_fmac_f32_e32 v156, v228, v228
	v_fmac_f32_e32 v156, v229, v229
	v_add_f32_dpp v149, v149, v149 row_shr:1 row_mask:0xf bank_mask:0xf bound_ctrl:0
	v_add_f32_dpp v150, v150, v150 row_shr:1 row_mask:0xf bank_mask:0xf bound_ctrl:0
	v_add_f32_dpp v151, v151, v151 row_shr:1 row_mask:0xf bank_mask:0xf bound_ctrl:0
	v_add_f32_dpp v152, v152, v152 row_shr:1 row_mask:0xf bank_mask:0xf bound_ctrl:0
	v_add_f32_dpp v153, v153, v153 row_shr:1 row_mask:0xf bank_mask:0xf bound_ctrl:0
	v_add_f32_dpp v154, v154, v154 row_shr:1 row_mask:0xf bank_mask:0xf bound_ctrl:0
	v_add_f32_dpp v155, v155, v155 row_shr:1 row_mask:0xf bank_mask:0xf bound_ctrl:0
	v_add_f32_dpp v156, v156, v156 row_shr:1 row_mask:0xf bank_mask:0xf bound_ctrl:0
	v_add_f32_dpp v149, v149, v149 row_shr:2 row_mask:0xf bank_mask:0xf bound_ctrl:0
	v_add_f32_dpp v150, v150, v150 row_shr:2 row_mask:0xf bank_mask:0xf bound_ctrl:0
	v_add_f32_dpp v151, v151, v151 row_shr:2 row_mask:0xf bank_mask:0xf bound_ctrl:0
	v_add_f32_dpp v152, v152, v152 row_shr:2 row_mask:0xf bank_mask:0xf bound_ctrl:0
	v_add_f32_dpp v153, v153, v153 row_shr:2 row_mask:0xf bank_mask:0xf bound_ctrl:0
	v_add_f32_dpp v154, v154, v154 row_shr:2 row_mask:0xf bank_mask:0xf bound_ctrl:0
	v_add_f32_dpp v155, v155, v155 row_shr:2 row_mask:0xf bank_mask:0xf bound_ctrl:0
	v_add_f32_dpp v156, v156, v156 row_shr:2 row_mask:0xf bank_mask:0xf bound_ctrl:0
	v_add_f32_dpp v149, v149, v149 row_shr:4 row_mask:0xf bank_mask:0xf bound_ctrl:0
	v_add_f32_dpp v150, v150, v150 row_shr:4 row_mask:0xf bank_mask:0xf bound_ctrl:0
	v_add_f32_dpp v151, v151, v151 row_shr:4 row_mask:0xf bank_mask:0xf bound_ctrl:0
	v_add_f32_dpp v152, v152, v152 row_shr:4 row_mask:0xf bank_mask:0xf bound_ctrl:0
	v_add_f32_dpp v153, v153, v153 row_shr:4 row_mask:0xf bank_mask:0xf bound_ctrl:0
	v_add_f32_dpp v154, v154, v154 row_shr:4 row_mask:0xf bank_mask:0xf bound_ctrl:0
	v_add_f32_dpp v155, v155, v155 row_shr:4 row_mask:0xf bank_mask:0xf bound_ctrl:0
	v_add_f32_dpp v156, v156, v156 row_shr:4 row_mask:0xf bank_mask:0xf bound_ctrl:0
	v_add_f32_dpp v149, v149, v149 row_shr:8 row_mask:0xf bank_mask:0xf bound_ctrl:0
	v_add_f32_dpp v150, v150, v150 row_shr:8 row_mask:0xf bank_mask:0xf bound_ctrl:0
	v_add_f32_dpp v151, v151, v151 row_shr:8 row_mask:0xf bank_mask:0xf bound_ctrl:0
	v_add_f32_dpp v152, v152, v152 row_shr:8 row_mask:0xf bank_mask:0xf bound_ctrl:0
	v_add_f32_dpp v153, v153, v153 row_shr:8 row_mask:0xf bank_mask:0xf bound_ctrl:0
	v_add_f32_dpp v154, v154, v154 row_shr:8 row_mask:0xf bank_mask:0xf bound_ctrl:0
	v_add_f32_dpp v155, v155, v155 row_shr:8 row_mask:0xf bank_mask:0xf bound_ctrl:0
	v_add_f32_dpp v156, v156, v156 row_shr:8 row_mask:0xf bank_mask:0xf bound_ctrl:0
	v_cmp_eq_u32_e32 vcc, 15, v138
	s_and_saveexec_b64 s[6:7], vcc
	global_store_dword v148, v149, s[94:95] offset:512
	global_store_dword v148, v150, s[94:95] offset:528
	global_store_dword v148, v151, s[94:95] offset:544
	global_store_dword v148, v152, s[94:95] offset:560
	global_store_dword v148, v153, s[94:95] offset:576
	global_store_dword v148, v154, s[94:95] offset:592
	global_store_dword v148, v155, s[94:95] offset:608
	global_store_dword v148, v156, s[94:95] offset:624
	s_branch .LBB0_2006

; DEVI float silu(float x) { return x * __builtin_amdgcn_rcpf(1.f + __expf(-x)); }
; template <int EPI, int NRM>
; DEVI void epilogue(acc_t& acc, int pn, int trow, const EpiArgs& e, const float* rl, bf16* shmx) {
;   int tid_ = threadIdx.x; asm volatile("" : "+v"(tid_));
;   const int wid = tid_ >> 6, lane = tid_ & 63, wr = wid >> 2, wc = wid & 3, fr = lane & 15, fq = lane >> 4;
;   const int fl0 = wr * 64 + fq * 4;
;   const int tk0 = trow + wc * 32 + fr;
;   float rs[2][2];
;   if constexpr (NRM) {
; #pragma unroll
;     for (int bj = 0; bj < 2; ++bj)
; #pragma unroll
;       for (int n = 0; n < 2; ++n) rs[bj][n] = rl[wc * 32 + fr + bj * 128 + n * 16];
;     ...
;   } else if constexpr (EPI == EPI_SWIGLU) {
; #pragma unroll
;     for (int bj = 0; bj < 2; ++bj)
; #pragma unroll
;       for (int m = 0; m < 4; ++m)
; #pragma unroll
;         for (int n = 0; n < 2; ++n) {
;           float r[4];
; #pragma unroll
;           for (int j = 0; j < 4; ++j) r[j] = silu(acc[0][bj][m][n][j] * rs[bj][n]) * (acc[1][bj][m][n][j] * rs[bj][n]);
;           uint2 o; o.x = pack2(r[0], r[1]); o.y = pack2(r[2], r[3]);
;           const unsigned off = (unsigned)((tk0 + bj * 128 + n * 16) * DFF + pn * 128 + m * 16 + fl0);
;           *reinterpret_cast<uint2*>(e.o0 + off) = o;
;         }
.LBB0_2055:
	v_and_b32_e32 v170, 15, v1
	v_bfe_u32 v171, v1, 4, 2
	v_lshrrev_b32_e32 v172, 6, v1
	v_and_b32_e32 v173, 3, v172
	v_lshrrev_b32_e32 v174, 2, v172
	v_lshlrev_b32_e32 v175, 13, v173
	v_lshl_add_u32 v175, v174, 16, v175
	v_add_u32_e32 v175, 0x8000, v175
	v_lshl_add_u32 v176, v170, 7, v175
	v_and_b32_e32 v177, 1, v171
	v_lshl_add_u32 v176, v177, 3, v176
	v_lshrrev_b32_e32 v177, 1, v171
	v_and_b32_e32 v178, 7, v170
	v_add_u32_e32 v179, 0, v177
	v_xor_b32_e32 v179, v179, v178
	v_lshl_add_u32 v164, v179, 4, v176
	v_add_u32_e32 v179, 2, v177
	v_xor_b32_e32 v179, v179, v178
	v_lshl_add_u32 v165, v179, 4, v176
	v_add_u32_e32 v179, 4, v177
	v_xor_b32_e32 v179, v179, v178
	v_lshl_add_u32 v166, v179, 4, v176
	v_add_u32_e32 v179, 6, v177
	v_xor_b32_e32 v179, v179, v178
	v_lshl_add_u32 v167, v179, 4, v176
	v_and_b32_e32 v180, 63, v1
	v_lshl_add_u32 v168, v180, 4, v175
	v_lshrrev_b32_e32 v181, 3, v180
	v_and_b32_e32 v182, 7, v180
	v_xor_b32_e32 v182, v182, v181
	s_lshl_b32 s9, s12, 8
	v_lshl_add_u32 v183, v173, 5, v181
	v_add_u32_e32 v183, s9, v183
	v_mul_u32_u24_e32 v183, 0x1600, v183
	s_lshl_b32 s9, s14, 7
	v_lshl_add_u32 v179, v174, 6, s9
	v_lshl_add_u32 v179, v182, 3, v179
	v_add_lshl_u32 v169, v183, v179, 1
	v_mov_b32_e32 v132, v1
	s_lshl_b32 s11, s16, 10
	s_and_b32 s11, s11, 0x400
	v_and_b32_e32 v141, 15, v132
	v_ashrrev_i32_e32 v142, 2, v132
	v_lshrrev_b32_e32 v143, 2, v132
	v_lshrrev_b32_e32 v132, 1, v132
	s_add_i32 s11, s11, 0
	v_and_b32_e32 v132, 0x60, v132
	s_add_i32 s11, s11, 0x20000
	v_lshlrev_b32_e32 v134, 2, v132
	v_lshlrev_b32_e32 v135, 2, v141
	v_add3_u32 v134, s11, v134, v135
	ds_read2_b32 v[136:137], v134 offset1:16
	ds_read2_b32 v[134:135], v134 offset0:128 offset1:144
	s_lshl_b32 s9, s12, 8
	v_or3_b32 v132, v141, s9, v132
	s_lshl_b32 s9, s14, 7
	s_waitcnt lgkmcnt(1)
	v_pk_mul_f32 v[122:123], v[122:123], v[136:137] op_sel_hi:[1,0]
	v_and_or_b32 v141, v143, 12, s9
	v_mul_f32_e32 v143, 0xbfb8aa3b, v122
	v_mul_f32_e32 v144, 0xbfb8aa3b, v123
	v_exp_f32_e32 v143, v143
	v_exp_f32_e32 v144, v144
	v_and_b32_e32 v142, 0xffffffc0, v142
	v_pk_mul_f32 v[124:125], v[124:125], v[136:137] op_sel_hi:[1,0]
	v_add_u32_e32 v141, v141, v142
	v_add_f32_e32 v142, 1.0, v143
	v_add_f32_e32 v143, 1.0, v144
	v_mul_f32_e32 v144, 0xbfb8aa3b, v124
	v_mul_f32_e32 v145, 0xbfb8aa3b, v125
	v_rcp_f32_e32 v142, v142
	v_rcp_f32_e32 v143, v143
	v_exp_f32_e32 v144, v144
	v_exp_f32_e32 v145, v145
	v_pk_mul_f32 v[126:127], v[126:127], v[136:137] op_sel_hi:[1,0]
	v_pk_mul_f32 v[122:123], v[122:123], v[142:143]
	v_add_f32_e32 v142, 1.0, v144
	v_add_f32_e32 v143, 1.0, v145
	v_rcp_f32_e32 v142, v142
	v_rcp_f32_e32 v143, v143
	v_pk_mul_f32 v[122:123], v[126:127], v[122:123]
	v_pk_mul_f32 v[106:107], v[106:107], v[136:137] op_sel_hi:[1,0]
	v_cvt_pk_bf16_f32 v126, v122, v123
	v_pk_mul_f32 v[122:123], v[124:125], v[142:143]
	v_pk_mul_f32 v[124:125], v[128:129], v[136:137] op_sel_hi:[1,0]
	v_pk_mul_f32 v[108:109], v[108:109], v[136:137] op_sel_hi:[1,0]
	v_pk_mul_f32 v[122:123], v[124:125], v[122:123]
	v_pk_mul_f32 v[110:111], v[110:111], v[136:137] op_sel_hi:[1,0]
	v_cvt_pk_bf16_f32 v127, v122, v123
	v_mul_lo_u32 v123, v132, s41
	v_mov_b32_e32 v122, v137
	v_pk_mul_f32 v[114:115], v[114:115], v[122:123] op_sel_hi:[1,0]
	v_add_u32_e32 v132, v141, v123
	v_mul_f32_e32 v128, 0xbfb8aa3b, v114
	v_mul_f32_e32 v129, 0xbfb8aa3b, v115
	v_exp_f32_e32 v128, v128
	v_exp_f32_e32 v129, v129
	v_lshl_add_u64 v[124:125], v[132:133], 1, s[2:3]
	v_pk_mul_f32 v[116:117], v[116:117], v[122:123] op_sel_hi:[1,0]
	ds_write_b64 v164, v[126:127]
	v_add_f32_e32 v124, 1.0, v128
	v_add_f32_e32 v125, 1.0, v129
	v_mul_f32_e32 v126, 0xbfb8aa3b, v116
	v_mul_f32_e32 v127, 0xbfb8aa3b, v117
	v_rcp_f32_e32 v124, v124
	v_rcp_f32_e32 v125, v125
	v_exp_f32_e32 v126, v126
	v_exp_f32_e32 v127, v127
	v_pk_mul_f32 v[118:119], v[118:119], v[122:123] op_sel_hi:[1,0]
	v_pk_mul_f32 v[114:115], v[114:115], v[124:125]
	v_add_f32_e32 v124, 1.0, v126
	v_add_f32_e32 v125, 1.0, v127
	v_rcp_f32_e32 v124, v124
	v_rcp_f32_e32 v125, v125
	v_pk_mul_f32 v[114:115], v[118:119], v[114:115]
	v_pk_mul_f32 v[118:119], v[120:121], v[122:123] op_sel_hi:[1,0]
	v_cvt_pk_bf16_f32 v114, v114, v115
	v_pk_mul_f32 v[116:117], v[116:117], v[124:125]
	v_pk_mul_f32 v[98:99], v[98:99], v[122:123] op_sel_hi:[1,0]
	v_pk_mul_f32 v[116:117], v[118:119], v[116:117]
	v_add_u32_e32 v118, 0x16000, v123
	v_add_u32_e32 v132, v118, v141
	v_cvt_pk_bf16_f32 v115, v116, v117
	v_lshl_add_u64 v[116:117], v[132:133], 1, s[2:3]
	ds_write_b64 v164, v[114:115] offset:2048
	v_mul_f32_e32 v114, 0xbfb8aa3b, v106
	v_mul_f32_e32 v115, 0xbfb8aa3b, v107
	v_exp_f32_e32 v114, v114
	v_exp_f32_e32 v115, v115
	v_mul_f32_e32 v117, 0xbfb8aa3b, v108
	v_mul_f32_e32 v119, 0xbfb8aa3b, v109
	v_add_f32_e32 v114, 1.0, v114
	v_add_f32_e32 v115, 1.0, v115
	v_rcp_f32_e32 v114, v114
	v_rcp_f32_e32 v115, v115
	v_exp_f32_e32 v117, v117
	v_exp_f32_e32 v119, v119
	v_or_b32_e32 v116, 16, v141
	v_pk_mul_f32 v[106:107], v[106:107], v[114:115]
	v_add_f32_e32 v114, 1.0, v117
	v_add_f32_e32 v115, 1.0, v119
	v_rcp_f32_e32 v114, v114
	v_rcp_f32_e32 v115, v115
	v_pk_mul_f32 v[106:107], v[110:111], v[106:107]
	v_pk_mul_f32 v[110:111], v[112:113], v[136:137] op_sel_hi:[1,0]
	v_add_u32_e32 v132, v116, v123
	v_pk_mul_f32 v[108:109], v[108:109], v[114:115]
	v_cvt_pk_bf16_f32 v106, v106, v107
	v_pk_mul_f32 v[108:109], v[110:111], v[108:109]
	v_mul_f32_e32 v110, 0xbfb8aa3b, v98
	v_mul_f32_e32 v111, 0xbfb8aa3b, v99
	v_exp_f32_e32 v110, v110
	v_exp_f32_e32 v111, v111
	v_cvt_pk_bf16_f32 v107, v108, v109
	v_lshl_add_u64 v[108:109], v[132:133], 1, s[2:3]
	v_pk_mul_f32 v[100:101], v[100:101], v[122:123] op_sel_hi:[1,0]
; DEVI float silu(float x) { return x * __builtin_amdgcn_rcpf(1.f + __expf(-x)); }
; template <int EPI, int NRM>
; DEVI void epilogue(acc_t& acc, int pn, int trow, const EpiArgs& e, const float* rl, bf16* shmx) {
;     ...
;   } else if constexpr (EPI == EPI_SWIGLU) {
; #pragma unroll
;     for (int bj = 0; bj < 2; ++bj)
; #pragma unroll
;       for (int m = 0; m < 4; ++m)
; #pragma unroll
;         for (int n = 0; n < 2; ++n) {
;           float r[4];
; #pragma unroll
;           for (int j = 0; j < 4; ++j) r[j] = silu(acc[0][bj][m][n][j] * rs[bj][n]) * (acc[1][bj][m][n][j] * rs[bj][n]);
;           uint2 o; o.x = pack2(r[0], r[1]); o.y = pack2(r[2], r[3]);
;           const unsigned off = (unsigned)((tk0 + bj * 128 + n * 16) * DFF + pn * 128 + m * 16 + fl0);
;           *reinterpret_cast<uint2*>(e.o0 + off) = o;
;         }
	ds_write_b64 v165, v[106:107]
	v_add_f32_e32 v106, 1.0, v110
	v_add_f32_e32 v107, 1.0, v111
	v_mul_f32_e32 v108, 0xbfb8aa3b, v100
	v_mul_f32_e32 v109, 0xbfb8aa3b, v101
	v_rcp_f32_e32 v106, v106
	v_rcp_f32_e32 v107, v107
	v_exp_f32_e32 v108, v108
	v_exp_f32_e32 v109, v109
	v_pk_mul_f32 v[102:103], v[102:103], v[122:123] op_sel_hi:[1,0]
	v_pk_mul_f32 v[98:99], v[98:99], v[106:107]
	v_add_f32_e32 v106, 1.0, v108
	v_add_f32_e32 v107, 1.0, v109
	v_rcp_f32_e32 v106, v106
	v_rcp_f32_e32 v107, v107
	v_pk_mul_f32 v[98:99], v[102:103], v[98:99]
	v_pk_mul_f32 v[102:103], v[104:105], v[122:123] op_sel_hi:[1,0]
	v_add_u32_e32 v132, v116, v118
	v_pk_mul_f32 v[100:101], v[100:101], v[106:107]
	v_cvt_pk_bf16_f32 v98, v98, v99
	v_pk_mul_f32 v[100:101], v[102:103], v[100:101]
	v_pk_mul_f32 v[90:91], v[90:91], v[136:137] op_sel_hi:[1,0]
	v_cvt_pk_bf16_f32 v99, v100, v101
	v_lshl_add_u64 v[100:101], v[132:133], 1, s[2:3]
	ds_write_b64 v165, v[98:99] offset:2048
	v_mul_f32_e32 v98, 0xbfb8aa3b, v90
	v_mul_f32_e32 v99, 0xbfb8aa3b, v91
	v_exp_f32_e32 v98, v98
	v_exp_f32_e32 v99, v99
	v_pk_mul_f32 v[92:93], v[92:93], v[136:137] op_sel_hi:[1,0]
	v_pk_mul_f32 v[94:95], v[94:95], v[136:137] op_sel_hi:[1,0]
	v_add_f32_e32 v98, 1.0, v98
	v_add_f32_e32 v99, 1.0, v99
	v_mul_f32_e32 v101, 0xbfb8aa3b, v92
	v_mul_f32_e32 v102, 0xbfb8aa3b, v93
	v_rcp_f32_e32 v98, v98
	v_rcp_f32_e32 v99, v99
	v_exp_f32_e32 v101, v101
	v_exp_f32_e32 v102, v102
	v_pk_mul_f32 v[82:83], v[82:83], v[122:123] op_sel_hi:[1,0]
	v_pk_mul_f32 v[90:91], v[90:91], v[98:99]
	v_add_f32_e32 v98, 1.0, v101
	v_add_f32_e32 v99, 1.0, v102
	v_rcp_f32_e32 v98, v98
	v_rcp_f32_e32 v99, v99
	v_pk_mul_f32 v[90:91], v[94:95], v[90:91]
	v_pk_mul_f32 v[94:95], v[96:97], v[136:137] op_sel_hi:[1,0]
	v_or_b32_e32 v100, 32, v141
	v_pk_mul_f32 v[92:93], v[92:93], v[98:99]
	v_add_u32_e32 v132, v100, v123
	v_pk_mul_f32 v[92:93], v[94:95], v[92:93]
	v_mul_f32_e32 v94, 0xbfb8aa3b, v82
	v_mul_f32_e32 v95, 0xbfb8aa3b, v83
	v_exp_f32_e32 v94, v94
	v_exp_f32_e32 v95, v95
	v_cvt_pk_bf16_f32 v90, v90, v91
	v_cvt_pk_bf16_f32 v91, v92, v93
	v_lshl_add_u64 v[92:93], v[132:133], 1, s[2:3]
	v_pk_mul_f32 v[84:85], v[84:85], v[122:123] op_sel_hi:[1,0]
	ds_write_b64 v166, v[90:91]
	v_add_f32_e32 v90, 1.0, v94
	v_add_f32_e32 v91, 1.0, v95
	v_mul_f32_e32 v92, 0xbfb8aa3b, v84
	v_mul_f32_e32 v93, 0xbfb8aa3b, v85
	v_rcp_f32_e32 v90, v90
	v_rcp_f32_e32 v91, v91
	v_exp_f32_e32 v92, v92
	v_exp_f32_e32 v93, v93
	v_pk_mul_f32 v[86:87], v[86:87], v[122:123] op_sel_hi:[1,0]
	v_pk_mul_f32 v[82:83], v[82:83], v[90:91]
	v_add_f32_e32 v90, 1.0, v92
	v_add_f32_e32 v91, 1.0, v93
	v_rcp_f32_e32 v90, v90
	v_rcp_f32_e32 v91, v91
	v_pk_mul_f32 v[82:83], v[86:87], v[82:83]
	v_pk_mul_f32 v[86:87], v[88:89], v[122:123] op_sel_hi:[1,0]
	v_add_u32_e32 v132, v100, v118
	v_pk_mul_f32 v[84:85], v[84:85], v[90:91]
	v_cvt_pk_bf16_f32 v82, v82, v83
	v_pk_mul_f32 v[84:85], v[86:87], v[84:85]
	v_pk_mul_f32 v[74:75], v[74:75], v[136:137] op_sel_hi:[1,0]
	v_cvt_pk_bf16_f32 v83, v84, v85
	v_lshl_add_u64 v[84:85], v[132:133], 1, s[2:3]
	ds_write_b64 v166, v[82:83] offset:2048
	v_mul_f32_e32 v82, 0xbfb8aa3b, v74
	v_mul_f32_e32 v83, 0xbfb8aa3b, v75
	v_exp_f32_e32 v82, v82
	v_exp_f32_e32 v83, v83
	v_pk_mul_f32 v[76:77], v[76:77], v[136:137] op_sel_hi:[1,0]
	v_pk_mul_f32 v[78:79], v[78:79], v[136:137] op_sel_hi:[1,0]
	v_add_f32_e32 v82, 1.0, v82
	v_add_f32_e32 v83, 1.0, v83
	v_mul_f32_e32 v85, 0xbfb8aa3b, v76
	v_mul_f32_e32 v86, 0xbfb8aa3b, v77
	v_rcp_f32_e32 v82, v82
	v_rcp_f32_e32 v83, v83
	v_exp_f32_e32 v85, v85
	v_exp_f32_e32 v86, v86
	v_pk_mul_f32 v[66:67], v[66:67], v[122:123] op_sel_hi:[1,0]
	v_pk_mul_f32 v[74:75], v[74:75], v[82:83]
	v_add_f32_e32 v82, 1.0, v85
	v_add_f32_e32 v83, 1.0, v86
	v_rcp_f32_e32 v82, v82
	v_rcp_f32_e32 v83, v83
	v_pk_mul_f32 v[74:75], v[78:79], v[74:75]
	v_pk_mul_f32 v[78:79], v[80:81], v[136:137] op_sel_hi:[1,0]
	v_or_b32_e32 v84, 48, v141
	v_pk_mul_f32 v[76:77], v[76:77], v[82:83]
	v_add_u32_e32 v132, v84, v123
	v_pk_mul_f32 v[76:77], v[78:79], v[76:77]
	v_mul_f32_e32 v78, 0xbfb8aa3b, v66
	v_mul_f32_e32 v79, 0xbfb8aa3b, v67
	v_exp_f32_e32 v78, v78
	v_exp_f32_e32 v79, v79
	v_cvt_pk_bf16_f32 v74, v74, v75
	v_cvt_pk_bf16_f32 v75, v76, v77
	v_lshl_add_u64 v[76:77], v[132:133], 1, s[2:3]
	v_pk_mul_f32 v[68:69], v[68:69], v[122:123] op_sel_hi:[1,0]
	ds_write_b64 v167, v[74:75]
	v_add_f32_e32 v74, 1.0, v78
	v_add_f32_e32 v75, 1.0, v79
	v_mul_f32_e32 v76, 0xbfb8aa3b, v68
	v_mul_f32_e32 v77, 0xbfb8aa3b, v69
	v_rcp_f32_e32 v74, v74
	v_rcp_f32_e32 v75, v75
	v_exp_f32_e32 v76, v76
	v_exp_f32_e32 v77, v77
	v_pk_mul_f32 v[70:71], v[70:71], v[122:123] op_sel_hi:[1,0]
	v_pk_mul_f32 v[66:67], v[66:67], v[74:75]
	v_add_f32_e32 v74, 1.0, v76
	v_add_f32_e32 v75, 1.0, v77
	v_rcp_f32_e32 v74, v74
	v_rcp_f32_e32 v75, v75
	v_pk_mul_f32 v[66:67], v[70:71], v[66:67]
	v_pk_mul_f32 v[70:71], v[72:73], v[122:123] op_sel_hi:[1,0]
	s_waitcnt lgkmcnt(0)
; DEVI float silu(float x) { return x * __builtin_amdgcn_rcpf(1.f + __expf(-x)); }
; template <int EPI, int NRM>
; DEVI void epilogue(acc_t& acc, int pn, int trow, const EpiArgs& e, const float* rl, bf16* shmx) {
;     ...
;   } else if constexpr (EPI == EPI_SWIGLU) {
; #pragma unroll
;     for (int bj = 0; bj < 2; ++bj)
; #pragma unroll
;       for (int m = 0; m < 4; ++m)
; #pragma unroll
;         for (int n = 0; n < 2; ++n) {
;           float r[4];
; #pragma unroll
;           for (int j = 0; j < 4; ++j) r[j] = silu(acc[0][bj][m][n][j] * rs[bj][n]) * (acc[1][bj][m][n][j] * rs[bj][n]);
;           uint2 o; o.x = pack2(r[0], r[1]); o.y = pack2(r[2], r[3]);
;           const unsigned off = (unsigned)((tk0 + bj * 128 + n * 16) * DFF + pn * 128 + m * 16 + fl0);
;           *reinterpret_cast<uint2*>(e.o0 + off) = o;
;         }
	v_pk_mul_f32 v[58:59], v[58:59], v[134:135] op_sel_hi:[1,0]
	v_pk_mul_f32 v[68:69], v[68:69], v[74:75]
	v_add_u32_e32 v132, v84, v118
	v_pk_mul_f32 v[68:69], v[70:71], v[68:69]
	v_mul_f32_e32 v70, 0xbfb8aa3b, v58
	v_mul_f32_e32 v71, 0xbfb8aa3b, v59
	v_exp_f32_e32 v70, v70
	v_exp_f32_e32 v71, v71
	v_cvt_pk_bf16_f32 v66, v66, v67
	v_cvt_pk_bf16_f32 v67, v68, v69
	v_lshl_add_u64 v[68:69], v[132:133], 1, s[2:3]
	v_pk_mul_f32 v[60:61], v[60:61], v[134:135] op_sel_hi:[1,0]
	ds_write_b64 v167, v[66:67] offset:2048
	v_add_f32_e32 v66, 1.0, v70
	v_add_f32_e32 v67, 1.0, v71
	v_mul_f32_e32 v68, 0xbfb8aa3b, v60
	v_mul_f32_e32 v69, 0xbfb8aa3b, v61
	v_rcp_f32_e32 v66, v66
	v_rcp_f32_e32 v67, v67
	v_exp_f32_e32 v68, v68
	v_exp_f32_e32 v69, v69
	v_pk_mul_f32 v[62:63], v[62:63], v[134:135] op_sel_hi:[1,0]
	v_pk_mul_f32 v[58:59], v[58:59], v[66:67]
	v_add_f32_e32 v66, 1.0, v68
	v_add_f32_e32 v67, 1.0, v69
	v_rcp_f32_e32 v66, v66
	v_rcp_f32_e32 v67, v67
	v_pk_mul_f32 v[58:59], v[62:63], v[58:59]
	v_pk_mul_f32 v[42:43], v[42:43], v[134:135] op_sel_hi:[1,0]
	v_cvt_pk_bf16_f32 v62, v58, v59
	v_pk_mul_f32 v[58:59], v[60:61], v[66:67]
	v_pk_mul_f32 v[60:61], v[64:65], v[134:135] op_sel_hi:[1,0]
	v_pk_mul_f32 v[44:45], v[44:45], v[134:135] op_sel_hi:[1,0]
	v_pk_mul_f32 v[58:59], v[60:61], v[58:59]
	v_pk_mul_f32 v[46:47], v[46:47], v[134:135] op_sel_hi:[1,0]
	v_cvt_pk_bf16_f32 v63, v58, v59
	v_add_u32_e32 v59, 0xb0000, v123
	v_mov_b32_e32 v58, v135
	v_pk_mul_f32 v[50:51], v[50:51], v[58:59] op_sel_hi:[1,0]
	v_add_u32_e32 v132, v59, v141
	v_mul_f32_e32 v64, 0xbfb8aa3b, v50
	v_mul_f32_e32 v65, 0xbfb8aa3b, v51
	v_exp_f32_e32 v64, v64
	v_exp_f32_e32 v65, v65
	v_lshl_add_u64 v[60:61], v[132:133], 1, s[2:3]
	v_pk_mul_f32 v[52:53], v[52:53], v[58:59] op_sel_hi:[1,0]
	ds_write_b64 v164, v[62:63] offset:4096
	v_add_f32_e32 v60, 1.0, v64
	v_add_f32_e32 v61, 1.0, v65
	v_mul_f32_e32 v62, 0xbfb8aa3b, v52
	v_mul_f32_e32 v63, 0xbfb8aa3b, v53
	v_rcp_f32_e32 v60, v60
	v_rcp_f32_e32 v61, v61
	v_exp_f32_e32 v62, v62
	v_exp_f32_e32 v63, v63
	v_pk_mul_f32 v[54:55], v[54:55], v[58:59] op_sel_hi:[1,0]
	v_pk_mul_f32 v[50:51], v[50:51], v[60:61]
	v_add_f32_e32 v60, 1.0, v62
	v_add_f32_e32 v61, 1.0, v63
	v_rcp_f32_e32 v60, v60
	v_rcp_f32_e32 v61, v61
	v_pk_mul_f32 v[50:51], v[54:55], v[50:51]
	v_pk_mul_f32 v[54:55], v[56:57], v[58:59] op_sel_hi:[1,0]
	v_mul_f32_e32 v56, 0xbfb8aa3b, v43
	v_pk_mul_f32 v[52:53], v[52:53], v[60:61]
	v_exp_f32_e32 v56, v56
	v_pk_mul_f32 v[52:53], v[54:55], v[52:53]
	v_mul_f32_e32 v55, 0xbfb8aa3b, v42
	v_exp_f32_e32 v55, v55
	v_add_u32_e32 v54, 0xc6000, v123
	v_add_u32_e32 v132, v54, v141
	v_cvt_pk_bf16_f32 v50, v50, v51
	v_cvt_pk_bf16_f32 v51, v52, v53
	v_lshl_add_u64 v[52:53], v[132:133], 1, s[2:3]
	ds_write_b64 v164, v[50:51] offset:6144
	v_add_f32_e32 v50, 1.0, v55
	v_add_f32_e32 v51, 1.0, v56
	v_mul_f32_e32 v52, 0xbfb8aa3b, v44
	v_mul_f32_e32 v53, 0xbfb8aa3b, v45
	v_rcp_f32_e32 v50, v50
	v_rcp_f32_e32 v51, v51
	v_exp_f32_e32 v52, v52
	v_exp_f32_e32 v53, v53
	v_pk_mul_f32 v[34:35], v[34:35], v[58:59] op_sel_hi:[1,0]
	v_pk_mul_f32 v[42:43], v[42:43], v[50:51]
	v_add_f32_e32 v50, 1.0, v52
	v_add_f32_e32 v51, 1.0, v53
	v_rcp_f32_e32 v50, v50
	v_rcp_f32_e32 v51, v51
	v_pk_mul_f32 v[42:43], v[46:47], v[42:43]
	v_pk_mul_f32 v[46:47], v[48:49], v[134:135] op_sel_hi:[1,0]
	v_add_u32_e32 v132, v116, v59
	v_pk_mul_f32 v[44:45], v[44:45], v[50:51]
	v_cvt_pk_bf16_f32 v42, v42, v43
	v_pk_mul_f32 v[44:45], v[46:47], v[44:45]
	v_mul_f32_e32 v46, 0xbfb8aa3b, v34
	v_mul_f32_e32 v47, 0xbfb8aa3b, v35
	v_exp_f32_e32 v46, v46
	v_exp_f32_e32 v47, v47
	v_cvt_pk_bf16_f32 v43, v44, v45
	v_lshl_add_u64 v[44:45], v[132:133], 1, s[2:3]
	v_pk_mul_f32 v[36:37], v[36:37], v[58:59] op_sel_hi:[1,0]
	ds_write_b64 v165, v[42:43] offset:4096
	v_add_f32_e32 v42, 1.0, v46
	v_add_f32_e32 v43, 1.0, v47
	v_mul_f32_e32 v44, 0xbfb8aa3b, v36
	v_mul_f32_e32 v45, 0xbfb8aa3b, v37
	v_rcp_f32_e32 v42, v42
	v_rcp_f32_e32 v43, v43
	v_exp_f32_e32 v44, v44
	v_exp_f32_e32 v45, v45
	v_pk_mul_f32 v[38:39], v[38:39], v[58:59] op_sel_hi:[1,0]
	v_pk_mul_f32 v[34:35], v[34:35], v[42:43]
	v_add_f32_e32 v42, 1.0, v44
	v_add_f32_e32 v43, 1.0, v45
	v_rcp_f32_e32 v42, v42
	v_rcp_f32_e32 v43, v43
	v_pk_mul_f32 v[34:35], v[38:39], v[34:35]
	v_pk_mul_f32 v[38:39], v[40:41], v[58:59] op_sel_hi:[1,0]
	v_pk_mul_f32 v[26:27], v[26:27], v[134:135] op_sel_hi:[1,0]
	v_pk_mul_f32 v[36:37], v[36:37], v[42:43]
	v_add_u32_e32 v132, v116, v54
	v_pk_mul_f32 v[36:37], v[38:39], v[36:37]
	v_mul_f32_e32 v38, 0xbfb8aa3b, v26
	v_mul_f32_e32 v39, 0xbfb8aa3b, v27
	v_exp_f32_e32 v38, v38
	v_exp_f32_e32 v39, v39
	v_cvt_pk_bf16_f32 v34, v34, v35
	v_cvt_pk_bf16_f32 v35, v36, v37
	v_lshl_add_u64 v[36:37], v[132:133], 1, s[2:3]
	v_pk_mul_f32 v[28:29], v[28:29], v[134:135] op_sel_hi:[1,0]
	ds_write_b64 v165, v[34:35] offset:6144
	v_add_f32_e32 v34, 1.0, v38
	v_add_f32_e32 v35, 1.0, v39
	v_mul_f32_e32 v36, 0xbfb8aa3b, v28
	v_mul_f32_e32 v37, 0xbfb8aa3b, v29
	v_rcp_f32_e32 v34, v34
	v_rcp_f32_e32 v35, v35
	v_exp_f32_e32 v36, v36
; DEVI float silu(float x) { return x * __builtin_amdgcn_rcpf(1.f + __expf(-x)); }
; template <int EPI, int NRM>
; DEVI void epilogue(acc_t& acc, int pn, int trow, const EpiArgs& e, const float* rl, bf16* shmx) {
;     ...
;   } else if constexpr (EPI == EPI_SWIGLU) {
; #pragma unroll
;     for (int bj = 0; bj < 2; ++bj)
; #pragma unroll
;       for (int m = 0; m < 4; ++m)
; #pragma unroll
;         for (int n = 0; n < 2; ++n) {
;           float r[4];
; #pragma unroll
;           for (int j = 0; j < 4; ++j) r[j] = silu(acc[0][bj][m][n][j] * rs[bj][n]) * (acc[1][bj][m][n][j] * rs[bj][n]);
;           uint2 o; o.x = pack2(r[0], r[1]); o.y = pack2(r[2], r[3]);
;           const unsigned off = (unsigned)((tk0 + bj * 128 + n * 16) * DFF + pn * 128 + m * 16 + fl0);
;           *reinterpret_cast<uint2*>(e.o0 + off) = o;
;         }
	v_exp_f32_e32 v37, v37
	v_pk_mul_f32 v[30:31], v[30:31], v[134:135] op_sel_hi:[1,0]
	v_pk_mul_f32 v[26:27], v[26:27], v[34:35]
	v_add_f32_e32 v34, 1.0, v36
	v_add_f32_e32 v35, 1.0, v37
	v_rcp_f32_e32 v34, v34
	v_rcp_f32_e32 v35, v35
	v_pk_mul_f32 v[26:27], v[30:31], v[26:27]
	v_pk_mul_f32 v[30:31], v[32:33], v[134:135] op_sel_hi:[1,0]
	v_pk_mul_f32 v[18:19], v[18:19], v[58:59] op_sel_hi:[1,0]
	v_pk_mul_f32 v[28:29], v[28:29], v[34:35]
	v_add_u32_e32 v132, v100, v59
	v_pk_mul_f32 v[28:29], v[30:31], v[28:29]
	v_mul_f32_e32 v30, 0xbfb8aa3b, v18
	v_mul_f32_e32 v31, 0xbfb8aa3b, v19
	v_exp_f32_e32 v30, v30
	v_exp_f32_e32 v31, v31
	v_cvt_pk_bf16_f32 v26, v26, v27
	v_cvt_pk_bf16_f32 v27, v28, v29
	v_lshl_add_u64 v[28:29], v[132:133], 1, s[2:3]
	v_pk_mul_f32 v[20:21], v[20:21], v[58:59] op_sel_hi:[1,0]
	ds_write_b64 v166, v[26:27] offset:4096
	v_add_f32_e32 v26, 1.0, v30
	v_add_f32_e32 v27, 1.0, v31
	v_mul_f32_e32 v28, 0xbfb8aa3b, v20
	v_mul_f32_e32 v29, 0xbfb8aa3b, v21
	v_rcp_f32_e32 v26, v26
	v_rcp_f32_e32 v27, v27
	v_exp_f32_e32 v28, v28
	v_exp_f32_e32 v29, v29
	v_pk_mul_f32 v[22:23], v[22:23], v[58:59] op_sel_hi:[1,0]
	v_pk_mul_f32 v[18:19], v[18:19], v[26:27]
	v_add_f32_e32 v26, 1.0, v28
	v_add_f32_e32 v27, 1.0, v29
	v_rcp_f32_e32 v26, v26
	v_rcp_f32_e32 v27, v27
	v_pk_mul_f32 v[18:19], v[22:23], v[18:19]
	v_pk_mul_f32 v[22:23], v[24:25], v[58:59] op_sel_hi:[1,0]
	v_pk_mul_f32 v[10:11], v[10:11], v[134:135] op_sel_hi:[1,0]
	v_pk_mul_f32 v[20:21], v[20:21], v[26:27]
	v_add_u32_e32 v132, v100, v54
	v_pk_mul_f32 v[20:21], v[22:23], v[20:21]
	v_mul_f32_e32 v22, 0xbfb8aa3b, v10
	v_mul_f32_e32 v23, 0xbfb8aa3b, v11
	v_exp_f32_e32 v22, v22
	v_exp_f32_e32 v23, v23
	v_cvt_pk_bf16_f32 v18, v18, v19
	v_cvt_pk_bf16_f32 v19, v20, v21
	v_lshl_add_u64 v[20:21], v[132:133], 1, s[2:3]
	v_pk_mul_f32 v[12:13], v[12:13], v[134:135] op_sel_hi:[1,0]
	ds_write_b64 v166, v[18:19] offset:6144
	v_add_f32_e32 v18, 1.0, v22
	v_add_f32_e32 v19, 1.0, v23
	v_mul_f32_e32 v20, 0xbfb8aa3b, v12
	v_mul_f32_e32 v21, 0xbfb8aa3b, v13
	v_rcp_f32_e32 v18, v18
	v_rcp_f32_e32 v19, v19
	v_exp_f32_e32 v20, v20
	v_exp_f32_e32 v21, v21
	v_pk_mul_f32 v[14:15], v[14:15], v[134:135] op_sel_hi:[1,0]
	v_pk_mul_f32 v[10:11], v[10:11], v[18:19]
	v_add_f32_e32 v18, 1.0, v20
	v_add_f32_e32 v19, 1.0, v21
	v_rcp_f32_e32 v18, v18
	v_rcp_f32_e32 v19, v19
	v_pk_mul_f32 v[10:11], v[14:15], v[10:11]
	v_pk_mul_f32 v[14:15], v[16:17], v[134:135] op_sel_hi:[1,0]
	v_pk_mul_f32 v[2:3], v[2:3], v[58:59] op_sel_hi:[1,0]
	v_pk_mul_f32 v[12:13], v[12:13], v[18:19]
	v_add_u32_e32 v132, v84, v59
	v_pk_mul_f32 v[12:13], v[14:15], v[12:13]
	v_mul_f32_e32 v14, 0xbfb8aa3b, v2
	v_mul_f32_e32 v15, 0xbfb8aa3b, v3
	v_exp_f32_e32 v14, v14
	v_exp_f32_e32 v15, v15
	v_cvt_pk_bf16_f32 v10, v10, v11
	v_cvt_pk_bf16_f32 v11, v12, v13
	v_lshl_add_u64 v[12:13], v[132:133], 1, s[2:3]
	v_pk_mul_f32 v[4:5], v[4:5], v[58:59] op_sel_hi:[1,0]
	ds_write_b64 v167, v[10:11] offset:4096
	v_add_f32_e32 v10, 1.0, v14
	v_add_f32_e32 v11, 1.0, v15
	v_mul_f32_e32 v12, 0xbfb8aa3b, v4
	v_mul_f32_e32 v13, 0xbfb8aa3b, v5
	v_rcp_f32_e32 v10, v10
	v_rcp_f32_e32 v11, v11
	v_exp_f32_e32 v12, v12
	v_exp_f32_e32 v13, v13
	v_pk_mul_f32 v[6:7], v[6:7], v[58:59] op_sel_hi:[1,0]
	v_pk_mul_f32 v[2:3], v[2:3], v[10:11]
	v_add_f32_e32 v10, 1.0, v12
	v_add_f32_e32 v11, 1.0, v13
	v_rcp_f32_e32 v10, v10
	v_rcp_f32_e32 v11, v11
	v_pk_mul_f32 v[2:3], v[6:7], v[2:3]
	v_pk_mul_f32 v[6:7], v[8:9], v[58:59] op_sel_hi:[1,0]
	v_add_u32_e32 v132, v84, v54
	v_pk_mul_f32 v[4:5], v[4:5], v[10:11]
	v_cvt_pk_bf16_f32 v2, v2, v3
	v_pk_mul_f32 v[4:5], v[6:7], v[4:5]
	s_add_i32 s16, s16, 1
	v_cvt_pk_bf16_f32 v3, v4, v5
	v_lshl_add_u64 v[4:5], v[132:133], 1, s[2:3]
	s_andn2_b64 vcc, exec, s[4:5]
	s_mov_b32 s14, s8
	s_mov_b32 s12, s10
	ds_write_b64 v167, v[2:3] offset:6144
	s_waitcnt lgkmcnt(0)
	ds_read_b128 v[172:175], v168
	ds_read_b128 v[176:179], v168 offset:1024
	ds_read_b128 v[180:183], v168 offset:2048
	ds_read_b128 v[184:187], v168 offset:3072
	ds_read_b128 v[188:191], v168 offset:4096
	ds_read_b128 v[192:195], v168 offset:5120
	ds_read_b128 v[196:199], v168 offset:6144
	ds_read_b128 v[200:203], v168 offset:7168
	v_add_u32_e32 v204, 0x16000, v169
	v_add_u32_e32 v205, 0x2c000, v169
	v_add_u32_e32 v206, 0x42000, v169
	v_add_u32_e32 v207, 0x160000, v169
	v_add_u32_e32 v208, 0x176000, v169
	v_add_u32_e32 v209, 0x18c000, v169
	v_add_u32_e32 v210, 0x1a2000, v169
	s_waitcnt lgkmcnt(7)
	global_store_dwordx4 v169, v[172:175], s[2:3] nt
	s_waitcnt lgkmcnt(6)
	global_store_dwordx4 v204, v[176:179], s[2:3] nt
	s_waitcnt lgkmcnt(5)
	global_store_dwordx4 v205, v[180:183], s[2:3] nt
	s_waitcnt lgkmcnt(4)
	global_store_dwordx4 v206, v[184:187], s[2:3] nt
	s_waitcnt lgkmcnt(3)
	global_store_dwordx4 v207, v[188:191], s[2:3] nt
	s_waitcnt lgkmcnt(2)
	global_store_dwordx4 v208, v[192:195], s[2:3] nt
	s_waitcnt lgkmcnt(1)
	global_store_dwordx4 v209, v[196:199], s[2:3] nt
	s_waitcnt lgkmcnt(0)
	global_store_dwordx4 v210, v[200:203], s[2:3] nt
	s_cbranch_vccz .LBB0_2068

; template <int EPI, int NRM>
; DEVI void epilogue(acc_t& acc, int pn, int trow, const EpiArgs& e, const float* rl, bf16* shmx) {
;     ...
;   if constexpr (EPI == EPI_RESID) {
;     float ss[2][2] = {{0.f, 0.f}, {0.f, 0.f}};
;     __amdgpu_buffer_rsrc_t rsX = __builtin_amdgcn_make_buffer_rsrc((void*)e.xin, 0, 0x7fffffff, 0x00020000);
;     char* lbase = reinterpret_cast<char*>(shmx) + wid * 16384;
;     const int vx = ((tk0 * DM) + pn * 256 + fl0) * 4;
; #pragma unroll
;     for (int ai = 0; ai < 2; ++ai) {
; #pragma unroll
;       for (int bj = 0; bj < 2; ++bj)
; #pragma unroll
;         for (int m = 0; m < 4; ++m)
; #pragma unroll
;           for (int n = 0; n < 2; ++n) {
;             const int idx = (bj * 4 + m) * 2 + n;
;             const int so = ((bj * 128 + n * 16) * DM + ai * 128 + m * 16) * 4;
;             __builtin_amdgcn_raw_ptr_buffer_load_lds(rsX, (__attribute__((address_space(3))) unsigned*)(lbase + idx * 1024 + lane * 16), 16, vx, so, 0, 0);
;           }
;       asm volatile("s_waitcnt vmcnt(0)" ::: "memory");
; #pragma unroll
;       for (int bj = 0; bj < 2; ++bj)
; #pragma unroll
;         for (int m = 0; m < 4; ++m)
; #pragma unroll
;           for (int n = 0; n < 2; ++n) {
;             const int idx = (bj * 4 + m) * 2 + n;
;             const unsigned off = (unsigned)((tk0 + bj * 128 + n * 16) * DM + pn * 256 + ai * 128 + m * 16 + fl0);
;             const float4 xx = *reinterpret_cast<const float4*>(lbase + idx * 1024 + lane * 16);
;             float4 o;
;             o.x = xx.x + acc[ai][bj][m][n][0]; o.y = xx.y + acc[ai][bj][m][n][1];
;             o.z = xx.z + acc[ai][bj][m][n][2]; o.w = xx.w + acc[ai][bj][m][n][3];
;             *reinterpret_cast<float4*>(e.xout + off) = o;
;             uint2 ob; ob.x = pack2(o.x, o.y); ob.y = pack2(o.z, o.w);
;             *reinterpret_cast<uint2*>(e.o0 + off) = ob;
;             ss[bj][n] += o.x * o.x + o.y * o.y + o.z * o.z + o.w * o.w;
;           }
;       asm volatile("s_waitcnt lgkmcnt(0)" ::: "memory");
;     }
; #pragma unroll
;     for (int bj = 0; bj < 2; ++bj)
; #pragma unroll
;       for (int n = 0; n < 2; ++n) {
;         float v = ss[bj][n];
;         v += __shfl_xor(v, 16); v += __shfl_xor(v, 32);
;         if (fq == 0) e.stw[(pn * 2 + wr) * TOK + tk0 + bj * 128 + n * 16] = v;
;       }
;     asm volatile("s_waitcnt lgkmcnt(0)" ::: "memory");
;     __builtin_amdgcn_s_barrier();
.LBB0_2110:
	v_and_b32_e32 v138, 15, v1
	v_bfe_u32 v198, v1, 4, 2
	v_lshrrev_b32_e32 v199, 6, v1
	v_and_b32_e32 v200, 3, v199
	v_lshrrev_b32_e32 v201, 2, v199
	v_lshlrev_b32_e32 v202, 14, v199
	v_and_b32_e32 v203, 63, v1
	v_lshl_add_u32 v143, v203, 4, v202
	v_lshl_add_u32 v202, v138, 8, v202
	v_and_b32_e32 v203, 7, v138
	v_add_u32_e32 v204, 0, v198
	v_xor_b32_e32 v204, v204, v203
	v_lshl_add_u32 v139, v204, 4, v202
	v_add_u32_e32 v204, 4, v198
	v_xor_b32_e32 v204, v204, v203
	v_lshl_add_u32 v140, v204, 4, v202
	v_add_u32_e32 v204, 8, v198
	v_xor_b32_e32 v204, v204, v203
	v_lshl_add_u32 v141, v204, 4, v202
	v_add_u32_e32 v204, 12, v198
	v_xor_b32_e32 v204, v204, v203
	v_lshl_add_u32 v142, v204, 4, v202
	s_lshl_b32 s6, s65, 8
	v_lshl_add_u32 v202, v200, 5, v198
	v_add_u32_e32 v202, s6, v202
	s_lshl_b32 s6, s64, 1
	v_add_u32_e32 v204, s6, v201
	v_lshl_add_u32 v204, v204, 15, v202
	v_lshlrev_b32_e32 v148, 2, v204
	v_lshlrev_b32_e32 v202, 11, v202
	s_lshl_b32 s6, s64, 8
	v_lshl_add_u32 v204, v201, 6, s6
	v_add_u32_e32 v202, v202, v204
	v_add_u32_e32 v203, 0, v198
	v_xor_b32_e32 v203, v203, v138
	v_lshl_add_u32 v203, v203, 2, v202
	v_lshlrev_b32_e32 v144, 2, v203
	v_lshlrev_b32_e32 v146, 1, v203
	v_add_u32_e32 v203, 4, v198
	v_xor_b32_e32 v203, v203, v138
	v_lshl_add_u32 v203, v203, 2, v202
	v_lshlrev_b32_e32 v145, 2, v203
	v_lshlrev_b32_e32 v147, 1, v203
	v_add_u32_e32 v157, 0x0, v144
	global_load_dwordx4 v[166:169], v157, s[4:5] nt
	v_add_u32_e32 v160, 0x8000, v145
	global_load_dwordx4 v[170:173], v160, s[4:5] nt
	v_add_u32_e32 v157, 0x10000, v144
	global_load_dwordx4 v[174:177], v157, s[4:5] nt
	v_add_u32_e32 v160, 0x18000, v145
	global_load_dwordx4 v[178:181], v160, s[4:5] nt
	v_add_u32_e32 v157, 0x20000, v144
	global_load_dwordx4 v[182:185], v157, s[4:5] nt
	v_add_u32_e32 v160, 0x28000, v145
	global_load_dwordx4 v[186:189], v160, s[4:5] nt
	v_add_u32_e32 v157, 0x30000, v144
	global_load_dwordx4 v[190:193], v157, s[4:5] nt
	v_add_u32_e32 v160, 0x38000, v145
	global_load_dwordx4 v[194:197], v160, s[4:5] nt
	v_add_u32_e32 v157, 0x200, v144
	global_load_dwordx4 v[198:201], v157, s[4:5] nt
	v_add_u32_e32 v160, 0x8200, v145
	global_load_dwordx4 v[202:205], v160, s[4:5] nt
	v_add_u32_e32 v157, 0x10200, v144
	global_load_dwordx4 v[206:209], v157, s[4:5] nt
	v_add_u32_e32 v160, 0x18200, v145
	global_load_dwordx4 v[210:213], v160, s[4:5] nt
	v_add_u32_e32 v157, 0x20200, v144
	global_load_dwordx4 v[214:217], v157, s[4:5] nt
	v_add_u32_e32 v160, 0x28200, v145
	global_load_dwordx4 v[218:221], v160, s[4:5] nt
	v_add_u32_e32 v157, 0x30200, v144
	global_load_dwordx4 v[222:225], v157, s[4:5] nt
	v_add_u32_e32 v160, 0x38200, v145
	global_load_dwordx4 v[226:229], v160, s[4:5] nt
	ds_write_b128 v139, v[126:129]
	ds_write_b128 v139, v[30:33] offset:4096
	ds_write_b128 v140, v[122:125]
	ds_write_b128 v140, v[42:45] offset:4096
	ds_write_b128 v141, v[118:121]
	ds_write_b128 v141, v[54:57] offset:4096
	ds_write_b128 v142, v[114:117]
	ds_write_b128 v142, v[70:73] offset:4096
	ds_write_b128 v139, v[106:109] offset:8192
	ds_write_b128 v139, v[102:105] offset:12288
	ds_write_b128 v140, v[90:93] offset:8192
	ds_write_b128 v140, v[86:89] offset:12288
	ds_write_b128 v141, v[74:77] offset:8192
	ds_write_b128 v141, v[62:65] offset:12288
	ds_write_b128 v142, v[46:49] offset:8192
	ds_write_b128 v142, v[38:41] offset:12288
	s_waitcnt lgkmcnt(0)
	ds_read_b128 v[126:129], v143
	ds_read_b128 v[30:33], v143 offset:1024
	ds_read_b128 v[122:125], v143 offset:2048
	ds_read_b128 v[42:45], v143 offset:3072
	ds_read_b128 v[118:121], v143 offset:4096
	ds_read_b128 v[54:57], v143 offset:5120
	ds_read_b128 v[114:117], v143 offset:6144
	ds_read_b128 v[70:73], v143 offset:7168
	ds_read_b128 v[106:109], v143 offset:8192
	ds_read_b128 v[102:105], v143 offset:9216
	ds_read_b128 v[90:93], v143 offset:10240
	ds_read_b128 v[86:89], v143 offset:11264
	ds_read_b128 v[74:77], v143 offset:12288
	ds_read_b128 v[62:65], v143 offset:13312
	ds_read_b128 v[46:49], v143 offset:14336
	ds_read_b128 v[38:41], v143 offset:15360
	s_waitcnt lgkmcnt(0)
	ds_write_b128 v139, v[58:61]
	ds_write_b128 v139, v[50:53] offset:4096
	ds_write_b128 v140, v[78:81]
	ds_write_b128 v140, v[66:69] offset:4096
	ds_write_b128 v141, v[94:97]
	ds_write_b128 v141, v[82:85] offset:4096
	ds_write_b128 v142, v[110:113]
	ds_write_b128 v142, v[98:101] offset:4096
	ds_write_b128 v139, v[34:37] offset:8192
	ds_write_b128 v139, v[26:29] offset:12288
	ds_write_b128 v140, v[22:25] offset:8192
	ds_write_b128 v140, v[18:21] offset:12288
	ds_write_b128 v141, v[14:17] offset:8192
	ds_write_b128 v141, v[10:13] offset:12288
	ds_write_b128 v142, v[6:9] offset:8192
	ds_write_b128 v142, v[2:5] offset:12288
	s_waitcnt vmcnt(15)
	v_pk_add_f32 v[166:167], v[166:167], v[126:127]
	v_pk_add_f32 v[168:169], v[168:169], v[128:129]
	v_add_u32_e32 v157, 0x0, v144
	v_cvt_pk_bf16_f32 v158, v166, v167
	v_cvt_pk_bf16_f32 v159, v168, v169
	global_store_dwordx4 v157, v[166:169], s[26:27] nt
	v_add_u32_e32 v126, 0x0, v146
	v_mul_f32_e32 v149, v166, v166
	global_store_dwordx2 v126, v[158:159], s[96:97]
	v_fmac_f32_e32 v149, v167, v167
	v_fmac_f32_e32 v149, v168, v168
	v_fmac_f32_e32 v149, v169, v169
	s_waitcnt vmcnt(16)
	v_pk_add_f32 v[170:171], v[170:171], v[30:31]
	v_pk_add_f32 v[172:173], v[172:173], v[32:33]
	v_add_u32_e32 v160, 0x8000, v145
	v_cvt_pk_bf16_f32 v164, v170, v171
	v_cvt_pk_bf16_f32 v165, v172, v173
	global_store_dwordx4 v160, v[170:173], s[26:27] nt
	v_add_u32_e32 v30, 0x4000, v147
	v_mul_f32_e32 v150, v170, v170
	global_store_dwordx2 v30, v[164:165], s[96:97]
	v_fmac_f32_e32 v150, v171, v171
	v_fmac_f32_e32 v150, v172, v172
	v_fmac_f32_e32 v150, v173, v173
	s_waitcnt vmcnt(17)
; template <int EPI, int NRM>
; DEVI void epilogue(acc_t& acc, int pn, int trow, const EpiArgs& e, const float* rl, bf16* shmx) {
;     ...
;   if constexpr (EPI == EPI_RESID) {
;     float ss[2][2] = {{0.f, 0.f}, {0.f, 0.f}};
;     __amdgpu_buffer_rsrc_t rsX = __builtin_amdgcn_make_buffer_rsrc((void*)e.xin, 0, 0x7fffffff, 0x00020000);
;     char* lbase = reinterpret_cast<char*>(shmx) + wid * 16384;
;     const int vx = ((tk0 * DM) + pn * 256 + fl0) * 4;
; #pragma unroll
;     for (int ai = 0; ai < 2; ++ai) {
; #pragma unroll
;       for (int bj = 0; bj < 2; ++bj)
; #pragma unroll
;         for (int m = 0; m < 4; ++m)
; #pragma unroll
;           for (int n = 0; n < 2; ++n) {
;             const int idx = (bj * 4 + m) * 2 + n;
;             const int so = ((bj * 128 + n * 16) * DM + ai * 128 + m * 16) * 4;
;             __builtin_amdgcn_raw_ptr_buffer_load_lds(rsX, (__attribute__((address_space(3))) unsigned*)(lbase + idx * 1024 + lane * 16), 16, vx, so, 0, 0);
;           }
;       asm volatile("s_waitcnt vmcnt(0)" ::: "memory");
; #pragma unroll
;       for (int bj = 0; bj < 2; ++bj)
; #pragma unroll
;         for (int m = 0; m < 4; ++m)
; #pragma unroll
;           for (int n = 0; n < 2; ++n) {
;             const int idx = (bj * 4 + m) * 2 + n;
;             const unsigned off = (unsigned)((tk0 + bj * 128 + n * 16) * DM + pn * 256 + ai * 128 + m * 16 + fl0);
;             const float4 xx = *reinterpret_cast<const float4*>(lbase + idx * 1024 + lane * 16);
;             float4 o;
;             o.x = xx.x + acc[ai][bj][m][n][0]; o.y = xx.y + acc[ai][bj][m][n][1];
;             o.z = xx.z + acc[ai][bj][m][n][2]; o.w = xx.w + acc[ai][bj][m][n][3];
;             *reinterpret_cast<float4*>(e.xout + off) = o;
;             uint2 ob; ob.x = pack2(o.x, o.y); ob.y = pack2(o.z, o.w);
;             *reinterpret_cast<uint2*>(e.o0 + off) = ob;
;             ss[bj][n] += o.x * o.x + o.y * o.y + o.z * o.z + o.w * o.w;
;           }
;       asm volatile("s_waitcnt lgkmcnt(0)" ::: "memory");
;     }
; #pragma unroll
;     for (int bj = 0; bj < 2; ++bj)
; #pragma unroll
;       for (int n = 0; n < 2; ++n) {
;         float v = ss[bj][n];
;         v += __shfl_xor(v, 16); v += __shfl_xor(v, 32);
;         if (fq == 0) e.stw[(pn * 2 + wr) * TOK + tk0 + bj * 128 + n * 16] = v;
;       }
;     asm volatile("s_waitcnt lgkmcnt(0)" ::: "memory");
;     __builtin_amdgcn_s_barrier();
	v_pk_add_f32 v[174:175], v[174:175], v[122:123]
	v_pk_add_f32 v[176:177], v[176:177], v[124:125]
	v_add_u32_e32 v157, 0x10000, v144
	v_cvt_pk_bf16_f32 v158, v174, v175
	v_cvt_pk_bf16_f32 v159, v176, v177
	global_store_dwordx4 v157, v[174:177], s[26:27] nt
	v_add_u32_e32 v122, 0x8000, v146
	v_mul_f32_e32 v151, v174, v174
	global_store_dwordx2 v122, v[158:159], s[96:97]
	v_fmac_f32_e32 v151, v175, v175
	v_fmac_f32_e32 v151, v176, v176
	v_fmac_f32_e32 v151, v177, v177
	s_waitcnt vmcnt(18)
	v_pk_add_f32 v[178:179], v[178:179], v[42:43]
	v_pk_add_f32 v[180:181], v[180:181], v[44:45]
	v_add_u32_e32 v160, 0x18000, v145
	v_cvt_pk_bf16_f32 v164, v178, v179
	v_cvt_pk_bf16_f32 v165, v180, v181
	global_store_dwordx4 v160, v[178:181], s[26:27] nt
	v_add_u32_e32 v42, 0xc000, v147
	v_mul_f32_e32 v152, v178, v178
	global_store_dwordx2 v42, v[164:165], s[96:97]
	v_fmac_f32_e32 v152, v179, v179
	v_fmac_f32_e32 v152, v180, v180
	v_fmac_f32_e32 v152, v181, v181
	s_waitcnt vmcnt(19)
	v_pk_add_f32 v[182:183], v[182:183], v[118:119]
	v_pk_add_f32 v[184:185], v[184:185], v[120:121]
	v_add_u32_e32 v157, 0x20000, v144
	v_cvt_pk_bf16_f32 v158, v182, v183
	v_cvt_pk_bf16_f32 v159, v184, v185
	global_store_dwordx4 v157, v[182:185], s[26:27] nt
	v_add_u32_e32 v118, 0x10000, v146
	v_mul_f32_e32 v153, v182, v182
	global_store_dwordx2 v118, v[158:159], s[96:97]
	v_fmac_f32_e32 v153, v183, v183
	v_fmac_f32_e32 v153, v184, v184
	v_fmac_f32_e32 v153, v185, v185
	s_waitcnt vmcnt(20)
	v_pk_add_f32 v[186:187], v[186:187], v[54:55]
	v_pk_add_f32 v[188:189], v[188:189], v[56:57]
	v_add_u32_e32 v160, 0x28000, v145
	v_cvt_pk_bf16_f32 v164, v186, v187
	v_cvt_pk_bf16_f32 v165, v188, v189
	global_store_dwordx4 v160, v[186:189], s[26:27] nt
	v_add_u32_e32 v54, 0x14000, v147
	v_mul_f32_e32 v154, v186, v186
	global_store_dwordx2 v54, v[164:165], s[96:97]
	v_fmac_f32_e32 v154, v187, v187
	v_fmac_f32_e32 v154, v188, v188
	v_fmac_f32_e32 v154, v189, v189
	s_waitcnt vmcnt(21)
	v_pk_add_f32 v[190:191], v[190:191], v[114:115]
	v_pk_add_f32 v[192:193], v[192:193], v[116:117]
	v_add_u32_e32 v157, 0x30000, v144
	v_cvt_pk_bf16_f32 v158, v190, v191
	v_cvt_pk_bf16_f32 v159, v192, v193
	global_store_dwordx4 v157, v[190:193], s[26:27] nt
	v_add_u32_e32 v114, 0x18000, v146
	v_mul_f32_e32 v155, v190, v190
	global_store_dwordx2 v114, v[158:159], s[96:97]
	v_fmac_f32_e32 v155, v191, v191
	v_fmac_f32_e32 v155, v192, v192
	v_fmac_f32_e32 v155, v193, v193
	s_waitcnt vmcnt(22)
	v_pk_add_f32 v[194:195], v[194:195], v[70:71]
	v_pk_add_f32 v[196:197], v[196:197], v[72:73]
	v_add_u32_e32 v160, 0x38000, v145
	v_cvt_pk_bf16_f32 v164, v194, v195
	v_cvt_pk_bf16_f32 v165, v196, v197
	global_store_dwordx4 v160, v[194:197], s[26:27] nt
	v_add_u32_e32 v70, 0x1c000, v147
	v_mul_f32_e32 v156, v194, v194
	global_store_dwordx2 v70, v[164:165], s[96:97]
	v_fmac_f32_e32 v156, v195, v195
	v_fmac_f32_e32 v156, v196, v196
	v_fmac_f32_e32 v156, v197, v197
	v_add_u32_e32 v157, 0x100000, v144
	global_load_dwordx4 v[166:169], v157, s[4:5] nt
	v_add_u32_e32 v160, 0x108000, v145
	global_load_dwordx4 v[170:173], v160, s[4:5] nt
	v_add_u32_e32 v157, 0x110000, v144
	global_load_dwordx4 v[174:177], v157, s[4:5] nt
	v_add_u32_e32 v160, 0x118000, v145
	global_load_dwordx4 v[178:181], v160, s[4:5] nt
	v_add_u32_e32 v157, 0x120000, v144
	global_load_dwordx4 v[182:185], v157, s[4:5] nt
	v_add_u32_e32 v160, 0x128000, v145
	global_load_dwordx4 v[186:189], v160, s[4:5] nt
	v_add_u32_e32 v157, 0x130000, v144
	global_load_dwordx4 v[190:193], v157, s[4:5] nt
	v_add_u32_e32 v160, 0x138000, v145
	global_load_dwordx4 v[194:197], v160, s[4:5] nt
	s_waitcnt vmcnt(31)
	v_pk_add_f32 v[198:199], v[198:199], v[106:107]
	v_pk_add_f32 v[200:201], v[200:201], v[108:109]
	v_add_u32_e32 v157, 0x200, v144
	v_cvt_pk_bf16_f32 v158, v198, v199
	v_cvt_pk_bf16_f32 v159, v200, v201
	global_store_dwordx4 v157, v[198:201], s[26:27] nt
	v_add_u32_e32 v106, 0x100, v146
	v_fmac_f32_e32 v149, v198, v198
	global_store_dwordx2 v106, v[158:159], s[96:97]
	v_fmac_f32_e32 v149, v199, v199
	v_fmac_f32_e32 v149, v200, v200
	v_fmac_f32_e32 v149, v201, v201
	s_waitcnt vmcnt(32)
	v_pk_add_f32 v[202:203], v[202:203], v[102:103]
	v_pk_add_f32 v[204:205], v[204:205], v[104:105]
	v_add_u32_e32 v160, 0x8200, v145
	v_cvt_pk_bf16_f32 v164, v202, v203
	v_cvt_pk_bf16_f32 v165, v204, v205
	global_store_dwordx4 v160, v[202:205], s[26:27] nt
	v_add_u32_e32 v102, 0x4100, v147
	v_fmac_f32_e32 v150, v202, v202
	global_store_dwordx2 v102, v[164:165], s[96:97]
	v_fmac_f32_e32 v150, v203, v203
	v_fmac_f32_e32 v150, v204, v204
	v_fmac_f32_e32 v150, v205, v205
	s_waitcnt vmcnt(33)
	v_pk_add_f32 v[206:207], v[206:207], v[90:91]
	v_pk_add_f32 v[208:209], v[208:209], v[92:93]
	v_add_u32_e32 v157, 0x10200, v144
	v_cvt_pk_bf16_f32 v158, v206, v207
	v_cvt_pk_bf16_f32 v159, v208, v209
	global_store_dwordx4 v157, v[206:209], s[26:27] nt
	v_add_u32_e32 v90, 0x8100, v146
	v_fmac_f32_e32 v151, v206, v206
	global_store_dwordx2 v90, v[158:159], s[96:97]
	v_fmac_f32_e32 v151, v207, v207
	v_fmac_f32_e32 v151, v208, v208
	v_fmac_f32_e32 v151, v209, v209
	s_waitcnt vmcnt(34)
	v_pk_add_f32 v[210:211], v[210:211], v[86:87]
	v_pk_add_f32 v[212:213], v[212:213], v[88:89]
	v_add_u32_e32 v160, 0x18200, v145
	v_cvt_pk_bf16_f32 v164, v210, v211
	v_cvt_pk_bf16_f32 v165, v212, v213
	global_store_dwordx4 v160, v[210:213], s[26:27] nt
	v_add_u32_e32 v86, 0xc100, v147
	v_fmac_f32_e32 v152, v210, v210
	global_store_dwordx2 v86, v[164:165], s[96:97]
	v_fmac_f32_e32 v152, v211, v211
	v_fmac_f32_e32 v152, v212, v212
	v_fmac_f32_e32 v152, v213, v213
	s_waitcnt vmcnt(35)
; template <int EPI, int NRM>
; DEVI void epilogue(acc_t& acc, int pn, int trow, const EpiArgs& e, const float* rl, bf16* shmx) {
;     ...
;   if constexpr (EPI == EPI_RESID) {
;     float ss[2][2] = {{0.f, 0.f}, {0.f, 0.f}};
;     __amdgpu_buffer_rsrc_t rsX = __builtin_amdgcn_make_buffer_rsrc((void*)e.xin, 0, 0x7fffffff, 0x00020000);
;     char* lbase = reinterpret_cast<char*>(shmx) + wid * 16384;
;     const int vx = ((tk0 * DM) + pn * 256 + fl0) * 4;
; #pragma unroll
;     for (int ai = 0; ai < 2; ++ai) {
; #pragma unroll
;       for (int bj = 0; bj < 2; ++bj)
; #pragma unroll
;         for (int m = 0; m < 4; ++m)
; #pragma unroll
;           for (int n = 0; n < 2; ++n) {
;             const int idx = (bj * 4 + m) * 2 + n;
;             const int so = ((bj * 128 + n * 16) * DM + ai * 128 + m * 16) * 4;
;             __builtin_amdgcn_raw_ptr_buffer_load_lds(rsX, (__attribute__((address_space(3))) unsigned*)(lbase + idx * 1024 + lane * 16), 16, vx, so, 0, 0);
;           }
;       asm volatile("s_waitcnt vmcnt(0)" ::: "memory");
; #pragma unroll
;       for (int bj = 0; bj < 2; ++bj)
; #pragma unroll
;         for (int m = 0; m < 4; ++m)
; #pragma unroll
;           for (int n = 0; n < 2; ++n) {
;             const int idx = (bj * 4 + m) * 2 + n;
;             const unsigned off = (unsigned)((tk0 + bj * 128 + n * 16) * DM + pn * 256 + ai * 128 + m * 16 + fl0);
;             const float4 xx = *reinterpret_cast<const float4*>(lbase + idx * 1024 + lane * 16);
;             float4 o;
;             o.x = xx.x + acc[ai][bj][m][n][0]; o.y = xx.y + acc[ai][bj][m][n][1];
;             o.z = xx.z + acc[ai][bj][m][n][2]; o.w = xx.w + acc[ai][bj][m][n][3];
;             *reinterpret_cast<float4*>(e.xout + off) = o;
;             uint2 ob; ob.x = pack2(o.x, o.y); ob.y = pack2(o.z, o.w);
;             *reinterpret_cast<uint2*>(e.o0 + off) = ob;
;             ss[bj][n] += o.x * o.x + o.y * o.y + o.z * o.z + o.w * o.w;
;           }
;       asm volatile("s_waitcnt lgkmcnt(0)" ::: "memory");
;     }
; #pragma unroll
;     for (int bj = 0; bj < 2; ++bj)
; #pragma unroll
;       for (int n = 0; n < 2; ++n) {
;         float v = ss[bj][n];
;         v += __shfl_xor(v, 16); v += __shfl_xor(v, 32);
;         if (fq == 0) e.stw[(pn * 2 + wr) * TOK + tk0 + bj * 128 + n * 16] = v;
;       }
;     asm volatile("s_waitcnt lgkmcnt(0)" ::: "memory");
;     __builtin_amdgcn_s_barrier();
	v_pk_add_f32 v[214:215], v[214:215], v[74:75]
	v_pk_add_f32 v[216:217], v[216:217], v[76:77]
	v_add_u32_e32 v157, 0x20200, v144
	v_cvt_pk_bf16_f32 v158, v214, v215
	v_cvt_pk_bf16_f32 v159, v216, v217
	global_store_dwordx4 v157, v[214:217], s[26:27] nt
	v_add_u32_e32 v74, 0x10100, v146
	v_fmac_f32_e32 v153, v214, v214
	global_store_dwordx2 v74, v[158:159], s[96:97]
	v_fmac_f32_e32 v153, v215, v215
	v_fmac_f32_e32 v153, v216, v216
	v_fmac_f32_e32 v153, v217, v217
	s_waitcnt vmcnt(36)
	v_pk_add_f32 v[218:219], v[218:219], v[62:63]
	v_pk_add_f32 v[220:221], v[220:221], v[64:65]
	v_add_u32_e32 v160, 0x28200, v145
	v_cvt_pk_bf16_f32 v164, v218, v219
	v_cvt_pk_bf16_f32 v165, v220, v221
	global_store_dwordx4 v160, v[218:221], s[26:27] nt
	v_add_u32_e32 v62, 0x14100, v147
	v_fmac_f32_e32 v154, v218, v218
	global_store_dwordx2 v62, v[164:165], s[96:97]
	v_fmac_f32_e32 v154, v219, v219
	v_fmac_f32_e32 v154, v220, v220
	v_fmac_f32_e32 v154, v221, v221
	s_waitcnt vmcnt(37)
	v_pk_add_f32 v[222:223], v[222:223], v[46:47]
	v_pk_add_f32 v[224:225], v[224:225], v[48:49]
	v_add_u32_e32 v157, 0x30200, v144
	v_cvt_pk_bf16_f32 v158, v222, v223
	v_cvt_pk_bf16_f32 v159, v224, v225
	global_store_dwordx4 v157, v[222:225], s[26:27] nt
	v_add_u32_e32 v46, 0x18100, v146
	v_fmac_f32_e32 v155, v222, v222
	global_store_dwordx2 v46, v[158:159], s[96:97]
	v_fmac_f32_e32 v155, v223, v223
	v_fmac_f32_e32 v155, v224, v224
	v_fmac_f32_e32 v155, v225, v225
	s_waitcnt vmcnt(38)
	v_pk_add_f32 v[226:227], v[226:227], v[38:39]
	v_pk_add_f32 v[228:229], v[228:229], v[40:41]
	v_add_u32_e32 v160, 0x38200, v145
	v_cvt_pk_bf16_f32 v164, v226, v227
	v_cvt_pk_bf16_f32 v165, v228, v229
	global_store_dwordx4 v160, v[226:229], s[26:27] nt
	v_add_u32_e32 v38, 0x1c100, v147
	v_fmac_f32_e32 v156, v226, v226
	global_store_dwordx2 v38, v[164:165], s[96:97]
	v_fmac_f32_e32 v156, v227, v227
	v_fmac_f32_e32 v156, v228, v228
	v_fmac_f32_e32 v156, v229, v229
	v_add_u32_e32 v157, 0x100200, v144
	global_load_dwordx4 v[198:201], v157, s[4:5] nt
	v_add_u32_e32 v160, 0x108200, v145
	global_load_dwordx4 v[202:205], v160, s[4:5] nt
	v_add_u32_e32 v157, 0x110200, v144
	global_load_dwordx4 v[206:209], v157, s[4:5] nt
	v_add_u32_e32 v160, 0x118200, v145
	global_load_dwordx4 v[210:213], v160, s[4:5] nt
	v_add_u32_e32 v157, 0x120200, v144
	global_load_dwordx4 v[214:217], v157, s[4:5] nt
	v_add_u32_e32 v160, 0x128200, v145
	global_load_dwordx4 v[218:221], v160, s[4:5] nt
	v_add_u32_e32 v157, 0x130200, v144
	global_load_dwordx4 v[222:225], v157, s[4:5] nt
	v_add_u32_e32 v160, 0x138200, v145
	global_load_dwordx4 v[226:229], v160, s[4:5] nt
	v_add_f32_dpp v149, v149, v149 row_shr:1 row_mask:0xf bank_mask:0xf bound_ctrl:0
	v_add_f32_dpp v150, v150, v150 row_shr:1 row_mask:0xf bank_mask:0xf bound_ctrl:0
	v_add_f32_dpp v151, v151, v151 row_shr:1 row_mask:0xf bank_mask:0xf bound_ctrl:0
	v_add_f32_dpp v152, v152, v152 row_shr:1 row_mask:0xf bank_mask:0xf bound_ctrl:0
	v_add_f32_dpp v153, v153, v153 row_shr:1 row_mask:0xf bank_mask:0xf bound_ctrl:0
	v_add_f32_dpp v154, v154, v154 row_shr:1 row_mask:0xf bank_mask:0xf bound_ctrl:0
	v_add_f32_dpp v155, v155, v155 row_shr:1 row_mask:0xf bank_mask:0xf bound_ctrl:0
	v_add_f32_dpp v156, v156, v156 row_shr:1 row_mask:0xf bank_mask:0xf bound_ctrl:0
	v_add_f32_dpp v149, v149, v149 row_shr:2 row_mask:0xf bank_mask:0xf bound_ctrl:0
	v_add_f32_dpp v150, v150, v150 row_shr:2 row_mask:0xf bank_mask:0xf bound_ctrl:0
	v_add_f32_dpp v151, v151, v151 row_shr:2 row_mask:0xf bank_mask:0xf bound_ctrl:0
	v_add_f32_dpp v152, v152, v152 row_shr:2 row_mask:0xf bank_mask:0xf bound_ctrl:0
	v_add_f32_dpp v153, v153, v153 row_shr:2 row_mask:0xf bank_mask:0xf bound_ctrl:0
	v_add_f32_dpp v154, v154, v154 row_shr:2 row_mask:0xf bank_mask:0xf bound_ctrl:0
	v_add_f32_dpp v155, v155, v155 row_shr:2 row_mask:0xf bank_mask:0xf bound_ctrl:0
	v_add_f32_dpp v156, v156, v156 row_shr:2 row_mask:0xf bank_mask:0xf bound_ctrl:0
	v_add_f32_dpp v149, v149, v149 row_shr:4 row_mask:0xf bank_mask:0xf bound_ctrl:0
	v_add_f32_dpp v150, v150, v150 row_shr:4 row_mask:0xf bank_mask:0xf bound_ctrl:0
	v_add_f32_dpp v151, v151, v151 row_shr:4 row_mask:0xf bank_mask:0xf bound_ctrl:0
	v_add_f32_dpp v152, v152, v152 row_shr:4 row_mask:0xf bank_mask:0xf bound_ctrl:0
	v_add_f32_dpp v153, v153, v153 row_shr:4 row_mask:0xf bank_mask:0xf bound_ctrl:0
	v_add_f32_dpp v154, v154, v154 row_shr:4 row_mask:0xf bank_mask:0xf bound_ctrl:0
	v_add_f32_dpp v155, v155, v155 row_shr:4 row_mask:0xf bank_mask:0xf bound_ctrl:0
	v_add_f32_dpp v156, v156, v156 row_shr:4 row_mask:0xf bank_mask:0xf bound_ctrl:0
	v_add_f32_dpp v149, v149, v149 row_shr:8 row_mask:0xf bank_mask:0xf bound_ctrl:0
	v_add_f32_dpp v150, v150, v150 row_shr:8 row_mask:0xf bank_mask:0xf bound_ctrl:0
	v_add_f32_dpp v151, v151, v151 row_shr:8 row_mask:0xf bank_mask:0xf bound_ctrl:0
	v_add_f32_dpp v152, v152, v152 row_shr:8 row_mask:0xf bank_mask:0xf bound_ctrl:0
	v_add_f32_dpp v153, v153, v153 row_shr:8 row_mask:0xf bank_mask:0xf bound_ctrl:0
	v_add_f32_dpp v154, v154, v154 row_shr:8 row_mask:0xf bank_mask:0xf bound_ctrl:0
	v_add_f32_dpp v155, v155, v155 row_shr:8 row_mask:0xf bank_mask:0xf bound_ctrl:0
	v_add_f32_dpp v156, v156, v156 row_shr:8 row_mask:0xf bank_mask:0xf bound_ctrl:0
	v_cmp_eq_u32_e32 vcc, 15, v138
	s_and_saveexec_b64 s[6:7], vcc
	global_store_dword v148, v149, s[88:89]
	global_store_dword v148, v150, s[88:89] offset:16
	global_store_dword v148, v151, s[88:89] offset:32
	global_store_dword v148, v152, s[88:89] offset:48
	global_store_dword v148, v153, s[88:89] offset:64
	global_store_dword v148, v154, s[88:89] offset:80
	global_store_dword v148, v155, s[88:89] offset:96
	global_store_dword v148, v156, s[88:89] offset:112
	s_or_b64 exec, exec, s[6:7]
	s_waitcnt lgkmcnt(0)
; template <int EPI, int NRM>
; DEVI void epilogue(acc_t& acc, int pn, int trow, const EpiArgs& e, const float* rl, bf16* shmx) {
;     ...
;   if constexpr (EPI == EPI_RESID) {
;     float ss[2][2] = {{0.f, 0.f}, {0.f, 0.f}};
;     __amdgpu_buffer_rsrc_t rsX = __builtin_amdgcn_make_buffer_rsrc((void*)e.xin, 0, 0x7fffffff, 0x00020000);
;     char* lbase = reinterpret_cast<char*>(shmx) + wid * 16384;
;     const int vx = ((tk0 * DM) + pn * 256 + fl0) * 4;
; #pragma unroll
;     for (int ai = 0; ai < 2; ++ai) {
; #pragma unroll
;       for (int bj = 0; bj < 2; ++bj)
; #pragma unroll
;         for (int m = 0; m < 4; ++m)
; #pragma unroll
;           for (int n = 0; n < 2; ++n) {
;             const int idx = (bj * 4 + m) * 2 + n;
;             const int so = ((bj * 128 + n * 16) * DM + ai * 128 + m * 16) * 4;
;             __builtin_amdgcn_raw_ptr_buffer_load_lds(rsX, (__attribute__((address_space(3))) unsigned*)(lbase + idx * 1024 + lane * 16), 16, vx, so, 0, 0);
;           }
;       asm volatile("s_waitcnt vmcnt(0)" ::: "memory");
; #pragma unroll
;       for (int bj = 0; bj < 2; ++bj)
; #pragma unroll
;         for (int m = 0; m < 4; ++m)
; #pragma unroll
;           for (int n = 0; n < 2; ++n) {
;             const int idx = (bj * 4 + m) * 2 + n;
;             const unsigned off = (unsigned)((tk0 + bj * 128 + n * 16) * DM + pn * 256 + ai * 128 + m * 16 + fl0);
;             const float4 xx = *reinterpret_cast<const float4*>(lbase + idx * 1024 + lane * 16);
;             float4 o;
;             o.x = xx.x + acc[ai][bj][m][n][0]; o.y = xx.y + acc[ai][bj][m][n][1];
;             o.z = xx.z + acc[ai][bj][m][n][2]; o.w = xx.w + acc[ai][bj][m][n][3];
;             *reinterpret_cast<float4*>(e.xout + off) = o;
;             uint2 ob; ob.x = pack2(o.x, o.y); ob.y = pack2(o.z, o.w);
;             *reinterpret_cast<uint2*>(e.o0 + off) = ob;
;             ss[bj][n] += o.x * o.x + o.y * o.y + o.z * o.z + o.w * o.w;
;           }
;       asm volatile("s_waitcnt lgkmcnt(0)" ::: "memory");
;     }
; #pragma unroll
;     for (int bj = 0; bj < 2; ++bj)
; #pragma unroll
;       for (int n = 0; n < 2; ++n) {
;         float v = ss[bj][n];
;         v += __shfl_xor(v, 16); v += __shfl_xor(v, 32);
;         if (fq == 0) e.stw[(pn * 2 + wr) * TOK + tk0 + bj * 128 + n * 16] = v;
;       }
;     asm volatile("s_waitcnt lgkmcnt(0)" ::: "memory");
;     __builtin_amdgcn_s_barrier();
	ds_read_b128 v[58:61], v143
	ds_read_b128 v[50:53], v143 offset:1024
	ds_read_b128 v[78:81], v143 offset:2048
	ds_read_b128 v[66:69], v143 offset:3072
	ds_read_b128 v[94:97], v143 offset:4096
	ds_read_b128 v[82:85], v143 offset:5120
	ds_read_b128 v[110:113], v143 offset:6144
	ds_read_b128 v[98:101], v143 offset:7168
	ds_read_b128 v[34:37], v143 offset:8192
	ds_read_b128 v[26:29], v143 offset:9216
	ds_read_b128 v[22:25], v143 offset:10240
	ds_read_b128 v[18:21], v143 offset:11264
	ds_read_b128 v[14:17], v143 offset:12288
	ds_read_b128 v[10:13], v143 offset:13312
	ds_read_b128 v[6:9], v143 offset:14336
	ds_read_b128 v[2:5], v143 offset:15360
	s_waitcnt lgkmcnt(0)
	s_waitcnt vmcnt(39)
	v_pk_add_f32 v[166:167], v[166:167], v[58:59]
	v_pk_add_f32 v[168:169], v[168:169], v[60:61]
	v_add_u32_e32 v157, 0x100000, v144
	v_cvt_pk_bf16_f32 v158, v166, v167
	v_cvt_pk_bf16_f32 v159, v168, v169
	global_store_dwordx4 v157, v[166:169], s[26:27] nt
	v_add_u32_e32 v58, 0x80000, v146
	v_mul_f32_e32 v149, v166, v166
	global_store_dwordx2 v58, v[158:159], s[96:97]
	v_fmac_f32_e32 v149, v167, v167
	v_fmac_f32_e32 v149, v168, v168
	v_fmac_f32_e32 v149, v169, v169
	s_waitcnt vmcnt(40)
	v_pk_add_f32 v[170:171], v[170:171], v[50:51]
	v_pk_add_f32 v[172:173], v[172:173], v[52:53]
	v_add_u32_e32 v160, 0x108000, v145
	v_cvt_pk_bf16_f32 v164, v170, v171
	v_cvt_pk_bf16_f32 v165, v172, v173
	global_store_dwordx4 v160, v[170:173], s[26:27] nt
	v_add_u32_e32 v50, 0x84000, v147
	v_mul_f32_e32 v150, v170, v170
	global_store_dwordx2 v50, v[164:165], s[96:97]
	v_fmac_f32_e32 v150, v171, v171
	v_fmac_f32_e32 v150, v172, v172
	v_fmac_f32_e32 v150, v173, v173
	s_waitcnt vmcnt(41)
	v_pk_add_f32 v[174:175], v[174:175], v[78:79]
	v_pk_add_f32 v[176:177], v[176:177], v[80:81]
	v_add_u32_e32 v157, 0x110000, v144
	v_cvt_pk_bf16_f32 v158, v174, v175
	v_cvt_pk_bf16_f32 v159, v176, v177
	global_store_dwordx4 v157, v[174:177], s[26:27] nt
	v_add_u32_e32 v78, 0x88000, v146
	v_mul_f32_e32 v151, v174, v174
	global_store_dwordx2 v78, v[158:159], s[96:97]
	v_fmac_f32_e32 v151, v175, v175
	v_fmac_f32_e32 v151, v176, v176
	v_fmac_f32_e32 v151, v177, v177
	s_waitcnt vmcnt(42)
	v_pk_add_f32 v[178:179], v[178:179], v[66:67]
	v_pk_add_f32 v[180:181], v[180:181], v[68:69]
	v_add_u32_e32 v160, 0x118000, v145
	v_cvt_pk_bf16_f32 v164, v178, v179
	v_cvt_pk_bf16_f32 v165, v180, v181
	global_store_dwordx4 v160, v[178:181], s[26:27] nt
	v_add_u32_e32 v66, 0x8c000, v147
	v_mul_f32_e32 v152, v178, v178
	global_store_dwordx2 v66, v[164:165], s[96:97]
	v_fmac_f32_e32 v152, v179, v179
	v_fmac_f32_e32 v152, v180, v180
	v_fmac_f32_e32 v152, v181, v181
	s_waitcnt vmcnt(43)
	v_pk_add_f32 v[182:183], v[182:183], v[94:95]
	v_pk_add_f32 v[184:185], v[184:185], v[96:97]
	v_add_u32_e32 v157, 0x120000, v144
	v_cvt_pk_bf16_f32 v158, v182, v183
	v_cvt_pk_bf16_f32 v159, v184, v185
	global_store_dwordx4 v157, v[182:185], s[26:27] nt
	v_add_u32_e32 v94, 0x90000, v146
	v_mul_f32_e32 v153, v182, v182
	global_store_dwordx2 v94, v[158:159], s[96:97]
	v_fmac_f32_e32 v153, v183, v183
	v_fmac_f32_e32 v153, v184, v184
	v_fmac_f32_e32 v153, v185, v185
	s_waitcnt vmcnt(44)
	v_pk_add_f32 v[186:187], v[186:187], v[82:83]
	v_pk_add_f32 v[188:189], v[188:189], v[84:85]
	v_add_u32_e32 v160, 0x128000, v145
	v_cvt_pk_bf16_f32 v164, v186, v187
	v_cvt_pk_bf16_f32 v165, v188, v189
	global_store_dwordx4 v160, v[186:189], s[26:27] nt
	v_add_u32_e32 v82, 0x94000, v147
	v_mul_f32_e32 v154, v186, v186
	global_store_dwordx2 v82, v[164:165], s[96:97]
	v_fmac_f32_e32 v154, v187, v187
	v_fmac_f32_e32 v154, v188, v188
	v_fmac_f32_e32 v154, v189, v189
	s_waitcnt vmcnt(45)
	v_pk_add_f32 v[190:191], v[190:191], v[110:111]
	v_pk_add_f32 v[192:193], v[192:193], v[112:113]
	v_add_u32_e32 v157, 0x130000, v144
	v_cvt_pk_bf16_f32 v158, v190, v191
	v_cvt_pk_bf16_f32 v159, v192, v193
	global_store_dwordx4 v157, v[190:193], s[26:27] nt
	v_add_u32_e32 v110, 0x98000, v146
	v_mul_f32_e32 v155, v190, v190
	global_store_dwordx2 v110, v[158:159], s[96:97]
	v_fmac_f32_e32 v155, v191, v191
	v_fmac_f32_e32 v155, v192, v192
	v_fmac_f32_e32 v155, v193, v193
	s_waitcnt vmcnt(46)
	v_pk_add_f32 v[194:195], v[194:195], v[98:99]
	v_pk_add_f32 v[196:197], v[196:197], v[100:101]
	v_add_u32_e32 v160, 0x138000, v145
	v_cvt_pk_bf16_f32 v164, v194, v195
	v_cvt_pk_bf16_f32 v165, v196, v197
	global_store_dwordx4 v160, v[194:197], s[26:27] nt
	v_add_u32_e32 v98, 0x9c000, v147
	v_mul_f32_e32 v156, v194, v194
	global_store_dwordx2 v98, v[164:165], s[96:97]
	v_fmac_f32_e32 v156, v195, v195
	v_fmac_f32_e32 v156, v196, v196
	v_fmac_f32_e32 v156, v197, v197
	s_waitcnt vmcnt(31)
	v_pk_add_f32 v[198:199], v[198:199], v[34:35]
	v_pk_add_f32 v[200:201], v[200:201], v[36:37]
	v_add_u32_e32 v157, 0x100200, v144
	v_cvt_pk_bf16_f32 v158, v198, v199
	v_cvt_pk_bf16_f32 v159, v200, v201
	global_store_dwordx4 v157, v[198:201], s[26:27] nt
	v_add_u32_e32 v34, 0x80100, v146
	v_fmac_f32_e32 v149, v198, v198
	global_store_dwordx2 v34, v[158:159], s[96:97]
	v_fmac_f32_e32 v149, v199, v199
	v_fmac_f32_e32 v149, v200, v200
	v_fmac_f32_e32 v149, v201, v201
	s_waitcnt vmcnt(32)
	v_pk_add_f32 v[202:203], v[202:203], v[26:27]
	v_pk_add_f32 v[204:205], v[204:205], v[28:29]
	v_add_u32_e32 v160, 0x108200, v145
	v_cvt_pk_bf16_f32 v164, v202, v203
	v_cvt_pk_bf16_f32 v165, v204, v205
	global_store_dwordx4 v160, v[202:205], s[26:27] nt
	v_add_u32_e32 v26, 0x84100, v147
	v_fmac_f32_e32 v150, v202, v202
	global_store_dwordx2 v26, v[164:165], s[96:97]
	v_fmac_f32_e32 v150, v203, v203
	v_fmac_f32_e32 v150, v204, v204
	v_fmac_f32_e32 v150, v205, v205
	s_waitcnt vmcnt(33)
; template <int EPI, int NRM>
; DEVI void epilogue(acc_t& acc, int pn, int trow, const EpiArgs& e, const float* rl, bf16* shmx) {
;     ...
;   if constexpr (EPI == EPI_RESID) {
;     float ss[2][2] = {{0.f, 0.f}, {0.f, 0.f}};
;     __amdgpu_buffer_rsrc_t rsX = __builtin_amdgcn_make_buffer_rsrc((void*)e.xin, 0, 0x7fffffff, 0x00020000);
;     char* lbase = reinterpret_cast<char*>(shmx) + wid * 16384;
;     const int vx = ((tk0 * DM) + pn * 256 + fl0) * 4;
; #pragma unroll
;     for (int ai = 0; ai < 2; ++ai) {
; #pragma unroll
;       for (int bj = 0; bj < 2; ++bj)
; #pragma unroll
;         for (int m = 0; m < 4; ++m)
; #pragma unroll
;           for (int n = 0; n < 2; ++n) {
;             const int idx = (bj * 4 + m) * 2 + n;
;             const int so = ((bj * 128 + n * 16) * DM + ai * 128 + m * 16) * 4;
;             __builtin_amdgcn_raw_ptr_buffer_load_lds(rsX, (__attribute__((address_space(3))) unsigned*)(lbase + idx * 1024 + lane * 16), 16, vx, so, 0, 0);
;           }
;       asm volatile("s_waitcnt vmcnt(0)" ::: "memory");
; #pragma unroll
;       for (int bj = 0; bj < 2; ++bj)
; #pragma unroll
;         for (int m = 0; m < 4; ++m)
; #pragma unroll
;           for (int n = 0; n < 2; ++n) {
;             const int idx = (bj * 4 + m) * 2 + n;
;             const unsigned off = (unsigned)((tk0 + bj * 128 + n * 16) * DM + pn * 256 + ai * 128 + m * 16 + fl0);
;             const float4 xx = *reinterpret_cast<const float4*>(lbase + idx * 1024 + lane * 16);
;             float4 o;
;             o.x = xx.x + acc[ai][bj][m][n][0]; o.y = xx.y + acc[ai][bj][m][n][1];
;             o.z = xx.z + acc[ai][bj][m][n][2]; o.w = xx.w + acc[ai][bj][m][n][3];
;             *reinterpret_cast<float4*>(e.xout + off) = o;
;             uint2 ob; ob.x = pack2(o.x, o.y); ob.y = pack2(o.z, o.w);
;             *reinterpret_cast<uint2*>(e.o0 + off) = ob;
;             ss[bj][n] += o.x * o.x + o.y * o.y + o.z * o.z + o.w * o.w;
;           }
;       asm volatile("s_waitcnt lgkmcnt(0)" ::: "memory");
;     }
; #pragma unroll
;     for (int bj = 0; bj < 2; ++bj)
; #pragma unroll
;       for (int n = 0; n < 2; ++n) {
;         float v = ss[bj][n];
;         v += __shfl_xor(v, 16); v += __shfl_xor(v, 32);
;         if (fq == 0) e.stw[(pn * 2 + wr) * TOK + tk0 + bj * 128 + n * 16] = v;
;       }
;     asm volatile("s_waitcnt lgkmcnt(0)" ::: "memory");
;     __builtin_amdgcn_s_barrier();
	v_pk_add_f32 v[206:207], v[206:207], v[22:23]
	v_pk_add_f32 v[208:209], v[208:209], v[24:25]
	v_add_u32_e32 v157, 0x110200, v144
	v_cvt_pk_bf16_f32 v158, v206, v207
	v_cvt_pk_bf16_f32 v159, v208, v209
	global_store_dwordx4 v157, v[206:209], s[26:27] nt
	v_add_u32_e32 v22, 0x88100, v146
	v_fmac_f32_e32 v151, v206, v206
	global_store_dwordx2 v22, v[158:159], s[96:97]
	v_fmac_f32_e32 v151, v207, v207
	v_fmac_f32_e32 v151, v208, v208
	v_fmac_f32_e32 v151, v209, v209
	s_waitcnt vmcnt(34)
	v_pk_add_f32 v[210:211], v[210:211], v[18:19]
	v_pk_add_f32 v[212:213], v[212:213], v[20:21]
	v_add_u32_e32 v160, 0x118200, v145
	v_cvt_pk_bf16_f32 v164, v210, v211
	v_cvt_pk_bf16_f32 v165, v212, v213
	global_store_dwordx4 v160, v[210:213], s[26:27] nt
	v_add_u32_e32 v18, 0x8c100, v147
	v_fmac_f32_e32 v152, v210, v210
	global_store_dwordx2 v18, v[164:165], s[96:97]
	v_fmac_f32_e32 v152, v211, v211
	v_fmac_f32_e32 v152, v212, v212
	v_fmac_f32_e32 v152, v213, v213
	s_waitcnt vmcnt(35)
	v_pk_add_f32 v[214:215], v[214:215], v[14:15]
	v_pk_add_f32 v[216:217], v[216:217], v[16:17]
	v_add_u32_e32 v157, 0x120200, v144
	v_cvt_pk_bf16_f32 v158, v214, v215
	v_cvt_pk_bf16_f32 v159, v216, v217
	global_store_dwordx4 v157, v[214:217], s[26:27] nt
	v_add_u32_e32 v14, 0x90100, v146
	v_fmac_f32_e32 v153, v214, v214
	global_store_dwordx2 v14, v[158:159], s[96:97]
	v_fmac_f32_e32 v153, v215, v215
	v_fmac_f32_e32 v153, v216, v216
	v_fmac_f32_e32 v153, v217, v217
	s_waitcnt vmcnt(36)
	v_pk_add_f32 v[218:219], v[218:219], v[10:11]
	v_pk_add_f32 v[220:221], v[220:221], v[12:13]
	v_add_u32_e32 v160, 0x128200, v145
	v_cvt_pk_bf16_f32 v164, v218, v219
	v_cvt_pk_bf16_f32 v165, v220, v221
	global_store_dwordx4 v160, v[218:221], s[26:27] nt
	v_add_u32_e32 v10, 0x94100, v147
	v_fmac_f32_e32 v154, v218, v218
	global_store_dwordx2 v10, v[164:165], s[96:97]
	v_fmac_f32_e32 v154, v219, v219
	v_fmac_f32_e32 v154, v220, v220
	v_fmac_f32_e32 v154, v221, v221
	s_waitcnt vmcnt(37)
	v_pk_add_f32 v[222:223], v[222:223], v[6:7]
	v_pk_add_f32 v[224:225], v[224:225], v[8:9]
	v_add_u32_e32 v157, 0x130200, v144
	v_cvt_pk_bf16_f32 v158, v222, v223
	v_cvt_pk_bf16_f32 v159, v224, v225
	global_store_dwordx4 v157, v[222:225], s[26:27] nt
	v_add_u32_e32 v6, 0x98100, v146
	v_fmac_f32_e32 v155, v222, v222
	global_store_dwordx2 v6, v[158:159], s[96:97]
	v_fmac_f32_e32 v155, v223, v223
	v_fmac_f32_e32 v155, v224, v224
	v_fmac_f32_e32 v155, v225, v225
	s_waitcnt vmcnt(38)
	v_pk_add_f32 v[226:227], v[226:227], v[2:3]
	v_pk_add_f32 v[228:229], v[228:229], v[4:5]
	v_add_u32_e32 v160, 0x138200, v145
	v_cvt_pk_bf16_f32 v164, v226, v227
	v_cvt_pk_bf16_f32 v165, v228, v229
	global_store_dwordx4 v160, v[226:229], s[26:27] nt
	v_add_u32_e32 v2, 0x9c100, v147
	v_fmac_f32_e32 v156, v226, v226
	global_store_dwordx2 v2, v[164:165], s[96:97]
	v_fmac_f32_e32 v156, v227, v227
	v_fmac_f32_e32 v156, v228, v228
	v_fmac_f32_e32 v156, v229, v229
	v_add_f32_dpp v149, v149, v149 row_shr:1 row_mask:0xf bank_mask:0xf bound_ctrl:0
	v_add_f32_dpp v150, v150, v150 row_shr:1 row_mask:0xf bank_mask:0xf bound_ctrl:0
	v_add_f32_dpp v151, v151, v151 row_shr:1 row_mask:0xf bank_mask:0xf bound_ctrl:0
	v_add_f32_dpp v152, v152, v152 row_shr:1 row_mask:0xf bank_mask:0xf bound_ctrl:0
	v_add_f32_dpp v153, v153, v153 row_shr:1 row_mask:0xf bank_mask:0xf bound_ctrl:0
	v_add_f32_dpp v154, v154, v154 row_shr:1 row_mask:0xf bank_mask:0xf bound_ctrl:0
	v_add_f32_dpp v155, v155, v155 row_shr:1 row_mask:0xf bank_mask:0xf bound_ctrl:0
	v_add_f32_dpp v156, v156, v156 row_shr:1 row_mask:0xf bank_mask:0xf bound_ctrl:0
	v_add_f32_dpp v149, v149, v149 row_shr:2 row_mask:0xf bank_mask:0xf bound_ctrl:0
	v_add_f32_dpp v150, v150, v150 row_shr:2 row_mask:0xf bank_mask:0xf bound_ctrl:0
	v_add_f32_dpp v151, v151, v151 row_shr:2 row_mask:0xf bank_mask:0xf bound_ctrl:0
	v_add_f32_dpp v152, v152, v152 row_shr:2 row_mask:0xf bank_mask:0xf bound_ctrl:0
	v_add_f32_dpp v153, v153, v153 row_shr:2 row_mask:0xf bank_mask:0xf bound_ctrl:0
	v_add_f32_dpp v154, v154, v154 row_shr:2 row_mask:0xf bank_mask:0xf bound_ctrl:0
	v_add_f32_dpp v155, v155, v155 row_shr:2 row_mask:0xf bank_mask:0xf bound_ctrl:0
	v_add_f32_dpp v156, v156, v156 row_shr:2 row_mask:0xf bank_mask:0xf bound_ctrl:0
	v_add_f32_dpp v149, v149, v149 row_shr:4 row_mask:0xf bank_mask:0xf bound_ctrl:0
	v_add_f32_dpp v150, v150, v150 row_shr:4 row_mask:0xf bank_mask:0xf bound_ctrl:0
	v_add_f32_dpp v151, v151, v151 row_shr:4 row_mask:0xf bank_mask:0xf bound_ctrl:0
	v_add_f32_dpp v152, v152, v152 row_shr:4 row_mask:0xf bank_mask:0xf bound_ctrl:0
	v_add_f32_dpp v153, v153, v153 row_shr:4 row_mask:0xf bank_mask:0xf bound_ctrl:0
	v_add_f32_dpp v154, v154, v154 row_shr:4 row_mask:0xf bank_mask:0xf bound_ctrl:0
	v_add_f32_dpp v155, v155, v155 row_shr:4 row_mask:0xf bank_mask:0xf bound_ctrl:0
	v_add_f32_dpp v156, v156, v156 row_shr:4 row_mask:0xf bank_mask:0xf bound_ctrl:0
	v_add_f32_dpp v149, v149, v149 row_shr:8 row_mask:0xf bank_mask:0xf bound_ctrl:0
	v_add_f32_dpp v150, v150, v150 row_shr:8 row_mask:0xf bank_mask:0xf bound_ctrl:0
	v_add_f32_dpp v151, v151, v151 row_shr:8 row_mask:0xf bank_mask:0xf bound_ctrl:0
	v_add_f32_dpp v152, v152, v152 row_shr:8 row_mask:0xf bank_mask:0xf bound_ctrl:0
	v_add_f32_dpp v153, v153, v153 row_shr:8 row_mask:0xf bank_mask:0xf bound_ctrl:0
	v_add_f32_dpp v154, v154, v154 row_shr:8 row_mask:0xf bank_mask:0xf bound_ctrl:0
	v_add_f32_dpp v155, v155, v155 row_shr:8 row_mask:0xf bank_mask:0xf bound_ctrl:0
	v_add_f32_dpp v156, v156, v156 row_shr:8 row_mask:0xf bank_mask:0xf bound_ctrl:0
	v_cmp_eq_u32_e32 vcc, 15, v138
	s_and_saveexec_b64 s[6:7], vcc
	global_store_dword v148, v149, s[88:89] offset:512
	global_store_dword v148, v150, s[88:89] offset:528
	global_store_dword v148, v151, s[88:89] offset:544
	global_store_dword v148, v152, s[88:89] offset:560
	global_store_dword v148, v153, s[88:89] offset:576
	global_store_dword v148, v154, s[88:89] offset:592
	global_store_dword v148, v155, s[88:89] offset:608
	global_store_dword v148, v156, s[88:89] offset:624
	s_branch .LBB0_2097
